# epilogue: the leading half's align barrier moved down to its first store, so its register-only epilogue work runs under the lagging half's last MFMA segment; on top of v61
# speedup vs baseline: 1.0038x; 1.0038x over previous
; #define PG8_STAGE(bufoff, gbase, voff) do { _Pragma("unroll") for (int _i = 0; _i < 2; ++_i) \
;         __builtin_amdgcn_global_load_lds((const unsigned*)((const char*)(gbase) + (voff)[_i]), (LAS unsigned*)(lds + (bufoff) + ldsw + _i * 8192), 16, 0, 0); } while (0)
; #define PG8_LDA(dst, b, h) do { _Pragma("unroll") for (int m = 0; m < 4; ++m) _Pragma("unroll") for (int k = 0; k < 2; ++k) dst[m][k] = *(const LAS bf16x8*)(lds + PG8_SA(b, h) + aoff + m * 2048 + k * 1024); } while (0)
; #define PG8_LDB(dst, b, h) do { _Pragma("unroll") for (int n = 0; n < 2; ++n) _Pragma("unroll") for (int k = 0; k < 2; ++k) dst[n][k] = *(const LAS bf16x8*)(lds + PG8_SB(b, h) + boff + n * 2048 + k * 1024); } while (0)
; #define PG8_MMA(ai, bj, At, Bt) do { __builtin_amdgcn_s_setprio(1); _Pragma("unroll") for (int m = 0; m < 4; ++m) _Pragma("unroll") for (int n = 0; n < 2; ++n) _Pragma("unroll") for (int k = 0; k < 2; ++k) \
;         acc[ai][bj][m][n] = __builtin_amdgcn_mfma_f32_16x16x32_bf16(Bt[n][k], At[m][k], acc[ai][bj][m][n], 0, 0, 0); __builtin_amdgcn_s_setprio(0); } while (0)
; #define PG8_WAIT_V(n) asm volatile("s_waitcnt vmcnt(" #n ")" ::: "memory")
; template <class Epi, class Sched, bool ABLK = false, bool ALIGN_EPI = true, bool SP2 = true, bool BBLK = true>
; __device__ __forceinline__ void gemm_phase(LAS unsigned char* lds, const Gemm g, const Sched& S, const Epi& E) {
;     ...
;         for (int t = 0; t < nt; t += 2) {
;             const bool last = (t == nt - 2);
;             const char* a1 = a_tile(uA, tbA + t + 1);
;             const char* a2 = last ? a_tile(nuA, ntbA) : a_tile(uA, tbA + t + 2); const char* b2 = last ? nB : cB + (size_t)(t + 2) * kstepB;
;             const char* a3 = last ? a_tile(nuA, ntbA + 1) : a_tile(uA, tbA + t + 3); const char* b3 = b2 + kstepB;
;             if (last && has_next) S.a_ready(nxt);
;             if constexpr (SP2) {
;             PG8_LDB(B0, 0, 0); PG8_LDB(B1, 0, 1); PG8_SCHED; PG8_LDA(At, 0, 0); PG8_STAGE(PG8_SA(1, 1), a1 + hstepA, voffA);
;             PG8_WAIT_V(8); PG8_WAIT_L(0); PG8_BAR; PG8_MMA(0, 0, At, B0); PG8_MMA(0, 1, At, B1); PG8_BAR; PG8_SCHED;
;             PG8_LDA(At, 0, 1); PG8_STAGE(PG8_SB(0, 0), b2, voffB); PG8_STAGE(PG8_SB(0, 1), b2 + hstepB, voffB); PG8_STAGE(PG8_SA(0, 0), a2, voffA);
;             PG8_WAIT_V(8); PG8_WAIT_L(0); PG8_BAR; PG8_MMA(1, 0, At, B0); PG8_MMA(1, 1, At, B1); PG8_BAR; PG8_SCHED;
.LBB0_475:
	ds_read_b128 v[172:175], v168
	ds_read_b128 v[176:179], v168 offset:1024
	ds_read_b128 v[180:183], v168 offset:2048
	ds_read_b128 v[184:187], v168 offset:3072
	ds_read_b128 v[188:191], v169
	ds_read_b128 v[192:195], v169 offset:1024
	ds_read_b128 v[196:199], v169 offset:2048
	ds_read_b128 v[200:203], v169 offset:3072
	s_add_u32 s30, s26, s28
	s_addc_u32 s31, s27, s29
	s_add_u32 s36, s30, 0x100
	s_addc_u32 s37, s31, 0
	s_add_u32 s30, s30, 0x180
	s_addc_u32 s31, s31, 0
	s_cmpk_eq_i32 s28, 0xf00
	s_cselect_b32 s31, s57, s31
	s_cselect_b32 s30, s23, s30
	s_cselect_b32 s35, s11, s59
	s_cselect_b32 s34, s13, s58
	s_cselect_b32 s37, s4, s37
	s_cselect_b32 s36, s5, s36
	s_mov_b32 m0, s53
	v_lshl_add_u64 v[236:237], v[164:165], 0, s[28:29]
	ds_read_b128 v[204:207], v170
	ds_read_b128 v[208:211], v170 offset:1024
	ds_read_b128 v[212:215], v170 offset:2048
	ds_read_b128 v[216:219], v170 offset:3072
	ds_read_b128 v[220:223], v170 offset:4096
	ds_read_b128 v[224:227], v170 offset:5120
	ds_read_b128 v[228:231], v170 offset:6144
	ds_read_b128 v[232:235], v170 offset:7168
	global_load_lds_dwordx4 v[236:237], off
	v_lshl_add_u64 v[236:237], v[166:167], 0, s[28:29]
	s_mov_b32 m0, s54
	s_nop 0
	global_load_lds_dwordx4 v[236:237], off
	s_waitcnt vmcnt(8) lgkmcnt(0)
	s_barrier
	v_mfma_f32_16x16x32_bf16 v[126:129], v[172:175], v[204:207], v[126:129]
	v_mfma_f32_16x16x32_bf16 v[122:125], v[180:183], v[204:207], v[122:125]
	v_mfma_f32_16x16x32_bf16 v[110:113], v[172:175], v[212:215], v[110:113]
	v_mfma_f32_16x16x32_bf16 v[106:109], v[180:183], v[212:215], v[106:109]
	v_mfma_f32_16x16x32_bf16 v[94:97], v[172:175], v[220:223], v[94:97]
	v_mfma_f32_16x16x32_bf16 v[90:93], v[180:183], v[220:223], v[90:93]
	v_mfma_f32_16x16x32_bf16 v[78:81], v[172:175], v[228:231], v[78:81]
	v_mfma_f32_16x16x32_bf16 v[74:77], v[180:183], v[228:231], v[74:77]
	v_mfma_f32_16x16x32_bf16 v[126:129], v[176:179], v[208:211], v[126:129]
	v_mfma_f32_16x16x32_bf16 v[122:125], v[184:187], v[208:211], v[122:125]
	v_mfma_f32_16x16x32_bf16 v[110:113], v[176:179], v[216:219], v[110:113]
	v_mfma_f32_16x16x32_bf16 v[106:109], v[184:187], v[216:219], v[106:109]
	v_mfma_f32_16x16x32_bf16 v[94:97], v[176:179], v[224:227], v[94:97]
	v_mfma_f32_16x16x32_bf16 v[90:93], v[184:187], v[224:227], v[90:93]
	v_mfma_f32_16x16x32_bf16 v[78:81], v[176:179], v[232:235], v[78:81]
	v_mfma_f32_16x16x32_bf16 v[74:77], v[184:187], v[232:235], v[74:77]
	v_mfma_f32_16x16x32_bf16 v[118:121], v[188:191], v[204:207], v[118:121]
	v_mfma_f32_16x16x32_bf16 v[114:117], v[196:199], v[204:207], v[114:117]
	v_mfma_f32_16x16x32_bf16 v[102:105], v[188:191], v[212:215], v[102:105]
	v_mfma_f32_16x16x32_bf16 v[98:101], v[196:199], v[212:215], v[98:101]
	v_mfma_f32_16x16x32_bf16 v[86:89], v[188:191], v[220:223], v[86:89]
	v_mfma_f32_16x16x32_bf16 v[82:85], v[196:199], v[220:223], v[82:85]
	v_mfma_f32_16x16x32_bf16 v[70:73], v[188:191], v[228:231], v[70:73]
	v_mfma_f32_16x16x32_bf16 v[66:69], v[196:199], v[228:231], v[66:69]
	v_mfma_f32_16x16x32_bf16 v[118:121], v[192:195], v[208:211], v[118:121]
	v_mfma_f32_16x16x32_bf16 v[114:117], v[200:203], v[208:211], v[114:117]
	v_mfma_f32_16x16x32_bf16 v[102:105], v[192:195], v[216:219], v[102:105]
	v_mfma_f32_16x16x32_bf16 v[98:101], v[200:203], v[216:219], v[98:101]
	v_mfma_f32_16x16x32_bf16 v[86:89], v[192:195], v[224:227], v[86:89]
	v_mfma_f32_16x16x32_bf16 v[82:85], v[200:203], v[224:227], v[82:85]
	v_mfma_f32_16x16x32_bf16 v[70:73], v[192:195], v[232:235], v[70:73]
	v_mfma_f32_16x16x32_bf16 v[66:69], v[200:203], v[232:235], v[66:69]
	s_barrier
	s_mov_b32 m0, s55
	s_add_u32 s62, s34, 0x4000
	ds_read_b128 v[204:207], v170 offset:16384
	ds_read_b128 v[208:211], v170 offset:17408
	ds_read_b128 v[212:215], v170 offset:18432
	ds_read_b128 v[216:219], v170 offset:19456
	ds_read_b128 v[220:223], v170 offset:20480
	ds_read_b128 v[224:227], v170 offset:21504
	ds_read_b128 v[228:231], v170 offset:22528
	ds_read_b128 v[232:235], v170 offset:23552
	global_load_lds_dwordx4 v134, s[34:35]
	s_mov_b32 m0, s56
	s_addc_u32 s63, s35, 0
	s_add_i32 s61, s52, s40
	global_load_lds_dwordx4 v130, s[34:35]
	s_mov_b32 m0, s61
	s_nop 0
	global_load_lds_dwordx4 v134, s[62:63]
	s_add_i32 m0, s61, 0x2000
	s_nop 0
	global_load_lds_dwordx4 v130, s[62:63]
	s_mov_b32 m0, s25
	s_nop 0
	global_load_lds_dwordx4 v136, s[36:37]
	s_mov_b32 m0, s43
	s_nop 0
	global_load_lds_dwordx4 v132, s[36:37]
	s_waitcnt vmcnt(8) lgkmcnt(0)
	s_barrier
	v_mfma_f32_16x16x32_bf16 v[62:65], v[172:175], v[204:207], v[62:65]
	v_mfma_f32_16x16x32_bf16 v[58:61], v[180:183], v[204:207], v[58:61]
	v_mfma_f32_16x16x32_bf16 v[46:49], v[172:175], v[212:215], v[46:49]
	v_mfma_f32_16x16x32_bf16 v[42:45], v[180:183], v[212:215], v[42:45]
	v_mfma_f32_16x16x32_bf16 v[30:33], v[172:175], v[220:223], v[30:33]
	v_mfma_f32_16x16x32_bf16 v[26:29], v[180:183], v[220:223], v[26:29]
	v_mfma_f32_16x16x32_bf16 v[14:17], v[172:175], v[228:231], v[14:17]
	v_mfma_f32_16x16x32_bf16 v[10:13], v[180:183], v[228:231], v[10:13]
	v_mfma_f32_16x16x32_bf16 v[62:65], v[176:179], v[208:211], v[62:65]
	v_mfma_f32_16x16x32_bf16 v[58:61], v[184:187], v[208:211], v[58:61]
	v_mfma_f32_16x16x32_bf16 v[46:49], v[176:179], v[216:219], v[46:49]
	v_mfma_f32_16x16x32_bf16 v[42:45], v[184:187], v[216:219], v[42:45]
	v_mfma_f32_16x16x32_bf16 v[30:33], v[176:179], v[224:227], v[30:33]
	v_mfma_f32_16x16x32_bf16 v[26:29], v[184:187], v[224:227], v[26:29]
	v_mfma_f32_16x16x32_bf16 v[14:17], v[176:179], v[232:235], v[14:17]
	v_mfma_f32_16x16x32_bf16 v[10:13], v[184:187], v[232:235], v[10:13]
	v_mfma_f32_16x16x32_bf16 v[54:57], v[188:191], v[204:207], v[54:57]
	v_mfma_f32_16x16x32_bf16 v[50:53], v[196:199], v[204:207], v[50:53]
	v_mfma_f32_16x16x32_bf16 v[38:41], v[188:191], v[212:215], v[38:41]
	v_mfma_f32_16x16x32_bf16 v[34:37], v[196:199], v[212:215], v[34:37]
	v_mfma_f32_16x16x32_bf16 v[22:25], v[188:191], v[220:223], v[22:25]
	v_mfma_f32_16x16x32_bf16 v[18:21], v[196:199], v[220:223], v[18:21]
	v_mfma_f32_16x16x32_bf16 v[6:9], v[188:191], v[228:231], v[6:9]
	v_mfma_f32_16x16x32_bf16 v[2:5], v[196:199], v[228:231], v[2:5]
	v_mfma_f32_16x16x32_bf16 v[54:57], v[192:195], v[208:211], v[54:57]
	v_mfma_f32_16x16x32_bf16 v[50:53], v[200:203], v[208:211], v[50:53]
	v_mfma_f32_16x16x32_bf16 v[38:41], v[192:195], v[216:219], v[38:41]
	v_mfma_f32_16x16x32_bf16 v[34:37], v[200:203], v[216:219], v[34:37]
	v_mfma_f32_16x16x32_bf16 v[22:25], v[192:195], v[224:227], v[22:25]
	v_mfma_f32_16x16x32_bf16 v[18:21], v[200:203], v[224:227], v[18:21]
	v_mfma_f32_16x16x32_bf16 v[6:9], v[192:195], v[232:235], v[6:9]
	v_mfma_f32_16x16x32_bf16 v[2:5], v[200:203], v[232:235], v[2:5]
	s_barrier
; #define PG8_STAGE(bufoff, gbase, voff) do { _Pragma("unroll") for (int _i = 0; _i < 2; ++_i) \
;         __builtin_amdgcn_global_load_lds((const unsigned*)((const char*)(gbase) + (voff)[_i]), (LAS unsigned*)(lds + (bufoff) + ldsw + _i * 8192), 16, 0, 0); } while (0)
; #define PG8_LDA(dst, b, h) do { _Pragma("unroll") for (int m = 0; m < 4; ++m) _Pragma("unroll") for (int k = 0; k < 2; ++k) dst[m][k] = *(const LAS bf16x8*)(lds + PG8_SA(b, h) + aoff + m * 2048 + k * 1024); } while (0)
; #define PG8_LDB(dst, b, h) do { _Pragma("unroll") for (int n = 0; n < 2; ++n) _Pragma("unroll") for (int k = 0; k < 2; ++k) dst[n][k] = *(const LAS bf16x8*)(lds + PG8_SB(b, h) + boff + n * 2048 + k * 1024); } while (0)
; #define PG8_MMA(ai, bj, At, Bt) do { __builtin_amdgcn_s_setprio(1); _Pragma("unroll") for (int m = 0; m < 4; ++m) _Pragma("unroll") for (int n = 0; n < 2; ++n) _Pragma("unroll") for (int k = 0; k < 2; ++k) \
;         acc[ai][bj][m][n] = __builtin_amdgcn_mfma_f32_16x16x32_bf16(Bt[n][k], At[m][k], acc[ai][bj][m][n], 0, 0, 0); __builtin_amdgcn_s_setprio(0); } while (0)
; #define PG8_WAIT_V(n) asm volatile("s_waitcnt vmcnt(" #n ")" ::: "memory")
; #define PG8_WAIT_L(n) asm volatile("s_waitcnt lgkmcnt(" #n ")" ::: "memory")
; #define PG8_BAR __builtin_amdgcn_s_barrier()
; #define PG8_SCHED __builtin_amdgcn_sched_barrier(0)
; template <class Epi, class Sched, bool ABLK = false, bool ALIGN_EPI = true, bool SP2 = true, bool BBLK = true>
; __device__ __forceinline__ void gemm_phase(LAS unsigned char* lds, const Gemm g, const Sched& S, const Epi& E) {
;     ...
;             PG8_LDB(B0, 1, 0); PG8_LDB(B1, 1, 1); PG8_SCHED; PG8_LDA(At, 1, 0); PG8_STAGE(PG8_SA(0, 1), a2 + hstepA, voffA);
;             PG8_WAIT_V(8); PG8_WAIT_L(0); PG8_BAR; PG8_MMA(0, 0, At, B0); PG8_MMA(0, 1, At, B1); PG8_BAR; PG8_SCHED;
;             PG8_LDA(At, 1, 1); PG8_STAGE(PG8_SB(1, 0), b3, voffB); PG8_STAGE(PG8_SB(1, 1), b3 + hstepB, voffB); PG8_STAGE(PG8_SA(1, 0), a3, voffA);
;             PG8_WAIT_V(8); PG8_WAIT_L(0); PG8_BAR; PG8_MMA(1, 0, At, B0); PG8_MMA(1, 1, At, B1); PG8_BAR; PG8_SCHED;
	s_add_i32 s61, 0, 0x18000
	v_add_u32_e32 v171, s61, v1
	s_add_i32 s62, 0, 0x1c000
	ds_read_b128 v[172:175], v171
	ds_read_b128 v[176:179], v171 offset:1024
	ds_read_b128 v[180:183], v171 offset:2048
	ds_read_b128 v[184:187], v171 offset:3072
	v_add_u32_e32 v171, s62, v1
	ds_read_b128 v[188:191], v171
	ds_read_b128 v[192:195], v171 offset:1024
	ds_read_b128 v[196:199], v171 offset:2048
	ds_read_b128 v[200:203], v171 offset:3072
	s_add_u32 s36, s36, 0x80000
	s_addc_u32 s37, s37, 0
	s_mov_b32 m0, s46
	ds_read_b128 v[204:207], v170 offset:32768
	ds_read_b128 v[208:211], v170 offset:33792
	ds_read_b128 v[212:215], v170 offset:34816
	ds_read_b128 v[216:219], v170 offset:35840
	ds_read_b128 v[220:223], v170 offset:36864
	ds_read_b128 v[224:227], v170 offset:37888
	ds_read_b128 v[228:231], v170 offset:38912
	ds_read_b128 v[232:235], v170 offset:39936
	global_load_lds_dwordx4 v136, s[36:37]
	s_mov_b32 m0, s47
	s_nop 0
	global_load_lds_dwordx4 v132, s[36:37]
	s_waitcnt vmcnt(8) lgkmcnt(0)
	s_barrier
	v_mfma_f32_16x16x32_bf16 v[126:129], v[172:175], v[204:207], v[126:129]
	v_mfma_f32_16x16x32_bf16 v[122:125], v[180:183], v[204:207], v[122:125]
	v_mfma_f32_16x16x32_bf16 v[110:113], v[172:175], v[212:215], v[110:113]
	v_mfma_f32_16x16x32_bf16 v[106:109], v[180:183], v[212:215], v[106:109]
	v_mfma_f32_16x16x32_bf16 v[94:97], v[172:175], v[220:223], v[94:97]
	v_mfma_f32_16x16x32_bf16 v[90:93], v[180:183], v[220:223], v[90:93]
	v_mfma_f32_16x16x32_bf16 v[78:81], v[172:175], v[228:231], v[78:81]
	v_mfma_f32_16x16x32_bf16 v[74:77], v[180:183], v[228:231], v[74:77]
	v_mfma_f32_16x16x32_bf16 v[126:129], v[176:179], v[208:211], v[126:129]
	v_mfma_f32_16x16x32_bf16 v[122:125], v[184:187], v[208:211], v[122:125]
	v_mfma_f32_16x16x32_bf16 v[110:113], v[176:179], v[216:219], v[110:113]
	v_mfma_f32_16x16x32_bf16 v[106:109], v[184:187], v[216:219], v[106:109]
	v_mfma_f32_16x16x32_bf16 v[94:97], v[176:179], v[224:227], v[94:97]
	v_mfma_f32_16x16x32_bf16 v[90:93], v[184:187], v[224:227], v[90:93]
	v_mfma_f32_16x16x32_bf16 v[78:81], v[176:179], v[232:235], v[78:81]
	v_mfma_f32_16x16x32_bf16 v[74:77], v[184:187], v[232:235], v[74:77]
	v_mfma_f32_16x16x32_bf16 v[118:121], v[188:191], v[204:207], v[118:121]
	v_mfma_f32_16x16x32_bf16 v[114:117], v[196:199], v[204:207], v[114:117]
	v_mfma_f32_16x16x32_bf16 v[102:105], v[188:191], v[212:215], v[102:105]
	v_mfma_f32_16x16x32_bf16 v[98:101], v[196:199], v[212:215], v[98:101]
	v_mfma_f32_16x16x32_bf16 v[86:89], v[188:191], v[220:223], v[86:89]
	v_mfma_f32_16x16x32_bf16 v[82:85], v[196:199], v[220:223], v[82:85]
	v_mfma_f32_16x16x32_bf16 v[70:73], v[188:191], v[228:231], v[70:73]
	v_mfma_f32_16x16x32_bf16 v[66:69], v[196:199], v[228:231], v[66:69]
	v_mfma_f32_16x16x32_bf16 v[118:121], v[192:195], v[208:211], v[118:121]
	v_mfma_f32_16x16x32_bf16 v[114:117], v[200:203], v[208:211], v[114:117]
	v_mfma_f32_16x16x32_bf16 v[102:105], v[192:195], v[216:219], v[102:105]
	v_mfma_f32_16x16x32_bf16 v[98:101], v[200:203], v[216:219], v[98:101]
	v_mfma_f32_16x16x32_bf16 v[86:89], v[192:195], v[224:227], v[86:89]
	v_mfma_f32_16x16x32_bf16 v[82:85], v[200:203], v[224:227], v[82:85]
	v_mfma_f32_16x16x32_bf16 v[70:73], v[192:195], v[232:235], v[70:73]
	v_mfma_f32_16x16x32_bf16 v[66:69], v[200:203], v[232:235], v[66:69]
	s_barrier
	s_add_u32 s36, s34, 0x8000
	s_addc_u32 s37, s35, 0
	s_add_i32 s61, s61, s40
	s_mov_b32 m0, s61
	ds_read_b128 v[204:207], v170 offset:49152
	ds_read_b128 v[208:211], v170 offset:50176
	ds_read_b128 v[212:215], v170 offset:51200
	ds_read_b128 v[216:219], v170 offset:52224
	ds_read_b128 v[220:223], v170 offset:53248
	ds_read_b128 v[224:227], v170 offset:54272
	ds_read_b128 v[228:231], v170 offset:55296
	ds_read_b128 v[232:235], v170 offset:56320
	global_load_lds_dwordx4 v134, s[36:37]
	s_add_i32 m0, s61, 0x2000
	s_add_u32 s34, s34, 0xc000
	v_lshl_add_u64 v[236:237], s[36:37], 0, v[130:131]
	s_addc_u32 s35, s35, 0
	s_add_i32 s36, s62, s40
	global_load_lds_dwordx4 v[236:237], off
	s_mov_b32 m0, s36
	s_nop 0
	global_load_lds_dwordx4 v134, s[34:35]
	s_add_i32 m0, s36, 0x2000
	s_nop 0
	global_load_lds_dwordx4 v130, s[34:35]
	s_mov_b32 m0, s50
	s_nop 0
	global_load_lds_dwordx4 v136, s[30:31]
	s_mov_b32 m0, s51
	s_nop 0
	global_load_lds_dwordx4 v132, s[30:31]
	s_waitcnt vmcnt(8) lgkmcnt(0)
	s_barrier
	v_mfma_f32_16x16x32_bf16 v[62:65], v[172:175], v[204:207], v[62:65]
	v_mfma_f32_16x16x32_bf16 v[58:61], v[180:183], v[204:207], v[58:61]
	v_mfma_f32_16x16x32_bf16 v[46:49], v[172:175], v[212:215], v[46:49]
	v_mfma_f32_16x16x32_bf16 v[42:45], v[180:183], v[212:215], v[42:45]
	v_mfma_f32_16x16x32_bf16 v[30:33], v[172:175], v[220:223], v[30:33]
	v_mfma_f32_16x16x32_bf16 v[26:29], v[180:183], v[220:223], v[26:29]
	v_mfma_f32_16x16x32_bf16 v[14:17], v[172:175], v[228:231], v[14:17]
	v_mfma_f32_16x16x32_bf16 v[10:13], v[180:183], v[228:231], v[10:13]
	v_mfma_f32_16x16x32_bf16 v[62:65], v[176:179], v[208:211], v[62:65]
	v_mfma_f32_16x16x32_bf16 v[58:61], v[184:187], v[208:211], v[58:61]
	v_mfma_f32_16x16x32_bf16 v[46:49], v[176:179], v[216:219], v[46:49]
	v_mfma_f32_16x16x32_bf16 v[42:45], v[184:187], v[216:219], v[42:45]
	v_mfma_f32_16x16x32_bf16 v[30:33], v[176:179], v[224:227], v[30:33]
	v_mfma_f32_16x16x32_bf16 v[26:29], v[184:187], v[224:227], v[26:29]
	v_mfma_f32_16x16x32_bf16 v[14:17], v[176:179], v[232:235], v[14:17]
	v_mfma_f32_16x16x32_bf16 v[10:13], v[184:187], v[232:235], v[10:13]
	v_mfma_f32_16x16x32_bf16 v[54:57], v[188:191], v[204:207], v[54:57]
	v_mfma_f32_16x16x32_bf16 v[50:53], v[196:199], v[204:207], v[50:53]
	v_mfma_f32_16x16x32_bf16 v[38:41], v[188:191], v[212:215], v[38:41]
	v_mfma_f32_16x16x32_bf16 v[34:37], v[196:199], v[212:215], v[34:37]
	v_mfma_f32_16x16x32_bf16 v[22:25], v[188:191], v[220:223], v[22:25]
	v_mfma_f32_16x16x32_bf16 v[18:21], v[196:199], v[220:223], v[18:21]
	v_mfma_f32_16x16x32_bf16 v[6:9], v[188:191], v[228:231], v[6:9]
	v_mfma_f32_16x16x32_bf16 v[2:5], v[196:199], v[228:231], v[2:5]
	v_mfma_f32_16x16x32_bf16 v[54:57], v[192:195], v[208:211], v[54:57]
	v_mfma_f32_16x16x32_bf16 v[50:53], v[200:203], v[208:211], v[50:53]
	v_mfma_f32_16x16x32_bf16 v[38:41], v[192:195], v[216:219], v[38:41]
	v_mfma_f32_16x16x32_bf16 v[34:37], v[200:203], v[216:219], v[34:37]
	v_mfma_f32_16x16x32_bf16 v[22:25], v[192:195], v[224:227], v[22:25]
	v_mfma_f32_16x16x32_bf16 v[18:21], v[200:203], v[224:227], v[18:21]
	v_mfma_f32_16x16x32_bf16 v[6:9], v[192:195], v[232:235], v[6:9]
	v_mfma_f32_16x16x32_bf16 v[2:5], v[200:203], v[232:235], v[2:5]
	s_barrier
; __device__ __forceinline__ unsigned pk2(float lo, float hi) { const f32x2 v = {lo, hi}; return __builtin_bit_cast(unsigned, __builtin_convertvector(v, bf16x2_t)); }
; __device__ __forceinline__ u32x4 ror8(u32x4 v) { u32x4 r;
; #pragma unroll
;     for (int i = 0; i < 4; ++i) r[i] = (unsigned)__builtin_amdgcn_mov_dpp((int)v[i], 0x128, 0xf, 0xf, true);
;     return r; }
; __device__ __forceinline__ void store_pair(unsigned char* own, size_t stride8, int hi_off, u32x4 lo, u32x4 hi, bool upper) {
;     const u32x4 tlo = ror8(lo), thi = ror8(hi);
;     const u32x4 A = upper ? thi : lo, B = upper ? hi : tlo;
;     unsigned char* pa = upper ? own - stride8 + hi_off : own;
;     unsigned char* pb = upper ? own + hi_off : own + stride8;
;     *(u32x4*)pa = A; *(u32x4*)pb = B;
; }
;     __device__ __forceinline__ void operator()(const f32x4 (&acc)[2][2][4][2], const Unit& u, int wr, int wc, int fr, int fq) const {
; #pragma unroll
;         for (int ai = 0; ai < 2; ++ai)
; #pragma unroll
;             for (int m = 0; m < 4; ++m) { unsigned char* rowp = (unsigned char*)(H + ((size_t)(u.pm * (FF / 64) + u.pn * 4 + wc) * 256 + (wr * 64 + fr + ai * 128 + m * 16)) * 64 + 8 * fq); u32x4 w[2];
; #pragma unroll
;                 for (int bj = 0; bj < 2; ++bj) { f32x4 v0 = acc[ai][bj][m][0], v1 = acc[ai][bj][m][1];
; #pragma unroll
;                     for (int j = 0; j < 4; ++j) { const float a = fmaxf(v0[j], 0.f), b = fmaxf(v1[j], 0.f); v0[j] = a * a; v1[j] = b * b; }
;                     w[bj].x = pk2(v0[0], v0[1]); w[bj].y = pk2(v0[2], v0[3]); w[bj].z = pk2(v1[0], v1[1]); w[bj].w = pk2(v1[2], v1[3]); }
;                 store_pair(rowp, (size_t)8 * 64 * 2, 64, w[0], w[1], fr >= 8); }
	s_add_i32 s60, s60, 2
	s_add_u32 s28, s28, 0x100
	s_addc_u32 s29, s29, 0
	s_add_u32 s58, s58, 0x10000
	s_addc_u32 s59, s59, 0
	s_cmp_gt_u32 s60, 29
	s_cbranch_scc0 .LBB0_475
	s_lshl_b32 s4, s22, 7
	s_lshl_b32 s5, s24, 2
	s_add_i32 s5, s5, s4
	s_or_b32 s4, s5, s49
	s_ashr_i32 s5, s4, 31
	s_lshl_b64 s[4:5], s[4:5], 15
	s_add_u32 s22, s1, s4
	v_max_f32_e32 v126, 0, v126
	v_max_f32_e32 v122, 0, v122
	v_max_f32_e32 v127, 0, v127
	v_max_f32_e32 v123, 0, v123
	v_max_f32_e32 v128, 0, v128
	v_max_f32_e32 v124, 0, v124
	v_max_f32_e32 v129, 0, v129
	v_max_f32_e32 v125, 0, v125
	v_max_f32_e32 v118, 0, v118
	v_max_f32_e32 v114, 0, v114
	v_max_f32_e32 v119, 0, v119
	v_max_f32_e32 v115, 0, v115
	v_max_f32_e32 v120, 0, v120
	v_max_f32_e32 v116, 0, v116
	v_max_f32_e32 v121, 0, v121
	v_max_f32_e32 v117, 0, v117
	s_addc_u32 s23, s33, s5
	v_pk_mul_f32 v[126:127], v[126:127], v[126:127]
	v_pk_mul_f32 v[122:123], v[122:123], v[122:123]
	v_pk_mul_f32 v[128:129], v[128:129], v[128:129]
	v_pk_mul_f32 v[124:125], v[124:125], v[124:125]
	v_pk_mul_f32 v[118:119], v[118:119], v[118:119]
	v_pk_mul_f32 v[114:115], v[114:115], v[114:115]
	v_pk_mul_f32 v[120:121], v[120:121], v[120:121]
	v_pk_mul_f32 v[116:117], v[116:117], v[116:117]
	v_lshl_add_u64 v[164:165], s[22:23], 0, v[144:145]
	v_cvt_pk_bf16_f32 v126, v126, v127
	v_cvt_pk_bf16_f32 v127, v128, v129
	v_cvt_pk_bf16_f32 v128, v122, v123
	v_cvt_pk_bf16_f32 v129, v124, v125
	v_cvt_pk_bf16_f32 v118, v118, v119
	v_cvt_pk_bf16_f32 v119, v120, v121
	v_cvt_pk_bf16_f32 v114, v114, v115
	v_cvt_pk_bf16_f32 v115, v116, v117
	v_lshl_add_u64 v[122:123], v[164:165], 0, v[138:139]
	v_mov_b32_dpp v120, v126 row_ror:8 row_mask:0xf bank_mask:0xf bound_ctrl:1
	v_mov_b32_dpp v121, v127 row_ror:8 row_mask:0xf bank_mask:0xf bound_ctrl:1
	v_mov_b32_dpp v116, v128 row_ror:8 row_mask:0xf bank_mask:0xf bound_ctrl:1
	v_mov_b32_dpp v117, v129 row_ror:8 row_mask:0xf bank_mask:0xf bound_ctrl:1
	v_mov_b32_dpp v164, v118 row_ror:8 row_mask:0xf bank_mask:0xf bound_ctrl:1
	v_mov_b32_dpp v165, v119 row_ror:8 row_mask:0xf bank_mask:0xf bound_ctrl:1
	v_mov_b32_dpp v166, v114 row_ror:8 row_mask:0xf bank_mask:0xf bound_ctrl:1
	v_mov_b32_dpp v167, v115 row_ror:8 row_mask:0xf bank_mask:0xf bound_ctrl:1
	v_max_f32_e32 v110, 0, v110
	v_max_f32_e32 v106, 0, v106
	v_max_f32_e32 v111, 0, v111
	v_max_f32_e32 v107, 0, v107
	v_max_f32_e32 v112, 0, v112
	v_max_f32_e32 v108, 0, v108
	v_max_f32_e32 v113, 0, v113
	v_max_f32_e32 v109, 0, v109
	v_max_f32_e32 v102, 0, v102
	v_max_f32_e32 v98, 0, v98
	v_max_f32_e32 v103, 0, v103
	v_max_f32_e32 v99, 0, v99
	v_max_f32_e32 v104, 0, v104
	v_max_f32_e32 v100, 0, v100
	v_max_f32_e32 v105, 0, v105
	v_max_f32_e32 v101, 0, v101
	v_lshl_add_u64 v[124:125], v[122:123], 0, v[140:141]
	v_cndmask_b32_e64 v117, v117, v115, s[6:7]
	v_cndmask_b32_e64 v116, v116, v114, s[6:7]
	v_cndmask_b32_e64 v115, v121, v119, s[6:7]
	v_cndmask_b32_e64 v114, v120, v118, s[6:7]
	v_cndmask_b32_e64 v121, v129, v167, s[6:7]
	v_cndmask_b32_e64 v120, v128, v166, s[6:7]
	v_cndmask_b32_e64 v119, v127, v165, s[6:7]
	v_cndmask_b32_e64 v118, v126, v164, s[6:7]
	v_pk_mul_f32 v[110:111], v[110:111], v[110:111]
	v_pk_mul_f32 v[106:107], v[106:107], v[106:107]
	v_pk_mul_f32 v[112:113], v[112:113], v[112:113]
	v_pk_mul_f32 v[108:109], v[108:109], v[108:109]
	v_pk_mul_f32 v[102:103], v[102:103], v[102:103]
	v_pk_mul_f32 v[98:99], v[98:99], v[98:99]
	v_pk_mul_f32 v[104:105], v[104:105], v[104:105]
	v_pk_mul_f32 v[100:101], v[100:101], v[100:101]
	v_lshl_add_u64 v[122:123], v[122:123], 0, v[142:143]
	s_and_b64 vcc, exec, s[8:9]
	s_cbranch_vccz .LBB0_478
	s_barrier
.LBB0_478:
	global_store_dwordx4 v[124:125], v[118:121], off
	global_store_dwordx4 v[122:123], v[114:117], off
	v_cvt_pk_bf16_f32 v110, v110, v111
	v_cvt_pk_bf16_f32 v111, v112, v113
	v_lshl_add_u64 v[114:115], s[22:23], 0, v[146:147]
	v_cvt_pk_bf16_f32 v112, v106, v107
	v_cvt_pk_bf16_f32 v113, v108, v109
	v_cvt_pk_bf16_f32 v102, v102, v103
	v_cvt_pk_bf16_f32 v103, v104, v105
	v_cvt_pk_bf16_f32 v98, v98, v99
	v_cvt_pk_bf16_f32 v99, v100, v101
	v_lshl_add_u64 v[106:107], v[114:115], 0, v[138:139]
	v_mov_b32_dpp v104, v110 row_ror:8 row_mask:0xf bank_mask:0xf bound_ctrl:1
	v_mov_b32_dpp v105, v111 row_ror:8 row_mask:0xf bank_mask:0xf bound_ctrl:1
	v_mov_b32_dpp v100, v112 row_ror:8 row_mask:0xf bank_mask:0xf bound_ctrl:1
	v_mov_b32_dpp v101, v113 row_ror:8 row_mask:0xf bank_mask:0xf bound_ctrl:1
	v_mov_b32_dpp v114, v102 row_ror:8 row_mask:0xf bank_mask:0xf bound_ctrl:1
	v_mov_b32_dpp v115, v103 row_ror:8 row_mask:0xf bank_mask:0xf bound_ctrl:1
	v_mov_b32_dpp v116, v98 row_ror:8 row_mask:0xf bank_mask:0xf bound_ctrl:1
	v_mov_b32_dpp v117, v99 row_ror:8 row_mask:0xf bank_mask:0xf bound_ctrl:1
	v_max_f32_e32 v94, 0, v94
	v_max_f32_e32 v90, 0, v90
	v_max_f32_e32 v95, 0, v95
	v_max_f32_e32 v91, 0, v91
	v_max_f32_e32 v96, 0, v96
	v_max_f32_e32 v92, 0, v92
	v_max_f32_e32 v97, 0, v97
	v_max_f32_e32 v93, 0, v93
	v_max_f32_e32 v86, 0, v86
	v_max_f32_e32 v82, 0, v82
	v_max_f32_e32 v87, 0, v87
	v_max_f32_e32 v83, 0, v83
	v_max_f32_e32 v88, 0, v88
	v_max_f32_e32 v84, 0, v84
	v_max_f32_e32 v89, 0, v89
	v_max_f32_e32 v85, 0, v85
	v_lshl_add_u64 v[108:109], v[106:107], 0, v[140:141]
	v_cndmask_b32_e64 v101, v101, v99, s[6:7]
	v_cndmask_b32_e64 v100, v100, v98, s[6:7]
	v_cndmask_b32_e64 v99, v105, v103, s[6:7]
	v_cndmask_b32_e64 v98, v104, v102, s[6:7]
	v_cndmask_b32_e64 v105, v113, v117, s[6:7]
	v_cndmask_b32_e64 v104, v112, v116, s[6:7]
	v_cndmask_b32_e64 v103, v111, v115, s[6:7]
	v_cndmask_b32_e64 v102, v110, v114, s[6:7]
	v_pk_mul_f32 v[94:95], v[94:95], v[94:95]
	v_pk_mul_f32 v[90:91], v[90:91], v[90:91]
; __device__ __forceinline__ unsigned pk2(float lo, float hi) { const f32x2 v = {lo, hi}; return __builtin_bit_cast(unsigned, __builtin_convertvector(v, bf16x2_t)); }
; __device__ __forceinline__ u32x4 ror8(u32x4 v) { u32x4 r;
; #pragma unroll
;     for (int i = 0; i < 4; ++i) r[i] = (unsigned)__builtin_amdgcn_mov_dpp((int)v[i], 0x128, 0xf, 0xf, true);
;     return r; }
; __device__ __forceinline__ void store_pair(unsigned char* own, size_t stride8, int hi_off, u32x4 lo, u32x4 hi, bool upper) {
;     const u32x4 tlo = ror8(lo), thi = ror8(hi);
;     const u32x4 A = upper ? thi : lo, B = upper ? hi : tlo;
;     unsigned char* pa = upper ? own - stride8 + hi_off : own;
;     unsigned char* pb = upper ? own + hi_off : own + stride8;
;     *(u32x4*)pa = A; *(u32x4*)pb = B;
; }
;     __device__ __forceinline__ void operator()(const f32x4 (&acc)[2][2][4][2], const Unit& u, int wr, int wc, int fr, int fq) const {
; #pragma unroll
;         for (int ai = 0; ai < 2; ++ai)
; #pragma unroll
;             for (int m = 0; m < 4; ++m) { unsigned char* rowp = (unsigned char*)(H + ((size_t)(u.pm * (FF / 64) + u.pn * 4 + wc) * 256 + (wr * 64 + fr + ai * 128 + m * 16)) * 64 + 8 * fq); u32x4 w[2];
; #pragma unroll
;                 for (int bj = 0; bj < 2; ++bj) { f32x4 v0 = acc[ai][bj][m][0], v1 = acc[ai][bj][m][1];
; #pragma unroll
;                     for (int j = 0; j < 4; ++j) { const float a = fmaxf(v0[j], 0.f), b = fmaxf(v1[j], 0.f); v0[j] = a * a; v1[j] = b * b; }
;                     w[bj].x = pk2(v0[0], v0[1]); w[bj].y = pk2(v0[2], v0[3]); w[bj].z = pk2(v1[0], v1[1]); w[bj].w = pk2(v1[2], v1[3]); }
;                 store_pair(rowp, (size_t)8 * 64 * 2, 64, w[0], w[1], fr >= 8); }
	v_pk_mul_f32 v[96:97], v[96:97], v[96:97]
	v_pk_mul_f32 v[92:93], v[92:93], v[92:93]
	v_pk_mul_f32 v[86:87], v[86:87], v[86:87]
	v_pk_mul_f32 v[82:83], v[82:83], v[82:83]
	v_pk_mul_f32 v[88:89], v[88:89], v[88:89]
	v_pk_mul_f32 v[84:85], v[84:85], v[84:85]
	v_lshl_add_u64 v[106:107], v[106:107], 0, v[142:143]
	global_store_dwordx4 v[108:109], v[102:105], off
	global_store_dwordx4 v[106:107], v[98:101], off
	v_cvt_pk_bf16_f32 v94, v94, v95
	v_cvt_pk_bf16_f32 v95, v96, v97
	v_lshl_add_u64 v[98:99], s[22:23], 0, v[148:149]
	v_cvt_pk_bf16_f32 v96, v90, v91
	v_cvt_pk_bf16_f32 v97, v92, v93
	v_cvt_pk_bf16_f32 v86, v86, v87
	v_cvt_pk_bf16_f32 v87, v88, v89
	v_cvt_pk_bf16_f32 v82, v82, v83
	v_cvt_pk_bf16_f32 v83, v84, v85
	v_lshl_add_u64 v[90:91], v[98:99], 0, v[138:139]
	v_mov_b32_dpp v88, v94 row_ror:8 row_mask:0xf bank_mask:0xf bound_ctrl:1
	v_mov_b32_dpp v89, v95 row_ror:8 row_mask:0xf bank_mask:0xf bound_ctrl:1
	v_mov_b32_dpp v84, v96 row_ror:8 row_mask:0xf bank_mask:0xf bound_ctrl:1
	v_mov_b32_dpp v85, v97 row_ror:8 row_mask:0xf bank_mask:0xf bound_ctrl:1
	v_mov_b32_dpp v98, v86 row_ror:8 row_mask:0xf bank_mask:0xf bound_ctrl:1
	v_mov_b32_dpp v99, v87 row_ror:8 row_mask:0xf bank_mask:0xf bound_ctrl:1
	v_mov_b32_dpp v100, v82 row_ror:8 row_mask:0xf bank_mask:0xf bound_ctrl:1
	v_mov_b32_dpp v101, v83 row_ror:8 row_mask:0xf bank_mask:0xf bound_ctrl:1
	v_max_f32_e32 v78, 0, v78
	v_max_f32_e32 v74, 0, v74
	v_max_f32_e32 v79, 0, v79
	v_max_f32_e32 v75, 0, v75
	v_max_f32_e32 v80, 0, v80
	v_max_f32_e32 v76, 0, v76
	v_max_f32_e32 v81, 0, v81
	v_max_f32_e32 v77, 0, v77
	v_max_f32_e32 v70, 0, v70
	v_max_f32_e32 v66, 0, v66
	v_max_f32_e32 v71, 0, v71
	v_max_f32_e32 v67, 0, v67
	v_max_f32_e32 v72, 0, v72
	v_max_f32_e32 v68, 0, v68
	v_max_f32_e32 v73, 0, v73
	v_max_f32_e32 v69, 0, v69
	v_lshl_add_u64 v[92:93], v[90:91], 0, v[140:141]
	v_cndmask_b32_e64 v85, v85, v83, s[6:7]
	v_cndmask_b32_e64 v84, v84, v82, s[6:7]
	v_cndmask_b32_e64 v83, v89, v87, s[6:7]
	v_cndmask_b32_e64 v82, v88, v86, s[6:7]
	v_cndmask_b32_e64 v89, v97, v101, s[6:7]
	v_cndmask_b32_e64 v88, v96, v100, s[6:7]
	v_cndmask_b32_e64 v87, v95, v99, s[6:7]
	v_cndmask_b32_e64 v86, v94, v98, s[6:7]
	v_pk_mul_f32 v[78:79], v[78:79], v[78:79]
	v_pk_mul_f32 v[74:75], v[74:75], v[74:75]
	v_pk_mul_f32 v[80:81], v[80:81], v[80:81]
	v_pk_mul_f32 v[76:77], v[76:77], v[76:77]
	v_pk_mul_f32 v[70:71], v[70:71], v[70:71]
	v_pk_mul_f32 v[66:67], v[66:67], v[66:67]
	v_pk_mul_f32 v[72:73], v[72:73], v[72:73]
	v_pk_mul_f32 v[68:69], v[68:69], v[68:69]
	v_lshl_add_u64 v[90:91], v[90:91], 0, v[142:143]
	global_store_dwordx4 v[92:93], v[86:89], off
	global_store_dwordx4 v[90:91], v[82:85], off
	v_cvt_pk_bf16_f32 v78, v78, v79
	v_cvt_pk_bf16_f32 v79, v80, v81
	v_lshl_add_u64 v[82:83], s[22:23], 0, v[150:151]
	v_cvt_pk_bf16_f32 v80, v74, v75
	v_cvt_pk_bf16_f32 v81, v76, v77
	v_cvt_pk_bf16_f32 v70, v70, v71
	v_cvt_pk_bf16_f32 v71, v72, v73
	v_cvt_pk_bf16_f32 v66, v66, v67
	v_cvt_pk_bf16_f32 v67, v68, v69
	v_lshl_add_u64 v[74:75], v[82:83], 0, v[138:139]
	v_mov_b32_dpp v72, v78 row_ror:8 row_mask:0xf bank_mask:0xf bound_ctrl:1
	v_mov_b32_dpp v73, v79 row_ror:8 row_mask:0xf bank_mask:0xf bound_ctrl:1
	v_mov_b32_dpp v68, v80 row_ror:8 row_mask:0xf bank_mask:0xf bound_ctrl:1
	v_mov_b32_dpp v69, v81 row_ror:8 row_mask:0xf bank_mask:0xf bound_ctrl:1
	v_mov_b32_dpp v82, v70 row_ror:8 row_mask:0xf bank_mask:0xf bound_ctrl:1
	v_mov_b32_dpp v83, v71 row_ror:8 row_mask:0xf bank_mask:0xf bound_ctrl:1
	v_mov_b32_dpp v84, v66 row_ror:8 row_mask:0xf bank_mask:0xf bound_ctrl:1
	v_mov_b32_dpp v85, v67 row_ror:8 row_mask:0xf bank_mask:0xf bound_ctrl:1
	v_max_f32_e32 v62, 0, v62
	v_max_f32_e32 v58, 0, v58
	v_max_f32_e32 v63, 0, v63
	v_max_f32_e32 v59, 0, v59
	v_max_f32_e32 v64, 0, v64
	v_max_f32_e32 v60, 0, v60
	v_max_f32_e32 v65, 0, v65
	v_max_f32_e32 v61, 0, v61
	v_max_f32_e32 v54, 0, v54
	v_max_f32_e32 v50, 0, v50
	v_max_f32_e32 v55, 0, v55
	v_max_f32_e32 v51, 0, v51
	v_max_f32_e32 v56, 0, v56
	v_max_f32_e32 v52, 0, v52
	v_max_f32_e32 v57, 0, v57
	v_max_f32_e32 v53, 0, v53
	v_lshl_add_u64 v[76:77], v[74:75], 0, v[140:141]
	v_cndmask_b32_e64 v69, v69, v67, s[6:7]
	v_cndmask_b32_e64 v68, v68, v66, s[6:7]
	v_cndmask_b32_e64 v67, v73, v71, s[6:7]
	v_cndmask_b32_e64 v66, v72, v70, s[6:7]
	v_cndmask_b32_e64 v73, v81, v85, s[6:7]
	v_cndmask_b32_e64 v72, v80, v84, s[6:7]
	v_cndmask_b32_e64 v71, v79, v83, s[6:7]
	v_cndmask_b32_e64 v70, v78, v82, s[6:7]
	v_pk_mul_f32 v[62:63], v[62:63], v[62:63]
	v_pk_mul_f32 v[58:59], v[58:59], v[58:59]
	v_pk_mul_f32 v[64:65], v[64:65], v[64:65]
	v_pk_mul_f32 v[60:61], v[60:61], v[60:61]
	v_pk_mul_f32 v[54:55], v[54:55], v[54:55]
	v_pk_mul_f32 v[50:51], v[50:51], v[50:51]
	v_pk_mul_f32 v[56:57], v[56:57], v[56:57]
	v_pk_mul_f32 v[52:53], v[52:53], v[52:53]
	v_lshl_add_u64 v[74:75], v[74:75], 0, v[142:143]
	global_store_dwordx4 v[76:77], v[70:73], off
	global_store_dwordx4 v[74:75], v[66:69], off
	v_cvt_pk_bf16_f32 v62, v62, v63
	v_cvt_pk_bf16_f32 v63, v64, v65
	v_lshl_add_u64 v[66:67], s[22:23], 0, v[152:153]
	v_cvt_pk_bf16_f32 v64, v58, v59
	v_cvt_pk_bf16_f32 v65, v60, v61
	v_cvt_pk_bf16_f32 v54, v54, v55
	v_cvt_pk_bf16_f32 v55, v56, v57
	v_cvt_pk_bf16_f32 v50, v50, v51
	v_cvt_pk_bf16_f32 v51, v52, v53
	v_lshl_add_u64 v[58:59], v[66:67], 0, v[138:139]
	v_mov_b32_dpp v56, v62 row_ror:8 row_mask:0xf bank_mask:0xf bound_ctrl:1
	v_mov_b32_dpp v57, v63 row_ror:8 row_mask:0xf bank_mask:0xf bound_ctrl:1
	v_mov_b32_dpp v52, v64 row_ror:8 row_mask:0xf bank_mask:0xf bound_ctrl:1
	v_mov_b32_dpp v53, v65 row_ror:8 row_mask:0xf bank_mask:0xf bound_ctrl:1
	v_mov_b32_dpp v66, v54 row_ror:8 row_mask:0xf bank_mask:0xf bound_ctrl:1
; __device__ __forceinline__ unsigned pk2(float lo, float hi) { const f32x2 v = {lo, hi}; return __builtin_bit_cast(unsigned, __builtin_convertvector(v, bf16x2_t)); }
; __device__ __forceinline__ u32x4 ror8(u32x4 v) { u32x4 r;
; #pragma unroll
;     for (int i = 0; i < 4; ++i) r[i] = (unsigned)__builtin_amdgcn_mov_dpp((int)v[i], 0x128, 0xf, 0xf, true);
;     return r; }
; __device__ __forceinline__ void store_pair(unsigned char* own, size_t stride8, int hi_off, u32x4 lo, u32x4 hi, bool upper) {
;     const u32x4 tlo = ror8(lo), thi = ror8(hi);
;     const u32x4 A = upper ? thi : lo, B = upper ? hi : tlo;
;     unsigned char* pa = upper ? own - stride8 + hi_off : own;
;     unsigned char* pb = upper ? own + hi_off : own + stride8;
;     *(u32x4*)pa = A; *(u32x4*)pb = B;
; }
;     __device__ __forceinline__ void operator()(const f32x4 (&acc)[2][2][4][2], const Unit& u, int wr, int wc, int fr, int fq) const {
; #pragma unroll
;         for (int ai = 0; ai < 2; ++ai)
; #pragma unroll
;             for (int m = 0; m < 4; ++m) { unsigned char* rowp = (unsigned char*)(H + ((size_t)(u.pm * (FF / 64) + u.pn * 4 + wc) * 256 + (wr * 64 + fr + ai * 128 + m * 16)) * 64 + 8 * fq); u32x4 w[2];
; #pragma unroll
;                 for (int bj = 0; bj < 2; ++bj) { f32x4 v0 = acc[ai][bj][m][0], v1 = acc[ai][bj][m][1];
; #pragma unroll
;                     for (int j = 0; j < 4; ++j) { const float a = fmaxf(v0[j], 0.f), b = fmaxf(v1[j], 0.f); v0[j] = a * a; v1[j] = b * b; }
;                     w[bj].x = pk2(v0[0], v0[1]); w[bj].y = pk2(v0[2], v0[3]); w[bj].z = pk2(v1[0], v1[1]); w[bj].w = pk2(v1[2], v1[3]); }
;                 store_pair(rowp, (size_t)8 * 64 * 2, 64, w[0], w[1], fr >= 8); }
	v_mov_b32_dpp v67, v55 row_ror:8 row_mask:0xf bank_mask:0xf bound_ctrl:1
	v_mov_b32_dpp v68, v50 row_ror:8 row_mask:0xf bank_mask:0xf bound_ctrl:1
	v_mov_b32_dpp v69, v51 row_ror:8 row_mask:0xf bank_mask:0xf bound_ctrl:1
	v_max_f32_e32 v46, 0, v46
	v_max_f32_e32 v42, 0, v42
	v_max_f32_e32 v47, 0, v47
	v_max_f32_e32 v43, 0, v43
	v_max_f32_e32 v48, 0, v48
	v_max_f32_e32 v44, 0, v44
	v_max_f32_e32 v49, 0, v49
	v_max_f32_e32 v45, 0, v45
	v_max_f32_e32 v38, 0, v38
	v_max_f32_e32 v34, 0, v34
	v_max_f32_e32 v39, 0, v39
	v_max_f32_e32 v35, 0, v35
	v_max_f32_e32 v40, 0, v40
	v_max_f32_e32 v36, 0, v36
	v_max_f32_e32 v41, 0, v41
	v_max_f32_e32 v37, 0, v37
	v_lshl_add_u64 v[60:61], v[58:59], 0, v[140:141]
	v_cndmask_b32_e64 v53, v53, v51, s[6:7]
	v_cndmask_b32_e64 v52, v52, v50, s[6:7]
	v_cndmask_b32_e64 v51, v57, v55, s[6:7]
	v_cndmask_b32_e64 v50, v56, v54, s[6:7]
	v_cndmask_b32_e64 v57, v65, v69, s[6:7]
	v_cndmask_b32_e64 v56, v64, v68, s[6:7]
	v_cndmask_b32_e64 v55, v63, v67, s[6:7]
	v_cndmask_b32_e64 v54, v62, v66, s[6:7]
	v_pk_mul_f32 v[46:47], v[46:47], v[46:47]
	v_pk_mul_f32 v[42:43], v[42:43], v[42:43]
	v_pk_mul_f32 v[48:49], v[48:49], v[48:49]
	v_pk_mul_f32 v[44:45], v[44:45], v[44:45]
	v_pk_mul_f32 v[38:39], v[38:39], v[38:39]
	v_pk_mul_f32 v[34:35], v[34:35], v[34:35]
	v_pk_mul_f32 v[40:41], v[40:41], v[40:41]
	v_pk_mul_f32 v[36:37], v[36:37], v[36:37]
	v_lshl_add_u64 v[58:59], v[58:59], 0, v[142:143]
	global_store_dwordx4 v[60:61], v[54:57], off
	global_store_dwordx4 v[58:59], v[50:53], off
	v_cvt_pk_bf16_f32 v46, v46, v47
	v_cvt_pk_bf16_f32 v47, v48, v49
	v_lshl_add_u64 v[50:51], s[22:23], 0, v[154:155]
	v_cvt_pk_bf16_f32 v48, v42, v43
	v_cvt_pk_bf16_f32 v49, v44, v45
	v_cvt_pk_bf16_f32 v38, v38, v39
	v_cvt_pk_bf16_f32 v39, v40, v41
	v_cvt_pk_bf16_f32 v34, v34, v35
	v_cvt_pk_bf16_f32 v35, v36, v37
	v_lshl_add_u64 v[42:43], v[50:51], 0, v[138:139]
	v_mov_b32_dpp v40, v46 row_ror:8 row_mask:0xf bank_mask:0xf bound_ctrl:1
	v_mov_b32_dpp v41, v47 row_ror:8 row_mask:0xf bank_mask:0xf bound_ctrl:1
	v_mov_b32_dpp v36, v48 row_ror:8 row_mask:0xf bank_mask:0xf bound_ctrl:1
	v_mov_b32_dpp v37, v49 row_ror:8 row_mask:0xf bank_mask:0xf bound_ctrl:1
	v_mov_b32_dpp v50, v38 row_ror:8 row_mask:0xf bank_mask:0xf bound_ctrl:1
	v_mov_b32_dpp v51, v39 row_ror:8 row_mask:0xf bank_mask:0xf bound_ctrl:1
	v_mov_b32_dpp v52, v34 row_ror:8 row_mask:0xf bank_mask:0xf bound_ctrl:1
	v_mov_b32_dpp v53, v35 row_ror:8 row_mask:0xf bank_mask:0xf bound_ctrl:1
	v_max_f32_e32 v30, 0, v30
	v_max_f32_e32 v26, 0, v26
	v_max_f32_e32 v31, 0, v31
	v_max_f32_e32 v27, 0, v27
	v_max_f32_e32 v32, 0, v32
	v_max_f32_e32 v28, 0, v28
	v_max_f32_e32 v33, 0, v33
	v_max_f32_e32 v29, 0, v29
	v_max_f32_e32 v22, 0, v22
	v_max_f32_e32 v18, 0, v18
	v_max_f32_e32 v23, 0, v23
	v_max_f32_e32 v19, 0, v19
	v_max_f32_e32 v24, 0, v24
	v_max_f32_e32 v20, 0, v20
	v_max_f32_e32 v25, 0, v25
	v_max_f32_e32 v21, 0, v21
	v_lshl_add_u64 v[44:45], v[42:43], 0, v[140:141]
	v_cndmask_b32_e64 v37, v37, v35, s[6:7]
	v_cndmask_b32_e64 v36, v36, v34, s[6:7]
	v_cndmask_b32_e64 v35, v41, v39, s[6:7]
	v_cndmask_b32_e64 v34, v40, v38, s[6:7]
	v_cndmask_b32_e64 v41, v49, v53, s[6:7]
	v_cndmask_b32_e64 v40, v48, v52, s[6:7]
	v_cndmask_b32_e64 v39, v47, v51, s[6:7]
	v_cndmask_b32_e64 v38, v46, v50, s[6:7]
	v_pk_mul_f32 v[30:31], v[30:31], v[30:31]
	v_pk_mul_f32 v[26:27], v[26:27], v[26:27]
	v_pk_mul_f32 v[32:33], v[32:33], v[32:33]
	v_pk_mul_f32 v[28:29], v[28:29], v[28:29]
	v_pk_mul_f32 v[22:23], v[22:23], v[22:23]
	v_pk_mul_f32 v[18:19], v[18:19], v[18:19]
	v_pk_mul_f32 v[24:25], v[24:25], v[24:25]
	v_pk_mul_f32 v[20:21], v[20:21], v[20:21]
	v_lshl_add_u64 v[42:43], v[42:43], 0, v[142:143]
	global_store_dwordx4 v[44:45], v[38:41], off
	global_store_dwordx4 v[42:43], v[34:37], off
	v_cvt_pk_bf16_f32 v30, v30, v31
; __device__ __forceinline__ unsigned pk2(float lo, float hi) { const f32x2 v = {lo, hi}; return __builtin_bit_cast(unsigned, __builtin_convertvector(v, bf16x2_t)); }
; #define PG8_BAR __builtin_amdgcn_s_barrier()
; template <class Epi, class Sched, bool ABLK = false, bool ALIGN_EPI = true, bool SP2 = true, bool BBLK = true>
; __device__ __forceinline__ void gemm_phase(LAS unsigned char* lds, const Gemm g, const Sched& S, const Epi& E) {
;     ...
;         if (!has_next) break;
; #pragma unroll
;         for (int a = 0; a < 2; ++a)
; #pragma unroll
;             for (int b = 0; b < 2; ++b)
; #pragma unroll
;                 for (int m = 0; m < 4; ++m)
; #pragma unroll
;                     for (int n = 0; n < 2; ++n) acc[a][b][m][n] = (f32x4){0.f, 0.f, 0.f, 0.f};
;         cur = nxt; uA = nuA; tbA = ntbA; cB = nB; ++ui;
;         if constexpr (ALIGN_EPI) { if (wr == 1) PG8_BAR; }
;     __device__ __forceinline__ void operator()(const f32x4 (&acc)[2][2][4][2], const Unit& u, int wr, int wc, int fr, int fq) const {
; #pragma unroll
;         for (int ai = 0; ai < 2; ++ai)
; #pragma unroll
;             for (int m = 0; m < 4; ++m) { unsigned char* rowp = (unsigned char*)(H + ((size_t)(u.pm * (FF / 64) + u.pn * 4 + wc) * 256 + (wr * 64 + fr + ai * 128 + m * 16)) * 64 + 8 * fq); u32x4 w[2];
; #pragma unroll
;                 for (int bj = 0; bj < 2; ++bj) { f32x4 v0 = acc[ai][bj][m][0], v1 = acc[ai][bj][m][1];
; #pragma unroll
;                     for (int j = 0; j < 4; ++j) { const float a = fmaxf(v0[j], 0.f), b = fmaxf(v1[j], 0.f); v0[j] = a * a; v1[j] = b * b; }
;                     w[bj].x = pk2(v0[0], v0[1]); w[bj].y = pk2(v0[2], v0[3]); w[bj].z = pk2(v1[0], v1[1]); w[bj].w = pk2(v1[2], v1[3]); }
;                 store_pair(rowp, (size_t)8 * 64 * 2, 64, w[0], w[1], fr >= 8); }
	v_cvt_pk_bf16_f32 v31, v32, v33
	v_lshl_add_u64 v[34:35], s[22:23], 0, v[156:157]
	v_cvt_pk_bf16_f32 v32, v26, v27
	v_cvt_pk_bf16_f32 v33, v28, v29
	v_cvt_pk_bf16_f32 v22, v22, v23
	v_cvt_pk_bf16_f32 v23, v24, v25
	v_cvt_pk_bf16_f32 v18, v18, v19
	v_cvt_pk_bf16_f32 v19, v20, v21
	v_lshl_add_u64 v[26:27], v[34:35], 0, v[138:139]
	v_mov_b32_dpp v24, v30 row_ror:8 row_mask:0xf bank_mask:0xf bound_ctrl:1
	v_mov_b32_dpp v25, v31 row_ror:8 row_mask:0xf bank_mask:0xf bound_ctrl:1
	v_mov_b32_dpp v20, v32 row_ror:8 row_mask:0xf bank_mask:0xf bound_ctrl:1
	v_mov_b32_dpp v21, v33 row_ror:8 row_mask:0xf bank_mask:0xf bound_ctrl:1
	v_mov_b32_dpp v34, v22 row_ror:8 row_mask:0xf bank_mask:0xf bound_ctrl:1
	v_mov_b32_dpp v35, v23 row_ror:8 row_mask:0xf bank_mask:0xf bound_ctrl:1
	v_mov_b32_dpp v36, v18 row_ror:8 row_mask:0xf bank_mask:0xf bound_ctrl:1
	v_mov_b32_dpp v37, v19 row_ror:8 row_mask:0xf bank_mask:0xf bound_ctrl:1
	v_max_f32_e32 v14, 0, v14
	v_max_f32_e32 v10, 0, v10
	v_max_f32_e32 v15, 0, v15
	v_max_f32_e32 v11, 0, v11
	v_max_f32_e32 v16, 0, v16
	v_max_f32_e32 v12, 0, v12
	v_max_f32_e32 v17, 0, v17
	v_max_f32_e32 v13, 0, v13
	v_max_f32_e32 v6, 0, v6
	v_max_f32_e32 v2, 0, v2
	v_max_f32_e32 v7, 0, v7
	v_max_f32_e32 v3, 0, v3
	v_max_f32_e32 v8, 0, v8
	v_max_f32_e32 v4, 0, v4
	v_max_f32_e32 v9, 0, v9
	v_max_f32_e32 v5, 0, v5
	v_lshl_add_u64 v[28:29], v[26:27], 0, v[140:141]
	v_cndmask_b32_e64 v21, v21, v19, s[6:7]
	v_cndmask_b32_e64 v20, v20, v18, s[6:7]
	v_cndmask_b32_e64 v19, v25, v23, s[6:7]
	v_cndmask_b32_e64 v18, v24, v22, s[6:7]
	v_cndmask_b32_e64 v25, v33, v37, s[6:7]
	v_cndmask_b32_e64 v24, v32, v36, s[6:7]
	v_cndmask_b32_e64 v23, v31, v35, s[6:7]
	v_cndmask_b32_e64 v22, v30, v34, s[6:7]
	v_pk_mul_f32 v[14:15], v[14:15], v[14:15]
	v_pk_mul_f32 v[10:11], v[10:11], v[10:11]
	v_pk_mul_f32 v[16:17], v[16:17], v[16:17]
	v_pk_mul_f32 v[12:13], v[12:13], v[12:13]
	v_pk_mul_f32 v[6:7], v[6:7], v[6:7]
	v_pk_mul_f32 v[2:3], v[2:3], v[2:3]
	v_pk_mul_f32 v[8:9], v[8:9], v[8:9]
	v_pk_mul_f32 v[4:5], v[4:5], v[4:5]
	v_lshl_add_u64 v[26:27], v[26:27], 0, v[142:143]
	global_store_dwordx4 v[28:29], v[22:25], off
	global_store_dwordx4 v[26:27], v[18:21], off
	v_cvt_pk_bf16_f32 v14, v14, v15
	v_cvt_pk_bf16_f32 v15, v16, v17
	v_lshl_add_u64 v[18:19], s[22:23], 0, v[158:159]
	v_cvt_pk_bf16_f32 v16, v10, v11
	v_cvt_pk_bf16_f32 v17, v12, v13
	v_cvt_pk_bf16_f32 v6, v6, v7
	v_cvt_pk_bf16_f32 v7, v8, v9
	v_cvt_pk_bf16_f32 v2, v2, v3
	v_cvt_pk_bf16_f32 v3, v4, v5
	v_lshl_add_u64 v[10:11], v[18:19], 0, v[138:139]
	v_mov_b32_dpp v8, v14 row_ror:8 row_mask:0xf bank_mask:0xf bound_ctrl:1
	v_mov_b32_dpp v9, v15 row_ror:8 row_mask:0xf bank_mask:0xf bound_ctrl:1
	v_mov_b32_dpp v4, v16 row_ror:8 row_mask:0xf bank_mask:0xf bound_ctrl:1
	v_mov_b32_dpp v5, v17 row_ror:8 row_mask:0xf bank_mask:0xf bound_ctrl:1
	v_mov_b32_dpp v18, v6 row_ror:8 row_mask:0xf bank_mask:0xf bound_ctrl:1
	v_mov_b32_dpp v19, v7 row_ror:8 row_mask:0xf bank_mask:0xf bound_ctrl:1
	v_mov_b32_dpp v20, v2 row_ror:8 row_mask:0xf bank_mask:0xf bound_ctrl:1
	v_mov_b32_dpp v21, v3 row_ror:8 row_mask:0xf bank_mask:0xf bound_ctrl:1
	v_lshl_add_u64 v[12:13], v[10:11], 0, v[140:141]
	v_cndmask_b32_e64 v5, v5, v3, s[6:7]
	v_cndmask_b32_e64 v4, v4, v2, s[6:7]
	v_cndmask_b32_e64 v3, v9, v7, s[6:7]
	v_cndmask_b32_e64 v2, v8, v6, s[6:7]
	v_cndmask_b32_e64 v9, v17, v21, s[6:7]
	v_cndmask_b32_e64 v8, v16, v20, s[6:7]
	v_cndmask_b32_e64 v7, v15, v19, s[6:7]
	v_cndmask_b32_e64 v6, v14, v18, s[6:7]
	s_andn2_b64 vcc, exec, s[18:19]
	s_mov_b64 s[4:5], -1
	v_lshl_add_u64 v[10:11], v[10:11], 0, v[142:143]
	global_store_dwordx4 v[12:13], v[6:9], off
	global_store_dwordx4 v[10:11], v[2:5], off
	s_cbranch_vccnz .LBB0_471
	s_andn2_b64 vcc, exec, s[2:3]
	s_cbranch_vccnz .LBB0_470
	s_barrier
	s_branch .LBB0_470

; #define PG8_STAGE(bufoff, gbase, voff) do { _Pragma("unroll") for (int _i = 0; _i < 2; ++_i) \
;         __builtin_amdgcn_global_load_lds((const unsigned*)((const char*)(gbase) + (voff)[_i]), (LAS unsigned*)(lds + (bufoff) + ldsw + _i * 8192), 16, 0, 0); } while (0)
; #define PG8_LDA(dst, b, h) do { _Pragma("unroll") for (int m = 0; m < 4; ++m) _Pragma("unroll") for (int k = 0; k < 2; ++k) dst[m][k] = *(const LAS bf16x8*)(lds + PG8_SA(b, h) + aoff + m * 2048 + k * 1024); } while (0)
; #define PG8_LDB(dst, b, h) do { _Pragma("unroll") for (int n = 0; n < 2; ++n) _Pragma("unroll") for (int k = 0; k < 2; ++k) dst[n][k] = *(const LAS bf16x8*)(lds + PG8_SB(b, h) + boff + n * 2048 + k * 1024); } while (0)
; #define PG8_WAIT_V(n) asm volatile("s_waitcnt vmcnt(" #n ")" ::: "memory")
; #define PG8_WAIT_L(n) asm volatile("s_waitcnt lgkmcnt(" #n ")" ::: "memory")
; #define PG8_BAR __builtin_amdgcn_s_barrier()
; template <class Epi, class Sched, bool ABLK = false, bool ALIGN_EPI = true, bool SP2 = true, bool BBLK = true>
; __device__ __forceinline__ void gemm_phase(LAS unsigned char* lds, const Gemm g, const Sched& S, const Epi& E) {
;     ...
;         const char* nuA = has_next ? a_unit(nxt) : uA; const int ntbA = has_next ? nxt.k0 / BK : tbA; const char* nB = has_next ? (const char*)g.Bt + (size_t)nxt.pn * tstepB + b_k0(nxt.k0) : cB;
;         for (int t = 0; t < nt; t += 2) {
;             const bool last = (t == nt - 2);
;             const char* a1 = a_tile(uA, tbA + t + 1);
;             const char* a2 = last ? a_tile(nuA, ntbA) : a_tile(uA, tbA + t + 2); const char* b2 = last ? nB : cB + (size_t)(t + 2) * kstepB;
;             const char* a3 = last ? a_tile(nuA, ntbA + 1) : a_tile(uA, tbA + t + 3); const char* b3 = b2 + kstepB;
;             if (last && has_next) S.a_ready(nxt);
;             if constexpr (SP2) {
;             PG8_LDB(B0, 0, 0); PG8_LDB(B1, 0, 1); PG8_SCHED; PG8_LDA(At, 0, 0); PG8_STAGE(PG8_SA(1, 1), a1 + hstepA, voffA);
;             PG8_WAIT_V(8); PG8_WAIT_L(0); PG8_BAR; PG8_MMA(0, 0, At, B0); PG8_MMA(0, 1, At, B1); PG8_BAR; PG8_SCHED;
;             PG8_LDA(At, 0, 1); PG8_STAGE(PG8_SB(0, 0), b2, voffB); PG8_STAGE(PG8_SB(0, 1), b2 + hstepB, voffB); PG8_STAGE(PG8_SA(0, 0), a2, voffA);
;             PG8_WAIT_V(8); PG8_WAIT_L(0); PG8_BAR; PG8_MMA(1, 0, At, B0); PG8_MMA(1, 1, At, B1); PG8_BAR; PG8_SCHED;
.LBB0_540:
	ds_read_b128 v[152:155], v148
	ds_read_b128 v[156:159], v148 offset:1024
	ds_read_b128 v[160:163], v148 offset:2048
	ds_read_b128 v[164:167], v148 offset:3072
	ds_read_b128 v[168:171], v149
	ds_read_b128 v[172:175], v149 offset:1024
	ds_read_b128 v[176:179], v149 offset:2048
	ds_read_b128 v[180:183], v149 offset:3072
	s_add_u32 s42, s75, s40
	s_addc_u32 s43, s76, s41
	s_add_u32 s48, s42, 0x10000
	s_addc_u32 s49, s43, 0
	s_add_i32 s79, s79, 2
	s_add_u32 s46, s66, s40
	s_addc_u32 s47, s67, s41
	s_add_u32 s42, s42, 0x18000
	s_addc_u32 s43, s43, 0
	s_cmp_eq_u32 s77, s40
	s_cselect_b32 s43, s65, s43
	s_cselect_b32 s42, s64, s42
	s_cselect_b32 s47, s4, s47
	s_cselect_b32 s46, s5, s46
	s_cselect_b32 s49, s63, s49
	s_cselect_b32 s48, s35, s48
	v_lshl_add_u64 v[216:217], v[142:143], 0, s[40:41]
	s_add_i32 m0, s52, 0xc000
	ds_read_b128 v[184:187], v150
	ds_read_b128 v[188:191], v150 offset:1024
	ds_read_b128 v[192:195], v150 offset:2048
	ds_read_b128 v[196:199], v150 offset:3072
	ds_read_b128 v[200:203], v150 offset:4096
	ds_read_b128 v[204:207], v150 offset:5120
	ds_read_b128 v[208:211], v150 offset:6144
	ds_read_b128 v[212:215], v150 offset:7168
	global_load_lds_dwordx4 v[216:217], off
	v_lshl_add_u64 v[216:217], v[144:145], 0, s[40:41]
	s_add_i32 m0, s52, 0xe000
	s_nop 0
	global_load_lds_dwordx4 v[216:217], off
	s_waitcnt vmcnt(8) lgkmcnt(0)
	s_barrier
	v_mfma_f32_16x16x32_bf16 v[126:129], v[152:155], v[184:187], v[126:129]
	v_mfma_f32_16x16x32_bf16 v[122:125], v[160:163], v[184:187], v[122:125]
	v_mfma_f32_16x16x32_bf16 v[110:113], v[152:155], v[192:195], v[110:113]
	v_mfma_f32_16x16x32_bf16 v[106:109], v[160:163], v[192:195], v[106:109]
	v_mfma_f32_16x16x32_bf16 v[94:97], v[152:155], v[200:203], v[94:97]
	v_mfma_f32_16x16x32_bf16 v[90:93], v[160:163], v[200:203], v[90:93]
	v_mfma_f32_16x16x32_bf16 v[78:81], v[152:155], v[208:211], v[78:81]
	v_mfma_f32_16x16x32_bf16 v[74:77], v[160:163], v[208:211], v[74:77]
	v_mfma_f32_16x16x32_bf16 v[126:129], v[156:159], v[188:191], v[126:129]
	v_mfma_f32_16x16x32_bf16 v[122:125], v[164:167], v[188:191], v[122:125]
	v_mfma_f32_16x16x32_bf16 v[110:113], v[156:159], v[196:199], v[110:113]
	v_mfma_f32_16x16x32_bf16 v[106:109], v[164:167], v[196:199], v[106:109]
	v_mfma_f32_16x16x32_bf16 v[94:97], v[156:159], v[204:207], v[94:97]
	v_mfma_f32_16x16x32_bf16 v[90:93], v[164:167], v[204:207], v[90:93]
	v_mfma_f32_16x16x32_bf16 v[78:81], v[156:159], v[212:215], v[78:81]
	v_mfma_f32_16x16x32_bf16 v[74:77], v[164:167], v[212:215], v[74:77]
	v_mfma_f32_16x16x32_bf16 v[118:121], v[168:171], v[184:187], v[118:121]
	v_mfma_f32_16x16x32_bf16 v[114:117], v[176:179], v[184:187], v[114:117]
	v_mfma_f32_16x16x32_bf16 v[102:105], v[168:171], v[192:195], v[102:105]
	v_mfma_f32_16x16x32_bf16 v[98:101], v[176:179], v[192:195], v[98:101]
	v_mfma_f32_16x16x32_bf16 v[86:89], v[168:171], v[200:203], v[86:89]
	v_mfma_f32_16x16x32_bf16 v[82:85], v[176:179], v[200:203], v[82:85]
	v_mfma_f32_16x16x32_bf16 v[70:73], v[168:171], v[208:211], v[70:73]
	v_mfma_f32_16x16x32_bf16 v[66:69], v[176:179], v[208:211], v[66:69]
	v_mfma_f32_16x16x32_bf16 v[118:121], v[172:175], v[188:191], v[118:121]
	v_mfma_f32_16x16x32_bf16 v[114:117], v[180:183], v[188:191], v[114:117]
	v_mfma_f32_16x16x32_bf16 v[102:105], v[172:175], v[196:199], v[102:105]
	v_mfma_f32_16x16x32_bf16 v[98:101], v[180:183], v[196:199], v[98:101]
	v_mfma_f32_16x16x32_bf16 v[86:89], v[172:175], v[204:207], v[86:89]
	v_mfma_f32_16x16x32_bf16 v[82:85], v[180:183], v[204:207], v[82:85]
	v_mfma_f32_16x16x32_bf16 v[70:73], v[172:175], v[212:215], v[70:73]
	v_mfma_f32_16x16x32_bf16 v[66:69], v[180:183], v[212:215], v[66:69]
	s_barrier
	s_add_i32 s60, s72, s51
	s_mov_b32 m0, s60
	ds_read_b128 v[184:187], v150 offset:16384
	ds_read_b128 v[188:191], v150 offset:17408
	ds_read_b128 v[192:195], v150 offset:18432
	ds_read_b128 v[196:199], v150 offset:19456
	ds_read_b128 v[200:203], v150 offset:20480
	ds_read_b128 v[204:207], v150 offset:21504
	ds_read_b128 v[208:211], v150 offset:22528
	ds_read_b128 v[212:215], v150 offset:23552
	global_load_lds_dwordx4 v130, s[46:47]
	s_add_i32 m0, s60, 0x2000
	s_add_u32 s60, s46, 0x4000
	s_addc_u32 s61, s47, 0
	s_add_i32 s81, s73, s51
	global_load_lds_dwordx4 v132, s[46:47]
	s_mov_b32 m0, s81
	s_nop 0
	global_load_lds_dwordx4 v130, s[60:61]
	s_add_i32 m0, s81, 0x2000
	s_nop 0
	global_load_lds_dwordx4 v132, s[60:61]
	s_mov_b32 m0, s52
	s_nop 0
	global_load_lds_dwordx4 v130, s[48:49]
	s_mov_b32 m0, s53
	s_nop 0
	global_load_lds_dwordx4 v132, s[48:49]
	s_waitcnt vmcnt(8) lgkmcnt(0)
	s_barrier
; #define PG8_STAGE(bufoff, gbase, voff) do { _Pragma("unroll") for (int _i = 0; _i < 2; ++_i) \
;         __builtin_amdgcn_global_load_lds((const unsigned*)((const char*)(gbase) + (voff)[_i]), (LAS unsigned*)(lds + (bufoff) + ldsw + _i * 8192), 16, 0, 0); } while (0)
; #define PG8_LDA(dst, b, h) do { _Pragma("unroll") for (int m = 0; m < 4; ++m) _Pragma("unroll") for (int k = 0; k < 2; ++k) dst[m][k] = *(const LAS bf16x8*)(lds + PG8_SA(b, h) + aoff + m * 2048 + k * 1024); } while (0)
; #define PG8_LDB(dst, b, h) do { _Pragma("unroll") for (int n = 0; n < 2; ++n) _Pragma("unroll") for (int k = 0; k < 2; ++k) dst[n][k] = *(const LAS bf16x8*)(lds + PG8_SB(b, h) + boff + n * 2048 + k * 1024); } while (0)
; #define PG8_MMA(ai, bj, At, Bt) do { __builtin_amdgcn_s_setprio(1); _Pragma("unroll") for (int m = 0; m < 4; ++m) _Pragma("unroll") for (int n = 0; n < 2; ++n) _Pragma("unroll") for (int k = 0; k < 2; ++k) \
;         acc[ai][bj][m][n] = __builtin_amdgcn_mfma_f32_16x16x32_bf16(Bt[n][k], At[m][k], acc[ai][bj][m][n], 0, 0, 0); __builtin_amdgcn_s_setprio(0); } while (0)
; #define PG8_WAIT_V(n) asm volatile("s_waitcnt vmcnt(" #n ")" ::: "memory")
; #define PG8_WAIT_L(n) asm volatile("s_waitcnt lgkmcnt(" #n ")" ::: "memory")
; #define PG8_BAR __builtin_amdgcn_s_barrier()
; #define PG8_SCHED __builtin_amdgcn_sched_barrier(0)
; template <class Epi, class Sched, bool ABLK = false, bool ALIGN_EPI = true, bool SP2 = true, bool BBLK = true>
; __device__ __forceinline__ void gemm_phase(LAS unsigned char* lds, const Gemm g, const Sched& S, const Epi& E) {
;     ...
;             PG8_LDB(B0, 1, 0); PG8_LDB(B1, 1, 1); PG8_SCHED; PG8_LDA(At, 1, 0); PG8_STAGE(PG8_SA(0, 1), a2 + hstepA, voffA);
;             PG8_WAIT_V(8); PG8_WAIT_L(0); PG8_BAR; PG8_MMA(0, 0, At, B0); PG8_MMA(0, 1, At, B1); PG8_BAR; PG8_SCHED;
;             PG8_LDA(At, 1, 1); PG8_STAGE(PG8_SB(1, 0), b3, voffB); PG8_STAGE(PG8_SB(1, 1), b3 + hstepB, voffB); PG8_STAGE(PG8_SA(1, 0), a3, voffA);
;             PG8_WAIT_V(8); PG8_WAIT_L(0); PG8_BAR; PG8_MMA(1, 0, At, B0); PG8_MMA(1, 1, At, B1); PG8_BAR; PG8_SCHED;
	v_mfma_f32_16x16x32_bf16 v[62:65], v[152:155], v[184:187], v[62:65]
	v_mfma_f32_16x16x32_bf16 v[58:61], v[160:163], v[184:187], v[58:61]
	v_mfma_f32_16x16x32_bf16 v[46:49], v[152:155], v[192:195], v[46:49]
	v_mfma_f32_16x16x32_bf16 v[42:45], v[160:163], v[192:195], v[42:45]
	v_mfma_f32_16x16x32_bf16 v[30:33], v[152:155], v[200:203], v[30:33]
	v_mfma_f32_16x16x32_bf16 v[26:29], v[160:163], v[200:203], v[26:29]
	v_mfma_f32_16x16x32_bf16 v[14:17], v[152:155], v[208:211], v[14:17]
	v_mfma_f32_16x16x32_bf16 v[10:13], v[160:163], v[208:211], v[10:13]
	v_mfma_f32_16x16x32_bf16 v[62:65], v[156:159], v[188:191], v[62:65]
	v_mfma_f32_16x16x32_bf16 v[58:61], v[164:167], v[188:191], v[58:61]
	v_mfma_f32_16x16x32_bf16 v[46:49], v[156:159], v[196:199], v[46:49]
	v_mfma_f32_16x16x32_bf16 v[42:45], v[164:167], v[196:199], v[42:45]
	v_mfma_f32_16x16x32_bf16 v[30:33], v[156:159], v[204:207], v[30:33]
	v_mfma_f32_16x16x32_bf16 v[26:29], v[164:167], v[204:207], v[26:29]
	v_mfma_f32_16x16x32_bf16 v[14:17], v[156:159], v[212:215], v[14:17]
	v_mfma_f32_16x16x32_bf16 v[10:13], v[164:167], v[212:215], v[10:13]
	v_mfma_f32_16x16x32_bf16 v[54:57], v[168:171], v[184:187], v[54:57]
	v_mfma_f32_16x16x32_bf16 v[50:53], v[176:179], v[184:187], v[50:53]
	v_mfma_f32_16x16x32_bf16 v[38:41], v[168:171], v[192:195], v[38:41]
	v_mfma_f32_16x16x32_bf16 v[34:37], v[176:179], v[192:195], v[34:37]
	v_mfma_f32_16x16x32_bf16 v[22:25], v[168:171], v[200:203], v[22:25]
	v_mfma_f32_16x16x32_bf16 v[18:21], v[176:179], v[200:203], v[18:21]
	v_mfma_f32_16x16x32_bf16 v[6:9], v[168:171], v[208:211], v[6:9]
	v_mfma_f32_16x16x32_bf16 v[2:5], v[176:179], v[208:211], v[2:5]
	v_mfma_f32_16x16x32_bf16 v[54:57], v[172:175], v[188:191], v[54:57]
	v_mfma_f32_16x16x32_bf16 v[50:53], v[180:183], v[188:191], v[50:53]
	v_mfma_f32_16x16x32_bf16 v[38:41], v[172:175], v[196:199], v[38:41]
	v_mfma_f32_16x16x32_bf16 v[34:37], v[180:183], v[196:199], v[34:37]
	v_mfma_f32_16x16x32_bf16 v[22:25], v[172:175], v[204:207], v[22:25]
	v_mfma_f32_16x16x32_bf16 v[18:21], v[180:183], v[204:207], v[18:21]
	v_mfma_f32_16x16x32_bf16 v[6:9], v[172:175], v[212:215], v[6:9]
	v_mfma_f32_16x16x32_bf16 v[2:5], v[180:183], v[212:215], v[2:5]
	s_barrier
	s_add_i32 s60, 0, 0x18000
	v_add_u32_e32 v151, s60, v146
	s_add_i32 s61, 0, 0x1c000
	ds_read_b128 v[152:155], v151
	ds_read_b128 v[156:159], v151 offset:1024
	ds_read_b128 v[160:163], v151 offset:2048
	ds_read_b128 v[164:167], v151 offset:3072
	v_add_u32_e32 v151, s61, v146
	ds_read_b128 v[168:171], v151
	ds_read_b128 v[172:175], v151 offset:1024
	ds_read_b128 v[176:179], v151 offset:2048
	ds_read_b128 v[180:183], v151 offset:3072
	s_add_u32 s48, s48, 0x4000
	s_addc_u32 s49, s49, 0
	s_mov_b32 m0, s54
	ds_read_b128 v[184:187], v150 offset:32768
	ds_read_b128 v[188:191], v150 offset:33792
	ds_read_b128 v[192:195], v150 offset:34816
	ds_read_b128 v[196:199], v150 offset:35840
	ds_read_b128 v[200:203], v150 offset:36864
	ds_read_b128 v[204:207], v150 offset:37888
	ds_read_b128 v[208:211], v150 offset:38912
	ds_read_b128 v[212:215], v150 offset:39936
	global_load_lds_dwordx4 v130, s[48:49]
	s_mov_b32 m0, s55
	s_nop 0
	global_load_lds_dwordx4 v132, s[48:49]
	s_waitcnt vmcnt(8) lgkmcnt(0)
	s_barrier
	v_mfma_f32_16x16x32_bf16 v[126:129], v[152:155], v[184:187], v[126:129]
	v_mfma_f32_16x16x32_bf16 v[122:125], v[160:163], v[184:187], v[122:125]
	v_mfma_f32_16x16x32_bf16 v[110:113], v[152:155], v[192:195], v[110:113]
	v_mfma_f32_16x16x32_bf16 v[106:109], v[160:163], v[192:195], v[106:109]
	v_mfma_f32_16x16x32_bf16 v[94:97], v[152:155], v[200:203], v[94:97]
	v_mfma_f32_16x16x32_bf16 v[90:93], v[160:163], v[200:203], v[90:93]
	v_mfma_f32_16x16x32_bf16 v[78:81], v[152:155], v[208:211], v[78:81]
	v_mfma_f32_16x16x32_bf16 v[74:77], v[160:163], v[208:211], v[74:77]
	v_mfma_f32_16x16x32_bf16 v[126:129], v[156:159], v[188:191], v[126:129]
	v_mfma_f32_16x16x32_bf16 v[122:125], v[164:167], v[188:191], v[122:125]
	v_mfma_f32_16x16x32_bf16 v[110:113], v[156:159], v[196:199], v[110:113]
	v_mfma_f32_16x16x32_bf16 v[106:109], v[164:167], v[196:199], v[106:109]
	v_mfma_f32_16x16x32_bf16 v[94:97], v[156:159], v[204:207], v[94:97]
	v_mfma_f32_16x16x32_bf16 v[90:93], v[164:167], v[204:207], v[90:93]
	v_mfma_f32_16x16x32_bf16 v[78:81], v[156:159], v[212:215], v[78:81]
	v_mfma_f32_16x16x32_bf16 v[74:77], v[164:167], v[212:215], v[74:77]
	v_mfma_f32_16x16x32_bf16 v[118:121], v[168:171], v[184:187], v[118:121]
	v_mfma_f32_16x16x32_bf16 v[114:117], v[176:179], v[184:187], v[114:117]
	v_mfma_f32_16x16x32_bf16 v[102:105], v[168:171], v[192:195], v[102:105]
	v_mfma_f32_16x16x32_bf16 v[98:101], v[176:179], v[192:195], v[98:101]
	v_mfma_f32_16x16x32_bf16 v[86:89], v[168:171], v[200:203], v[86:89]
	v_mfma_f32_16x16x32_bf16 v[82:85], v[176:179], v[200:203], v[82:85]
	v_mfma_f32_16x16x32_bf16 v[70:73], v[168:171], v[208:211], v[70:73]
	v_mfma_f32_16x16x32_bf16 v[66:69], v[176:179], v[208:211], v[66:69]
	v_mfma_f32_16x16x32_bf16 v[118:121], v[172:175], v[188:191], v[118:121]
	v_mfma_f32_16x16x32_bf16 v[114:117], v[180:183], v[188:191], v[114:117]
	v_mfma_f32_16x16x32_bf16 v[102:105], v[172:175], v[196:199], v[102:105]
	v_mfma_f32_16x16x32_bf16 v[98:101], v[180:183], v[196:199], v[98:101]
	v_mfma_f32_16x16x32_bf16 v[86:89], v[172:175], v[204:207], v[86:89]
	v_mfma_f32_16x16x32_bf16 v[82:85], v[180:183], v[204:207], v[82:85]
	v_mfma_f32_16x16x32_bf16 v[70:73], v[172:175], v[212:215], v[70:73]
	v_mfma_f32_16x16x32_bf16 v[66:69], v[180:183], v[212:215], v[66:69]
	s_barrier
; __device__ __forceinline__ unsigned pk2(float lo, float hi) { const f32x2 v = {lo, hi}; return __builtin_bit_cast(unsigned, __builtin_convertvector(v, bf16x2_t)); }
; #define PG8_STAGE(bufoff, gbase, voff) do { _Pragma("unroll") for (int _i = 0; _i < 2; ++_i) \
;         __builtin_amdgcn_global_load_lds((const unsigned*)((const char*)(gbase) + (voff)[_i]), (LAS unsigned*)(lds + (bufoff) + ldsw + _i * 8192), 16, 0, 0); } while (0)
; #define PG8_LDA(dst, b, h) do { _Pragma("unroll") for (int m = 0; m < 4; ++m) _Pragma("unroll") for (int k = 0; k < 2; ++k) dst[m][k] = *(const LAS bf16x8*)(lds + PG8_SA(b, h) + aoff + m * 2048 + k * 1024); } while (0)
; #define PG8_WAIT_V(n) asm volatile("s_waitcnt vmcnt(" #n ")" ::: "memory")
; #define PG8_WAIT_L(n) asm volatile("s_waitcnt lgkmcnt(" #n ")" ::: "memory")
; #define PG8_BAR __builtin_amdgcn_s_barrier()
; #define PG8_SCHED __builtin_amdgcn_sched_barrier(0)
; template <class Epi, class Sched, bool ABLK = false, bool ALIGN_EPI = true, bool SP2 = true, bool BBLK = true>
; __device__ __forceinline__ void gemm_phase(LAS unsigned char* lds, const Gemm g, const Sched& S, const Epi& E) {
;     ...
;             PG8_WAIT_V(8); PG8_WAIT_L(0); PG8_BAR; PG8_MMA(0, 0, At, B0); PG8_MMA(0, 1, At, B1); PG8_BAR; PG8_SCHED;
;             PG8_LDA(At, 1, 1); PG8_STAGE(PG8_SB(1, 0), b3, voffB); PG8_STAGE(PG8_SB(1, 1), b3 + hstepB, voffB); PG8_STAGE(PG8_SA(1, 0), a3, voffA);
;             PG8_WAIT_V(8); PG8_WAIT_L(0); PG8_BAR; PG8_MMA(1, 0, At, B0); PG8_MMA(1, 1, At, B1); PG8_BAR; PG8_SCHED;
;     __device__ __forceinline__ void operator()(const f32x4 (&acc)[2][2][4][2], const Unit& u, int wr, int wc, int fr, int fq) const {
;         const int row0 = u.pm * 256 + wr * 64 + fr, col0 = u.pn * 256 + wc * 64 + 8 * fq;
;         bf16_t* base = u.part == 0 ? Z + (size_t)row0 * D + col0 : P + ((size_t)(u.part - 1) * MS + (row0 - MP)) * D + col0;
; #pragma unroll
;         for (int ai = 0; ai < 2; ++ai)
; #pragma unroll
;             for (int m = 0; m < 4; ++m) { u32x4 w[2];
; #pragma unroll
;                 for (int bj = 0; bj < 2; ++bj) { const f32x4 v0 = acc[ai][bj][m][0], v1 = acc[ai][bj][m][1]; w[bj].x = pk2(v0[0], v0[1]); w[bj].y = pk2(v0[2], v0[3]); w[bj].z = pk2(v1[0], v1[1]); w[bj].w = pk2(v1[2], v1[3]); }
;                 store_pair((unsigned char*)(base + (size_t)(ai * 128 + m * 16) * D), (size_t)8 * D * 2, 64, w[0], w[1], fr >= 8); }
	s_add_u32 s48, s46, 0x8000
	s_addc_u32 s49, s47, 0
	s_add_i32 s81, s60, s51
	s_mov_b32 m0, s81
	ds_read_b128 v[184:187], v150 offset:49152
	ds_read_b128 v[188:191], v150 offset:50176
	ds_read_b128 v[192:195], v150 offset:51200
	ds_read_b128 v[196:199], v150 offset:52224
	ds_read_b128 v[200:203], v150 offset:53248
	ds_read_b128 v[204:207], v150 offset:54272
	ds_read_b128 v[208:211], v150 offset:55296
	ds_read_b128 v[212:215], v150 offset:56320
	global_load_lds_dwordx4 v130, s[48:49]
	s_add_i32 m0, s81, 0x2000
	s_add_u32 s46, s46, 0xc000
	v_lshl_add_u64 v[216:217], s[48:49], 0, v[132:133]
	s_addc_u32 s47, s47, 0
	s_add_i32 s48, s61, s51
	global_load_lds_dwordx4 v[216:217], off
	s_mov_b32 m0, s48
	s_nop 0
	global_load_lds_dwordx4 v130, s[46:47]
	s_add_i32 m0, s48, 0x2000
	s_nop 0
	global_load_lds_dwordx4 v132, s[46:47]
	s_mov_b32 m0, s56
	s_nop 0
	global_load_lds_dwordx4 v130, s[42:43]
	s_mov_b32 m0, s57
	s_nop 0
	global_load_lds_dwordx4 v132, s[42:43]
	s_waitcnt vmcnt(8) lgkmcnt(0)
	s_barrier
	v_mfma_f32_16x16x32_bf16 v[62:65], v[152:155], v[184:187], v[62:65]
	v_mfma_f32_16x16x32_bf16 v[58:61], v[160:163], v[184:187], v[58:61]
	v_mfma_f32_16x16x32_bf16 v[46:49], v[152:155], v[192:195], v[46:49]
	v_mfma_f32_16x16x32_bf16 v[42:45], v[160:163], v[192:195], v[42:45]
	v_mfma_f32_16x16x32_bf16 v[30:33], v[152:155], v[200:203], v[30:33]
	v_mfma_f32_16x16x32_bf16 v[26:29], v[160:163], v[200:203], v[26:29]
	v_mfma_f32_16x16x32_bf16 v[14:17], v[152:155], v[208:211], v[14:17]
	v_mfma_f32_16x16x32_bf16 v[10:13], v[160:163], v[208:211], v[10:13]
	v_mfma_f32_16x16x32_bf16 v[62:65], v[156:159], v[188:191], v[62:65]
	v_mfma_f32_16x16x32_bf16 v[58:61], v[164:167], v[188:191], v[58:61]
	v_mfma_f32_16x16x32_bf16 v[46:49], v[156:159], v[196:199], v[46:49]
	v_mfma_f32_16x16x32_bf16 v[42:45], v[164:167], v[196:199], v[42:45]
	v_mfma_f32_16x16x32_bf16 v[30:33], v[156:159], v[204:207], v[30:33]
	v_mfma_f32_16x16x32_bf16 v[26:29], v[164:167], v[204:207], v[26:29]
	v_mfma_f32_16x16x32_bf16 v[14:17], v[156:159], v[212:215], v[14:17]
	v_mfma_f32_16x16x32_bf16 v[10:13], v[164:167], v[212:215], v[10:13]
	v_mfma_f32_16x16x32_bf16 v[54:57], v[168:171], v[184:187], v[54:57]
	v_mfma_f32_16x16x32_bf16 v[50:53], v[176:179], v[184:187], v[50:53]
	v_mfma_f32_16x16x32_bf16 v[38:41], v[168:171], v[192:195], v[38:41]
	v_mfma_f32_16x16x32_bf16 v[34:37], v[176:179], v[192:195], v[34:37]
	v_mfma_f32_16x16x32_bf16 v[22:25], v[168:171], v[200:203], v[22:25]
	v_mfma_f32_16x16x32_bf16 v[18:21], v[176:179], v[200:203], v[18:21]
	v_mfma_f32_16x16x32_bf16 v[6:9], v[168:171], v[208:211], v[6:9]
	v_mfma_f32_16x16x32_bf16 v[2:5], v[176:179], v[208:211], v[2:5]
	v_mfma_f32_16x16x32_bf16 v[54:57], v[172:175], v[188:191], v[54:57]
	v_mfma_f32_16x16x32_bf16 v[50:53], v[180:183], v[188:191], v[50:53]
	v_mfma_f32_16x16x32_bf16 v[38:41], v[172:175], v[196:199], v[38:41]
	v_mfma_f32_16x16x32_bf16 v[34:37], v[180:183], v[196:199], v[34:37]
	v_mfma_f32_16x16x32_bf16 v[22:25], v[172:175], v[204:207], v[22:25]
	v_mfma_f32_16x16x32_bf16 v[18:21], v[180:183], v[204:207], v[18:21]
	v_mfma_f32_16x16x32_bf16 v[6:9], v[172:175], v[212:215], v[6:9]
	v_mfma_f32_16x16x32_bf16 v[2:5], v[180:183], v[212:215], v[2:5]
	s_barrier
	s_add_u32 s40, s40, 0x10000
	s_addc_u32 s41, s41, 0
	s_cmp_ge_u32 s79, s59
	s_cbranch_scc0 .LBB0_540
	v_lshl_add_u32 v143, s62, 8, v1
	v_add_u32_e32 v144, 0xffffe000, v143
	v_sub_co_u32_e64 v142, vcc, s58, 1
	v_mov_b32_e32 v145, s17
	s_nop 0
	v_cndmask_b32_e32 v144, v144, v143, vcc
	v_ashrrev_i32_e32 v143, 31, v142
	v_lshlrev_b64 v[142:143], 23, v[142:143]
	v_lshl_add_u64 v[142:143], s[10:11], 0, v[142:143]
	v_cndmask_b32_e32 v143, v143, v145, vcc
	v_mov_b32_e32 v145, s16
	v_cndmask_b32_e32 v142, v142, v145, vcc
	v_ashrrev_i32_e32 v145, 31, v144
	v_lshl_or_b32 v152, s78, 8, v147
	v_lshlrev_b64 v[144:145], 12, v[144:145]
	v_lshl_add_u64 v[142:143], v[142:143], 0, v[144:145]
	v_ashrrev_i32_e32 v153, 31, v152
	v_cvt_pk_bf16_f32 v126, v126, v127
	v_cvt_pk_bf16_f32 v127, v128, v129
	v_cvt_pk_bf16_f32 v128, v122, v123
	v_cvt_pk_bf16_f32 v124, v124, v125
	v_cvt_pk_bf16_f32 v118, v118, v119
	v_cvt_pk_bf16_f32 v119, v120, v121
	v_cvt_pk_bf16_f32 v114, v114, v115
	v_cvt_pk_bf16_f32 v115, v116, v117
	v_lshl_add_u64 v[142:143], v[152:153], 1, v[142:143]
	v_mov_b32_dpp v120, v126 row_ror:8 row_mask:0xf bank_mask:0xf bound_ctrl:1
	v_mov_b32_dpp v121, v127 row_ror:8 row_mask:0xf bank_mask:0xf bound_ctrl:1
	v_mov_b32_dpp v116, v128 row_ror:8 row_mask:0xf bank_mask:0xf bound_ctrl:1
	v_mov_b32_dpp v117, v124 row_ror:8 row_mask:0xf bank_mask:0xf bound_ctrl:1
	v_mov_b32_dpp v125, v118 row_ror:8 row_mask:0xf bank_mask:0xf bound_ctrl:1
	v_mov_b32_dpp v129, v119 row_ror:8 row_mask:0xf bank_mask:0xf bound_ctrl:1
	v_mov_b32_dpp v144, v114 row_ror:8 row_mask:0xf bank_mask:0xf bound_ctrl:1
	v_mov_b32_dpp v145, v115 row_ror:8 row_mask:0xf bank_mask:0xf bound_ctrl:1
	v_lshl_add_u64 v[122:123], v[142:143], 0, v[134:135]
	v_cndmask_b32_e64 v117, v117, v115, s[6:7]
	v_cndmask_b32_e64 v116, v116, v114, s[6:7]
	v_cndmask_b32_e64 v115, v121, v119, s[6:7]
	v_cndmask_b32_e64 v114, v120, v118, s[6:7]
	v_cndmask_b32_e64 v121, v124, v145, s[6:7]
	v_cndmask_b32_e64 v120, v128, v144, s[6:7]
	v_cndmask_b32_e64 v119, v127, v129, s[6:7]
	v_cndmask_b32_e64 v118, v126, v125, s[6:7]
	v_cvt_pk_bf16_f32 v110, v110, v111
	v_cvt_pk_bf16_f32 v111, v112, v113
	v_cvt_pk_bf16_f32 v112, v106, v107
	v_cvt_pk_bf16_f32 v113, v108, v109
	v_cvt_pk_bf16_f32 v102, v102, v103
	v_cvt_pk_bf16_f32 v103, v104, v105
	v_cvt_pk_bf16_f32 v98, v98, v99
	v_cvt_pk_bf16_f32 v99, v100, v101
	v_lshl_add_u64 v[124:125], v[142:143], 0, v[136:137]
	s_and_b64 vcc, exec, s[12:13]
	s_cbranch_vccz .LBB0_543
	s_barrier
; __device__ __forceinline__ unsigned pk2(float lo, float hi) { const f32x2 v = {lo, hi}; return __builtin_bit_cast(unsigned, __builtin_convertvector(v, bf16x2_t)); }
; __device__ __forceinline__ u32x4 ror8(u32x4 v) { u32x4 r;
; #pragma unroll
;     for (int i = 0; i < 4; ++i) r[i] = (unsigned)__builtin_amdgcn_mov_dpp((int)v[i], 0x128, 0xf, 0xf, true);
;     return r; }
; __device__ __forceinline__ void store_pair(unsigned char* own, size_t stride8, int hi_off, u32x4 lo, u32x4 hi, bool upper) {
;     const u32x4 tlo = ror8(lo), thi = ror8(hi);
;     const u32x4 A = upper ? thi : lo, B = upper ? hi : tlo;
;     unsigned char* pa = upper ? own - stride8 + hi_off : own;
;     unsigned char* pb = upper ? own + hi_off : own + stride8;
;     *(u32x4*)pa = A; *(u32x4*)pb = B;
; }
;     __device__ __forceinline__ void operator()(const f32x4 (&acc)[2][2][4][2], const Unit& u, int wr, int wc, int fr, int fq) const {
;         const int row0 = u.pm * 256 + wr * 64 + fr, col0 = u.pn * 256 + wc * 64 + 8 * fq;
;         bf16_t* base = u.part == 0 ? Z + (size_t)row0 * D + col0 : P + ((size_t)(u.part - 1) * MS + (row0 - MP)) * D + col0;
; #pragma unroll
;         for (int ai = 0; ai < 2; ++ai)
; #pragma unroll
;             for (int m = 0; m < 4; ++m) { u32x4 w[2];
; #pragma unroll
;                 for (int bj = 0; bj < 2; ++bj) { const f32x4 v0 = acc[ai][bj][m][0], v1 = acc[ai][bj][m][1]; w[bj].x = pk2(v0[0], v0[1]); w[bj].y = pk2(v0[2], v0[3]); w[bj].z = pk2(v1[0], v1[1]); w[bj].w = pk2(v1[2], v1[3]); }
;                 store_pair((unsigned char*)(base + (size_t)(ai * 128 + m * 16) * D), (size_t)8 * D * 2, 64, w[0], w[1], fr >= 8); }
.LBB0_543:
	global_store_dwordx4 v[122:123], v[118:121], off
	global_store_dwordx4 v[124:125], v[114:117], off
	v_lshl_add_u64 v[106:107], v[142:143], 0, s[14:15]
	v_mov_b32_dpp v104, v110 row_ror:8 row_mask:0xf bank_mask:0xf bound_ctrl:1
	v_mov_b32_dpp v105, v111 row_ror:8 row_mask:0xf bank_mask:0xf bound_ctrl:1
	v_mov_b32_dpp v100, v112 row_ror:8 row_mask:0xf bank_mask:0xf bound_ctrl:1
	v_mov_b32_dpp v101, v113 row_ror:8 row_mask:0xf bank_mask:0xf bound_ctrl:1
	v_mov_b32_dpp v114, v102 row_ror:8 row_mask:0xf bank_mask:0xf bound_ctrl:1
	v_mov_b32_dpp v115, v103 row_ror:8 row_mask:0xf bank_mask:0xf bound_ctrl:1
	v_mov_b32_dpp v116, v98 row_ror:8 row_mask:0xf bank_mask:0xf bound_ctrl:1
	v_mov_b32_dpp v117, v99 row_ror:8 row_mask:0xf bank_mask:0xf bound_ctrl:1
	v_lshl_add_u64 v[108:109], v[106:107], 0, v[134:135]
	v_cndmask_b32_e64 v101, v101, v99, s[6:7]
	v_cndmask_b32_e64 v100, v100, v98, s[6:7]
	v_cndmask_b32_e64 v99, v105, v103, s[6:7]
	v_cndmask_b32_e64 v98, v104, v102, s[6:7]
	v_cndmask_b32_e64 v105, v113, v117, s[6:7]
	v_cndmask_b32_e64 v104, v112, v116, s[6:7]
	v_cndmask_b32_e64 v103, v111, v115, s[6:7]
	v_cndmask_b32_e64 v102, v110, v114, s[6:7]
	v_cvt_pk_bf16_f32 v94, v94, v95
	v_cvt_pk_bf16_f32 v95, v96, v97
	v_cvt_pk_bf16_f32 v96, v90, v91
	v_cvt_pk_bf16_f32 v97, v92, v93
	v_cvt_pk_bf16_f32 v86, v86, v87
	v_cvt_pk_bf16_f32 v87, v88, v89
	v_cvt_pk_bf16_f32 v82, v82, v83
	v_cvt_pk_bf16_f32 v83, v84, v85
	v_lshl_add_u64 v[106:107], v[106:107], 0, v[136:137]
	global_store_dwordx4 v[108:109], v[102:105], off
	global_store_dwordx4 v[106:107], v[98:101], off
	v_lshl_add_u64 v[90:91], v[142:143], 0, s[18:19]
	v_mov_b32_dpp v88, v94 row_ror:8 row_mask:0xf bank_mask:0xf bound_ctrl:1
	v_mov_b32_dpp v89, v95 row_ror:8 row_mask:0xf bank_mask:0xf bound_ctrl:1
	v_mov_b32_dpp v84, v96 row_ror:8 row_mask:0xf bank_mask:0xf bound_ctrl:1
	v_mov_b32_dpp v85, v97 row_ror:8 row_mask:0xf bank_mask:0xf bound_ctrl:1
	v_mov_b32_dpp v98, v86 row_ror:8 row_mask:0xf bank_mask:0xf bound_ctrl:1
	v_mov_b32_dpp v99, v87 row_ror:8 row_mask:0xf bank_mask:0xf bound_ctrl:1
	v_mov_b32_dpp v100, v82 row_ror:8 row_mask:0xf bank_mask:0xf bound_ctrl:1
	v_mov_b32_dpp v101, v83 row_ror:8 row_mask:0xf bank_mask:0xf bound_ctrl:1
	v_lshl_add_u64 v[92:93], v[90:91], 0, v[134:135]
	v_cndmask_b32_e64 v85, v85, v83, s[6:7]
	v_cndmask_b32_e64 v84, v84, v82, s[6:7]
	v_cndmask_b32_e64 v83, v89, v87, s[6:7]
	v_cndmask_b32_e64 v82, v88, v86, s[6:7]
	v_cndmask_b32_e64 v89, v97, v101, s[6:7]
	v_cndmask_b32_e64 v88, v96, v100, s[6:7]
	v_cndmask_b32_e64 v87, v95, v99, s[6:7]
	v_cndmask_b32_e64 v86, v94, v98, s[6:7]
	v_cvt_pk_bf16_f32 v78, v78, v79
	v_cvt_pk_bf16_f32 v79, v80, v81
	v_cvt_pk_bf16_f32 v80, v74, v75
	v_cvt_pk_bf16_f32 v81, v76, v77
	v_cvt_pk_bf16_f32 v70, v70, v71
	v_cvt_pk_bf16_f32 v71, v72, v73
	v_cvt_pk_bf16_f32 v66, v66, v67
	v_cvt_pk_bf16_f32 v67, v68, v69
	v_lshl_add_u64 v[90:91], v[90:91], 0, v[136:137]
	global_store_dwordx4 v[92:93], v[86:89], off
	global_store_dwordx4 v[90:91], v[82:85], off
	v_lshl_add_u64 v[74:75], v[142:143], 0, s[20:21]
	v_mov_b32_dpp v72, v78 row_ror:8 row_mask:0xf bank_mask:0xf bound_ctrl:1
	v_mov_b32_dpp v73, v79 row_ror:8 row_mask:0xf bank_mask:0xf bound_ctrl:1
	v_mov_b32_dpp v68, v80 row_ror:8 row_mask:0xf bank_mask:0xf bound_ctrl:1
	v_mov_b32_dpp v69, v81 row_ror:8 row_mask:0xf bank_mask:0xf bound_ctrl:1
	v_mov_b32_dpp v82, v70 row_ror:8 row_mask:0xf bank_mask:0xf bound_ctrl:1
	v_mov_b32_dpp v83, v71 row_ror:8 row_mask:0xf bank_mask:0xf bound_ctrl:1
	v_mov_b32_dpp v84, v66 row_ror:8 row_mask:0xf bank_mask:0xf bound_ctrl:1
	v_mov_b32_dpp v85, v67 row_ror:8 row_mask:0xf bank_mask:0xf bound_ctrl:1
	v_lshl_add_u64 v[76:77], v[74:75], 0, v[134:135]
	v_cndmask_b32_e64 v69, v69, v67, s[6:7]
	v_cndmask_b32_e64 v68, v68, v66, s[6:7]
	v_cndmask_b32_e64 v67, v73, v71, s[6:7]
	v_cndmask_b32_e64 v66, v72, v70, s[6:7]
	v_cndmask_b32_e64 v73, v81, v85, s[6:7]
	v_cndmask_b32_e64 v72, v80, v84, s[6:7]
	v_cndmask_b32_e64 v71, v79, v83, s[6:7]
	v_cndmask_b32_e64 v70, v78, v82, s[6:7]
	v_cvt_pk_bf16_f32 v62, v62, v63
	v_cvt_pk_bf16_f32 v63, v64, v65
	v_cvt_pk_bf16_f32 v64, v58, v59
	v_cvt_pk_bf16_f32 v65, v60, v61
	v_cvt_pk_bf16_f32 v54, v54, v55
	v_cvt_pk_bf16_f32 v55, v56, v57
	v_cvt_pk_bf16_f32 v50, v50, v51
	v_cvt_pk_bf16_f32 v51, v52, v53
	v_lshl_add_u64 v[74:75], v[74:75], 0, v[136:137]
	global_store_dwordx4 v[76:77], v[70:73], off
	global_store_dwordx4 v[74:75], v[66:69], off
	v_lshl_add_u64 v[58:59], v[142:143], 0, s[22:23]
	v_mov_b32_dpp v56, v62 row_ror:8 row_mask:0xf bank_mask:0xf bound_ctrl:1
	v_mov_b32_dpp v57, v63 row_ror:8 row_mask:0xf bank_mask:0xf bound_ctrl:1
	v_mov_b32_dpp v52, v64 row_ror:8 row_mask:0xf bank_mask:0xf bound_ctrl:1
	v_mov_b32_dpp v53, v65 row_ror:8 row_mask:0xf bank_mask:0xf bound_ctrl:1
	v_mov_b32_dpp v66, v54 row_ror:8 row_mask:0xf bank_mask:0xf bound_ctrl:1
	v_mov_b32_dpp v67, v55 row_ror:8 row_mask:0xf bank_mask:0xf bound_ctrl:1
	v_mov_b32_dpp v68, v50 row_ror:8 row_mask:0xf bank_mask:0xf bound_ctrl:1
; __device__ __forceinline__ unsigned pk2(float lo, float hi) { const f32x2 v = {lo, hi}; return __builtin_bit_cast(unsigned, __builtin_convertvector(v, bf16x2_t)); }
; #define PG8_BAR __builtin_amdgcn_s_barrier()
; template <class Epi, class Sched, bool ABLK = false, bool ALIGN_EPI = true, bool SP2 = true, bool BBLK = true>
; __device__ __forceinline__ void gemm_phase(LAS unsigned char* lds, const Gemm g, const Sched& S, const Epi& E) {
;     ...
;         if (!has_next) break;
; #pragma unroll
;         for (int a = 0; a < 2; ++a)
; #pragma unroll
;             for (int b = 0; b < 2; ++b)
; #pragma unroll
;                 for (int m = 0; m < 4; ++m)
; #pragma unroll
;                     for (int n = 0; n < 2; ++n) acc[a][b][m][n] = (f32x4){0.f, 0.f, 0.f, 0.f};
;         cur = nxt; uA = nuA; tbA = ntbA; cB = nB; ++ui;
;         if constexpr (ALIGN_EPI) { if (wr == 1) PG8_BAR; }
;     __device__ __forceinline__ void operator()(const f32x4 (&acc)[2][2][4][2], const Unit& u, int wr, int wc, int fr, int fq) const {
;         const int row0 = u.pm * 256 + wr * 64 + fr, col0 = u.pn * 256 + wc * 64 + 8 * fq;
;         bf16_t* base = u.part == 0 ? Z + (size_t)row0 * D + col0 : P + ((size_t)(u.part - 1) * MS + (row0 - MP)) * D + col0;
; #pragma unroll
;         for (int ai = 0; ai < 2; ++ai)
; #pragma unroll
;             for (int m = 0; m < 4; ++m) { u32x4 w[2];
; #pragma unroll
;                 for (int bj = 0; bj < 2; ++bj) { const f32x4 v0 = acc[ai][bj][m][0], v1 = acc[ai][bj][m][1]; w[bj].x = pk2(v0[0], v0[1]); w[bj].y = pk2(v0[2], v0[3]); w[bj].z = pk2(v1[0], v1[1]); w[bj].w = pk2(v1[2], v1[3]); }
;                 store_pair((unsigned char*)(base + (size_t)(ai * 128 + m * 16) * D), (size_t)8 * D * 2, 64, w[0], w[1], fr >= 8); }
	v_mov_b32_dpp v69, v51 row_ror:8 row_mask:0xf bank_mask:0xf bound_ctrl:1
	v_lshl_add_u64 v[60:61], v[58:59], 0, v[134:135]
	v_cndmask_b32_e64 v53, v53, v51, s[6:7]
	v_cndmask_b32_e64 v52, v52, v50, s[6:7]
	v_cndmask_b32_e64 v51, v57, v55, s[6:7]
	v_cndmask_b32_e64 v50, v56, v54, s[6:7]
	v_cndmask_b32_e64 v57, v65, v69, s[6:7]
	v_cndmask_b32_e64 v56, v64, v68, s[6:7]
	v_cndmask_b32_e64 v55, v63, v67, s[6:7]
	v_cndmask_b32_e64 v54, v62, v66, s[6:7]
	v_cvt_pk_bf16_f32 v46, v46, v47
	v_cvt_pk_bf16_f32 v47, v48, v49
	v_cvt_pk_bf16_f32 v48, v42, v43
	v_cvt_pk_bf16_f32 v49, v44, v45
	v_cvt_pk_bf16_f32 v38, v38, v39
	v_cvt_pk_bf16_f32 v39, v40, v41
	v_cvt_pk_bf16_f32 v34, v34, v35
	v_cvt_pk_bf16_f32 v35, v36, v37
	v_lshl_add_u64 v[58:59], v[58:59], 0, v[136:137]
	global_store_dwordx4 v[60:61], v[54:57], off
	global_store_dwordx4 v[58:59], v[50:53], off
	v_lshl_add_u64 v[42:43], v[142:143], 0, s[24:25]
	v_mov_b32_dpp v40, v46 row_ror:8 row_mask:0xf bank_mask:0xf bound_ctrl:1
	v_mov_b32_dpp v41, v47 row_ror:8 row_mask:0xf bank_mask:0xf bound_ctrl:1
	v_mov_b32_dpp v36, v48 row_ror:8 row_mask:0xf bank_mask:0xf bound_ctrl:1
	v_mov_b32_dpp v37, v49 row_ror:8 row_mask:0xf bank_mask:0xf bound_ctrl:1
	v_mov_b32_dpp v50, v38 row_ror:8 row_mask:0xf bank_mask:0xf bound_ctrl:1
	v_mov_b32_dpp v51, v39 row_ror:8 row_mask:0xf bank_mask:0xf bound_ctrl:1
	v_mov_b32_dpp v52, v34 row_ror:8 row_mask:0xf bank_mask:0xf bound_ctrl:1
	v_mov_b32_dpp v53, v35 row_ror:8 row_mask:0xf bank_mask:0xf bound_ctrl:1
	v_lshl_add_u64 v[44:45], v[42:43], 0, v[134:135]
	v_cndmask_b32_e64 v37, v37, v35, s[6:7]
	v_cndmask_b32_e64 v36, v36, v34, s[6:7]
	v_cndmask_b32_e64 v35, v41, v39, s[6:7]
	v_cndmask_b32_e64 v34, v40, v38, s[6:7]
	v_cndmask_b32_e64 v41, v49, v53, s[6:7]
	v_cndmask_b32_e64 v40, v48, v52, s[6:7]
	v_cndmask_b32_e64 v39, v47, v51, s[6:7]
	v_cndmask_b32_e64 v38, v46, v50, s[6:7]
	v_cvt_pk_bf16_f32 v30, v30, v31
	v_cvt_pk_bf16_f32 v31, v32, v33
	v_cvt_pk_bf16_f32 v32, v26, v27
	v_cvt_pk_bf16_f32 v33, v28, v29
	v_cvt_pk_bf16_f32 v22, v22, v23
	v_cvt_pk_bf16_f32 v23, v24, v25
	v_cvt_pk_bf16_f32 v18, v18, v19
	v_cvt_pk_bf16_f32 v19, v20, v21
	v_lshl_add_u64 v[42:43], v[42:43], 0, v[136:137]
	global_store_dwordx4 v[44:45], v[38:41], off
	global_store_dwordx4 v[42:43], v[34:37], off
	v_lshl_add_u64 v[26:27], v[142:143], 0, s[26:27]
	v_mov_b32_dpp v24, v30 row_ror:8 row_mask:0xf bank_mask:0xf bound_ctrl:1
	v_mov_b32_dpp v25, v31 row_ror:8 row_mask:0xf bank_mask:0xf bound_ctrl:1
	v_mov_b32_dpp v20, v32 row_ror:8 row_mask:0xf bank_mask:0xf bound_ctrl:1
	v_mov_b32_dpp v21, v33 row_ror:8 row_mask:0xf bank_mask:0xf bound_ctrl:1
	v_mov_b32_dpp v34, v22 row_ror:8 row_mask:0xf bank_mask:0xf bound_ctrl:1
	v_mov_b32_dpp v35, v23 row_ror:8 row_mask:0xf bank_mask:0xf bound_ctrl:1
	v_mov_b32_dpp v36, v18 row_ror:8 row_mask:0xf bank_mask:0xf bound_ctrl:1
	v_mov_b32_dpp v37, v19 row_ror:8 row_mask:0xf bank_mask:0xf bound_ctrl:1
	v_lshl_add_u64 v[28:29], v[26:27], 0, v[134:135]
	v_cndmask_b32_e64 v21, v21, v19, s[6:7]
	v_cndmask_b32_e64 v20, v20, v18, s[6:7]
	v_cndmask_b32_e64 v19, v25, v23, s[6:7]
	v_cndmask_b32_e64 v18, v24, v22, s[6:7]
	v_cndmask_b32_e64 v25, v33, v37, s[6:7]
	v_cndmask_b32_e64 v24, v32, v36, s[6:7]
	v_cndmask_b32_e64 v23, v31, v35, s[6:7]
	v_cndmask_b32_e64 v22, v30, v34, s[6:7]
	v_cvt_pk_bf16_f32 v14, v14, v15
	v_cvt_pk_bf16_f32 v15, v16, v17
	v_cvt_pk_bf16_f32 v16, v10, v11
	v_cvt_pk_bf16_f32 v17, v12, v13
	v_cvt_pk_bf16_f32 v6, v6, v7
	v_cvt_pk_bf16_f32 v7, v8, v9
	v_cvt_pk_bf16_f32 v2, v2, v3
	v_cvt_pk_bf16_f32 v3, v4, v5
	v_lshl_add_u64 v[26:27], v[26:27], 0, v[136:137]
	global_store_dwordx4 v[28:29], v[22:25], off
	global_store_dwordx4 v[26:27], v[18:21], off
	v_lshl_add_u64 v[10:11], v[142:143], 0, s[28:29]
	v_mov_b32_dpp v8, v14 row_ror:8 row_mask:0xf bank_mask:0xf bound_ctrl:1
	v_mov_b32_dpp v9, v15 row_ror:8 row_mask:0xf bank_mask:0xf bound_ctrl:1
	v_mov_b32_dpp v4, v16 row_ror:8 row_mask:0xf bank_mask:0xf bound_ctrl:1
	v_mov_b32_dpp v5, v17 row_ror:8 row_mask:0xf bank_mask:0xf bound_ctrl:1
	v_mov_b32_dpp v18, v6 row_ror:8 row_mask:0xf bank_mask:0xf bound_ctrl:1
	v_mov_b32_dpp v19, v7 row_ror:8 row_mask:0xf bank_mask:0xf bound_ctrl:1
	v_mov_b32_dpp v20, v2 row_ror:8 row_mask:0xf bank_mask:0xf bound_ctrl:1
	v_mov_b32_dpp v21, v3 row_ror:8 row_mask:0xf bank_mask:0xf bound_ctrl:1
	v_lshl_add_u64 v[12:13], v[10:11], 0, v[134:135]
	v_cndmask_b32_e64 v5, v5, v3, s[6:7]
	v_cndmask_b32_e64 v4, v4, v2, s[6:7]
	v_cndmask_b32_e64 v3, v9, v7, s[6:7]
	v_cndmask_b32_e64 v2, v8, v6, s[6:7]
	v_cndmask_b32_e64 v9, v17, v21, s[6:7]
	v_cndmask_b32_e64 v8, v16, v20, s[6:7]
	v_cndmask_b32_e64 v7, v15, v19, s[6:7]
	v_cndmask_b32_e64 v6, v14, v18, s[6:7]
	s_and_b64 vcc, exec, s[8:9]
	s_mov_b64 s[8:9], -1
	v_lshl_add_u64 v[10:11], v[10:11], 0, v[136:137]
	global_store_dwordx4 v[12:13], v[6:9], off
	global_store_dwordx4 v[10:11], v[2:5], off
	s_cbranch_vccnz .LBB0_538
	s_andn2_b64 vcc, exec, s[2:3]
	s_cbranch_vccnz .LBB0_537
	s_barrier
	s_branch .LBB0_537

; #define PG8_STAGE(bufoff, gbase, voff) do { _Pragma("unroll") for (int _i = 0; _i < 2; ++_i) \
;         __builtin_amdgcn_global_load_lds((const unsigned*)((const char*)(gbase) + (voff)[_i]), (LAS unsigned*)(lds + (bufoff) + ldsw + _i * 8192), 16, 0, 0); } while (0)
; #define PG8_LDA(dst, b, h) do { _Pragma("unroll") for (int m = 0; m < 4; ++m) _Pragma("unroll") for (int k = 0; k < 2; ++k) dst[m][k] = *(const LAS bf16x8*)(lds + PG8_SA(b, h) + aoff + m * 2048 + k * 1024); } while (0)
; #define PG8_LDB(dst, b, h) do { _Pragma("unroll") for (int n = 0; n < 2; ++n) _Pragma("unroll") for (int k = 0; k < 2; ++k) dst[n][k] = *(const LAS bf16x8*)(lds + PG8_SB(b, h) + boff + n * 2048 + k * 1024); } while (0)
; #define PG8_WAIT_V(n) asm volatile("s_waitcnt vmcnt(" #n ")" ::: "memory")
; #define PG8_WAIT_L(n) asm volatile("s_waitcnt lgkmcnt(" #n ")" ::: "memory")
; #define PG8_BAR __builtin_amdgcn_s_barrier()
; template <class Epi, class Sched, bool ABLK = false, bool ALIGN_EPI = true, bool SP2 = true, bool BBLK = true>
; __device__ __forceinline__ void gemm_phase(LAS unsigned char* lds, const Gemm g, const Sched& S, const Epi& E) {
;     ...
;         const char* nuA = has_next ? a_unit(nxt) : uA; const int ntbA = has_next ? nxt.k0 / BK : tbA; const char* nB = has_next ? (const char*)g.Bt + (size_t)nxt.pn * tstepB + b_k0(nxt.k0) : cB;
;         for (int t = 0; t < nt; t += 2) {
;             const bool last = (t == nt - 2);
;             const char* a1 = a_tile(uA, tbA + t + 1);
;             const char* a2 = last ? a_tile(nuA, ntbA) : a_tile(uA, tbA + t + 2); const char* b2 = last ? nB : cB + (size_t)(t + 2) * kstepB;
;             const char* a3 = last ? a_tile(nuA, ntbA + 1) : a_tile(uA, tbA + t + 3); const char* b3 = b2 + kstepB;
;             if (last && has_next) S.a_ready(nxt);
;             if constexpr (SP2) {
;             PG8_LDB(B0, 0, 0); PG8_LDB(B1, 0, 1); PG8_SCHED; PG8_LDA(At, 0, 0); PG8_STAGE(PG8_SA(1, 1), a1 + hstepA, voffA);
;             PG8_WAIT_V(8); PG8_WAIT_L(0); PG8_BAR; PG8_MMA(0, 0, At, B0); PG8_MMA(0, 1, At, B1); PG8_BAR; PG8_SCHED;
;             PG8_LDA(At, 0, 1); PG8_STAGE(PG8_SB(0, 0), b2, voffB); PG8_STAGE(PG8_SB(0, 1), b2 + hstepB, voffB); PG8_STAGE(PG8_SA(0, 0), a2, voffA);
;             PG8_WAIT_V(8); PG8_WAIT_L(0); PG8_BAR; PG8_MMA(1, 0, At, B0); PG8_MMA(1, 1, At, B1); PG8_BAR; PG8_SCHED;
.LBB0_1038:
	ds_read_b128 v[156:159], v153
	ds_read_b128 v[160:163], v153 offset:1024
	ds_read_b128 v[164:167], v153 offset:2048
	ds_read_b128 v[168:171], v153 offset:3072
	ds_read_b128 v[172:175], v154
	ds_read_b128 v[176:179], v154 offset:1024
	ds_read_b128 v[180:183], v154 offset:2048
	ds_read_b128 v[184:187], v154 offset:3072
	s_add_u32 s22, s56, s20
	s_addc_u32 s23, s57, s21
	s_add_u32 s26, s22, 0x100
	s_addc_u32 s27, s23, 0
	s_add_i32 s65, s65, 2
	s_add_u32 s22, s22, 0x180
	s_addc_u32 s23, s23, 0
	s_cmp_eq_u32 s64, s20
	s_cselect_b32 s23, s50, s23
	s_cselect_b32 s22, s49, s22
	s_cselect_b32 s25, s4, s55
	s_cselect_b32 s24, s5, s51
	s_cselect_b32 s27, s48, s27
	s_cselect_b32 s26, s17, s26
	v_lshl_add_u64 v[220:221], v[146:147], 0, s[20:21]
	s_add_i32 m0, s35, 0xc000
	ds_read_b128 v[188:191], v155
	ds_read_b128 v[192:195], v155 offset:1024
	ds_read_b128 v[196:199], v155 offset:2048
	ds_read_b128 v[200:203], v155 offset:3072
	ds_read_b128 v[204:207], v155 offset:4096
	ds_read_b128 v[208:211], v155 offset:5120
	ds_read_b128 v[212:215], v155 offset:6144
	ds_read_b128 v[216:219], v155 offset:7168
	global_load_lds_dwordx4 v[220:221], off
	v_lshl_add_u64 v[220:221], v[148:149], 0, s[20:21]
	s_add_i32 m0, s35, 0xe000
	s_nop 0
	global_load_lds_dwordx4 v[220:221], off
	s_waitcnt vmcnt(8) lgkmcnt(0)
	s_barrier
	v_mfma_f32_16x16x32_bf16 v[126:129], v[156:159], v[188:191], v[126:129]
	v_mfma_f32_16x16x32_bf16 v[122:125], v[164:167], v[188:191], v[122:125]
	v_mfma_f32_16x16x32_bf16 v[110:113], v[156:159], v[196:199], v[110:113]
	v_mfma_f32_16x16x32_bf16 v[106:109], v[164:167], v[196:199], v[106:109]
	v_mfma_f32_16x16x32_bf16 v[94:97], v[156:159], v[204:207], v[94:97]
	v_mfma_f32_16x16x32_bf16 v[90:93], v[164:167], v[204:207], v[90:93]
	v_mfma_f32_16x16x32_bf16 v[78:81], v[156:159], v[212:215], v[78:81]
	v_mfma_f32_16x16x32_bf16 v[74:77], v[164:167], v[212:215], v[74:77]
	v_mfma_f32_16x16x32_bf16 v[126:129], v[160:163], v[192:195], v[126:129]
	v_mfma_f32_16x16x32_bf16 v[122:125], v[168:171], v[192:195], v[122:125]
	v_mfma_f32_16x16x32_bf16 v[110:113], v[160:163], v[200:203], v[110:113]
	v_mfma_f32_16x16x32_bf16 v[106:109], v[168:171], v[200:203], v[106:109]
	v_mfma_f32_16x16x32_bf16 v[94:97], v[160:163], v[208:211], v[94:97]
	v_mfma_f32_16x16x32_bf16 v[90:93], v[168:171], v[208:211], v[90:93]
	v_mfma_f32_16x16x32_bf16 v[78:81], v[160:163], v[216:219], v[78:81]
	v_mfma_f32_16x16x32_bf16 v[74:77], v[168:171], v[216:219], v[74:77]
	v_mfma_f32_16x16x32_bf16 v[118:121], v[172:175], v[188:191], v[118:121]
	v_mfma_f32_16x16x32_bf16 v[114:117], v[180:183], v[188:191], v[114:117]
	v_mfma_f32_16x16x32_bf16 v[102:105], v[172:175], v[196:199], v[102:105]
	v_mfma_f32_16x16x32_bf16 v[98:101], v[180:183], v[196:199], v[98:101]
	v_mfma_f32_16x16x32_bf16 v[86:89], v[172:175], v[204:207], v[86:89]
	v_mfma_f32_16x16x32_bf16 v[82:85], v[180:183], v[204:207], v[82:85]
	v_mfma_f32_16x16x32_bf16 v[70:73], v[172:175], v[212:215], v[70:73]
	v_mfma_f32_16x16x32_bf16 v[66:69], v[180:183], v[212:215], v[66:69]
	v_mfma_f32_16x16x32_bf16 v[118:121], v[176:179], v[192:195], v[118:121]
	v_mfma_f32_16x16x32_bf16 v[114:117], v[184:187], v[192:195], v[114:117]
	v_mfma_f32_16x16x32_bf16 v[102:105], v[176:179], v[200:203], v[102:105]
	v_mfma_f32_16x16x32_bf16 v[98:101], v[184:187], v[200:203], v[98:101]
	v_mfma_f32_16x16x32_bf16 v[86:89], v[176:179], v[208:211], v[86:89]
	v_mfma_f32_16x16x32_bf16 v[82:85], v[184:187], v[208:211], v[82:85]
	v_mfma_f32_16x16x32_bf16 v[70:73], v[176:179], v[216:219], v[70:73]
	v_mfma_f32_16x16x32_bf16 v[66:69], v[184:187], v[216:219], v[66:69]
	s_barrier
	s_add_i32 s66, s72, s34
	s_mov_b32 m0, s66
	ds_read_b128 v[188:191], v155 offset:16384
	ds_read_b128 v[192:195], v155 offset:17408
	ds_read_b128 v[196:199], v155 offset:18432
	ds_read_b128 v[200:203], v155 offset:19456
	ds_read_b128 v[204:207], v155 offset:20480
	ds_read_b128 v[208:211], v155 offset:21504
	ds_read_b128 v[212:215], v155 offset:22528
	ds_read_b128 v[216:219], v155 offset:23552
	global_load_lds_dwordx4 v132, s[24:25]
	s_add_i32 m0, s66, 0x2000
	s_add_u32 s66, s24, 0x4000
	s_addc_u32 s67, s25, 0
	s_add_i32 s75, s73, s34
	global_load_lds_dwordx4 v136, s[24:25]
	s_mov_b32 m0, s75
	s_nop 0
	global_load_lds_dwordx4 v132, s[66:67]
	s_add_i32 m0, s75, 0x2000
	s_nop 0
	global_load_lds_dwordx4 v136, s[66:67]
	s_mov_b32 m0, s35
	s_nop 0
	global_load_lds_dwordx4 v130, s[26:27]
	s_mov_b32 m0, s36
	s_nop 0
	global_load_lds_dwordx4 v134, s[26:27]
	s_waitcnt vmcnt(8) lgkmcnt(0)
	s_barrier
	v_mfma_f32_16x16x32_bf16 v[62:65], v[156:159], v[188:191], v[62:65]
	v_mfma_f32_16x16x32_bf16 v[58:61], v[164:167], v[188:191], v[58:61]
	v_mfma_f32_16x16x32_bf16 v[46:49], v[156:159], v[196:199], v[46:49]
	v_mfma_f32_16x16x32_bf16 v[42:45], v[164:167], v[196:199], v[42:45]
	v_mfma_f32_16x16x32_bf16 v[30:33], v[156:159], v[204:207], v[30:33]
	v_mfma_f32_16x16x32_bf16 v[26:29], v[164:167], v[204:207], v[26:29]
	v_mfma_f32_16x16x32_bf16 v[14:17], v[156:159], v[212:215], v[14:17]
	v_mfma_f32_16x16x32_bf16 v[10:13], v[164:167], v[212:215], v[10:13]
	v_mfma_f32_16x16x32_bf16 v[62:65], v[160:163], v[192:195], v[62:65]
	v_mfma_f32_16x16x32_bf16 v[58:61], v[168:171], v[192:195], v[58:61]
	v_mfma_f32_16x16x32_bf16 v[46:49], v[160:163], v[200:203], v[46:49]
	v_mfma_f32_16x16x32_bf16 v[42:45], v[168:171], v[200:203], v[42:45]
	v_mfma_f32_16x16x32_bf16 v[30:33], v[160:163], v[208:211], v[30:33]
	v_mfma_f32_16x16x32_bf16 v[26:29], v[168:171], v[208:211], v[26:29]
	v_mfma_f32_16x16x32_bf16 v[14:17], v[160:163], v[216:219], v[14:17]
	v_mfma_f32_16x16x32_bf16 v[10:13], v[168:171], v[216:219], v[10:13]
	v_mfma_f32_16x16x32_bf16 v[54:57], v[172:175], v[188:191], v[54:57]
	v_mfma_f32_16x16x32_bf16 v[50:53], v[180:183], v[188:191], v[50:53]
	v_mfma_f32_16x16x32_bf16 v[38:41], v[172:175], v[196:199], v[38:41]
	v_mfma_f32_16x16x32_bf16 v[34:37], v[180:183], v[196:199], v[34:37]
	v_mfma_f32_16x16x32_bf16 v[22:25], v[172:175], v[204:207], v[22:25]
	v_mfma_f32_16x16x32_bf16 v[18:21], v[180:183], v[204:207], v[18:21]
	v_mfma_f32_16x16x32_bf16 v[6:9], v[172:175], v[212:215], v[6:9]
	v_mfma_f32_16x16x32_bf16 v[2:5], v[180:183], v[212:215], v[2:5]
	v_mfma_f32_16x16x32_bf16 v[54:57], v[176:179], v[192:195], v[54:57]
	v_mfma_f32_16x16x32_bf16 v[50:53], v[184:187], v[192:195], v[50:53]
	v_mfma_f32_16x16x32_bf16 v[38:41], v[176:179], v[200:203], v[38:41]
	v_mfma_f32_16x16x32_bf16 v[34:37], v[184:187], v[200:203], v[34:37]
	v_mfma_f32_16x16x32_bf16 v[22:25], v[176:179], v[208:211], v[22:25]
	v_mfma_f32_16x16x32_bf16 v[18:21], v[184:187], v[208:211], v[18:21]
	v_mfma_f32_16x16x32_bf16 v[6:9], v[176:179], v[216:219], v[6:9]
	v_mfma_f32_16x16x32_bf16 v[2:5], v[184:187], v[216:219], v[2:5]
	s_barrier
; #define PG8_STAGE(bufoff, gbase, voff) do { _Pragma("unroll") for (int _i = 0; _i < 2; ++_i) \
;         __builtin_amdgcn_global_load_lds((const unsigned*)((const char*)(gbase) + (voff)[_i]), (LAS unsigned*)(lds + (bufoff) + ldsw + _i * 8192), 16, 0, 0); } while (0)
; #define PG8_LDA(dst, b, h) do { _Pragma("unroll") for (int m = 0; m < 4; ++m) _Pragma("unroll") for (int k = 0; k < 2; ++k) dst[m][k] = *(const LAS bf16x8*)(lds + PG8_SA(b, h) + aoff + m * 2048 + k * 1024); } while (0)
; #define PG8_LDB(dst, b, h) do { _Pragma("unroll") for (int n = 0; n < 2; ++n) _Pragma("unroll") for (int k = 0; k < 2; ++k) dst[n][k] = *(const LAS bf16x8*)(lds + PG8_SB(b, h) + boff + n * 2048 + k * 1024); } while (0)
; #define PG8_MMA(ai, bj, At, Bt) do { __builtin_amdgcn_s_setprio(1); _Pragma("unroll") for (int m = 0; m < 4; ++m) _Pragma("unroll") for (int n = 0; n < 2; ++n) _Pragma("unroll") for (int k = 0; k < 2; ++k) \
;         acc[ai][bj][m][n] = __builtin_amdgcn_mfma_f32_16x16x32_bf16(Bt[n][k], At[m][k], acc[ai][bj][m][n], 0, 0, 0); __builtin_amdgcn_s_setprio(0); } while (0)
; #define PG8_WAIT_V(n) asm volatile("s_waitcnt vmcnt(" #n ")" ::: "memory")
; #define PG8_WAIT_L(n) asm volatile("s_waitcnt lgkmcnt(" #n ")" ::: "memory")
; #define PG8_BAR __builtin_amdgcn_s_barrier()
; #define PG8_SCHED __builtin_amdgcn_sched_barrier(0)
; template <class Epi, class Sched, bool ABLK = false, bool ALIGN_EPI = true, bool SP2 = true, bool BBLK = true>
; __device__ __forceinline__ void gemm_phase(LAS unsigned char* lds, const Gemm g, const Sched& S, const Epi& E) {
;     ...
;             PG8_LDB(B0, 1, 0); PG8_LDB(B1, 1, 1); PG8_SCHED; PG8_LDA(At, 1, 0); PG8_STAGE(PG8_SA(0, 1), a2 + hstepA, voffA);
;             PG8_WAIT_V(8); PG8_WAIT_L(0); PG8_BAR; PG8_MMA(0, 0, At, B0); PG8_MMA(0, 1, At, B1); PG8_BAR; PG8_SCHED;
;             PG8_LDA(At, 1, 1); PG8_STAGE(PG8_SB(1, 0), b3, voffB); PG8_STAGE(PG8_SB(1, 1), b3 + hstepB, voffB); PG8_STAGE(PG8_SA(1, 0), a3, voffA);
;             PG8_WAIT_V(8); PG8_WAIT_L(0); PG8_BAR; PG8_MMA(1, 0, At, B0); PG8_MMA(1, 1, At, B1); PG8_BAR; PG8_SCHED;
	v_add_u32_e32 v168, s60, v151
	v_add_u32_e32 v184, s61, v151
	ds_read_b128 v[156:159], v168
	ds_read_b128 v[160:163], v168 offset:1024
	ds_read_b128 v[164:167], v168 offset:2048
	ds_read_b128 v[168:171], v168 offset:3072
	ds_read_b128 v[172:175], v184
	ds_read_b128 v[176:179], v184 offset:1024
	ds_read_b128 v[180:183], v184 offset:2048
	ds_read_b128 v[184:187], v184 offset:3072
	s_add_u32 s26, s26, 0x80000
	s_addc_u32 s27, s27, 0
	s_mov_b32 m0, s37
	ds_read_b128 v[188:191], v155 offset:32768
	ds_read_b128 v[192:195], v155 offset:33792
	ds_read_b128 v[196:199], v155 offset:34816
	ds_read_b128 v[200:203], v155 offset:35840
	ds_read_b128 v[204:207], v155 offset:36864
	ds_read_b128 v[208:211], v155 offset:37888
	ds_read_b128 v[212:215], v155 offset:38912
	ds_read_b128 v[216:219], v155 offset:39936
	global_load_lds_dwordx4 v130, s[26:27]
	s_mov_b32 m0, s40
	s_nop 0
	global_load_lds_dwordx4 v134, s[26:27]
	s_waitcnt vmcnt(8) lgkmcnt(0)
	s_barrier
	v_mfma_f32_16x16x32_bf16 v[126:129], v[156:159], v[188:191], v[126:129]
	v_mfma_f32_16x16x32_bf16 v[122:125], v[164:167], v[188:191], v[122:125]
	v_mfma_f32_16x16x32_bf16 v[110:113], v[156:159], v[196:199], v[110:113]
	v_mfma_f32_16x16x32_bf16 v[106:109], v[164:167], v[196:199], v[106:109]
	v_mfma_f32_16x16x32_bf16 v[94:97], v[156:159], v[204:207], v[94:97]
	v_mfma_f32_16x16x32_bf16 v[90:93], v[164:167], v[204:207], v[90:93]
	v_mfma_f32_16x16x32_bf16 v[78:81], v[156:159], v[212:215], v[78:81]
	v_mfma_f32_16x16x32_bf16 v[74:77], v[164:167], v[212:215], v[74:77]
	v_mfma_f32_16x16x32_bf16 v[126:129], v[160:163], v[192:195], v[126:129]
	v_mfma_f32_16x16x32_bf16 v[122:125], v[168:171], v[192:195], v[122:125]
	v_mfma_f32_16x16x32_bf16 v[110:113], v[160:163], v[200:203], v[110:113]
	v_mfma_f32_16x16x32_bf16 v[106:109], v[168:171], v[200:203], v[106:109]
	v_mfma_f32_16x16x32_bf16 v[94:97], v[160:163], v[208:211], v[94:97]
	v_mfma_f32_16x16x32_bf16 v[90:93], v[168:171], v[208:211], v[90:93]
	v_mfma_f32_16x16x32_bf16 v[78:81], v[160:163], v[216:219], v[78:81]
	v_mfma_f32_16x16x32_bf16 v[74:77], v[168:171], v[216:219], v[74:77]
	v_mfma_f32_16x16x32_bf16 v[118:121], v[172:175], v[188:191], v[118:121]
	v_mfma_f32_16x16x32_bf16 v[114:117], v[180:183], v[188:191], v[114:117]
	v_mfma_f32_16x16x32_bf16 v[102:105], v[172:175], v[196:199], v[102:105]
	v_mfma_f32_16x16x32_bf16 v[98:101], v[180:183], v[196:199], v[98:101]
	v_mfma_f32_16x16x32_bf16 v[86:89], v[172:175], v[204:207], v[86:89]
	v_mfma_f32_16x16x32_bf16 v[82:85], v[180:183], v[204:207], v[82:85]
	v_mfma_f32_16x16x32_bf16 v[70:73], v[172:175], v[212:215], v[70:73]
	v_mfma_f32_16x16x32_bf16 v[66:69], v[180:183], v[212:215], v[66:69]
	v_mfma_f32_16x16x32_bf16 v[118:121], v[176:179], v[192:195], v[118:121]
	v_mfma_f32_16x16x32_bf16 v[114:117], v[184:187], v[192:195], v[114:117]
	v_mfma_f32_16x16x32_bf16 v[102:105], v[176:179], v[200:203], v[102:105]
	v_mfma_f32_16x16x32_bf16 v[98:101], v[184:187], v[200:203], v[98:101]
	v_mfma_f32_16x16x32_bf16 v[86:89], v[176:179], v[208:211], v[86:89]
	v_mfma_f32_16x16x32_bf16 v[82:85], v[184:187], v[208:211], v[82:85]
	v_mfma_f32_16x16x32_bf16 v[70:73], v[176:179], v[216:219], v[70:73]
	v_mfma_f32_16x16x32_bf16 v[66:69], v[184:187], v[216:219], v[66:69]
	s_barrier
	s_add_u32 s26, s24, 0x8000
	s_addc_u32 s27, s25, 0
	s_add_i32 s66, s60, s34
	s_mov_b32 m0, s66
	ds_read_b128 v[188:191], v155 offset:49152
	ds_read_b128 v[192:195], v155 offset:50176
	ds_read_b128 v[196:199], v155 offset:51200
	ds_read_b128 v[200:203], v155 offset:52224
	ds_read_b128 v[204:207], v155 offset:53248
	ds_read_b128 v[208:211], v155 offset:54272
	ds_read_b128 v[212:215], v155 offset:55296
	ds_read_b128 v[216:219], v155 offset:56320
	global_load_lds_dwordx4 v132, s[26:27]
	s_add_i32 m0, s66, 0x2000
	s_add_u32 s24, s24, 0xc000
	v_lshl_add_u64 v[220:221], s[26:27], 0, v[136:137]
	s_addc_u32 s25, s25, 0
	s_add_i32 s26, s61, s34
	global_load_lds_dwordx4 v[220:221], off
	s_mov_b32 m0, s26
	s_nop 0
	global_load_lds_dwordx4 v132, s[24:25]
	s_add_i32 m0, s26, 0x2000
	s_nop 0
	global_load_lds_dwordx4 v136, s[24:25]
	s_mov_b32 m0, s41
	s_nop 0
	global_load_lds_dwordx4 v130, s[22:23]
	s_mov_b32 m0, s42
	s_nop 0
	global_load_lds_dwordx4 v134, s[22:23]
	s_waitcnt vmcnt(8) lgkmcnt(0)
	s_barrier
	v_mfma_f32_16x16x32_bf16 v[62:65], v[156:159], v[188:191], v[62:65]
	v_mfma_f32_16x16x32_bf16 v[58:61], v[164:167], v[188:191], v[58:61]
	v_mfma_f32_16x16x32_bf16 v[46:49], v[156:159], v[196:199], v[46:49]
	v_mfma_f32_16x16x32_bf16 v[42:45], v[164:167], v[196:199], v[42:45]
	v_mfma_f32_16x16x32_bf16 v[30:33], v[156:159], v[204:207], v[30:33]
	v_mfma_f32_16x16x32_bf16 v[26:29], v[164:167], v[204:207], v[26:29]
	v_mfma_f32_16x16x32_bf16 v[14:17], v[156:159], v[212:215], v[14:17]
	v_mfma_f32_16x16x32_bf16 v[10:13], v[164:167], v[212:215], v[10:13]
	v_mfma_f32_16x16x32_bf16 v[62:65], v[160:163], v[192:195], v[62:65]
	v_mfma_f32_16x16x32_bf16 v[58:61], v[168:171], v[192:195], v[58:61]
	v_mfma_f32_16x16x32_bf16 v[46:49], v[160:163], v[200:203], v[46:49]
	v_mfma_f32_16x16x32_bf16 v[42:45], v[168:171], v[200:203], v[42:45]
	v_mfma_f32_16x16x32_bf16 v[30:33], v[160:163], v[208:211], v[30:33]
	v_mfma_f32_16x16x32_bf16 v[26:29], v[168:171], v[208:211], v[26:29]
	v_mfma_f32_16x16x32_bf16 v[14:17], v[160:163], v[216:219], v[14:17]
	v_mfma_f32_16x16x32_bf16 v[10:13], v[168:171], v[216:219], v[10:13]
	v_mfma_f32_16x16x32_bf16 v[54:57], v[172:175], v[188:191], v[54:57]
	v_mfma_f32_16x16x32_bf16 v[50:53], v[180:183], v[188:191], v[50:53]
	v_mfma_f32_16x16x32_bf16 v[38:41], v[172:175], v[196:199], v[38:41]
	v_mfma_f32_16x16x32_bf16 v[34:37], v[180:183], v[196:199], v[34:37]
	v_mfma_f32_16x16x32_bf16 v[22:25], v[172:175], v[204:207], v[22:25]
	v_mfma_f32_16x16x32_bf16 v[18:21], v[180:183], v[204:207], v[18:21]
	v_mfma_f32_16x16x32_bf16 v[6:9], v[172:175], v[212:215], v[6:9]
	v_mfma_f32_16x16x32_bf16 v[2:5], v[180:183], v[212:215], v[2:5]
	v_mfma_f32_16x16x32_bf16 v[54:57], v[176:179], v[192:195], v[54:57]
	v_mfma_f32_16x16x32_bf16 v[50:53], v[184:187], v[192:195], v[50:53]
	v_mfma_f32_16x16x32_bf16 v[38:41], v[176:179], v[200:203], v[38:41]
	v_mfma_f32_16x16x32_bf16 v[34:37], v[184:187], v[200:203], v[34:37]
	v_mfma_f32_16x16x32_bf16 v[22:25], v[176:179], v[208:211], v[22:25]
	v_mfma_f32_16x16x32_bf16 v[18:21], v[184:187], v[208:211], v[18:21]
	v_mfma_f32_16x16x32_bf16 v[6:9], v[176:179], v[216:219], v[6:9]
	v_mfma_f32_16x16x32_bf16 v[2:5], v[184:187], v[216:219], v[2:5]
	s_barrier
; __device__ __forceinline__ unsigned pk2(float lo, float hi) { const f32x2 v = {lo, hi}; return __builtin_bit_cast(unsigned, __builtin_convertvector(v, bf16x2_t)); }
; #define PG8_BAR __builtin_amdgcn_s_barrier()
; template <class Epi, class Sched, bool ABLK = false, bool ALIGN_EPI = true, bool SP2 = true, bool BBLK = true>
; __device__ __forceinline__ void gemm_phase(LAS unsigned char* lds, const Gemm g, const Sched& S, const Epi& E) {
;     ...
;         if constexpr (ALIGN_EPI) { if (wr == 0) PG8_BAR; }
;         E(acc, cur, wr, wc, fr, fq); S.done(cur);
;     __device__ __forceinline__ void operator()(const f32x4 (&acc)[2][2][4][2], const Unit& u, int wr, int wc, int fr, int fq) const {
;         const int row0 = u.pm * 256 + wr * 64 + fr, col0 = u.pn * 256 + wc * 64 + 8 * fq;
;         bf16_t* base = u.part == 0 ? Z + (size_t)row0 * D + col0 : P + ((size_t)(u.part - 1) * MS + (row0 - MP)) * D + col0;
; #pragma unroll
;         for (int ai = 0; ai < 2; ++ai)
; #pragma unroll
;             for (int m = 0; m < 4; ++m) { u32x4 w[2];
; #pragma unroll
;                 for (int bj = 0; bj < 2; ++bj) { const f32x4 v0 = acc[ai][bj][m][0], v1 = acc[ai][bj][m][1]; w[bj].x = pk2(v0[0], v0[1]); w[bj].y = pk2(v0[2], v0[3]); w[bj].z = pk2(v1[0], v1[1]); w[bj].w = pk2(v1[2], v1[3]); }
;                 store_pair((unsigned char*)(base + (size_t)(ai * 128 + m * 16) * D), (size_t)8 * D * 2, 64, w[0], w[1], fr >= 8); }
	s_add_u32 s51, s51, 0x10000
	s_addc_u32 s55, s55, 0
	s_add_u32 s20, s20, 0x100
	s_addc_u32 s21, s21, 0
	s_cmp_ge_u32 s65, s46
	s_cbranch_scc0 .LBB0_1038
	v_lshl_add_u32 v147, s47, 8, v150
	v_add_u32_e32 v148, 0xffffe000, v147
	v_sub_co_u32_e64 v146, vcc, s43, 1
	v_mov_b32_e32 v149, s54
	s_nop 0
	v_cndmask_b32_e32 v148, v148, v147, vcc
	v_ashrrev_i32_e32 v147, 31, v146
	v_lshlrev_b64 v[146:147], 23, v[146:147]
	v_lshl_add_u64 v[146:147], s[12:13], 0, v[146:147]
	v_cndmask_b32_e32 v147, v147, v149, vcc
	v_mov_b32_e32 v149, s52
	v_cndmask_b32_e32 v146, v146, v149, vcc
	v_ashrrev_i32_e32 v149, 31, v148
	v_lshl_or_b32 v156, s78, 8, v152
	v_lshlrev_b64 v[148:149], 12, v[148:149]
	v_lshl_add_u64 v[146:147], v[146:147], 0, v[148:149]
	v_ashrrev_i32_e32 v157, 31, v156
	v_cvt_pk_bf16_f32 v126, v126, v127
	v_cvt_pk_bf16_f32 v127, v128, v129
	v_cvt_pk_bf16_f32 v128, v122, v123
	v_cvt_pk_bf16_f32 v124, v124, v125
	v_cvt_pk_bf16_f32 v118, v118, v119
	v_cvt_pk_bf16_f32 v119, v120, v121
	v_cvt_pk_bf16_f32 v114, v114, v115
	v_cvt_pk_bf16_f32 v115, v116, v117
	v_lshl_add_u64 v[146:147], v[156:157], 1, v[146:147]
	v_mov_b32_dpp v120, v126 row_ror:8 row_mask:0xf bank_mask:0xf bound_ctrl:1
	v_mov_b32_dpp v121, v127 row_ror:8 row_mask:0xf bank_mask:0xf bound_ctrl:1
	v_mov_b32_dpp v116, v128 row_ror:8 row_mask:0xf bank_mask:0xf bound_ctrl:1
	v_mov_b32_dpp v117, v124 row_ror:8 row_mask:0xf bank_mask:0xf bound_ctrl:1
	v_mov_b32_dpp v125, v118 row_ror:8 row_mask:0xf bank_mask:0xf bound_ctrl:1
	v_mov_b32_dpp v129, v119 row_ror:8 row_mask:0xf bank_mask:0xf bound_ctrl:1
	v_mov_b32_dpp v148, v114 row_ror:8 row_mask:0xf bank_mask:0xf bound_ctrl:1
	v_mov_b32_dpp v149, v115 row_ror:8 row_mask:0xf bank_mask:0xf bound_ctrl:1
	v_lshl_add_u64 v[122:123], v[146:147], 0, v[138:139]
	v_cndmask_b32_e64 v117, v117, v115, s[6:7]
	v_cndmask_b32_e64 v116, v116, v114, s[6:7]
	v_cndmask_b32_e64 v115, v121, v119, s[6:7]
	v_cndmask_b32_e64 v114, v120, v118, s[6:7]
	v_cndmask_b32_e64 v121, v124, v149, s[6:7]
	v_cndmask_b32_e64 v120, v128, v148, s[6:7]
	v_cndmask_b32_e64 v119, v127, v129, s[6:7]
	v_cndmask_b32_e64 v118, v126, v125, s[6:7]
	v_cvt_pk_bf16_f32 v110, v110, v111
	v_cvt_pk_bf16_f32 v111, v112, v113
	v_cvt_pk_bf16_f32 v112, v106, v107
	v_cvt_pk_bf16_f32 v113, v108, v109
	v_cvt_pk_bf16_f32 v102, v102, v103
	v_cvt_pk_bf16_f32 v103, v104, v105
	v_cvt_pk_bf16_f32 v98, v98, v99
	v_cvt_pk_bf16_f32 v99, v100, v101
	s_mov_b64 s[4:5], 0x10000
	v_lshl_add_u64 v[124:125], v[146:147], 0, v[140:141]
	s_and_b64 vcc, exec, s[10:11]
	s_cbranch_vccz .LBB0_1041
	s_barrier
.LBB0_1041:
	global_store_dwordx4 v[122:123], v[118:121], off
	global_store_dwordx4 v[124:125], v[114:117], off
	v_lshl_add_u64 v[106:107], v[146:147], 0, s[4:5]
	v_mov_b32_dpp v104, v110 row_ror:8 row_mask:0xf bank_mask:0xf bound_ctrl:1
	v_mov_b32_dpp v105, v111 row_ror:8 row_mask:0xf bank_mask:0xf bound_ctrl:1
	v_mov_b32_dpp v100, v112 row_ror:8 row_mask:0xf bank_mask:0xf bound_ctrl:1
	v_mov_b32_dpp v101, v113 row_ror:8 row_mask:0xf bank_mask:0xf bound_ctrl:1
	v_mov_b32_dpp v114, v102 row_ror:8 row_mask:0xf bank_mask:0xf bound_ctrl:1
	v_mov_b32_dpp v115, v103 row_ror:8 row_mask:0xf bank_mask:0xf bound_ctrl:1
	v_mov_b32_dpp v116, v98 row_ror:8 row_mask:0xf bank_mask:0xf bound_ctrl:1
	v_mov_b32_dpp v117, v99 row_ror:8 row_mask:0xf bank_mask:0xf bound_ctrl:1
	v_lshl_add_u64 v[108:109], v[106:107], 0, v[138:139]
	v_cndmask_b32_e64 v101, v101, v99, s[6:7]
	v_cndmask_b32_e64 v100, v100, v98, s[6:7]
	v_cndmask_b32_e64 v99, v105, v103, s[6:7]
	v_cndmask_b32_e64 v98, v104, v102, s[6:7]
	v_cndmask_b32_e64 v105, v113, v117, s[6:7]
	v_cndmask_b32_e64 v104, v112, v116, s[6:7]
	v_cndmask_b32_e64 v103, v111, v115, s[6:7]
	v_cndmask_b32_e64 v102, v110, v114, s[6:7]
	v_cvt_pk_bf16_f32 v94, v94, v95
	v_cvt_pk_bf16_f32 v95, v96, v97
	v_cvt_pk_bf16_f32 v96, v90, v91
	v_cvt_pk_bf16_f32 v97, v92, v93
	v_cvt_pk_bf16_f32 v86, v86, v87
	v_cvt_pk_bf16_f32 v87, v88, v89
	v_cvt_pk_bf16_f32 v82, v82, v83
	v_cvt_pk_bf16_f32 v83, v84, v85
	s_mov_b64 s[4:5], 0x20000
	v_lshl_add_u64 v[106:107], v[106:107], 0, v[140:141]
	global_store_dwordx4 v[108:109], v[102:105], off
	global_store_dwordx4 v[106:107], v[98:101], off
	v_lshl_add_u64 v[90:91], v[146:147], 0, s[4:5]
	v_mov_b32_dpp v88, v94 row_ror:8 row_mask:0xf bank_mask:0xf bound_ctrl:1
	v_mov_b32_dpp v89, v95 row_ror:8 row_mask:0xf bank_mask:0xf bound_ctrl:1
	v_mov_b32_dpp v84, v96 row_ror:8 row_mask:0xf bank_mask:0xf bound_ctrl:1
	v_mov_b32_dpp v85, v97 row_ror:8 row_mask:0xf bank_mask:0xf bound_ctrl:1
	v_mov_b32_dpp v98, v86 row_ror:8 row_mask:0xf bank_mask:0xf bound_ctrl:1
	v_mov_b32_dpp v99, v87 row_ror:8 row_mask:0xf bank_mask:0xf bound_ctrl:1
	v_mov_b32_dpp v100, v82 row_ror:8 row_mask:0xf bank_mask:0xf bound_ctrl:1
	v_mov_b32_dpp v101, v83 row_ror:8 row_mask:0xf bank_mask:0xf bound_ctrl:1
	v_lshl_add_u64 v[92:93], v[90:91], 0, v[138:139]
	v_cndmask_b32_e64 v85, v85, v83, s[6:7]
	v_cndmask_b32_e64 v84, v84, v82, s[6:7]
	v_cndmask_b32_e64 v83, v89, v87, s[6:7]
	v_cndmask_b32_e64 v82, v88, v86, s[6:7]
	v_cndmask_b32_e64 v89, v97, v101, s[6:7]
	v_cndmask_b32_e64 v88, v96, v100, s[6:7]
	v_cndmask_b32_e64 v87, v95, v99, s[6:7]
	v_cndmask_b32_e64 v86, v94, v98, s[6:7]
	v_cvt_pk_bf16_f32 v78, v78, v79
	v_cvt_pk_bf16_f32 v79, v80, v81
	v_cvt_pk_bf16_f32 v80, v74, v75
	v_cvt_pk_bf16_f32 v81, v76, v77
	v_cvt_pk_bf16_f32 v70, v70, v71
	v_cvt_pk_bf16_f32 v71, v72, v73
	v_cvt_pk_bf16_f32 v66, v66, v67
	v_cvt_pk_bf16_f32 v67, v68, v69
	s_mov_b64 s[4:5], 0x30000
	v_lshl_add_u64 v[90:91], v[90:91], 0, v[140:141]
	global_store_dwordx4 v[92:93], v[86:89], off
	global_store_dwordx4 v[90:91], v[82:85], off
; __device__ __forceinline__ unsigned pk2(float lo, float hi) { const f32x2 v = {lo, hi}; return __builtin_bit_cast(unsigned, __builtin_convertvector(v, bf16x2_t)); }
; __device__ __forceinline__ u32x4 ror8(u32x4 v) { u32x4 r;
; #pragma unroll
;     for (int i = 0; i < 4; ++i) r[i] = (unsigned)__builtin_amdgcn_mov_dpp((int)v[i], 0x128, 0xf, 0xf, true);
;     return r; }
; __device__ __forceinline__ void store_pair(unsigned char* own, size_t stride8, int hi_off, u32x4 lo, u32x4 hi, bool upper) {
;     const u32x4 tlo = ror8(lo), thi = ror8(hi);
;     const u32x4 A = upper ? thi : lo, B = upper ? hi : tlo;
;     unsigned char* pa = upper ? own - stride8 + hi_off : own;
;     unsigned char* pb = upper ? own + hi_off : own + stride8;
;     *(u32x4*)pa = A; *(u32x4*)pb = B;
; }
;     __device__ __forceinline__ void operator()(const f32x4 (&acc)[2][2][4][2], const Unit& u, int wr, int wc, int fr, int fq) const {
;         const int row0 = u.pm * 256 + wr * 64 + fr, col0 = u.pn * 256 + wc * 64 + 8 * fq;
;         bf16_t* base = u.part == 0 ? Z + (size_t)row0 * D + col0 : P + ((size_t)(u.part - 1) * MS + (row0 - MP)) * D + col0;
; #pragma unroll
;         for (int ai = 0; ai < 2; ++ai)
; #pragma unroll
;             for (int m = 0; m < 4; ++m) { u32x4 w[2];
; #pragma unroll
;                 for (int bj = 0; bj < 2; ++bj) { const f32x4 v0 = acc[ai][bj][m][0], v1 = acc[ai][bj][m][1]; w[bj].x = pk2(v0[0], v0[1]); w[bj].y = pk2(v0[2], v0[3]); w[bj].z = pk2(v1[0], v1[1]); w[bj].w = pk2(v1[2], v1[3]); }
;                 store_pair((unsigned char*)(base + (size_t)(ai * 128 + m * 16) * D), (size_t)8 * D * 2, 64, w[0], w[1], fr >= 8); }
	v_lshl_add_u64 v[74:75], v[146:147], 0, s[4:5]
	v_mov_b32_dpp v72, v78 row_ror:8 row_mask:0xf bank_mask:0xf bound_ctrl:1
	v_mov_b32_dpp v73, v79 row_ror:8 row_mask:0xf bank_mask:0xf bound_ctrl:1
	v_mov_b32_dpp v68, v80 row_ror:8 row_mask:0xf bank_mask:0xf bound_ctrl:1
	v_mov_b32_dpp v69, v81 row_ror:8 row_mask:0xf bank_mask:0xf bound_ctrl:1
	v_mov_b32_dpp v82, v70 row_ror:8 row_mask:0xf bank_mask:0xf bound_ctrl:1
	v_mov_b32_dpp v83, v71 row_ror:8 row_mask:0xf bank_mask:0xf bound_ctrl:1
	v_mov_b32_dpp v84, v66 row_ror:8 row_mask:0xf bank_mask:0xf bound_ctrl:1
	v_mov_b32_dpp v85, v67 row_ror:8 row_mask:0xf bank_mask:0xf bound_ctrl:1
	v_lshl_add_u64 v[76:77], v[74:75], 0, v[138:139]
	v_cndmask_b32_e64 v69, v69, v67, s[6:7]
	v_cndmask_b32_e64 v68, v68, v66, s[6:7]
	v_cndmask_b32_e64 v67, v73, v71, s[6:7]
	v_cndmask_b32_e64 v66, v72, v70, s[6:7]
	v_cndmask_b32_e64 v73, v81, v85, s[6:7]
	v_cndmask_b32_e64 v72, v80, v84, s[6:7]
	v_cndmask_b32_e64 v71, v79, v83, s[6:7]
	v_cndmask_b32_e64 v70, v78, v82, s[6:7]
	v_cvt_pk_bf16_f32 v62, v62, v63
	v_cvt_pk_bf16_f32 v63, v64, v65
	v_cvt_pk_bf16_f32 v64, v58, v59
	v_cvt_pk_bf16_f32 v65, v60, v61
	v_cvt_pk_bf16_f32 v54, v54, v55
	v_cvt_pk_bf16_f32 v55, v56, v57
	v_cvt_pk_bf16_f32 v50, v50, v51
	v_cvt_pk_bf16_f32 v51, v52, v53
	s_mov_b64 s[4:5], 0x80000
	v_lshl_add_u64 v[74:75], v[74:75], 0, v[140:141]
	global_store_dwordx4 v[76:77], v[70:73], off
	global_store_dwordx4 v[74:75], v[66:69], off
	v_lshl_add_u64 v[58:59], v[146:147], 0, s[4:5]
	v_mov_b32_dpp v56, v62 row_ror:8 row_mask:0xf bank_mask:0xf bound_ctrl:1
	v_mov_b32_dpp v57, v63 row_ror:8 row_mask:0xf bank_mask:0xf bound_ctrl:1
	v_mov_b32_dpp v52, v64 row_ror:8 row_mask:0xf bank_mask:0xf bound_ctrl:1
	v_mov_b32_dpp v53, v65 row_ror:8 row_mask:0xf bank_mask:0xf bound_ctrl:1
	v_mov_b32_dpp v66, v54 row_ror:8 row_mask:0xf bank_mask:0xf bound_ctrl:1
	v_mov_b32_dpp v67, v55 row_ror:8 row_mask:0xf bank_mask:0xf bound_ctrl:1
	v_mov_b32_dpp v68, v50 row_ror:8 row_mask:0xf bank_mask:0xf bound_ctrl:1
	v_mov_b32_dpp v69, v51 row_ror:8 row_mask:0xf bank_mask:0xf bound_ctrl:1
	v_lshl_add_u64 v[60:61], v[58:59], 0, v[138:139]
	v_cndmask_b32_e64 v53, v53, v51, s[6:7]
	v_cndmask_b32_e64 v52, v52, v50, s[6:7]
	v_cndmask_b32_e64 v51, v57, v55, s[6:7]
	v_cndmask_b32_e64 v50, v56, v54, s[6:7]
	v_cndmask_b32_e64 v57, v65, v69, s[6:7]
	v_cndmask_b32_e64 v56, v64, v68, s[6:7]
	v_cndmask_b32_e64 v55, v63, v67, s[6:7]
	v_cndmask_b32_e64 v54, v62, v66, s[6:7]
	v_cvt_pk_bf16_f32 v46, v46, v47
	v_cvt_pk_bf16_f32 v47, v48, v49
	v_cvt_pk_bf16_f32 v48, v42, v43
	v_cvt_pk_bf16_f32 v49, v44, v45
	v_cvt_pk_bf16_f32 v38, v38, v39
	v_cvt_pk_bf16_f32 v39, v40, v41
	v_cvt_pk_bf16_f32 v34, v34, v35
	v_cvt_pk_bf16_f32 v35, v36, v37
	s_mov_b64 s[4:5], 0x90000
	v_lshl_add_u64 v[58:59], v[58:59], 0, v[140:141]
	global_store_dwordx4 v[60:61], v[54:57], off
	global_store_dwordx4 v[58:59], v[50:53], off
	v_lshl_add_u64 v[42:43], v[146:147], 0, s[4:5]
	v_mov_b32_dpp v40, v46 row_ror:8 row_mask:0xf bank_mask:0xf bound_ctrl:1
	v_mov_b32_dpp v41, v47 row_ror:8 row_mask:0xf bank_mask:0xf bound_ctrl:1
	v_mov_b32_dpp v36, v48 row_ror:8 row_mask:0xf bank_mask:0xf bound_ctrl:1
	v_mov_b32_dpp v37, v49 row_ror:8 row_mask:0xf bank_mask:0xf bound_ctrl:1
	v_mov_b32_dpp v50, v38 row_ror:8 row_mask:0xf bank_mask:0xf bound_ctrl:1
	v_mov_b32_dpp v51, v39 row_ror:8 row_mask:0xf bank_mask:0xf bound_ctrl:1
	v_mov_b32_dpp v52, v34 row_ror:8 row_mask:0xf bank_mask:0xf bound_ctrl:1
	v_mov_b32_dpp v53, v35 row_ror:8 row_mask:0xf bank_mask:0xf bound_ctrl:1
	v_lshl_add_u64 v[44:45], v[42:43], 0, v[138:139]
	v_cndmask_b32_e64 v37, v37, v35, s[6:7]
	v_cndmask_b32_e64 v36, v36, v34, s[6:7]
	v_cndmask_b32_e64 v35, v41, v39, s[6:7]
	v_cndmask_b32_e64 v34, v40, v38, s[6:7]
	v_cndmask_b32_e64 v41, v49, v53, s[6:7]
	v_cndmask_b32_e64 v40, v48, v52, s[6:7]
	v_cndmask_b32_e64 v39, v47, v51, s[6:7]
	v_cndmask_b32_e64 v38, v46, v50, s[6:7]
	v_cvt_pk_bf16_f32 v30, v30, v31
	v_cvt_pk_bf16_f32 v31, v32, v33
	v_cvt_pk_bf16_f32 v32, v26, v27
	v_cvt_pk_bf16_f32 v33, v28, v29
	v_cvt_pk_bf16_f32 v22, v22, v23
	v_cvt_pk_bf16_f32 v23, v24, v25
	v_cvt_pk_bf16_f32 v18, v18, v19
	v_cvt_pk_bf16_f32 v19, v20, v21
	s_mov_b64 s[4:5], 0xa0000
	v_lshl_add_u64 v[42:43], v[42:43], 0, v[140:141]
	global_store_dwordx4 v[44:45], v[38:41], off
	global_store_dwordx4 v[42:43], v[34:37], off
	v_lshl_add_u64 v[26:27], v[146:147], 0, s[4:5]
	v_mov_b32_dpp v24, v30 row_ror:8 row_mask:0xf bank_mask:0xf bound_ctrl:1
	v_mov_b32_dpp v25, v31 row_ror:8 row_mask:0xf bank_mask:0xf bound_ctrl:1
	v_mov_b32_dpp v20, v32 row_ror:8 row_mask:0xf bank_mask:0xf bound_ctrl:1
	v_mov_b32_dpp v21, v33 row_ror:8 row_mask:0xf bank_mask:0xf bound_ctrl:1
	v_mov_b32_dpp v34, v22 row_ror:8 row_mask:0xf bank_mask:0xf bound_ctrl:1
	v_mov_b32_dpp v35, v23 row_ror:8 row_mask:0xf bank_mask:0xf bound_ctrl:1
	v_mov_b32_dpp v36, v18 row_ror:8 row_mask:0xf bank_mask:0xf bound_ctrl:1
	v_mov_b32_dpp v37, v19 row_ror:8 row_mask:0xf bank_mask:0xf bound_ctrl:1
	v_lshl_add_u64 v[28:29], v[26:27], 0, v[138:139]
	v_cndmask_b32_e64 v21, v21, v19, s[6:7]
	v_cndmask_b32_e64 v20, v20, v18, s[6:7]
	v_cndmask_b32_e64 v19, v25, v23, s[6:7]
	v_cndmask_b32_e64 v18, v24, v22, s[6:7]
	v_cndmask_b32_e64 v25, v33, v37, s[6:7]
	v_cndmask_b32_e64 v24, v32, v36, s[6:7]
	v_cndmask_b32_e64 v23, v31, v35, s[6:7]
	v_cndmask_b32_e64 v22, v30, v34, s[6:7]
	v_cvt_pk_bf16_f32 v14, v14, v15
	v_cvt_pk_bf16_f32 v15, v16, v17
	v_cvt_pk_bf16_f32 v16, v10, v11
	v_cvt_pk_bf16_f32 v17, v12, v13
	v_cvt_pk_bf16_f32 v6, v6, v7
	v_cvt_pk_bf16_f32 v7, v8, v9
	v_cvt_pk_bf16_f32 v2, v2, v3
	v_cvt_pk_bf16_f32 v3, v4, v5
	s_mov_b64 s[4:5], 0xb0000
	v_lshl_add_u64 v[26:27], v[26:27], 0, v[140:141]
	global_store_dwordx4 v[28:29], v[22:25], off
	global_store_dwordx4 v[26:27], v[18:21], off
	v_lshl_add_u64 v[10:11], v[146:147], 0, s[4:5]
	v_mov_b32_dpp v8, v14 row_ror:8 row_mask:0xf bank_mask:0xf bound_ctrl:1
	v_mov_b32_dpp v9, v15 row_ror:8 row_mask:0xf bank_mask:0xf bound_ctrl:1
	v_mov_b32_dpp v4, v16 row_ror:8 row_mask:0xf bank_mask:0xf bound_ctrl:1
	v_mov_b32_dpp v5, v17 row_ror:8 row_mask:0xf bank_mask:0xf bound_ctrl:1
	v_mov_b32_dpp v18, v6 row_ror:8 row_mask:0xf bank_mask:0xf bound_ctrl:1
	v_mov_b32_dpp v19, v7 row_ror:8 row_mask:0xf bank_mask:0xf bound_ctrl:1
	v_mov_b32_dpp v20, v2 row_ror:8 row_mask:0xf bank_mask:0xf bound_ctrl:1
	v_mov_b32_dpp v21, v3 row_ror:8 row_mask:0xf bank_mask:0xf bound_ctrl:1
	v_lshl_add_u64 v[12:13], v[10:11], 0, v[138:139]
	v_cndmask_b32_e64 v5, v5, v3, s[6:7]
	v_cndmask_b32_e64 v4, v4, v2, s[6:7]
	v_cndmask_b32_e64 v3, v9, v7, s[6:7]
	v_cndmask_b32_e64 v2, v8, v6, s[6:7]
	v_cndmask_b32_e64 v9, v17, v21, s[6:7]
	v_cndmask_b32_e64 v8, v16, v20, s[6:7]
	v_cndmask_b32_e64 v7, v15, v19, s[6:7]
	v_cndmask_b32_e64 v6, v14, v18, s[6:7]
	s_and_b64 vcc, exec, s[8:9]
	s_mov_b64 s[8:9], -1
	v_lshl_add_u64 v[10:11], v[10:11], 0, v[140:141]
	global_store_dwordx4 v[12:13], v[6:9], off
	global_store_dwordx4 v[10:11], v[2:5], off
	s_cbranch_vccnz .LBB0_1036
; #define PG8_BAR __builtin_amdgcn_s_barrier()
; template <class Epi, class Sched, bool ABLK = false, bool ALIGN_EPI = true, bool SP2 = true, bool BBLK = true>
; __device__ __forceinline__ void gemm_phase(LAS unsigned char* lds, const Gemm g, const Sched& S, const Epi& E) {
;     ...
;         if (!has_next) break;
; #pragma unroll
;         for (int a = 0; a < 2; ++a)
; #pragma unroll
;             for (int b = 0; b < 2; ++b)
; #pragma unroll
;                 for (int m = 0; m < 4; ++m)
; #pragma unroll
;                     for (int n = 0; n < 2; ++n) acc[a][b][m][n] = (f32x4){0.f, 0.f, 0.f, 0.f};
;         cur = nxt; uA = nuA; tbA = ntbA; cB = nB; ++ui;
;         if constexpr (ALIGN_EPI) { if (wr == 1) PG8_BAR; }
	s_andn2_b64 vcc, exec, s[2:3]
	s_cbranch_vccnz .LBB0_1035
	s_barrier
	s_branch .LBB0_1035

; #define PG8_STAGE(bufoff, gbase, voff) do { _Pragma("unroll") for (int _i = 0; _i < 2; ++_i) \
;         __builtin_amdgcn_global_load_lds((const unsigned*)((const char*)(gbase) + (voff)[_i]), (LAS unsigned*)(lds + (bufoff) + ldsw + _i * 8192), 16, 0, 0); } while (0)
; #define PG8_LDA(dst, b, h) do { _Pragma("unroll") for (int m = 0; m < 4; ++m) _Pragma("unroll") for (int k = 0; k < 2; ++k) dst[m][k] = *(const LAS bf16x8*)(lds + PG8_SA(b, h) + aoff + m * 2048 + k * 1024); } while (0)
; #define PG8_LDB(dst, b, h) do { _Pragma("unroll") for (int n = 0; n < 2; ++n) _Pragma("unroll") for (int k = 0; k < 2; ++k) dst[n][k] = *(const LAS bf16x8*)(lds + PG8_SB(b, h) + boff + n * 2048 + k * 1024); } while (0)
; #define PG8_WAIT_V(n) asm volatile("s_waitcnt vmcnt(" #n ")" ::: "memory")
; #define PG8_WAIT_L(n) asm volatile("s_waitcnt lgkmcnt(" #n ")" ::: "memory")
; #define PG8_BAR __builtin_amdgcn_s_barrier()
; template <class Epi, class Sched, bool ABLK = false, bool ALIGN_EPI = true, bool SP2 = true, bool BBLK = true>
; __device__ __forceinline__ void gemm_phase(LAS unsigned char* lds, const Gemm g, const Sched& S, const Epi& E) {
;     ...
;         const char* nuA = has_next ? a_unit(nxt) : uA; const int ntbA = has_next ? nxt.k0 / BK : tbA; const char* nB = has_next ? (const char*)g.Bt + (size_t)nxt.pn * tstepB + b_k0(nxt.k0) : cB;
;         for (int t = 0; t < nt; t += 2) {
;             const bool last = (t == nt - 2);
;             const char* a1 = a_tile(uA, tbA + t + 1);
;             const char* a2 = last ? a_tile(nuA, ntbA) : a_tile(uA, tbA + t + 2); const char* b2 = last ? nB : cB + (size_t)(t + 2) * kstepB;
;             const char* a3 = last ? a_tile(nuA, ntbA + 1) : a_tile(uA, tbA + t + 3); const char* b3 = b2 + kstepB;
;             if (last && has_next) S.a_ready(nxt);
;             if constexpr (SP2) {
;             PG8_LDB(B0, 0, 0); PG8_LDB(B1, 0, 1); PG8_SCHED; PG8_LDA(At, 0, 0); PG8_STAGE(PG8_SA(1, 1), a1 + hstepA, voffA);
;             PG8_WAIT_V(8); PG8_WAIT_L(0); PG8_BAR; PG8_MMA(0, 0, At, B0); PG8_MMA(0, 1, At, B1); PG8_BAR; PG8_SCHED;
;             PG8_LDA(At, 0, 1); PG8_STAGE(PG8_SB(0, 0), b2, voffB); PG8_STAGE(PG8_SB(0, 1), b2 + hstepB, voffB); PG8_STAGE(PG8_SA(0, 0), a2, voffA);
;             PG8_WAIT_V(8); PG8_WAIT_L(0); PG8_BAR; PG8_MMA(1, 0, At, B0); PG8_MMA(1, 1, At, B1); PG8_BAR; PG8_SCHED;
.LBB0_1164:
	ds_read_b128 v[172:175], v169
	ds_read_b128 v[176:179], v169 offset:1024
	ds_read_b128 v[180:183], v169 offset:2048
	ds_read_b128 v[184:187], v169 offset:3072
	ds_read_b128 v[188:191], v170
	ds_read_b128 v[192:195], v170 offset:1024
	ds_read_b128 v[196:199], v170 offset:2048
	ds_read_b128 v[200:203], v170 offset:3072
	s_add_u32 s30, s26, s28
	s_addc_u32 s31, s27, s29
	s_add_u32 s36, s30, 0x100
	s_addc_u32 s37, s31, 0
	s_add_u32 s30, s30, 0x180
	s_addc_u32 s31, s31, 0
	s_cmpk_eq_i32 s28, 0xf00
	s_cselect_b32 s31, s57, s31
	s_cselect_b32 s30, s23, s30
	s_cselect_b32 s35, s11, s65
	s_cselect_b32 s34, s15, s64
	s_cselect_b32 s37, s4, s37
	s_cselect_b32 s36, s5, s36
	s_mov_b32 m0, s50
	v_lshl_add_u64 v[236:237], v[164:165], 0, s[28:29]
	ds_read_b128 v[204:207], v171
	ds_read_b128 v[208:211], v171 offset:1024
	ds_read_b128 v[212:215], v171 offset:2048
	ds_read_b128 v[216:219], v171 offset:3072
	ds_read_b128 v[220:223], v171 offset:4096
	ds_read_b128 v[224:227], v171 offset:5120
	ds_read_b128 v[228:231], v171 offset:6144
	ds_read_b128 v[232:235], v171 offset:7168
	global_load_lds_dwordx4 v[236:237], off
	v_lshl_add_u64 v[236:237], v[166:167], 0, s[28:29]
	s_mov_b32 m0, s51
	s_nop 0
	global_load_lds_dwordx4 v[236:237], off
	s_waitcnt vmcnt(8) lgkmcnt(0)
	s_barrier
	v_mfma_f32_16x16x32_bf16 v[126:129], v[172:175], v[204:207], v[126:129]
	v_mfma_f32_16x16x32_bf16 v[122:125], v[180:183], v[204:207], v[122:125]
	v_mfma_f32_16x16x32_bf16 v[110:113], v[172:175], v[212:215], v[110:113]
	v_mfma_f32_16x16x32_bf16 v[106:109], v[180:183], v[212:215], v[106:109]
	v_mfma_f32_16x16x32_bf16 v[94:97], v[172:175], v[220:223], v[94:97]
	v_mfma_f32_16x16x32_bf16 v[90:93], v[180:183], v[220:223], v[90:93]
	v_mfma_f32_16x16x32_bf16 v[78:81], v[172:175], v[228:231], v[78:81]
	v_mfma_f32_16x16x32_bf16 v[74:77], v[180:183], v[228:231], v[74:77]
	v_mfma_f32_16x16x32_bf16 v[126:129], v[176:179], v[208:211], v[126:129]
	v_mfma_f32_16x16x32_bf16 v[122:125], v[184:187], v[208:211], v[122:125]
	v_mfma_f32_16x16x32_bf16 v[110:113], v[176:179], v[216:219], v[110:113]
	v_mfma_f32_16x16x32_bf16 v[106:109], v[184:187], v[216:219], v[106:109]
	v_mfma_f32_16x16x32_bf16 v[94:97], v[176:179], v[224:227], v[94:97]
	v_mfma_f32_16x16x32_bf16 v[90:93], v[184:187], v[224:227], v[90:93]
	v_mfma_f32_16x16x32_bf16 v[78:81], v[176:179], v[232:235], v[78:81]
	v_mfma_f32_16x16x32_bf16 v[74:77], v[184:187], v[232:235], v[74:77]
	v_mfma_f32_16x16x32_bf16 v[118:121], v[188:191], v[204:207], v[118:121]
	v_mfma_f32_16x16x32_bf16 v[114:117], v[196:199], v[204:207], v[114:117]
	v_mfma_f32_16x16x32_bf16 v[102:105], v[188:191], v[212:215], v[102:105]
	v_mfma_f32_16x16x32_bf16 v[98:101], v[196:199], v[212:215], v[98:101]
	v_mfma_f32_16x16x32_bf16 v[86:89], v[188:191], v[220:223], v[86:89]
	v_mfma_f32_16x16x32_bf16 v[82:85], v[196:199], v[220:223], v[82:85]
	v_mfma_f32_16x16x32_bf16 v[70:73], v[188:191], v[228:231], v[70:73]
	v_mfma_f32_16x16x32_bf16 v[66:69], v[196:199], v[228:231], v[66:69]
	v_mfma_f32_16x16x32_bf16 v[118:121], v[192:195], v[208:211], v[118:121]
	v_mfma_f32_16x16x32_bf16 v[114:117], v[200:203], v[208:211], v[114:117]
	v_mfma_f32_16x16x32_bf16 v[102:105], v[192:195], v[216:219], v[102:105]
	v_mfma_f32_16x16x32_bf16 v[98:101], v[200:203], v[216:219], v[98:101]
	v_mfma_f32_16x16x32_bf16 v[86:89], v[192:195], v[224:227], v[86:89]
	v_mfma_f32_16x16x32_bf16 v[82:85], v[200:203], v[224:227], v[82:85]
	v_mfma_f32_16x16x32_bf16 v[70:73], v[192:195], v[232:235], v[70:73]
	v_mfma_f32_16x16x32_bf16 v[66:69], v[200:203], v[232:235], v[66:69]
	s_barrier
	s_mov_b32 m0, s55
	s_add_u32 s76, s34, 0x4000
	ds_read_b128 v[204:207], v171 offset:16384
	ds_read_b128 v[208:211], v171 offset:17408
	ds_read_b128 v[212:215], v171 offset:18432
	ds_read_b128 v[216:219], v171 offset:19456
	ds_read_b128 v[220:223], v171 offset:20480
	ds_read_b128 v[224:227], v171 offset:21504
	ds_read_b128 v[228:231], v171 offset:22528
	ds_read_b128 v[232:235], v171 offset:23552
	global_load_lds_dwordx4 v134, s[34:35]
	s_mov_b32 m0, s56
	s_addc_u32 s77, s35, 0
	s_add_i32 s67, s73, s42
	global_load_lds_dwordx4 v130, s[34:35]
	s_mov_b32 m0, s67
	s_nop 0
	global_load_lds_dwordx4 v134, s[76:77]
	s_add_i32 m0, s67, 0x2000
	s_nop 0
	global_load_lds_dwordx4 v130, s[76:77]
	s_mov_b32 m0, s25
	s_nop 0
	global_load_lds_dwordx4 v136, s[36:37]
	s_mov_b32 m0, s43
	s_nop 0
	global_load_lds_dwordx4 v132, s[36:37]
	s_waitcnt vmcnt(8) lgkmcnt(0)
	s_barrier
	v_mfma_f32_16x16x32_bf16 v[62:65], v[172:175], v[204:207], v[62:65]
	v_mfma_f32_16x16x32_bf16 v[58:61], v[180:183], v[204:207], v[58:61]
	v_mfma_f32_16x16x32_bf16 v[46:49], v[172:175], v[212:215], v[46:49]
	v_mfma_f32_16x16x32_bf16 v[42:45], v[180:183], v[212:215], v[42:45]
	v_mfma_f32_16x16x32_bf16 v[30:33], v[172:175], v[220:223], v[30:33]
	v_mfma_f32_16x16x32_bf16 v[26:29], v[180:183], v[220:223], v[26:29]
	v_mfma_f32_16x16x32_bf16 v[14:17], v[172:175], v[228:231], v[14:17]
	v_mfma_f32_16x16x32_bf16 v[10:13], v[180:183], v[228:231], v[10:13]
	v_mfma_f32_16x16x32_bf16 v[62:65], v[176:179], v[208:211], v[62:65]
	v_mfma_f32_16x16x32_bf16 v[58:61], v[184:187], v[208:211], v[58:61]
	v_mfma_f32_16x16x32_bf16 v[46:49], v[176:179], v[216:219], v[46:49]
	v_mfma_f32_16x16x32_bf16 v[42:45], v[184:187], v[216:219], v[42:45]
	v_mfma_f32_16x16x32_bf16 v[30:33], v[176:179], v[224:227], v[30:33]
	v_mfma_f32_16x16x32_bf16 v[26:29], v[184:187], v[224:227], v[26:29]
	v_mfma_f32_16x16x32_bf16 v[14:17], v[176:179], v[232:235], v[14:17]
	v_mfma_f32_16x16x32_bf16 v[10:13], v[184:187], v[232:235], v[10:13]
	v_mfma_f32_16x16x32_bf16 v[54:57], v[188:191], v[204:207], v[54:57]
	v_mfma_f32_16x16x32_bf16 v[50:53], v[196:199], v[204:207], v[50:53]
	v_mfma_f32_16x16x32_bf16 v[38:41], v[188:191], v[212:215], v[38:41]
	v_mfma_f32_16x16x32_bf16 v[34:37], v[196:199], v[212:215], v[34:37]
	v_mfma_f32_16x16x32_bf16 v[22:25], v[188:191], v[220:223], v[22:25]
	v_mfma_f32_16x16x32_bf16 v[18:21], v[196:199], v[220:223], v[18:21]
	v_mfma_f32_16x16x32_bf16 v[6:9], v[188:191], v[228:231], v[6:9]
	v_mfma_f32_16x16x32_bf16 v[2:5], v[196:199], v[228:231], v[2:5]
	v_mfma_f32_16x16x32_bf16 v[54:57], v[192:195], v[208:211], v[54:57]
	v_mfma_f32_16x16x32_bf16 v[50:53], v[200:203], v[208:211], v[50:53]
	v_mfma_f32_16x16x32_bf16 v[38:41], v[192:195], v[216:219], v[38:41]
	v_mfma_f32_16x16x32_bf16 v[34:37], v[200:203], v[216:219], v[34:37]
	v_mfma_f32_16x16x32_bf16 v[22:25], v[192:195], v[224:227], v[22:25]
	v_mfma_f32_16x16x32_bf16 v[18:21], v[200:203], v[224:227], v[18:21]
	v_mfma_f32_16x16x32_bf16 v[6:9], v[192:195], v[232:235], v[6:9]
	v_mfma_f32_16x16x32_bf16 v[2:5], v[200:203], v[232:235], v[2:5]
	s_barrier
; #define PG8_STAGE(bufoff, gbase, voff) do { _Pragma("unroll") for (int _i = 0; _i < 2; ++_i) \
;         __builtin_amdgcn_global_load_lds((const unsigned*)((const char*)(gbase) + (voff)[_i]), (LAS unsigned*)(lds + (bufoff) + ldsw + _i * 8192), 16, 0, 0); } while (0)
; #define PG8_LDA(dst, b, h) do { _Pragma("unroll") for (int m = 0; m < 4; ++m) _Pragma("unroll") for (int k = 0; k < 2; ++k) dst[m][k] = *(const LAS bf16x8*)(lds + PG8_SA(b, h) + aoff + m * 2048 + k * 1024); } while (0)
; #define PG8_LDB(dst, b, h) do { _Pragma("unroll") for (int n = 0; n < 2; ++n) _Pragma("unroll") for (int k = 0; k < 2; ++k) dst[n][k] = *(const LAS bf16x8*)(lds + PG8_SB(b, h) + boff + n * 2048 + k * 1024); } while (0)
; #define PG8_MMA(ai, bj, At, Bt) do { __builtin_amdgcn_s_setprio(1); _Pragma("unroll") for (int m = 0; m < 4; ++m) _Pragma("unroll") for (int n = 0; n < 2; ++n) _Pragma("unroll") for (int k = 0; k < 2; ++k) \
;         acc[ai][bj][m][n] = __builtin_amdgcn_mfma_f32_16x16x32_bf16(Bt[n][k], At[m][k], acc[ai][bj][m][n], 0, 0, 0); __builtin_amdgcn_s_setprio(0); } while (0)
; #define PG8_WAIT_V(n) asm volatile("s_waitcnt vmcnt(" #n ")" ::: "memory")
; #define PG8_WAIT_L(n) asm volatile("s_waitcnt lgkmcnt(" #n ")" ::: "memory")
; #define PG8_BAR __builtin_amdgcn_s_barrier()
; #define PG8_SCHED __builtin_amdgcn_sched_barrier(0)
; template <class Epi, class Sched, bool ABLK = false, bool ALIGN_EPI = true, bool SP2 = true, bool BBLK = true>
; __device__ __forceinline__ void gemm_phase(LAS unsigned char* lds, const Gemm g, const Sched& S, const Epi& E) {
;     ...
;             PG8_LDB(B0, 1, 0); PG8_LDB(B1, 1, 1); PG8_SCHED; PG8_LDA(At, 1, 0); PG8_STAGE(PG8_SA(0, 1), a2 + hstepA, voffA);
;             PG8_WAIT_V(8); PG8_WAIT_L(0); PG8_BAR; PG8_MMA(0, 0, At, B0); PG8_MMA(0, 1, At, B1); PG8_BAR; PG8_SCHED;
;             PG8_LDA(At, 1, 1); PG8_STAGE(PG8_SB(1, 0), b3, voffB); PG8_STAGE(PG8_SB(1, 1), b3 + hstepB, voffB); PG8_STAGE(PG8_SA(1, 0), a3, voffA);
;             PG8_WAIT_V(8); PG8_WAIT_L(0); PG8_BAR; PG8_MMA(1, 0, At, B0); PG8_MMA(1, 1, At, B1); PG8_BAR; PG8_SCHED;
	v_add_u32_e32 v184, s60, v168
	v_add_u32_e32 v200, s61, v168
	ds_read_b128 v[172:175], v184
	ds_read_b128 v[176:179], v184 offset:1024
	ds_read_b128 v[180:183], v184 offset:2048
	ds_read_b128 v[184:187], v184 offset:3072
	ds_read_b128 v[188:191], v200
	ds_read_b128 v[192:195], v200 offset:1024
	ds_read_b128 v[196:199], v200 offset:2048
	ds_read_b128 v[200:203], v200 offset:3072
	s_add_u32 s36, s36, 0x80000
	s_addc_u32 s37, s37, 0
	s_mov_b32 m0, s44
	ds_read_b128 v[204:207], v171 offset:32768
	ds_read_b128 v[208:211], v171 offset:33792
	ds_read_b128 v[212:215], v171 offset:34816
	ds_read_b128 v[216:219], v171 offset:35840
	ds_read_b128 v[220:223], v171 offset:36864
	ds_read_b128 v[224:227], v171 offset:37888
	ds_read_b128 v[228:231], v171 offset:38912
	ds_read_b128 v[232:235], v171 offset:39936
	global_load_lds_dwordx4 v136, s[36:37]
	s_mov_b32 m0, s45
	s_nop 0
	global_load_lds_dwordx4 v132, s[36:37]
	s_waitcnt vmcnt(8) lgkmcnt(0)
	s_barrier
	v_mfma_f32_16x16x32_bf16 v[126:129], v[172:175], v[204:207], v[126:129]
	v_mfma_f32_16x16x32_bf16 v[122:125], v[180:183], v[204:207], v[122:125]
	v_mfma_f32_16x16x32_bf16 v[110:113], v[172:175], v[212:215], v[110:113]
	v_mfma_f32_16x16x32_bf16 v[106:109], v[180:183], v[212:215], v[106:109]
	v_mfma_f32_16x16x32_bf16 v[94:97], v[172:175], v[220:223], v[94:97]
	v_mfma_f32_16x16x32_bf16 v[90:93], v[180:183], v[220:223], v[90:93]
	v_mfma_f32_16x16x32_bf16 v[78:81], v[172:175], v[228:231], v[78:81]
	v_mfma_f32_16x16x32_bf16 v[74:77], v[180:183], v[228:231], v[74:77]
	v_mfma_f32_16x16x32_bf16 v[126:129], v[176:179], v[208:211], v[126:129]
	v_mfma_f32_16x16x32_bf16 v[122:125], v[184:187], v[208:211], v[122:125]
	v_mfma_f32_16x16x32_bf16 v[110:113], v[176:179], v[216:219], v[110:113]
	v_mfma_f32_16x16x32_bf16 v[106:109], v[184:187], v[216:219], v[106:109]
	v_mfma_f32_16x16x32_bf16 v[94:97], v[176:179], v[224:227], v[94:97]
	v_mfma_f32_16x16x32_bf16 v[90:93], v[184:187], v[224:227], v[90:93]
	v_mfma_f32_16x16x32_bf16 v[78:81], v[176:179], v[232:235], v[78:81]
	v_mfma_f32_16x16x32_bf16 v[74:77], v[184:187], v[232:235], v[74:77]
	v_mfma_f32_16x16x32_bf16 v[118:121], v[188:191], v[204:207], v[118:121]
	v_mfma_f32_16x16x32_bf16 v[114:117], v[196:199], v[204:207], v[114:117]
	v_mfma_f32_16x16x32_bf16 v[102:105], v[188:191], v[212:215], v[102:105]
	v_mfma_f32_16x16x32_bf16 v[98:101], v[196:199], v[212:215], v[98:101]
	v_mfma_f32_16x16x32_bf16 v[86:89], v[188:191], v[220:223], v[86:89]
	v_mfma_f32_16x16x32_bf16 v[82:85], v[196:199], v[220:223], v[82:85]
	v_mfma_f32_16x16x32_bf16 v[70:73], v[188:191], v[228:231], v[70:73]
	v_mfma_f32_16x16x32_bf16 v[66:69], v[196:199], v[228:231], v[66:69]
	v_mfma_f32_16x16x32_bf16 v[118:121], v[192:195], v[208:211], v[118:121]
	v_mfma_f32_16x16x32_bf16 v[114:117], v[200:203], v[208:211], v[114:117]
	v_mfma_f32_16x16x32_bf16 v[102:105], v[192:195], v[216:219], v[102:105]
	v_mfma_f32_16x16x32_bf16 v[98:101], v[200:203], v[216:219], v[98:101]
	v_mfma_f32_16x16x32_bf16 v[86:89], v[192:195], v[224:227], v[86:89]
	v_mfma_f32_16x16x32_bf16 v[82:85], v[200:203], v[224:227], v[82:85]
	v_mfma_f32_16x16x32_bf16 v[70:73], v[192:195], v[232:235], v[70:73]
	v_mfma_f32_16x16x32_bf16 v[66:69], v[200:203], v[232:235], v[66:69]
	s_barrier
	s_add_u32 s36, s34, 0x8000
	s_addc_u32 s37, s35, 0
	s_add_i32 s67, s60, s42
	s_mov_b32 m0, s67
	ds_read_b128 v[204:207], v171 offset:49152
	ds_read_b128 v[208:211], v171 offset:50176
	ds_read_b128 v[212:215], v171 offset:51200
	ds_read_b128 v[216:219], v171 offset:52224
	ds_read_b128 v[220:223], v171 offset:53248
	ds_read_b128 v[224:227], v171 offset:54272
	ds_read_b128 v[228:231], v171 offset:55296
	ds_read_b128 v[232:235], v171 offset:56320
	global_load_lds_dwordx4 v134, s[36:37]
	s_add_i32 m0, s67, 0x2000
	s_add_u32 s34, s34, 0xc000
	v_lshl_add_u64 v[236:237], s[36:37], 0, v[130:131]
	s_addc_u32 s35, s35, 0
	s_add_i32 s36, s61, s42
	global_load_lds_dwordx4 v[236:237], off
	s_mov_b32 m0, s36
	s_nop 0
	global_load_lds_dwordx4 v134, s[34:35]
	s_add_i32 m0, s36, 0x2000
	s_nop 0
	global_load_lds_dwordx4 v130, s[34:35]
	s_mov_b32 m0, s48
	s_nop 0
	global_load_lds_dwordx4 v136, s[30:31]
	s_mov_b32 m0, s49
	s_nop 0
	global_load_lds_dwordx4 v132, s[30:31]
	s_waitcnt vmcnt(8) lgkmcnt(0)
	s_barrier
	v_mfma_f32_16x16x32_bf16 v[62:65], v[172:175], v[204:207], v[62:65]
	v_mfma_f32_16x16x32_bf16 v[58:61], v[180:183], v[204:207], v[58:61]
	v_mfma_f32_16x16x32_bf16 v[46:49], v[172:175], v[212:215], v[46:49]
	v_mfma_f32_16x16x32_bf16 v[42:45], v[180:183], v[212:215], v[42:45]
	v_mfma_f32_16x16x32_bf16 v[30:33], v[172:175], v[220:223], v[30:33]
	v_mfma_f32_16x16x32_bf16 v[26:29], v[180:183], v[220:223], v[26:29]
	v_mfma_f32_16x16x32_bf16 v[14:17], v[172:175], v[228:231], v[14:17]
	v_mfma_f32_16x16x32_bf16 v[10:13], v[180:183], v[228:231], v[10:13]
	v_mfma_f32_16x16x32_bf16 v[62:65], v[176:179], v[208:211], v[62:65]
	v_mfma_f32_16x16x32_bf16 v[58:61], v[184:187], v[208:211], v[58:61]
	v_mfma_f32_16x16x32_bf16 v[46:49], v[176:179], v[216:219], v[46:49]
	v_mfma_f32_16x16x32_bf16 v[42:45], v[184:187], v[216:219], v[42:45]
	v_mfma_f32_16x16x32_bf16 v[30:33], v[176:179], v[224:227], v[30:33]
	v_mfma_f32_16x16x32_bf16 v[26:29], v[184:187], v[224:227], v[26:29]
	v_mfma_f32_16x16x32_bf16 v[14:17], v[176:179], v[232:235], v[14:17]
	v_mfma_f32_16x16x32_bf16 v[10:13], v[184:187], v[232:235], v[10:13]
	v_mfma_f32_16x16x32_bf16 v[54:57], v[188:191], v[204:207], v[54:57]
	v_mfma_f32_16x16x32_bf16 v[50:53], v[196:199], v[204:207], v[50:53]
	v_mfma_f32_16x16x32_bf16 v[38:41], v[188:191], v[212:215], v[38:41]
	v_mfma_f32_16x16x32_bf16 v[34:37], v[196:199], v[212:215], v[34:37]
	v_mfma_f32_16x16x32_bf16 v[22:25], v[188:191], v[220:223], v[22:25]
	v_mfma_f32_16x16x32_bf16 v[18:21], v[196:199], v[220:223], v[18:21]
	v_mfma_f32_16x16x32_bf16 v[6:9], v[188:191], v[228:231], v[6:9]
	v_mfma_f32_16x16x32_bf16 v[2:5], v[196:199], v[228:231], v[2:5]
	v_mfma_f32_16x16x32_bf16 v[54:57], v[192:195], v[208:211], v[54:57]
	v_mfma_f32_16x16x32_bf16 v[50:53], v[200:203], v[208:211], v[50:53]
	v_mfma_f32_16x16x32_bf16 v[38:41], v[192:195], v[216:219], v[38:41]
	v_mfma_f32_16x16x32_bf16 v[34:37], v[200:203], v[216:219], v[34:37]
	v_mfma_f32_16x16x32_bf16 v[22:25], v[192:195], v[224:227], v[22:25]
	v_mfma_f32_16x16x32_bf16 v[18:21], v[200:203], v[224:227], v[18:21]
	v_mfma_f32_16x16x32_bf16 v[6:9], v[192:195], v[232:235], v[6:9]
	v_mfma_f32_16x16x32_bf16 v[2:5], v[200:203], v[232:235], v[2:5]
	s_barrier
; __device__ __forceinline__ unsigned pk2(float lo, float hi) { const f32x2 v = {lo, hi}; return __builtin_bit_cast(unsigned, __builtin_convertvector(v, bf16x2_t)); }
; #define PG8_BAR __builtin_amdgcn_s_barrier()
; template <class Epi, class Sched, bool ABLK = false, bool ALIGN_EPI = true, bool SP2 = true, bool BBLK = true>
; __device__ __forceinline__ void gemm_phase(LAS unsigned char* lds, const Gemm g, const Sched& S, const Epi& E) {
;     ...
;         if constexpr (ALIGN_EPI) { if (wr == 0) PG8_BAR; }
;         E(acc, cur, wr, wc, fr, fq); S.done(cur);
;     __device__ __forceinline__ void operator()(const f32x4 (&acc)[2][2][4][2], const Unit& u, int wr, int wc, int fr, int fq) const {
; #pragma unroll
;         for (int ai = 0; ai < 2; ++ai)
; #pragma unroll
;             for (int m = 0; m < 4; ++m) { unsigned char* rowp = (unsigned char*)(H + ((size_t)(u.pm * (FF / 64) + u.pn * 4 + wc) * 256 + (wr * 64 + fr + ai * 128 + m * 16)) * 64 + 8 * fq); u32x4 w[2];
; #pragma unroll
;                 for (int bj = 0; bj < 2; ++bj) { f32x4 v0 = acc[ai][bj][m][0], v1 = acc[ai][bj][m][1];
; #pragma unroll
;                     for (int j = 0; j < 4; ++j) { const float a = fmaxf(v0[j], 0.f), b = fmaxf(v1[j], 0.f); v0[j] = a * a; v1[j] = b * b; }
;                     w[bj].x = pk2(v0[0], v0[1]); w[bj].y = pk2(v0[2], v0[3]); w[bj].z = pk2(v1[0], v1[1]); w[bj].w = pk2(v1[2], v1[3]); }
;                 store_pair(rowp, (size_t)8 * 64 * 2, 64, w[0], w[1], fr >= 8); }
	s_add_i32 s66, s66, 2
	s_add_u32 s28, s28, 0x100
	s_addc_u32 s29, s29, 0
	s_add_u32 s64, s64, 0x10000
	s_addc_u32 s65, s65, 0
	s_cmp_gt_u32 s66, 29
	s_cbranch_scc0 .LBB0_1164
	s_lshl_b32 s4, s22, 7
	s_lshl_b32 s5, s24, 2
	s_add_i32 s5, s5, s4
	s_or_b32 s4, s5, s47
	s_ashr_i32 s5, s4, 31
	s_lshl_b64 s[4:5], s[4:5], 15
	s_add_u32 s22, s1, s4
	v_max_f32_e32 v126, 0, v126
	v_max_f32_e32 v122, 0, v122
	v_max_f32_e32 v127, 0, v127
	v_max_f32_e32 v123, 0, v123
	v_max_f32_e32 v128, 0, v128
	v_max_f32_e32 v124, 0, v124
	v_max_f32_e32 v129, 0, v129
	v_max_f32_e32 v125, 0, v125
	v_max_f32_e32 v118, 0, v118
	v_max_f32_e32 v114, 0, v114
	v_max_f32_e32 v119, 0, v119
	v_max_f32_e32 v115, 0, v115
	v_max_f32_e32 v120, 0, v120
	v_max_f32_e32 v116, 0, v116
	v_max_f32_e32 v121, 0, v121
	v_max_f32_e32 v117, 0, v117
	s_addc_u32 s23, s33, s5
	v_pk_mul_f32 v[126:127], v[126:127], v[126:127]
	v_pk_mul_f32 v[122:123], v[122:123], v[122:123]
	v_pk_mul_f32 v[128:129], v[128:129], v[128:129]
	v_pk_mul_f32 v[124:125], v[124:125], v[124:125]
	v_pk_mul_f32 v[118:119], v[118:119], v[118:119]
	v_pk_mul_f32 v[114:115], v[114:115], v[114:115]
	v_pk_mul_f32 v[120:121], v[120:121], v[120:121]
	v_pk_mul_f32 v[116:117], v[116:117], v[116:117]
	v_lshl_add_u64 v[164:165], s[22:23], 0, v[144:145]
	v_cvt_pk_bf16_f32 v126, v126, v127
	v_cvt_pk_bf16_f32 v127, v128, v129
	v_cvt_pk_bf16_f32 v128, v122, v123
	v_cvt_pk_bf16_f32 v129, v124, v125
	v_cvt_pk_bf16_f32 v118, v118, v119
	v_cvt_pk_bf16_f32 v119, v120, v121
	v_cvt_pk_bf16_f32 v114, v114, v115
	v_cvt_pk_bf16_f32 v115, v116, v117
	v_lshl_add_u64 v[122:123], v[164:165], 0, v[138:139]
	v_mov_b32_dpp v120, v126 row_ror:8 row_mask:0xf bank_mask:0xf bound_ctrl:1
	v_mov_b32_dpp v121, v127 row_ror:8 row_mask:0xf bank_mask:0xf bound_ctrl:1
	v_mov_b32_dpp v116, v128 row_ror:8 row_mask:0xf bank_mask:0xf bound_ctrl:1
	v_mov_b32_dpp v117, v129 row_ror:8 row_mask:0xf bank_mask:0xf bound_ctrl:1
	v_mov_b32_dpp v164, v118 row_ror:8 row_mask:0xf bank_mask:0xf bound_ctrl:1
	v_mov_b32_dpp v165, v119 row_ror:8 row_mask:0xf bank_mask:0xf bound_ctrl:1
	v_mov_b32_dpp v166, v114 row_ror:8 row_mask:0xf bank_mask:0xf bound_ctrl:1
	v_mov_b32_dpp v167, v115 row_ror:8 row_mask:0xf bank_mask:0xf bound_ctrl:1
	v_max_f32_e32 v110, 0, v110
	v_max_f32_e32 v106, 0, v106
	v_max_f32_e32 v111, 0, v111
	v_max_f32_e32 v107, 0, v107
	v_max_f32_e32 v112, 0, v112
	v_max_f32_e32 v108, 0, v108
	v_max_f32_e32 v113, 0, v113
	v_max_f32_e32 v109, 0, v109
	v_max_f32_e32 v102, 0, v102
	v_max_f32_e32 v98, 0, v98
	v_max_f32_e32 v103, 0, v103
	v_max_f32_e32 v99, 0, v99
	v_max_f32_e32 v104, 0, v104
	v_max_f32_e32 v100, 0, v100
	v_max_f32_e32 v105, 0, v105
	v_max_f32_e32 v101, 0, v101
	v_lshl_add_u64 v[124:125], v[122:123], 0, v[140:141]
	v_cndmask_b32_e64 v117, v117, v115, s[8:9]
	v_cndmask_b32_e64 v116, v116, v114, s[8:9]
	v_cndmask_b32_e64 v115, v121, v119, s[8:9]
	v_cndmask_b32_e64 v114, v120, v118, s[8:9]
	v_cndmask_b32_e64 v121, v129, v167, s[8:9]
	v_cndmask_b32_e64 v120, v128, v166, s[8:9]
	v_cndmask_b32_e64 v119, v127, v165, s[8:9]
	v_cndmask_b32_e64 v118, v126, v164, s[8:9]
	v_pk_mul_f32 v[110:111], v[110:111], v[110:111]
	v_pk_mul_f32 v[106:107], v[106:107], v[106:107]
	v_pk_mul_f32 v[112:113], v[112:113], v[112:113]
	v_pk_mul_f32 v[108:109], v[108:109], v[108:109]
	v_pk_mul_f32 v[102:103], v[102:103], v[102:103]
	v_pk_mul_f32 v[98:99], v[98:99], v[98:99]
	v_pk_mul_f32 v[104:105], v[104:105], v[104:105]
	v_pk_mul_f32 v[100:101], v[100:101], v[100:101]
	v_lshl_add_u64 v[122:123], v[122:123], 0, v[142:143]
	s_and_b64 vcc, exec, s[6:7]
	s_cbranch_vccz .LBB0_1167
	s_barrier
.LBB0_1167:
	global_store_dwordx4 v[124:125], v[118:121], off
	global_store_dwordx4 v[122:123], v[114:117], off
	v_cvt_pk_bf16_f32 v110, v110, v111
	v_cvt_pk_bf16_f32 v111, v112, v113
	v_lshl_add_u64 v[114:115], s[22:23], 0, v[146:147]
	v_cvt_pk_bf16_f32 v112, v106, v107
	v_cvt_pk_bf16_f32 v113, v108, v109
	v_cvt_pk_bf16_f32 v102, v102, v103
	v_cvt_pk_bf16_f32 v103, v104, v105
	v_cvt_pk_bf16_f32 v98, v98, v99
	v_cvt_pk_bf16_f32 v99, v100, v101
	v_lshl_add_u64 v[106:107], v[114:115], 0, v[138:139]
	v_mov_b32_dpp v104, v110 row_ror:8 row_mask:0xf bank_mask:0xf bound_ctrl:1
	v_mov_b32_dpp v105, v111 row_ror:8 row_mask:0xf bank_mask:0xf bound_ctrl:1
	v_mov_b32_dpp v100, v112 row_ror:8 row_mask:0xf bank_mask:0xf bound_ctrl:1
	v_mov_b32_dpp v101, v113 row_ror:8 row_mask:0xf bank_mask:0xf bound_ctrl:1
	v_mov_b32_dpp v114, v102 row_ror:8 row_mask:0xf bank_mask:0xf bound_ctrl:1
	v_mov_b32_dpp v115, v103 row_ror:8 row_mask:0xf bank_mask:0xf bound_ctrl:1
	v_mov_b32_dpp v116, v98 row_ror:8 row_mask:0xf bank_mask:0xf bound_ctrl:1
	v_mov_b32_dpp v117, v99 row_ror:8 row_mask:0xf bank_mask:0xf bound_ctrl:1
	v_max_f32_e32 v94, 0, v94
	v_max_f32_e32 v90, 0, v90
	v_max_f32_e32 v95, 0, v95
	v_max_f32_e32 v91, 0, v91
	v_max_f32_e32 v96, 0, v96
	v_max_f32_e32 v92, 0, v92
	v_max_f32_e32 v97, 0, v97
	v_max_f32_e32 v93, 0, v93
	v_max_f32_e32 v86, 0, v86
	v_max_f32_e32 v82, 0, v82
	v_max_f32_e32 v87, 0, v87
	v_max_f32_e32 v83, 0, v83
	v_max_f32_e32 v88, 0, v88
	v_max_f32_e32 v84, 0, v84
	v_max_f32_e32 v89, 0, v89
	v_max_f32_e32 v85, 0, v85
	v_lshl_add_u64 v[108:109], v[106:107], 0, v[140:141]
	v_cndmask_b32_e64 v101, v101, v99, s[8:9]
	v_cndmask_b32_e64 v100, v100, v98, s[8:9]
	v_cndmask_b32_e64 v99, v105, v103, s[8:9]
	v_cndmask_b32_e64 v98, v104, v102, s[8:9]
	v_cndmask_b32_e64 v105, v113, v117, s[8:9]
	v_cndmask_b32_e64 v104, v112, v116, s[8:9]
	v_cndmask_b32_e64 v103, v111, v115, s[8:9]
	v_cndmask_b32_e64 v102, v110, v114, s[8:9]
	v_pk_mul_f32 v[94:95], v[94:95], v[94:95]
	v_pk_mul_f32 v[90:91], v[90:91], v[90:91]
; __device__ __forceinline__ unsigned pk2(float lo, float hi) { const f32x2 v = {lo, hi}; return __builtin_bit_cast(unsigned, __builtin_convertvector(v, bf16x2_t)); }
; __device__ __forceinline__ u32x4 ror8(u32x4 v) { u32x4 r;
; #pragma unroll
;     for (int i = 0; i < 4; ++i) r[i] = (unsigned)__builtin_amdgcn_mov_dpp((int)v[i], 0x128, 0xf, 0xf, true);
;     return r; }
; __device__ __forceinline__ void store_pair(unsigned char* own, size_t stride8, int hi_off, u32x4 lo, u32x4 hi, bool upper) {
;     const u32x4 tlo = ror8(lo), thi = ror8(hi);
;     const u32x4 A = upper ? thi : lo, B = upper ? hi : tlo;
;     unsigned char* pa = upper ? own - stride8 + hi_off : own;
;     unsigned char* pb = upper ? own + hi_off : own + stride8;
;     *(u32x4*)pa = A; *(u32x4*)pb = B;
; }
;     __device__ __forceinline__ void operator()(const f32x4 (&acc)[2][2][4][2], const Unit& u, int wr, int wc, int fr, int fq) const {
; #pragma unroll
;         for (int ai = 0; ai < 2; ++ai)
; #pragma unroll
;             for (int m = 0; m < 4; ++m) { unsigned char* rowp = (unsigned char*)(H + ((size_t)(u.pm * (FF / 64) + u.pn * 4 + wc) * 256 + (wr * 64 + fr + ai * 128 + m * 16)) * 64 + 8 * fq); u32x4 w[2];
; #pragma unroll
;                 for (int bj = 0; bj < 2; ++bj) { f32x4 v0 = acc[ai][bj][m][0], v1 = acc[ai][bj][m][1];
; #pragma unroll
;                     for (int j = 0; j < 4; ++j) { const float a = fmaxf(v0[j], 0.f), b = fmaxf(v1[j], 0.f); v0[j] = a * a; v1[j] = b * b; }
;                     w[bj].x = pk2(v0[0], v0[1]); w[bj].y = pk2(v0[2], v0[3]); w[bj].z = pk2(v1[0], v1[1]); w[bj].w = pk2(v1[2], v1[3]); }
;                 store_pair(rowp, (size_t)8 * 64 * 2, 64, w[0], w[1], fr >= 8); }
	v_pk_mul_f32 v[96:97], v[96:97], v[96:97]
	v_pk_mul_f32 v[92:93], v[92:93], v[92:93]
	v_pk_mul_f32 v[86:87], v[86:87], v[86:87]
	v_pk_mul_f32 v[82:83], v[82:83], v[82:83]
	v_pk_mul_f32 v[88:89], v[88:89], v[88:89]
	v_pk_mul_f32 v[84:85], v[84:85], v[84:85]
	v_lshl_add_u64 v[106:107], v[106:107], 0, v[142:143]
	global_store_dwordx4 v[108:109], v[102:105], off
	global_store_dwordx4 v[106:107], v[98:101], off
	v_cvt_pk_bf16_f32 v94, v94, v95
	v_cvt_pk_bf16_f32 v95, v96, v97
	v_lshl_add_u64 v[98:99], s[22:23], 0, v[148:149]
	v_cvt_pk_bf16_f32 v96, v90, v91
	v_cvt_pk_bf16_f32 v97, v92, v93
	v_cvt_pk_bf16_f32 v86, v86, v87
	v_cvt_pk_bf16_f32 v87, v88, v89
	v_cvt_pk_bf16_f32 v82, v82, v83
	v_cvt_pk_bf16_f32 v83, v84, v85
	v_lshl_add_u64 v[90:91], v[98:99], 0, v[138:139]
	v_mov_b32_dpp v88, v94 row_ror:8 row_mask:0xf bank_mask:0xf bound_ctrl:1
	v_mov_b32_dpp v89, v95 row_ror:8 row_mask:0xf bank_mask:0xf bound_ctrl:1
	v_mov_b32_dpp v84, v96 row_ror:8 row_mask:0xf bank_mask:0xf bound_ctrl:1
	v_mov_b32_dpp v85, v97 row_ror:8 row_mask:0xf bank_mask:0xf bound_ctrl:1
	v_mov_b32_dpp v98, v86 row_ror:8 row_mask:0xf bank_mask:0xf bound_ctrl:1
	v_mov_b32_dpp v99, v87 row_ror:8 row_mask:0xf bank_mask:0xf bound_ctrl:1
	v_mov_b32_dpp v100, v82 row_ror:8 row_mask:0xf bank_mask:0xf bound_ctrl:1
	v_mov_b32_dpp v101, v83 row_ror:8 row_mask:0xf bank_mask:0xf bound_ctrl:1
	v_max_f32_e32 v78, 0, v78
	v_max_f32_e32 v74, 0, v74
	v_max_f32_e32 v79, 0, v79
	v_max_f32_e32 v75, 0, v75
	v_max_f32_e32 v80, 0, v80
	v_max_f32_e32 v76, 0, v76
	v_max_f32_e32 v81, 0, v81
	v_max_f32_e32 v77, 0, v77
	v_max_f32_e32 v70, 0, v70
	v_max_f32_e32 v66, 0, v66
	v_max_f32_e32 v71, 0, v71
	v_max_f32_e32 v67, 0, v67
	v_max_f32_e32 v72, 0, v72
	v_max_f32_e32 v68, 0, v68
	v_max_f32_e32 v73, 0, v73
	v_max_f32_e32 v69, 0, v69
	v_lshl_add_u64 v[92:93], v[90:91], 0, v[140:141]
	v_cndmask_b32_e64 v85, v85, v83, s[8:9]
	v_cndmask_b32_e64 v84, v84, v82, s[8:9]
	v_cndmask_b32_e64 v83, v89, v87, s[8:9]
	v_cndmask_b32_e64 v82, v88, v86, s[8:9]
	v_cndmask_b32_e64 v89, v97, v101, s[8:9]
	v_cndmask_b32_e64 v88, v96, v100, s[8:9]
	v_cndmask_b32_e64 v87, v95, v99, s[8:9]
	v_cndmask_b32_e64 v86, v94, v98, s[8:9]
	v_pk_mul_f32 v[78:79], v[78:79], v[78:79]
	v_pk_mul_f32 v[74:75], v[74:75], v[74:75]
	v_pk_mul_f32 v[80:81], v[80:81], v[80:81]
	v_pk_mul_f32 v[76:77], v[76:77], v[76:77]
	v_pk_mul_f32 v[70:71], v[70:71], v[70:71]
	v_pk_mul_f32 v[66:67], v[66:67], v[66:67]
	v_pk_mul_f32 v[72:73], v[72:73], v[72:73]
	v_pk_mul_f32 v[68:69], v[68:69], v[68:69]
	v_lshl_add_u64 v[90:91], v[90:91], 0, v[142:143]
	global_store_dwordx4 v[92:93], v[86:89], off
	global_store_dwordx4 v[90:91], v[82:85], off
	v_cvt_pk_bf16_f32 v78, v78, v79
	v_cvt_pk_bf16_f32 v79, v80, v81
	v_lshl_add_u64 v[82:83], s[22:23], 0, v[150:151]
	v_cvt_pk_bf16_f32 v80, v74, v75
	v_cvt_pk_bf16_f32 v81, v76, v77
	v_cvt_pk_bf16_f32 v70, v70, v71
	v_cvt_pk_bf16_f32 v71, v72, v73
	v_cvt_pk_bf16_f32 v66, v66, v67
	v_cvt_pk_bf16_f32 v67, v68, v69
	v_lshl_add_u64 v[74:75], v[82:83], 0, v[138:139]
	v_mov_b32_dpp v72, v78 row_ror:8 row_mask:0xf bank_mask:0xf bound_ctrl:1
	v_mov_b32_dpp v73, v79 row_ror:8 row_mask:0xf bank_mask:0xf bound_ctrl:1
	v_mov_b32_dpp v68, v80 row_ror:8 row_mask:0xf bank_mask:0xf bound_ctrl:1
	v_mov_b32_dpp v69, v81 row_ror:8 row_mask:0xf bank_mask:0xf bound_ctrl:1
	v_mov_b32_dpp v82, v70 row_ror:8 row_mask:0xf bank_mask:0xf bound_ctrl:1
	v_mov_b32_dpp v83, v71 row_ror:8 row_mask:0xf bank_mask:0xf bound_ctrl:1
	v_mov_b32_dpp v84, v66 row_ror:8 row_mask:0xf bank_mask:0xf bound_ctrl:1
	v_mov_b32_dpp v85, v67 row_ror:8 row_mask:0xf bank_mask:0xf bound_ctrl:1
	v_max_f32_e32 v62, 0, v62
	v_max_f32_e32 v58, 0, v58
	v_max_f32_e32 v63, 0, v63
	v_max_f32_e32 v59, 0, v59
	v_max_f32_e32 v64, 0, v64
	v_max_f32_e32 v60, 0, v60
	v_max_f32_e32 v65, 0, v65
	v_max_f32_e32 v61, 0, v61
	v_max_f32_e32 v54, 0, v54
	v_max_f32_e32 v50, 0, v50
	v_max_f32_e32 v55, 0, v55
	v_max_f32_e32 v51, 0, v51
	v_max_f32_e32 v56, 0, v56
	v_max_f32_e32 v52, 0, v52
	v_max_f32_e32 v57, 0, v57
	v_max_f32_e32 v53, 0, v53
	v_lshl_add_u64 v[76:77], v[74:75], 0, v[140:141]
	v_cndmask_b32_e64 v69, v69, v67, s[8:9]
	v_cndmask_b32_e64 v68, v68, v66, s[8:9]
	v_cndmask_b32_e64 v67, v73, v71, s[8:9]
	v_cndmask_b32_e64 v66, v72, v70, s[8:9]
	v_cndmask_b32_e64 v73, v81, v85, s[8:9]
	v_cndmask_b32_e64 v72, v80, v84, s[8:9]
	v_cndmask_b32_e64 v71, v79, v83, s[8:9]
	v_cndmask_b32_e64 v70, v78, v82, s[8:9]
	v_pk_mul_f32 v[62:63], v[62:63], v[62:63]
	v_pk_mul_f32 v[58:59], v[58:59], v[58:59]
	v_pk_mul_f32 v[64:65], v[64:65], v[64:65]
	v_pk_mul_f32 v[60:61], v[60:61], v[60:61]
	v_pk_mul_f32 v[54:55], v[54:55], v[54:55]
	v_pk_mul_f32 v[50:51], v[50:51], v[50:51]
	v_pk_mul_f32 v[56:57], v[56:57], v[56:57]
	v_pk_mul_f32 v[52:53], v[52:53], v[52:53]
	v_lshl_add_u64 v[74:75], v[74:75], 0, v[142:143]
	global_store_dwordx4 v[76:77], v[70:73], off
	global_store_dwordx4 v[74:75], v[66:69], off
	v_cvt_pk_bf16_f32 v62, v62, v63
	v_cvt_pk_bf16_f32 v63, v64, v65
	v_lshl_add_u64 v[66:67], s[22:23], 0, v[152:153]
	v_cvt_pk_bf16_f32 v64, v58, v59
	v_cvt_pk_bf16_f32 v65, v60, v61
	v_cvt_pk_bf16_f32 v54, v54, v55
	v_cvt_pk_bf16_f32 v55, v56, v57
	v_cvt_pk_bf16_f32 v50, v50, v51
	v_cvt_pk_bf16_f32 v51, v52, v53
	v_lshl_add_u64 v[58:59], v[66:67], 0, v[138:139]
	v_mov_b32_dpp v56, v62 row_ror:8 row_mask:0xf bank_mask:0xf bound_ctrl:1
	v_mov_b32_dpp v57, v63 row_ror:8 row_mask:0xf bank_mask:0xf bound_ctrl:1
	v_mov_b32_dpp v52, v64 row_ror:8 row_mask:0xf bank_mask:0xf bound_ctrl:1
	v_mov_b32_dpp v53, v65 row_ror:8 row_mask:0xf bank_mask:0xf bound_ctrl:1
	v_mov_b32_dpp v66, v54 row_ror:8 row_mask:0xf bank_mask:0xf bound_ctrl:1
; __device__ __forceinline__ unsigned pk2(float lo, float hi) { const f32x2 v = {lo, hi}; return __builtin_bit_cast(unsigned, __builtin_convertvector(v, bf16x2_t)); }
; __device__ __forceinline__ u32x4 ror8(u32x4 v) { u32x4 r;
; #pragma unroll
;     for (int i = 0; i < 4; ++i) r[i] = (unsigned)__builtin_amdgcn_mov_dpp((int)v[i], 0x128, 0xf, 0xf, true);
;     return r; }
; __device__ __forceinline__ void store_pair(unsigned char* own, size_t stride8, int hi_off, u32x4 lo, u32x4 hi, bool upper) {
;     const u32x4 tlo = ror8(lo), thi = ror8(hi);
;     const u32x4 A = upper ? thi : lo, B = upper ? hi : tlo;
;     unsigned char* pa = upper ? own - stride8 + hi_off : own;
;     unsigned char* pb = upper ? own + hi_off : own + stride8;
;     *(u32x4*)pa = A; *(u32x4*)pb = B;
; }
;     __device__ __forceinline__ void operator()(const f32x4 (&acc)[2][2][4][2], const Unit& u, int wr, int wc, int fr, int fq) const {
; #pragma unroll
;         for (int ai = 0; ai < 2; ++ai)
; #pragma unroll
;             for (int m = 0; m < 4; ++m) { unsigned char* rowp = (unsigned char*)(H + ((size_t)(u.pm * (FF / 64) + u.pn * 4 + wc) * 256 + (wr * 64 + fr + ai * 128 + m * 16)) * 64 + 8 * fq); u32x4 w[2];
; #pragma unroll
;                 for (int bj = 0; bj < 2; ++bj) { f32x4 v0 = acc[ai][bj][m][0], v1 = acc[ai][bj][m][1];
; #pragma unroll
;                     for (int j = 0; j < 4; ++j) { const float a = fmaxf(v0[j], 0.f), b = fmaxf(v1[j], 0.f); v0[j] = a * a; v1[j] = b * b; }
;                     w[bj].x = pk2(v0[0], v0[1]); w[bj].y = pk2(v0[2], v0[3]); w[bj].z = pk2(v1[0], v1[1]); w[bj].w = pk2(v1[2], v1[3]); }
;                 store_pair(rowp, (size_t)8 * 64 * 2, 64, w[0], w[1], fr >= 8); }
	v_mov_b32_dpp v67, v55 row_ror:8 row_mask:0xf bank_mask:0xf bound_ctrl:1
	v_mov_b32_dpp v68, v50 row_ror:8 row_mask:0xf bank_mask:0xf bound_ctrl:1
	v_mov_b32_dpp v69, v51 row_ror:8 row_mask:0xf bank_mask:0xf bound_ctrl:1
	v_max_f32_e32 v46, 0, v46
	v_max_f32_e32 v42, 0, v42
	v_max_f32_e32 v47, 0, v47
	v_max_f32_e32 v43, 0, v43
	v_max_f32_e32 v48, 0, v48
	v_max_f32_e32 v44, 0, v44
	v_max_f32_e32 v49, 0, v49
	v_max_f32_e32 v45, 0, v45
	v_max_f32_e32 v38, 0, v38
	v_max_f32_e32 v34, 0, v34
	v_max_f32_e32 v39, 0, v39
	v_max_f32_e32 v35, 0, v35
	v_max_f32_e32 v40, 0, v40
	v_max_f32_e32 v36, 0, v36
	v_max_f32_e32 v41, 0, v41
	v_max_f32_e32 v37, 0, v37
	v_lshl_add_u64 v[60:61], v[58:59], 0, v[140:141]
	v_cndmask_b32_e64 v53, v53, v51, s[8:9]
	v_cndmask_b32_e64 v52, v52, v50, s[8:9]
	v_cndmask_b32_e64 v51, v57, v55, s[8:9]
	v_cndmask_b32_e64 v50, v56, v54, s[8:9]
	v_cndmask_b32_e64 v57, v65, v69, s[8:9]
	v_cndmask_b32_e64 v56, v64, v68, s[8:9]
	v_cndmask_b32_e64 v55, v63, v67, s[8:9]
	v_cndmask_b32_e64 v54, v62, v66, s[8:9]
	v_pk_mul_f32 v[46:47], v[46:47], v[46:47]
	v_pk_mul_f32 v[42:43], v[42:43], v[42:43]
	v_pk_mul_f32 v[48:49], v[48:49], v[48:49]
	v_pk_mul_f32 v[44:45], v[44:45], v[44:45]
	v_pk_mul_f32 v[38:39], v[38:39], v[38:39]
	v_pk_mul_f32 v[34:35], v[34:35], v[34:35]
	v_pk_mul_f32 v[40:41], v[40:41], v[40:41]
	v_pk_mul_f32 v[36:37], v[36:37], v[36:37]
	v_lshl_add_u64 v[58:59], v[58:59], 0, v[142:143]
	global_store_dwordx4 v[60:61], v[54:57], off
	global_store_dwordx4 v[58:59], v[50:53], off
	v_cvt_pk_bf16_f32 v46, v46, v47
	v_cvt_pk_bf16_f32 v47, v48, v49
	v_lshl_add_u64 v[50:51], s[22:23], 0, v[154:155]
	v_cvt_pk_bf16_f32 v48, v42, v43
	v_cvt_pk_bf16_f32 v49, v44, v45
	v_cvt_pk_bf16_f32 v38, v38, v39
	v_cvt_pk_bf16_f32 v39, v40, v41
	v_cvt_pk_bf16_f32 v34, v34, v35
	v_cvt_pk_bf16_f32 v35, v36, v37
	v_lshl_add_u64 v[42:43], v[50:51], 0, v[138:139]
	v_mov_b32_dpp v40, v46 row_ror:8 row_mask:0xf bank_mask:0xf bound_ctrl:1
	v_mov_b32_dpp v41, v47 row_ror:8 row_mask:0xf bank_mask:0xf bound_ctrl:1
	v_mov_b32_dpp v36, v48 row_ror:8 row_mask:0xf bank_mask:0xf bound_ctrl:1
	v_mov_b32_dpp v37, v49 row_ror:8 row_mask:0xf bank_mask:0xf bound_ctrl:1
	v_mov_b32_dpp v50, v38 row_ror:8 row_mask:0xf bank_mask:0xf bound_ctrl:1
	v_mov_b32_dpp v51, v39 row_ror:8 row_mask:0xf bank_mask:0xf bound_ctrl:1
	v_mov_b32_dpp v52, v34 row_ror:8 row_mask:0xf bank_mask:0xf bound_ctrl:1
	v_mov_b32_dpp v53, v35 row_ror:8 row_mask:0xf bank_mask:0xf bound_ctrl:1
	v_max_f32_e32 v30, 0, v30
	v_max_f32_e32 v26, 0, v26
	v_max_f32_e32 v31, 0, v31
	v_max_f32_e32 v27, 0, v27
	v_max_f32_e32 v32, 0, v32
	v_max_f32_e32 v28, 0, v28
	v_max_f32_e32 v33, 0, v33
	v_max_f32_e32 v29, 0, v29
	v_max_f32_e32 v22, 0, v22
	v_max_f32_e32 v18, 0, v18
	v_max_f32_e32 v23, 0, v23
	v_max_f32_e32 v19, 0, v19
	v_max_f32_e32 v24, 0, v24
	v_max_f32_e32 v20, 0, v20
	v_max_f32_e32 v25, 0, v25
	v_max_f32_e32 v21, 0, v21
	v_lshl_add_u64 v[44:45], v[42:43], 0, v[140:141]
	v_cndmask_b32_e64 v37, v37, v35, s[8:9]
	v_cndmask_b32_e64 v36, v36, v34, s[8:9]
	v_cndmask_b32_e64 v35, v41, v39, s[8:9]
	v_cndmask_b32_e64 v34, v40, v38, s[8:9]
	v_cndmask_b32_e64 v41, v49, v53, s[8:9]
	v_cndmask_b32_e64 v40, v48, v52, s[8:9]
	v_cndmask_b32_e64 v39, v47, v51, s[8:9]
	v_cndmask_b32_e64 v38, v46, v50, s[8:9]
	v_pk_mul_f32 v[30:31], v[30:31], v[30:31]
	v_pk_mul_f32 v[26:27], v[26:27], v[26:27]
	v_pk_mul_f32 v[32:33], v[32:33], v[32:33]
	v_pk_mul_f32 v[28:29], v[28:29], v[28:29]
	v_pk_mul_f32 v[22:23], v[22:23], v[22:23]
	v_pk_mul_f32 v[18:19], v[18:19], v[18:19]
	v_pk_mul_f32 v[24:25], v[24:25], v[24:25]
	v_pk_mul_f32 v[20:21], v[20:21], v[20:21]
	v_lshl_add_u64 v[42:43], v[42:43], 0, v[142:143]
	global_store_dwordx4 v[44:45], v[38:41], off
	global_store_dwordx4 v[42:43], v[34:37], off
	v_cvt_pk_bf16_f32 v30, v30, v31
; __device__ __forceinline__ unsigned pk2(float lo, float hi) { const f32x2 v = {lo, hi}; return __builtin_bit_cast(unsigned, __builtin_convertvector(v, bf16x2_t)); }
; #define PG8_BAR __builtin_amdgcn_s_barrier()
; template <class Epi, class Sched, bool ABLK = false, bool ALIGN_EPI = true, bool SP2 = true, bool BBLK = true>
; __device__ __forceinline__ void gemm_phase(LAS unsigned char* lds, const Gemm g, const Sched& S, const Epi& E) {
;     ...
;         if (!has_next) break;
; #pragma unroll
;         for (int a = 0; a < 2; ++a)
; #pragma unroll
;             for (int b = 0; b < 2; ++b)
; #pragma unroll
;                 for (int m = 0; m < 4; ++m)
; #pragma unroll
;                     for (int n = 0; n < 2; ++n) acc[a][b][m][n] = (f32x4){0.f, 0.f, 0.f, 0.f};
;         cur = nxt; uA = nuA; tbA = ntbA; cB = nB; ++ui;
;         if constexpr (ALIGN_EPI) { if (wr == 1) PG8_BAR; }
;     __device__ __forceinline__ void operator()(const f32x4 (&acc)[2][2][4][2], const Unit& u, int wr, int wc, int fr, int fq) const {
; #pragma unroll
;         for (int ai = 0; ai < 2; ++ai)
; #pragma unroll
;             for (int m = 0; m < 4; ++m) { unsigned char* rowp = (unsigned char*)(H + ((size_t)(u.pm * (FF / 64) + u.pn * 4 + wc) * 256 + (wr * 64 + fr + ai * 128 + m * 16)) * 64 + 8 * fq); u32x4 w[2];
; #pragma unroll
;                 for (int bj = 0; bj < 2; ++bj) { f32x4 v0 = acc[ai][bj][m][0], v1 = acc[ai][bj][m][1];
; #pragma unroll
;                     for (int j = 0; j < 4; ++j) { const float a = fmaxf(v0[j], 0.f), b = fmaxf(v1[j], 0.f); v0[j] = a * a; v1[j] = b * b; }
;                     w[bj].x = pk2(v0[0], v0[1]); w[bj].y = pk2(v0[2], v0[3]); w[bj].z = pk2(v1[0], v1[1]); w[bj].w = pk2(v1[2], v1[3]); }
;                 store_pair(rowp, (size_t)8 * 64 * 2, 64, w[0], w[1], fr >= 8); }
	v_cvt_pk_bf16_f32 v31, v32, v33
	v_lshl_add_u64 v[34:35], s[22:23], 0, v[156:157]
	v_cvt_pk_bf16_f32 v32, v26, v27
	v_cvt_pk_bf16_f32 v33, v28, v29
	v_cvt_pk_bf16_f32 v22, v22, v23
	v_cvt_pk_bf16_f32 v23, v24, v25
	v_cvt_pk_bf16_f32 v18, v18, v19
	v_cvt_pk_bf16_f32 v19, v20, v21
	v_lshl_add_u64 v[26:27], v[34:35], 0, v[138:139]
	v_mov_b32_dpp v24, v30 row_ror:8 row_mask:0xf bank_mask:0xf bound_ctrl:1
	v_mov_b32_dpp v25, v31 row_ror:8 row_mask:0xf bank_mask:0xf bound_ctrl:1
	v_mov_b32_dpp v20, v32 row_ror:8 row_mask:0xf bank_mask:0xf bound_ctrl:1
	v_mov_b32_dpp v21, v33 row_ror:8 row_mask:0xf bank_mask:0xf bound_ctrl:1
	v_mov_b32_dpp v34, v22 row_ror:8 row_mask:0xf bank_mask:0xf bound_ctrl:1
	v_mov_b32_dpp v35, v23 row_ror:8 row_mask:0xf bank_mask:0xf bound_ctrl:1
	v_mov_b32_dpp v36, v18 row_ror:8 row_mask:0xf bank_mask:0xf bound_ctrl:1
	v_mov_b32_dpp v37, v19 row_ror:8 row_mask:0xf bank_mask:0xf bound_ctrl:1
	v_max_f32_e32 v14, 0, v14
	v_max_f32_e32 v10, 0, v10
	v_max_f32_e32 v15, 0, v15
	v_max_f32_e32 v11, 0, v11
	v_max_f32_e32 v16, 0, v16
	v_max_f32_e32 v12, 0, v12
	v_max_f32_e32 v17, 0, v17
	v_max_f32_e32 v13, 0, v13
	v_max_f32_e32 v6, 0, v6
	v_max_f32_e32 v2, 0, v2
	v_max_f32_e32 v7, 0, v7
	v_max_f32_e32 v3, 0, v3
	v_max_f32_e32 v8, 0, v8
	v_max_f32_e32 v4, 0, v4
	v_max_f32_e32 v9, 0, v9
	v_max_f32_e32 v5, 0, v5
	v_lshl_add_u64 v[28:29], v[26:27], 0, v[140:141]
	v_cndmask_b32_e64 v21, v21, v19, s[8:9]
	v_cndmask_b32_e64 v20, v20, v18, s[8:9]
	v_cndmask_b32_e64 v19, v25, v23, s[8:9]
	v_cndmask_b32_e64 v18, v24, v22, s[8:9]
	v_cndmask_b32_e64 v25, v33, v37, s[8:9]
	v_cndmask_b32_e64 v24, v32, v36, s[8:9]
	v_cndmask_b32_e64 v23, v31, v35, s[8:9]
	v_cndmask_b32_e64 v22, v30, v34, s[8:9]
	v_pk_mul_f32 v[14:15], v[14:15], v[14:15]
	v_pk_mul_f32 v[10:11], v[10:11], v[10:11]
	v_pk_mul_f32 v[16:17], v[16:17], v[16:17]
	v_pk_mul_f32 v[12:13], v[12:13], v[12:13]
	v_pk_mul_f32 v[6:7], v[6:7], v[6:7]
	v_pk_mul_f32 v[2:3], v[2:3], v[2:3]
	v_pk_mul_f32 v[8:9], v[8:9], v[8:9]
	v_pk_mul_f32 v[4:5], v[4:5], v[4:5]
	v_lshl_add_u64 v[26:27], v[26:27], 0, v[142:143]
	global_store_dwordx4 v[28:29], v[22:25], off
	global_store_dwordx4 v[26:27], v[18:21], off
	v_cvt_pk_bf16_f32 v14, v14, v15
	v_cvt_pk_bf16_f32 v15, v16, v17
	v_lshl_add_u64 v[18:19], s[22:23], 0, v[158:159]
	v_cvt_pk_bf16_f32 v16, v10, v11
	v_cvt_pk_bf16_f32 v17, v12, v13
	v_cvt_pk_bf16_f32 v6, v6, v7
	v_cvt_pk_bf16_f32 v7, v8, v9
	v_cvt_pk_bf16_f32 v2, v2, v3
	v_cvt_pk_bf16_f32 v3, v4, v5
	v_lshl_add_u64 v[10:11], v[18:19], 0, v[138:139]
	v_mov_b32_dpp v8, v14 row_ror:8 row_mask:0xf bank_mask:0xf bound_ctrl:1
	v_mov_b32_dpp v9, v15 row_ror:8 row_mask:0xf bank_mask:0xf bound_ctrl:1
	v_mov_b32_dpp v4, v16 row_ror:8 row_mask:0xf bank_mask:0xf bound_ctrl:1
	v_mov_b32_dpp v5, v17 row_ror:8 row_mask:0xf bank_mask:0xf bound_ctrl:1
	v_mov_b32_dpp v18, v6 row_ror:8 row_mask:0xf bank_mask:0xf bound_ctrl:1
	v_mov_b32_dpp v19, v7 row_ror:8 row_mask:0xf bank_mask:0xf bound_ctrl:1
	v_mov_b32_dpp v20, v2 row_ror:8 row_mask:0xf bank_mask:0xf bound_ctrl:1
	v_mov_b32_dpp v21, v3 row_ror:8 row_mask:0xf bank_mask:0xf bound_ctrl:1
	v_lshl_add_u64 v[12:13], v[10:11], 0, v[140:141]
	v_cndmask_b32_e64 v5, v5, v3, s[8:9]
	v_cndmask_b32_e64 v4, v4, v2, s[8:9]
	v_cndmask_b32_e64 v3, v9, v7, s[8:9]
	v_cndmask_b32_e64 v2, v8, v6, s[8:9]
	v_cndmask_b32_e64 v9, v17, v21, s[8:9]
	v_cndmask_b32_e64 v8, v16, v20, s[8:9]
	v_cndmask_b32_e64 v7, v15, v19, s[8:9]
	v_cndmask_b32_e64 v6, v14, v18, s[8:9]
	s_andn2_b64 vcc, exec, s[18:19]
	s_mov_b64 s[4:5], -1
	v_lshl_add_u64 v[10:11], v[10:11], 0, v[142:143]
	global_store_dwordx4 v[12:13], v[6:9], off
	global_store_dwordx4 v[10:11], v[2:5], off
	s_cbranch_vccnz .LBB0_1160
	s_andn2_b64 vcc, exec, s[2:3]
	s_cbranch_vccnz .LBB0_1159
	s_barrier
	s_branch .LBB0_1159

; #define PG8_STAGE(bufoff, gbase, voff) do { _Pragma("unroll") for (int _i = 0; _i < 2; ++_i) \
;         __builtin_amdgcn_global_load_lds((const unsigned*)((const char*)(gbase) + (voff)[_i]), (LAS unsigned*)(lds + (bufoff) + ldsw + _i * 8192), 16, 0, 0); } while (0)
; #define PG8_LDA(dst, b, h) do { _Pragma("unroll") for (int m = 0; m < 4; ++m) _Pragma("unroll") for (int k = 0; k < 2; ++k) dst[m][k] = *(const LAS bf16x8*)(lds + PG8_SA(b, h) + aoff + m * 2048 + k * 1024); } while (0)
; #define PG8_LDB(dst, b, h) do { _Pragma("unroll") for (int n = 0; n < 2; ++n) _Pragma("unroll") for (int k = 0; k < 2; ++k) dst[n][k] = *(const LAS bf16x8*)(lds + PG8_SB(b, h) + boff + n * 2048 + k * 1024); } while (0)
; #define PG8_WAIT_V(n) asm volatile("s_waitcnt vmcnt(" #n ")" ::: "memory")
; #define PG8_WAIT_L(n) asm volatile("s_waitcnt lgkmcnt(" #n ")" ::: "memory")
; #define PG8_BAR __builtin_amdgcn_s_barrier()
; template <class Epi, class Sched, bool ABLK = false, bool ALIGN_EPI = true, bool SP2 = true, bool BBLK = true>
; __device__ __forceinline__ void gemm_phase(LAS unsigned char* lds, const Gemm g, const Sched& S, const Epi& E) {
;     ...
;         const char* nuA = has_next ? a_unit(nxt) : uA; const int ntbA = has_next ? nxt.k0 / BK : tbA; const char* nB = has_next ? (const char*)g.Bt + (size_t)nxt.pn * tstepB + b_k0(nxt.k0) : cB;
;         for (int t = 0; t < nt; t += 2) {
;             const bool last = (t == nt - 2);
;             const char* a1 = a_tile(uA, tbA + t + 1);
;             const char* a2 = last ? a_tile(nuA, ntbA) : a_tile(uA, tbA + t + 2); const char* b2 = last ? nB : cB + (size_t)(t + 2) * kstepB;
;             const char* a3 = last ? a_tile(nuA, ntbA + 1) : a_tile(uA, tbA + t + 3); const char* b3 = b2 + kstepB;
;             if (last && has_next) S.a_ready(nxt);
;             if constexpr (SP2) {
;             PG8_LDB(B0, 0, 0); PG8_LDB(B1, 0, 1); PG8_SCHED; PG8_LDA(At, 0, 0); PG8_STAGE(PG8_SA(1, 1), a1 + hstepA, voffA);
;             PG8_WAIT_V(8); PG8_WAIT_L(0); PG8_BAR; PG8_MMA(0, 0, At, B0); PG8_MMA(0, 1, At, B1); PG8_BAR; PG8_SCHED;
;             PG8_LDA(At, 0, 1); PG8_STAGE(PG8_SB(0, 0), b2, voffB); PG8_STAGE(PG8_SB(0, 1), b2 + hstepB, voffB); PG8_STAGE(PG8_SA(0, 0), a2, voffA);
;             PG8_WAIT_V(8); PG8_WAIT_L(0); PG8_BAR; PG8_MMA(1, 0, At, B0); PG8_MMA(1, 1, At, B1); PG8_BAR; PG8_SCHED;
.LBB0_1229:
	ds_read_b128 v[152:155], v149
	ds_read_b128 v[156:159], v149 offset:1024
	ds_read_b128 v[160:163], v149 offset:2048
	ds_read_b128 v[164:167], v149 offset:3072
	ds_read_b128 v[168:171], v150
	ds_read_b128 v[172:175], v150 offset:1024
	ds_read_b128 v[176:179], v150 offset:2048
	ds_read_b128 v[180:183], v150 offset:3072
	s_add_u32 s24, s51, s22
	s_addc_u32 s25, s55, s23
	s_add_u32 s28, s24, 0x10000
	s_addc_u32 s29, s25, 0
	s_add_i32 s57, s57, 2
	s_add_u32 s26, s49, s22
	s_addc_u32 s27, s50, s23
	s_add_u32 s24, s24, 0x18000
	s_addc_u32 s25, s25, 0
	s_cmp_eq_u32 s56, s22
	s_cselect_b32 s25, s48, s25
	s_cselect_b32 s24, s47, s24
	s_cselect_b32 s27, s4, s27
	s_cselect_b32 s26, s5, s26
	s_cselect_b32 s29, s46, s29
	s_cselect_b32 s28, s19, s28
	v_lshl_add_u64 v[216:217], v[142:143], 0, s[22:23]
	s_add_i32 m0, s35, 0xc000
	ds_read_b128 v[184:187], v151
	ds_read_b128 v[188:191], v151 offset:1024
	ds_read_b128 v[192:195], v151 offset:2048
	ds_read_b128 v[196:199], v151 offset:3072
	ds_read_b128 v[200:203], v151 offset:4096
	ds_read_b128 v[204:207], v151 offset:5120
	ds_read_b128 v[208:211], v151 offset:6144
	ds_read_b128 v[212:215], v151 offset:7168
	global_load_lds_dwordx4 v[216:217], off
	v_lshl_add_u64 v[216:217], v[144:145], 0, s[22:23]
	s_add_i32 m0, s35, 0xe000
	s_nop 0
	global_load_lds_dwordx4 v[216:217], off
	s_waitcnt vmcnt(8) lgkmcnt(0)
	s_barrier
	v_mfma_f32_16x16x32_bf16 v[126:129], v[152:155], v[184:187], v[126:129]
	v_mfma_f32_16x16x32_bf16 v[122:125], v[160:163], v[184:187], v[122:125]
	v_mfma_f32_16x16x32_bf16 v[110:113], v[152:155], v[192:195], v[110:113]
	v_mfma_f32_16x16x32_bf16 v[106:109], v[160:163], v[192:195], v[106:109]
	v_mfma_f32_16x16x32_bf16 v[94:97], v[152:155], v[200:203], v[94:97]
	v_mfma_f32_16x16x32_bf16 v[90:93], v[160:163], v[200:203], v[90:93]
	v_mfma_f32_16x16x32_bf16 v[78:81], v[152:155], v[208:211], v[78:81]
	v_mfma_f32_16x16x32_bf16 v[74:77], v[160:163], v[208:211], v[74:77]
	v_mfma_f32_16x16x32_bf16 v[126:129], v[156:159], v[188:191], v[126:129]
	v_mfma_f32_16x16x32_bf16 v[122:125], v[164:167], v[188:191], v[122:125]
	v_mfma_f32_16x16x32_bf16 v[110:113], v[156:159], v[196:199], v[110:113]
	v_mfma_f32_16x16x32_bf16 v[106:109], v[164:167], v[196:199], v[106:109]
	v_mfma_f32_16x16x32_bf16 v[94:97], v[156:159], v[204:207], v[94:97]
	v_mfma_f32_16x16x32_bf16 v[90:93], v[164:167], v[204:207], v[90:93]
	v_mfma_f32_16x16x32_bf16 v[78:81], v[156:159], v[212:215], v[78:81]
	v_mfma_f32_16x16x32_bf16 v[74:77], v[164:167], v[212:215], v[74:77]
	v_mfma_f32_16x16x32_bf16 v[118:121], v[168:171], v[184:187], v[118:121]
	v_mfma_f32_16x16x32_bf16 v[114:117], v[176:179], v[184:187], v[114:117]
	v_mfma_f32_16x16x32_bf16 v[102:105], v[168:171], v[192:195], v[102:105]
	v_mfma_f32_16x16x32_bf16 v[98:101], v[176:179], v[192:195], v[98:101]
	v_mfma_f32_16x16x32_bf16 v[86:89], v[168:171], v[200:203], v[86:89]
	v_mfma_f32_16x16x32_bf16 v[82:85], v[176:179], v[200:203], v[82:85]
	v_mfma_f32_16x16x32_bf16 v[70:73], v[168:171], v[208:211], v[70:73]
	v_mfma_f32_16x16x32_bf16 v[66:69], v[176:179], v[208:211], v[66:69]
	v_mfma_f32_16x16x32_bf16 v[118:121], v[172:175], v[188:191], v[118:121]
	v_mfma_f32_16x16x32_bf16 v[114:117], v[180:183], v[188:191], v[114:117]
	v_mfma_f32_16x16x32_bf16 v[102:105], v[172:175], v[196:199], v[102:105]
	v_mfma_f32_16x16x32_bf16 v[98:101], v[180:183], v[196:199], v[98:101]
	v_mfma_f32_16x16x32_bf16 v[86:89], v[172:175], v[204:207], v[86:89]
	v_mfma_f32_16x16x32_bf16 v[82:85], v[180:183], v[204:207], v[82:85]
	v_mfma_f32_16x16x32_bf16 v[70:73], v[172:175], v[212:215], v[70:73]
	v_mfma_f32_16x16x32_bf16 v[66:69], v[180:183], v[212:215], v[66:69]
	s_barrier
	s_add_i32 s59, s72, s34
	s_mov_b32 m0, s59
	ds_read_b128 v[184:187], v151 offset:16384
	ds_read_b128 v[188:191], v151 offset:17408
	ds_read_b128 v[192:195], v151 offset:18432
	ds_read_b128 v[196:199], v151 offset:19456
	ds_read_b128 v[200:203], v151 offset:20480
	ds_read_b128 v[204:207], v151 offset:21504
	ds_read_b128 v[208:211], v151 offset:22528
	ds_read_b128 v[212:215], v151 offset:23552
	global_load_lds_dwordx4 v130, s[26:27]
	s_add_i32 m0, s59, 0x2000
	s_add_u32 s64, s26, 0x4000
	s_addc_u32 s65, s27, 0
	s_add_i32 s59, s73, s34
	global_load_lds_dwordx4 v132, s[26:27]
	s_mov_b32 m0, s59
	s_nop 0
	global_load_lds_dwordx4 v130, s[64:65]
	s_add_i32 m0, s59, 0x2000
	s_nop 0
	global_load_lds_dwordx4 v132, s[64:65]
	s_mov_b32 m0, s35
	s_nop 0
	global_load_lds_dwordx4 v130, s[28:29]
	s_mov_b32 m0, s36
	s_nop 0
	global_load_lds_dwordx4 v132, s[28:29]
	s_waitcnt vmcnt(8) lgkmcnt(0)
	s_barrier
; #define PG8_STAGE(bufoff, gbase, voff) do { _Pragma("unroll") for (int _i = 0; _i < 2; ++_i) \
;         __builtin_amdgcn_global_load_lds((const unsigned*)((const char*)(gbase) + (voff)[_i]), (LAS unsigned*)(lds + (bufoff) + ldsw + _i * 8192), 16, 0, 0); } while (0)
; #define PG8_LDA(dst, b, h) do { _Pragma("unroll") for (int m = 0; m < 4; ++m) _Pragma("unroll") for (int k = 0; k < 2; ++k) dst[m][k] = *(const LAS bf16x8*)(lds + PG8_SA(b, h) + aoff + m * 2048 + k * 1024); } while (0)
; #define PG8_LDB(dst, b, h) do { _Pragma("unroll") for (int n = 0; n < 2; ++n) _Pragma("unroll") for (int k = 0; k < 2; ++k) dst[n][k] = *(const LAS bf16x8*)(lds + PG8_SB(b, h) + boff + n * 2048 + k * 1024); } while (0)
; #define PG8_MMA(ai, bj, At, Bt) do { __builtin_amdgcn_s_setprio(1); _Pragma("unroll") for (int m = 0; m < 4; ++m) _Pragma("unroll") for (int n = 0; n < 2; ++n) _Pragma("unroll") for (int k = 0; k < 2; ++k) \
;         acc[ai][bj][m][n] = __builtin_amdgcn_mfma_f32_16x16x32_bf16(Bt[n][k], At[m][k], acc[ai][bj][m][n], 0, 0, 0); __builtin_amdgcn_s_setprio(0); } while (0)
; #define PG8_BAR __builtin_amdgcn_s_barrier()
; template <class Epi, class Sched, bool ABLK = false, bool ALIGN_EPI = true, bool SP2 = true, bool BBLK = true>
; __device__ __forceinline__ void gemm_phase(LAS unsigned char* lds, const Gemm g, const Sched& S, const Epi& E) {
;     ...
;             PG8_LDB(B0, 0, 0); PG8_LDB(B1, 0, 1); PG8_SCHED; PG8_LDA(At, 0, 0); PG8_STAGE(PG8_SA(1, 1), a1 + hstepA, voffA);
;             PG8_WAIT_V(8); PG8_WAIT_L(0); PG8_BAR; PG8_MMA(0, 0, At, B0); PG8_MMA(0, 1, At, B1); PG8_BAR; PG8_SCHED;
;             PG8_LDA(At, 0, 1); PG8_STAGE(PG8_SB(0, 0), b2, voffB); PG8_STAGE(PG8_SB(0, 1), b2 + hstepB, voffB); PG8_STAGE(PG8_SA(0, 0), a2, voffA);
;             PG8_WAIT_V(8); PG8_WAIT_L(0); PG8_BAR; PG8_MMA(1, 0, At, B0); PG8_MMA(1, 1, At, B1); PG8_BAR; PG8_SCHED;
;             PG8_LDB(B0, 1, 0); PG8_LDB(B1, 1, 1); PG8_SCHED; PG8_LDA(At, 1, 0); PG8_STAGE(PG8_SA(0, 1), a2 + hstepA, voffA);
;             PG8_WAIT_V(8); PG8_WAIT_L(0); PG8_BAR; PG8_MMA(0, 0, At, B0); PG8_MMA(0, 1, At, B1); PG8_BAR; PG8_SCHED;
;             PG8_LDA(At, 1, 1); PG8_STAGE(PG8_SB(1, 0), b3, voffB); PG8_STAGE(PG8_SB(1, 1), b3 + hstepB, voffB); PG8_STAGE(PG8_SA(1, 0), a3, voffA);
;             PG8_WAIT_V(8); PG8_WAIT_L(0); PG8_BAR; PG8_MMA(1, 0, At, B0); PG8_MMA(1, 1, At, B1); PG8_BAR; PG8_SCHED;
	v_mfma_f32_16x16x32_bf16 v[62:65], v[152:155], v[184:187], v[62:65]
	v_mfma_f32_16x16x32_bf16 v[58:61], v[160:163], v[184:187], v[58:61]
	v_mfma_f32_16x16x32_bf16 v[46:49], v[152:155], v[192:195], v[46:49]
	v_mfma_f32_16x16x32_bf16 v[42:45], v[160:163], v[192:195], v[42:45]
	v_mfma_f32_16x16x32_bf16 v[30:33], v[152:155], v[200:203], v[30:33]
	v_mfma_f32_16x16x32_bf16 v[26:29], v[160:163], v[200:203], v[26:29]
	v_mfma_f32_16x16x32_bf16 v[14:17], v[152:155], v[208:211], v[14:17]
	v_mfma_f32_16x16x32_bf16 v[10:13], v[160:163], v[208:211], v[10:13]
	v_mfma_f32_16x16x32_bf16 v[62:65], v[156:159], v[188:191], v[62:65]
	v_mfma_f32_16x16x32_bf16 v[58:61], v[164:167], v[188:191], v[58:61]
	v_mfma_f32_16x16x32_bf16 v[46:49], v[156:159], v[196:199], v[46:49]
	v_mfma_f32_16x16x32_bf16 v[42:45], v[164:167], v[196:199], v[42:45]
	v_mfma_f32_16x16x32_bf16 v[30:33], v[156:159], v[204:207], v[30:33]
	v_mfma_f32_16x16x32_bf16 v[26:29], v[164:167], v[204:207], v[26:29]
	v_mfma_f32_16x16x32_bf16 v[14:17], v[156:159], v[212:215], v[14:17]
	v_mfma_f32_16x16x32_bf16 v[10:13], v[164:167], v[212:215], v[10:13]
	v_mfma_f32_16x16x32_bf16 v[54:57], v[168:171], v[184:187], v[54:57]
	v_mfma_f32_16x16x32_bf16 v[50:53], v[176:179], v[184:187], v[50:53]
	v_mfma_f32_16x16x32_bf16 v[38:41], v[168:171], v[192:195], v[38:41]
	v_mfma_f32_16x16x32_bf16 v[34:37], v[176:179], v[192:195], v[34:37]
	v_mfma_f32_16x16x32_bf16 v[22:25], v[168:171], v[200:203], v[22:25]
	v_mfma_f32_16x16x32_bf16 v[18:21], v[176:179], v[200:203], v[18:21]
	v_mfma_f32_16x16x32_bf16 v[6:9], v[168:171], v[208:211], v[6:9]
	v_mfma_f32_16x16x32_bf16 v[2:5], v[176:179], v[208:211], v[2:5]
	v_mfma_f32_16x16x32_bf16 v[54:57], v[172:175], v[188:191], v[54:57]
	v_mfma_f32_16x16x32_bf16 v[50:53], v[180:183], v[188:191], v[50:53]
	v_mfma_f32_16x16x32_bf16 v[38:41], v[172:175], v[196:199], v[38:41]
	v_mfma_f32_16x16x32_bf16 v[34:37], v[180:183], v[196:199], v[34:37]
	v_mfma_f32_16x16x32_bf16 v[22:25], v[172:175], v[204:207], v[22:25]
	v_mfma_f32_16x16x32_bf16 v[18:21], v[180:183], v[204:207], v[18:21]
	v_mfma_f32_16x16x32_bf16 v[6:9], v[172:175], v[212:215], v[6:9]
	v_mfma_f32_16x16x32_bf16 v[2:5], v[180:183], v[212:215], v[2:5]
	s_barrier
	v_add_u32_e32 v164, s60, v147
	v_add_u32_e32 v180, s61, v147
	ds_read_b128 v[152:155], v164
	ds_read_b128 v[156:159], v164 offset:1024
	ds_read_b128 v[160:163], v164 offset:2048
	ds_read_b128 v[164:167], v164 offset:3072
	ds_read_b128 v[168:171], v180
	ds_read_b128 v[172:175], v180 offset:1024
	ds_read_b128 v[176:179], v180 offset:2048
	ds_read_b128 v[180:183], v180 offset:3072
	s_add_u32 s28, s28, 0x4000
	s_addc_u32 s29, s29, 0
	s_mov_b32 m0, s37
	ds_read_b128 v[184:187], v151 offset:32768
	ds_read_b128 v[188:191], v151 offset:33792
	ds_read_b128 v[192:195], v151 offset:34816
	ds_read_b128 v[196:199], v151 offset:35840
	ds_read_b128 v[200:203], v151 offset:36864
	ds_read_b128 v[204:207], v151 offset:37888
	ds_read_b128 v[208:211], v151 offset:38912
	ds_read_b128 v[212:215], v151 offset:39936
	global_load_lds_dwordx4 v130, s[28:29]
	s_mov_b32 m0, s40
	s_nop 0
	global_load_lds_dwordx4 v132, s[28:29]
	s_waitcnt vmcnt(8) lgkmcnt(0)
	s_barrier
	v_mfma_f32_16x16x32_bf16 v[126:129], v[152:155], v[184:187], v[126:129]
	v_mfma_f32_16x16x32_bf16 v[122:125], v[160:163], v[184:187], v[122:125]
	v_mfma_f32_16x16x32_bf16 v[110:113], v[152:155], v[192:195], v[110:113]
	v_mfma_f32_16x16x32_bf16 v[106:109], v[160:163], v[192:195], v[106:109]
	v_mfma_f32_16x16x32_bf16 v[94:97], v[152:155], v[200:203], v[94:97]
	v_mfma_f32_16x16x32_bf16 v[90:93], v[160:163], v[200:203], v[90:93]
	v_mfma_f32_16x16x32_bf16 v[78:81], v[152:155], v[208:211], v[78:81]
	v_mfma_f32_16x16x32_bf16 v[74:77], v[160:163], v[208:211], v[74:77]
	v_mfma_f32_16x16x32_bf16 v[126:129], v[156:159], v[188:191], v[126:129]
	v_mfma_f32_16x16x32_bf16 v[122:125], v[164:167], v[188:191], v[122:125]
	v_mfma_f32_16x16x32_bf16 v[110:113], v[156:159], v[196:199], v[110:113]
	v_mfma_f32_16x16x32_bf16 v[106:109], v[164:167], v[196:199], v[106:109]
	v_mfma_f32_16x16x32_bf16 v[94:97], v[156:159], v[204:207], v[94:97]
	v_mfma_f32_16x16x32_bf16 v[90:93], v[164:167], v[204:207], v[90:93]
	v_mfma_f32_16x16x32_bf16 v[78:81], v[156:159], v[212:215], v[78:81]
	v_mfma_f32_16x16x32_bf16 v[74:77], v[164:167], v[212:215], v[74:77]
	v_mfma_f32_16x16x32_bf16 v[118:121], v[168:171], v[184:187], v[118:121]
	v_mfma_f32_16x16x32_bf16 v[114:117], v[176:179], v[184:187], v[114:117]
	v_mfma_f32_16x16x32_bf16 v[102:105], v[168:171], v[192:195], v[102:105]
	v_mfma_f32_16x16x32_bf16 v[98:101], v[176:179], v[192:195], v[98:101]
	v_mfma_f32_16x16x32_bf16 v[86:89], v[168:171], v[200:203], v[86:89]
	v_mfma_f32_16x16x32_bf16 v[82:85], v[176:179], v[200:203], v[82:85]
	v_mfma_f32_16x16x32_bf16 v[70:73], v[168:171], v[208:211], v[70:73]
	v_mfma_f32_16x16x32_bf16 v[66:69], v[176:179], v[208:211], v[66:69]
	v_mfma_f32_16x16x32_bf16 v[118:121], v[172:175], v[188:191], v[118:121]
	v_mfma_f32_16x16x32_bf16 v[114:117], v[180:183], v[188:191], v[114:117]
	v_mfma_f32_16x16x32_bf16 v[102:105], v[172:175], v[196:199], v[102:105]
	v_mfma_f32_16x16x32_bf16 v[98:101], v[180:183], v[196:199], v[98:101]
	v_mfma_f32_16x16x32_bf16 v[86:89], v[172:175], v[204:207], v[86:89]
	v_mfma_f32_16x16x32_bf16 v[82:85], v[180:183], v[204:207], v[82:85]
	v_mfma_f32_16x16x32_bf16 v[70:73], v[172:175], v[212:215], v[70:73]
	v_mfma_f32_16x16x32_bf16 v[66:69], v[180:183], v[212:215], v[66:69]
	s_barrier
; __device__ __forceinline__ unsigned pk2(float lo, float hi) { const f32x2 v = {lo, hi}; return __builtin_bit_cast(unsigned, __builtin_convertvector(v, bf16x2_t)); }
; __device__ __forceinline__ void store_pair(unsigned char* own, size_t stride8, int hi_off, u32x4 lo, u32x4 hi, bool upper) {
;     const u32x4 tlo = ror8(lo), thi = ror8(hi);
;     const u32x4 A = upper ? thi : lo, B = upper ? hi : tlo;
;     unsigned char* pa = upper ? own - stride8 + hi_off : own;
;     unsigned char* pb = upper ? own + hi_off : own + stride8;
;     *(u32x4*)pa = A; *(u32x4*)pb = B;
; }
;     __device__ __forceinline__ void operator()(const f32x4 (&acc)[2][2][4][2], const Unit& u, int wr, int wc, int fr, int fq) const {
;         const int row0 = u.pm * 256 + wr * 64 + fr, col0 = u.pn * 256 + wc * 64 + 8 * fq;
;         bf16_t* base = u.part == 0 ? Z + (size_t)row0 * D + col0 : P + ((size_t)(u.part - 1) * MS + (row0 - MP)) * D + col0;
; #pragma unroll
;         for (int ai = 0; ai < 2; ++ai)
; #pragma unroll
;             for (int m = 0; m < 4; ++m) { u32x4 w[2];
; #pragma unroll
;                 for (int bj = 0; bj < 2; ++bj) { const f32x4 v0 = acc[ai][bj][m][0], v1 = acc[ai][bj][m][1]; w[bj].x = pk2(v0[0], v0[1]); w[bj].y = pk2(v0[2], v0[3]); w[bj].z = pk2(v1[0], v1[1]); w[bj].w = pk2(v1[2], v1[3]); }
;                 store_pair((unsigned char*)(base + (size_t)(ai * 128 + m * 16) * D), (size_t)8 * D * 2, 64, w[0], w[1], fr >= 8); }
	s_add_u32 s28, s26, 0x8000
	s_addc_u32 s29, s27, 0
	s_add_i32 s59, s60, s34
	s_mov_b32 m0, s59
	ds_read_b128 v[184:187], v151 offset:49152
	ds_read_b128 v[188:191], v151 offset:50176
	ds_read_b128 v[192:195], v151 offset:51200
	ds_read_b128 v[196:199], v151 offset:52224
	ds_read_b128 v[200:203], v151 offset:53248
	ds_read_b128 v[204:207], v151 offset:54272
	ds_read_b128 v[208:211], v151 offset:55296
	ds_read_b128 v[212:215], v151 offset:56320
	global_load_lds_dwordx4 v130, s[28:29]
	s_add_i32 m0, s59, 0x2000
	s_add_u32 s26, s26, 0xc000
	v_lshl_add_u64 v[216:217], s[28:29], 0, v[132:133]
	s_addc_u32 s27, s27, 0
	s_add_i32 s28, s61, s34
	global_load_lds_dwordx4 v[216:217], off
	s_mov_b32 m0, s28
	s_nop 0
	global_load_lds_dwordx4 v130, s[26:27]
	s_add_i32 m0, s28, 0x2000
	s_nop 0
	global_load_lds_dwordx4 v132, s[26:27]
	s_mov_b32 m0, s41
	s_nop 0
	global_load_lds_dwordx4 v130, s[24:25]
	s_mov_b32 m0, s42
	s_nop 0
	global_load_lds_dwordx4 v132, s[24:25]
	s_waitcnt vmcnt(8) lgkmcnt(0)
	s_barrier
	v_mfma_f32_16x16x32_bf16 v[62:65], v[152:155], v[184:187], v[62:65]
	v_mfma_f32_16x16x32_bf16 v[58:61], v[160:163], v[184:187], v[58:61]
	v_mfma_f32_16x16x32_bf16 v[46:49], v[152:155], v[192:195], v[46:49]
	v_mfma_f32_16x16x32_bf16 v[42:45], v[160:163], v[192:195], v[42:45]
	v_mfma_f32_16x16x32_bf16 v[30:33], v[152:155], v[200:203], v[30:33]
	v_mfma_f32_16x16x32_bf16 v[26:29], v[160:163], v[200:203], v[26:29]
	v_mfma_f32_16x16x32_bf16 v[14:17], v[152:155], v[208:211], v[14:17]
	v_mfma_f32_16x16x32_bf16 v[10:13], v[160:163], v[208:211], v[10:13]
	v_mfma_f32_16x16x32_bf16 v[62:65], v[156:159], v[188:191], v[62:65]
	v_mfma_f32_16x16x32_bf16 v[58:61], v[164:167], v[188:191], v[58:61]
	v_mfma_f32_16x16x32_bf16 v[46:49], v[156:159], v[196:199], v[46:49]
	v_mfma_f32_16x16x32_bf16 v[42:45], v[164:167], v[196:199], v[42:45]
	v_mfma_f32_16x16x32_bf16 v[30:33], v[156:159], v[204:207], v[30:33]
	v_mfma_f32_16x16x32_bf16 v[26:29], v[164:167], v[204:207], v[26:29]
	v_mfma_f32_16x16x32_bf16 v[14:17], v[156:159], v[212:215], v[14:17]
	v_mfma_f32_16x16x32_bf16 v[10:13], v[164:167], v[212:215], v[10:13]
	v_mfma_f32_16x16x32_bf16 v[54:57], v[168:171], v[184:187], v[54:57]
	v_mfma_f32_16x16x32_bf16 v[50:53], v[176:179], v[184:187], v[50:53]
	v_mfma_f32_16x16x32_bf16 v[38:41], v[168:171], v[192:195], v[38:41]
	v_mfma_f32_16x16x32_bf16 v[34:37], v[176:179], v[192:195], v[34:37]
	v_mfma_f32_16x16x32_bf16 v[22:25], v[168:171], v[200:203], v[22:25]
	v_mfma_f32_16x16x32_bf16 v[18:21], v[176:179], v[200:203], v[18:21]
	v_mfma_f32_16x16x32_bf16 v[6:9], v[168:171], v[208:211], v[6:9]
	v_mfma_f32_16x16x32_bf16 v[2:5], v[176:179], v[208:211], v[2:5]
	v_mfma_f32_16x16x32_bf16 v[54:57], v[172:175], v[188:191], v[54:57]
	v_mfma_f32_16x16x32_bf16 v[50:53], v[180:183], v[188:191], v[50:53]
	v_mfma_f32_16x16x32_bf16 v[38:41], v[172:175], v[196:199], v[38:41]
	v_mfma_f32_16x16x32_bf16 v[34:37], v[180:183], v[196:199], v[34:37]
	v_mfma_f32_16x16x32_bf16 v[22:25], v[172:175], v[204:207], v[22:25]
	v_mfma_f32_16x16x32_bf16 v[18:21], v[180:183], v[204:207], v[18:21]
	v_mfma_f32_16x16x32_bf16 v[6:9], v[172:175], v[212:215], v[6:9]
	v_mfma_f32_16x16x32_bf16 v[2:5], v[180:183], v[212:215], v[2:5]
	s_barrier
	s_add_u32 s22, s22, 0x10000
	s_addc_u32 s23, s23, 0
	s_cmp_ge_u32 s57, s44
	s_cbranch_scc0 .LBB0_1229
	v_lshl_add_u32 v143, s45, 8, v146
	v_add_u32_e32 v144, 0xffffe000, v143
	v_sub_co_u32_e64 v142, vcc, s43, 1
	v_mov_b32_e32 v145, s54
	s_nop 0
	v_cndmask_b32_e32 v144, v144, v143, vcc
	v_ashrrev_i32_e32 v143, 31, v142
	v_lshlrev_b64 v[142:143], 23, v[142:143]
	v_lshl_add_u64 v[142:143], s[12:13], 0, v[142:143]
	v_cndmask_b32_e32 v143, v143, v145, vcc
	v_mov_b32_e32 v145, s52
	v_cndmask_b32_e32 v142, v142, v145, vcc
	v_ashrrev_i32_e32 v145, 31, v144
	v_lshl_or_b32 v152, s78, 8, v148
	v_lshlrev_b64 v[144:145], 12, v[144:145]
	v_lshl_add_u64 v[142:143], v[142:143], 0, v[144:145]
	v_ashrrev_i32_e32 v153, 31, v152
	v_cvt_pk_bf16_f32 v126, v126, v127
	v_cvt_pk_bf16_f32 v127, v128, v129
	v_cvt_pk_bf16_f32 v128, v122, v123
	v_cvt_pk_bf16_f32 v124, v124, v125
	v_cvt_pk_bf16_f32 v118, v118, v119
	v_cvt_pk_bf16_f32 v119, v120, v121
	v_cvt_pk_bf16_f32 v114, v114, v115
	v_cvt_pk_bf16_f32 v115, v116, v117
	v_lshl_add_u64 v[142:143], v[152:153], 1, v[142:143]
	v_mov_b32_dpp v120, v126 row_ror:8 row_mask:0xf bank_mask:0xf bound_ctrl:1
	v_mov_b32_dpp v121, v127 row_ror:8 row_mask:0xf bank_mask:0xf bound_ctrl:1
	v_mov_b32_dpp v116, v128 row_ror:8 row_mask:0xf bank_mask:0xf bound_ctrl:1
	v_mov_b32_dpp v117, v124 row_ror:8 row_mask:0xf bank_mask:0xf bound_ctrl:1
	v_mov_b32_dpp v125, v118 row_ror:8 row_mask:0xf bank_mask:0xf bound_ctrl:1
	v_mov_b32_dpp v129, v119 row_ror:8 row_mask:0xf bank_mask:0xf bound_ctrl:1
	v_mov_b32_dpp v144, v114 row_ror:8 row_mask:0xf bank_mask:0xf bound_ctrl:1
	v_mov_b32_dpp v145, v115 row_ror:8 row_mask:0xf bank_mask:0xf bound_ctrl:1
	v_lshl_add_u64 v[122:123], v[142:143], 0, v[134:135]
	v_cndmask_b32_e64 v117, v117, v115, s[8:9]
	v_cndmask_b32_e64 v116, v116, v114, s[8:9]
	v_cndmask_b32_e64 v115, v121, v119, s[8:9]
	v_cndmask_b32_e64 v114, v120, v118, s[8:9]
	v_cndmask_b32_e64 v121, v124, v145, s[8:9]
	v_cndmask_b32_e64 v120, v128, v144, s[8:9]
	v_cndmask_b32_e64 v119, v127, v129, s[8:9]
	v_cndmask_b32_e64 v118, v126, v125, s[8:9]
	v_cvt_pk_bf16_f32 v110, v110, v111
	v_cvt_pk_bf16_f32 v111, v112, v113
	v_cvt_pk_bf16_f32 v112, v106, v107
	v_cvt_pk_bf16_f32 v113, v108, v109
	v_cvt_pk_bf16_f32 v102, v102, v103
	v_cvt_pk_bf16_f32 v103, v104, v105
	v_cvt_pk_bf16_f32 v98, v98, v99
	v_cvt_pk_bf16_f32 v99, v100, v101
	s_mov_b64 s[4:5], 0x10000
	v_lshl_add_u64 v[124:125], v[142:143], 0, v[136:137]
	s_and_b64 vcc, exec, s[6:7]
	s_cbranch_vccz .LBB0_1232
	s_barrier
; __device__ __forceinline__ unsigned pk2(float lo, float hi) { const f32x2 v = {lo, hi}; return __builtin_bit_cast(unsigned, __builtin_convertvector(v, bf16x2_t)); }
; __device__ __forceinline__ void store_pair(unsigned char* own, size_t stride8, int hi_off, u32x4 lo, u32x4 hi, bool upper) {
;     const u32x4 tlo = ror8(lo), thi = ror8(hi);
;     const u32x4 A = upper ? thi : lo, B = upper ? hi : tlo;
;     unsigned char* pa = upper ? own - stride8 + hi_off : own;
;     unsigned char* pb = upper ? own + hi_off : own + stride8;
;     *(u32x4*)pa = A; *(u32x4*)pb = B;
; }
;     __device__ __forceinline__ void operator()(const f32x4 (&acc)[2][2][4][2], const Unit& u, int wr, int wc, int fr, int fq) const {
;         const int row0 = u.pm * 256 + wr * 64 + fr, col0 = u.pn * 256 + wc * 64 + 8 * fq;
;         bf16_t* base = u.part == 0 ? Z + (size_t)row0 * D + col0 : P + ((size_t)(u.part - 1) * MS + (row0 - MP)) * D + col0;
; #pragma unroll
;         for (int ai = 0; ai < 2; ++ai)
; #pragma unroll
;             for (int m = 0; m < 4; ++m) { u32x4 w[2];
; #pragma unroll
;                 for (int bj = 0; bj < 2; ++bj) { const f32x4 v0 = acc[ai][bj][m][0], v1 = acc[ai][bj][m][1]; w[bj].x = pk2(v0[0], v0[1]); w[bj].y = pk2(v0[2], v0[3]); w[bj].z = pk2(v1[0], v1[1]); w[bj].w = pk2(v1[2], v1[3]); }
;                 store_pair((unsigned char*)(base + (size_t)(ai * 128 + m * 16) * D), (size_t)8 * D * 2, 64, w[0], w[1], fr >= 8); }
.LBB0_1232:
	global_store_dwordx4 v[122:123], v[118:121], off
	global_store_dwordx4 v[124:125], v[114:117], off
	v_lshl_add_u64 v[106:107], v[142:143], 0, s[4:5]
	v_mov_b32_dpp v104, v110 row_ror:8 row_mask:0xf bank_mask:0xf bound_ctrl:1
	v_mov_b32_dpp v105, v111 row_ror:8 row_mask:0xf bank_mask:0xf bound_ctrl:1
	v_mov_b32_dpp v100, v112 row_ror:8 row_mask:0xf bank_mask:0xf bound_ctrl:1
	v_mov_b32_dpp v101, v113 row_ror:8 row_mask:0xf bank_mask:0xf bound_ctrl:1
	v_mov_b32_dpp v114, v102 row_ror:8 row_mask:0xf bank_mask:0xf bound_ctrl:1
	v_mov_b32_dpp v115, v103 row_ror:8 row_mask:0xf bank_mask:0xf bound_ctrl:1
	v_mov_b32_dpp v116, v98 row_ror:8 row_mask:0xf bank_mask:0xf bound_ctrl:1
	v_mov_b32_dpp v117, v99 row_ror:8 row_mask:0xf bank_mask:0xf bound_ctrl:1
	v_lshl_add_u64 v[108:109], v[106:107], 0, v[134:135]
	v_cndmask_b32_e64 v101, v101, v99, s[8:9]
	v_cndmask_b32_e64 v100, v100, v98, s[8:9]
	v_cndmask_b32_e64 v99, v105, v103, s[8:9]
	v_cndmask_b32_e64 v98, v104, v102, s[8:9]
	v_cndmask_b32_e64 v105, v113, v117, s[8:9]
	v_cndmask_b32_e64 v104, v112, v116, s[8:9]
	v_cndmask_b32_e64 v103, v111, v115, s[8:9]
	v_cndmask_b32_e64 v102, v110, v114, s[8:9]
	v_cvt_pk_bf16_f32 v94, v94, v95
	v_cvt_pk_bf16_f32 v95, v96, v97
	v_cvt_pk_bf16_f32 v96, v90, v91
	v_cvt_pk_bf16_f32 v97, v92, v93
	v_cvt_pk_bf16_f32 v86, v86, v87
	v_cvt_pk_bf16_f32 v87, v88, v89
	v_cvt_pk_bf16_f32 v82, v82, v83
	v_cvt_pk_bf16_f32 v83, v84, v85
	s_mov_b64 s[4:5], 0x20000
	v_lshl_add_u64 v[106:107], v[106:107], 0, v[136:137]
	global_store_dwordx4 v[108:109], v[102:105], off
	global_store_dwordx4 v[106:107], v[98:101], off
	v_lshl_add_u64 v[90:91], v[142:143], 0, s[4:5]
	v_mov_b32_dpp v88, v94 row_ror:8 row_mask:0xf bank_mask:0xf bound_ctrl:1
	v_mov_b32_dpp v89, v95 row_ror:8 row_mask:0xf bank_mask:0xf bound_ctrl:1
	v_mov_b32_dpp v84, v96 row_ror:8 row_mask:0xf bank_mask:0xf bound_ctrl:1
	v_mov_b32_dpp v85, v97 row_ror:8 row_mask:0xf bank_mask:0xf bound_ctrl:1
	v_mov_b32_dpp v98, v86 row_ror:8 row_mask:0xf bank_mask:0xf bound_ctrl:1
	v_mov_b32_dpp v99, v87 row_ror:8 row_mask:0xf bank_mask:0xf bound_ctrl:1
	v_mov_b32_dpp v100, v82 row_ror:8 row_mask:0xf bank_mask:0xf bound_ctrl:1
	v_mov_b32_dpp v101, v83 row_ror:8 row_mask:0xf bank_mask:0xf bound_ctrl:1
	v_lshl_add_u64 v[92:93], v[90:91], 0, v[134:135]
	v_cndmask_b32_e64 v85, v85, v83, s[8:9]
	v_cndmask_b32_e64 v84, v84, v82, s[8:9]
	v_cndmask_b32_e64 v83, v89, v87, s[8:9]
	v_cndmask_b32_e64 v82, v88, v86, s[8:9]
	v_cndmask_b32_e64 v89, v97, v101, s[8:9]
	v_cndmask_b32_e64 v88, v96, v100, s[8:9]
	v_cndmask_b32_e64 v87, v95, v99, s[8:9]
	v_cndmask_b32_e64 v86, v94, v98, s[8:9]
	v_cvt_pk_bf16_f32 v78, v78, v79
	v_cvt_pk_bf16_f32 v79, v80, v81
	v_cvt_pk_bf16_f32 v80, v74, v75
	v_cvt_pk_bf16_f32 v81, v76, v77
	v_cvt_pk_bf16_f32 v70, v70, v71
	v_cvt_pk_bf16_f32 v71, v72, v73
	v_cvt_pk_bf16_f32 v66, v66, v67
	v_cvt_pk_bf16_f32 v67, v68, v69
	s_mov_b64 s[4:5], 0x30000
	v_lshl_add_u64 v[90:91], v[90:91], 0, v[136:137]
	global_store_dwordx4 v[92:93], v[86:89], off
	global_store_dwordx4 v[90:91], v[82:85], off
	v_lshl_add_u64 v[74:75], v[142:143], 0, s[4:5]
	v_mov_b32_dpp v72, v78 row_ror:8 row_mask:0xf bank_mask:0xf bound_ctrl:1
	v_mov_b32_dpp v73, v79 row_ror:8 row_mask:0xf bank_mask:0xf bound_ctrl:1
	v_mov_b32_dpp v68, v80 row_ror:8 row_mask:0xf bank_mask:0xf bound_ctrl:1
	v_mov_b32_dpp v69, v81 row_ror:8 row_mask:0xf bank_mask:0xf bound_ctrl:1
	v_mov_b32_dpp v82, v70 row_ror:8 row_mask:0xf bank_mask:0xf bound_ctrl:1
	v_mov_b32_dpp v83, v71 row_ror:8 row_mask:0xf bank_mask:0xf bound_ctrl:1
	v_mov_b32_dpp v84, v66 row_ror:8 row_mask:0xf bank_mask:0xf bound_ctrl:1
	v_mov_b32_dpp v85, v67 row_ror:8 row_mask:0xf bank_mask:0xf bound_ctrl:1
	v_lshl_add_u64 v[76:77], v[74:75], 0, v[134:135]
	v_cndmask_b32_e64 v69, v69, v67, s[8:9]
	v_cndmask_b32_e64 v68, v68, v66, s[8:9]
	v_cndmask_b32_e64 v67, v73, v71, s[8:9]
	v_cndmask_b32_e64 v66, v72, v70, s[8:9]
	v_cndmask_b32_e64 v73, v81, v85, s[8:9]
	v_cndmask_b32_e64 v72, v80, v84, s[8:9]
	v_cndmask_b32_e64 v71, v79, v83, s[8:9]
	v_cndmask_b32_e64 v70, v78, v82, s[8:9]
	v_cvt_pk_bf16_f32 v62, v62, v63
	v_cvt_pk_bf16_f32 v63, v64, v65
	v_cvt_pk_bf16_f32 v64, v58, v59
	v_cvt_pk_bf16_f32 v65, v60, v61
	v_cvt_pk_bf16_f32 v54, v54, v55
	v_cvt_pk_bf16_f32 v55, v56, v57
	v_cvt_pk_bf16_f32 v50, v50, v51
	v_cvt_pk_bf16_f32 v51, v52, v53
	s_mov_b64 s[4:5], 0x80000
	v_lshl_add_u64 v[74:75], v[74:75], 0, v[136:137]
	global_store_dwordx4 v[76:77], v[70:73], off
	global_store_dwordx4 v[74:75], v[66:69], off
	v_lshl_add_u64 v[58:59], v[142:143], 0, s[4:5]
	v_mov_b32_dpp v56, v62 row_ror:8 row_mask:0xf bank_mask:0xf bound_ctrl:1
	v_mov_b32_dpp v57, v63 row_ror:8 row_mask:0xf bank_mask:0xf bound_ctrl:1
	v_mov_b32_dpp v52, v64 row_ror:8 row_mask:0xf bank_mask:0xf bound_ctrl:1
	v_mov_b32_dpp v53, v65 row_ror:8 row_mask:0xf bank_mask:0xf bound_ctrl:1
	v_mov_b32_dpp v66, v54 row_ror:8 row_mask:0xf bank_mask:0xf bound_ctrl:1
	v_mov_b32_dpp v67, v55 row_ror:8 row_mask:0xf bank_mask:0xf bound_ctrl:1
	v_mov_b32_dpp v68, v50 row_ror:8 row_mask:0xf bank_mask:0xf bound_ctrl:1
; __device__ __forceinline__ unsigned pk2(float lo, float hi) { const f32x2 v = {lo, hi}; return __builtin_bit_cast(unsigned, __builtin_convertvector(v, bf16x2_t)); }
; #define PG8_BAR __builtin_amdgcn_s_barrier()
; template <class Epi, class Sched, bool ABLK = false, bool ALIGN_EPI = true, bool SP2 = true, bool BBLK = true>
; __device__ __forceinline__ void gemm_phase(LAS unsigned char* lds, const Gemm g, const Sched& S, const Epi& E) {
;     ...
;         if (!has_next) break;
; #pragma unroll
;         for (int a = 0; a < 2; ++a)
; #pragma unroll
;             for (int b = 0; b < 2; ++b)
; #pragma unroll
;                 for (int m = 0; m < 4; ++m)
; #pragma unroll
;                     for (int n = 0; n < 2; ++n) acc[a][b][m][n] = (f32x4){0.f, 0.f, 0.f, 0.f};
;         cur = nxt; uA = nuA; tbA = ntbA; cB = nB; ++ui;
;         if constexpr (ALIGN_EPI) { if (wr == 1) PG8_BAR; }
;     __device__ __forceinline__ void operator()(const f32x4 (&acc)[2][2][4][2], const Unit& u, int wr, int wc, int fr, int fq) const {
;         const int row0 = u.pm * 256 + wr * 64 + fr, col0 = u.pn * 256 + wc * 64 + 8 * fq;
;         bf16_t* base = u.part == 0 ? Z + (size_t)row0 * D + col0 : P + ((size_t)(u.part - 1) * MS + (row0 - MP)) * D + col0;
; #pragma unroll
;         for (int ai = 0; ai < 2; ++ai)
; #pragma unroll
;             for (int m = 0; m < 4; ++m) { u32x4 w[2];
; #pragma unroll
;                 for (int bj = 0; bj < 2; ++bj) { const f32x4 v0 = acc[ai][bj][m][0], v1 = acc[ai][bj][m][1]; w[bj].x = pk2(v0[0], v0[1]); w[bj].y = pk2(v0[2], v0[3]); w[bj].z = pk2(v1[0], v1[1]); w[bj].w = pk2(v1[2], v1[3]); }
;                 store_pair((unsigned char*)(base + (size_t)(ai * 128 + m * 16) * D), (size_t)8 * D * 2, 64, w[0], w[1], fr >= 8); }
	v_mov_b32_dpp v69, v51 row_ror:8 row_mask:0xf bank_mask:0xf bound_ctrl:1
	v_lshl_add_u64 v[60:61], v[58:59], 0, v[134:135]
	v_cndmask_b32_e64 v53, v53, v51, s[8:9]
	v_cndmask_b32_e64 v52, v52, v50, s[8:9]
	v_cndmask_b32_e64 v51, v57, v55, s[8:9]
	v_cndmask_b32_e64 v50, v56, v54, s[8:9]
	v_cndmask_b32_e64 v57, v65, v69, s[8:9]
	v_cndmask_b32_e64 v56, v64, v68, s[8:9]
	v_cndmask_b32_e64 v55, v63, v67, s[8:9]
	v_cndmask_b32_e64 v54, v62, v66, s[8:9]
	v_cvt_pk_bf16_f32 v46, v46, v47
	v_cvt_pk_bf16_f32 v47, v48, v49
	v_cvt_pk_bf16_f32 v48, v42, v43
	v_cvt_pk_bf16_f32 v49, v44, v45
	v_cvt_pk_bf16_f32 v38, v38, v39
	v_cvt_pk_bf16_f32 v39, v40, v41
	v_cvt_pk_bf16_f32 v34, v34, v35
	v_cvt_pk_bf16_f32 v35, v36, v37
	s_mov_b64 s[4:5], 0x90000
	v_lshl_add_u64 v[58:59], v[58:59], 0, v[136:137]
	global_store_dwordx4 v[60:61], v[54:57], off
	global_store_dwordx4 v[58:59], v[50:53], off
	v_lshl_add_u64 v[42:43], v[142:143], 0, s[4:5]
	v_mov_b32_dpp v40, v46 row_ror:8 row_mask:0xf bank_mask:0xf bound_ctrl:1
	v_mov_b32_dpp v41, v47 row_ror:8 row_mask:0xf bank_mask:0xf bound_ctrl:1
	v_mov_b32_dpp v36, v48 row_ror:8 row_mask:0xf bank_mask:0xf bound_ctrl:1
	v_mov_b32_dpp v37, v49 row_ror:8 row_mask:0xf bank_mask:0xf bound_ctrl:1
	v_mov_b32_dpp v50, v38 row_ror:8 row_mask:0xf bank_mask:0xf bound_ctrl:1
	v_mov_b32_dpp v51, v39 row_ror:8 row_mask:0xf bank_mask:0xf bound_ctrl:1
	v_mov_b32_dpp v52, v34 row_ror:8 row_mask:0xf bank_mask:0xf bound_ctrl:1
	v_mov_b32_dpp v53, v35 row_ror:8 row_mask:0xf bank_mask:0xf bound_ctrl:1
	v_lshl_add_u64 v[44:45], v[42:43], 0, v[134:135]
	v_cndmask_b32_e64 v37, v37, v35, s[8:9]
	v_cndmask_b32_e64 v36, v36, v34, s[8:9]
	v_cndmask_b32_e64 v35, v41, v39, s[8:9]
	v_cndmask_b32_e64 v34, v40, v38, s[8:9]
	v_cndmask_b32_e64 v41, v49, v53, s[8:9]
	v_cndmask_b32_e64 v40, v48, v52, s[8:9]
	v_cndmask_b32_e64 v39, v47, v51, s[8:9]
	v_cndmask_b32_e64 v38, v46, v50, s[8:9]
	v_cvt_pk_bf16_f32 v30, v30, v31
	v_cvt_pk_bf16_f32 v31, v32, v33
	v_cvt_pk_bf16_f32 v32, v26, v27
	v_cvt_pk_bf16_f32 v33, v28, v29
	v_cvt_pk_bf16_f32 v22, v22, v23
	v_cvt_pk_bf16_f32 v23, v24, v25
	v_cvt_pk_bf16_f32 v18, v18, v19
	v_cvt_pk_bf16_f32 v19, v20, v21
	s_mov_b64 s[4:5], 0xa0000
	v_lshl_add_u64 v[42:43], v[42:43], 0, v[136:137]
	global_store_dwordx4 v[44:45], v[38:41], off
	global_store_dwordx4 v[42:43], v[34:37], off
	v_lshl_add_u64 v[26:27], v[142:143], 0, s[4:5]
	v_mov_b32_dpp v24, v30 row_ror:8 row_mask:0xf bank_mask:0xf bound_ctrl:1
	v_mov_b32_dpp v25, v31 row_ror:8 row_mask:0xf bank_mask:0xf bound_ctrl:1
	v_mov_b32_dpp v20, v32 row_ror:8 row_mask:0xf bank_mask:0xf bound_ctrl:1
	v_mov_b32_dpp v21, v33 row_ror:8 row_mask:0xf bank_mask:0xf bound_ctrl:1
	v_mov_b32_dpp v34, v22 row_ror:8 row_mask:0xf bank_mask:0xf bound_ctrl:1
	v_mov_b32_dpp v35, v23 row_ror:8 row_mask:0xf bank_mask:0xf bound_ctrl:1
	v_mov_b32_dpp v36, v18 row_ror:8 row_mask:0xf bank_mask:0xf bound_ctrl:1
	v_mov_b32_dpp v37, v19 row_ror:8 row_mask:0xf bank_mask:0xf bound_ctrl:1
	v_lshl_add_u64 v[28:29], v[26:27], 0, v[134:135]
	v_cndmask_b32_e64 v21, v21, v19, s[8:9]
	v_cndmask_b32_e64 v20, v20, v18, s[8:9]
	v_cndmask_b32_e64 v19, v25, v23, s[8:9]
	v_cndmask_b32_e64 v18, v24, v22, s[8:9]
	v_cndmask_b32_e64 v25, v33, v37, s[8:9]
	v_cndmask_b32_e64 v24, v32, v36, s[8:9]
	v_cndmask_b32_e64 v23, v31, v35, s[8:9]
	v_cndmask_b32_e64 v22, v30, v34, s[8:9]
	v_cvt_pk_bf16_f32 v14, v14, v15
	v_cvt_pk_bf16_f32 v15, v16, v17
	v_cvt_pk_bf16_f32 v16, v10, v11
	v_cvt_pk_bf16_f32 v17, v12, v13
	v_cvt_pk_bf16_f32 v6, v6, v7
	v_cvt_pk_bf16_f32 v7, v8, v9
	v_cvt_pk_bf16_f32 v2, v2, v3
	v_cvt_pk_bf16_f32 v3, v4, v5
	v_lshl_add_u64 v[26:27], v[26:27], 0, v[136:137]
	global_store_dwordx4 v[28:29], v[22:25], off
	global_store_dwordx4 v[26:27], v[18:21], off
	v_lshl_add_u64 v[10:11], v[142:143], 0, s[14:15]
	v_mov_b32_dpp v8, v14 row_ror:8 row_mask:0xf bank_mask:0xf bound_ctrl:1
	v_mov_b32_dpp v9, v15 row_ror:8 row_mask:0xf bank_mask:0xf bound_ctrl:1
	v_mov_b32_dpp v4, v16 row_ror:8 row_mask:0xf bank_mask:0xf bound_ctrl:1
	v_mov_b32_dpp v5, v17 row_ror:8 row_mask:0xf bank_mask:0xf bound_ctrl:1
	v_mov_b32_dpp v18, v6 row_ror:8 row_mask:0xf bank_mask:0xf bound_ctrl:1
	v_mov_b32_dpp v19, v7 row_ror:8 row_mask:0xf bank_mask:0xf bound_ctrl:1
	v_mov_b32_dpp v20, v2 row_ror:8 row_mask:0xf bank_mask:0xf bound_ctrl:1
	v_mov_b32_dpp v21, v3 row_ror:8 row_mask:0xf bank_mask:0xf bound_ctrl:1
	v_lshl_add_u64 v[12:13], v[10:11], 0, v[134:135]
	v_cndmask_b32_e64 v5, v5, v3, s[8:9]
	v_cndmask_b32_e64 v4, v4, v2, s[8:9]
	v_cndmask_b32_e64 v3, v9, v7, s[8:9]
	v_cndmask_b32_e64 v2, v8, v6, s[8:9]
	v_cndmask_b32_e64 v9, v17, v21, s[8:9]
	v_cndmask_b32_e64 v8, v16, v20, s[8:9]
	v_cndmask_b32_e64 v7, v15, v19, s[8:9]
	v_cndmask_b32_e64 v6, v14, v18, s[8:9]
	s_and_b64 vcc, exec, s[10:11]
	s_mov_b64 s[10:11], -1
	v_lshl_add_u64 v[10:11], v[10:11], 0, v[136:137]
	global_store_dwordx4 v[12:13], v[6:9], off
	global_store_dwordx4 v[10:11], v[2:5], off
	s_cbranch_vccnz .LBB0_1227
	s_andn2_b64 vcc, exec, s[2:3]
	s_cbranch_vccnz .LBB0_1226
	s_barrier
	s_branch .LBB0_1226

; #define PG8_STAGE(bufoff, gbase, voff) do { _Pragma("unroll") for (int _i = 0; _i < 2; ++_i) \
;         __builtin_amdgcn_global_load_lds((const unsigned*)((const char*)(gbase) + (voff)[_i]), (LAS unsigned*)(lds + (bufoff) + ldsw + _i * 8192), 16, 0, 0); } while (0)
; #define PG8_LDA(dst, b, h) do { _Pragma("unroll") for (int m = 0; m < 4; ++m) _Pragma("unroll") for (int k = 0; k < 2; ++k) dst[m][k] = *(const LAS bf16x8*)(lds + PG8_SA(b, h) + aoff + m * 2048 + k * 1024); } while (0)
; #define PG8_LDB(dst, b, h) do { _Pragma("unroll") for (int n = 0; n < 2; ++n) _Pragma("unroll") for (int k = 0; k < 2; ++k) dst[n][k] = *(const LAS bf16x8*)(lds + PG8_SB(b, h) + boff + n * 2048 + k * 1024); } while (0)
; #define PG8_MMA(ai, bj, At, Bt) do { __builtin_amdgcn_s_setprio(1); _Pragma("unroll") for (int m = 0; m < 4; ++m) _Pragma("unroll") for (int n = 0; n < 2; ++n) _Pragma("unroll") for (int k = 0; k < 2; ++k) \
;         acc[ai][bj][m][n] = __builtin_amdgcn_mfma_f32_16x16x32_bf16(Bt[n][k], At[m][k], acc[ai][bj][m][n], 0, 0, 0); __builtin_amdgcn_s_setprio(0); } while (0)
; #define PG8_WAIT_V(n) asm volatile("s_waitcnt vmcnt(" #n ")" ::: "memory")
; template <class Epi, class Sched, bool ABLK = false, bool ALIGN_EPI = true, bool SP2 = true, bool BBLK = true>
; __device__ __forceinline__ void gemm_phase(LAS unsigned char* lds, const Gemm g, const Sched& S, const Epi& E) {
;     ...
;         for (int t = 0; t < nt; t += 2) {
;             const bool last = (t == nt - 2);
;             const char* a1 = a_tile(uA, tbA + t + 1);
;             const char* a2 = last ? a_tile(nuA, ntbA) : a_tile(uA, tbA + t + 2); const char* b2 = last ? nB : cB + (size_t)(t + 2) * kstepB;
;             const char* a3 = last ? a_tile(nuA, ntbA + 1) : a_tile(uA, tbA + t + 3); const char* b3 = b2 + kstepB;
;             if (last && has_next) S.a_ready(nxt);
;             if constexpr (SP2) {
;             PG8_LDB(B0, 0, 0); PG8_LDB(B1, 0, 1); PG8_SCHED; PG8_LDA(At, 0, 0); PG8_STAGE(PG8_SA(1, 1), a1 + hstepA, voffA);
;             PG8_WAIT_V(8); PG8_WAIT_L(0); PG8_BAR; PG8_MMA(0, 0, At, B0); PG8_MMA(0, 1, At, B1); PG8_BAR; PG8_SCHED;
;             PG8_LDA(At, 0, 1); PG8_STAGE(PG8_SB(0, 0), b2, voffB); PG8_STAGE(PG8_SB(0, 1), b2 + hstepB, voffB); PG8_STAGE(PG8_SA(0, 0), a2, voffA);
;             PG8_WAIT_V(8); PG8_WAIT_L(0); PG8_BAR; PG8_MMA(1, 0, At, B0); PG8_MMA(1, 1, At, B1); PG8_BAR; PG8_SCHED;
.LBB0_1716:
	ds_read_b128 v[156:159], v152
	ds_read_b128 v[160:163], v152 offset:1024
	ds_read_b128 v[164:167], v152 offset:2048
	ds_read_b128 v[168:171], v152 offset:3072
	ds_read_b128 v[172:175], v153
	ds_read_b128 v[176:179], v153 offset:1024
	ds_read_b128 v[180:183], v153 offset:2048
	ds_read_b128 v[184:187], v153 offset:3072
	s_add_u32 s28, s54, s26
	s_addc_u32 s29, s55, s27
	s_add_u32 s34, s28, 0x100
	s_addc_u32 s35, s29, 0
	s_add_i32 s57, s57, 2
	s_add_u32 s28, s28, 0x180
	s_addc_u32 s29, s29, 0
	s_cmp_eq_u32 s56, s26
	s_cselect_b32 s29, s51, s29
	s_cselect_b32 s28, s50, s28
	s_cselect_b32 s31, s4, s53
	s_cselect_b32 s30, s5, s52
	s_cselect_b32 s35, s49, s35
	s_cselect_b32 s34, s23, s34
	v_lshl_add_u64 v[220:221], v[146:147], 0, s[26:27]
	s_add_i32 m0, s40, 0xc000
	ds_read_b128 v[188:191], v154
	ds_read_b128 v[192:195], v154 offset:1024
	ds_read_b128 v[196:199], v154 offset:2048
	ds_read_b128 v[200:203], v154 offset:3072
	ds_read_b128 v[204:207], v154 offset:4096
	ds_read_b128 v[208:211], v154 offset:5120
	ds_read_b128 v[212:215], v154 offset:6144
	ds_read_b128 v[216:219], v154 offset:7168
	global_load_lds_dwordx4 v[220:221], off
	v_lshl_add_u64 v[220:221], v[148:149], 0, s[26:27]
	s_add_i32 m0, s40, 0xe000
	s_nop 0
	global_load_lds_dwordx4 v[220:221], off
	s_waitcnt vmcnt(8) lgkmcnt(0)
	s_barrier
	v_mfma_f32_16x16x32_bf16 v[126:129], v[156:159], v[188:191], v[126:129]
	v_mfma_f32_16x16x32_bf16 v[122:125], v[164:167], v[188:191], v[122:125]
	v_mfma_f32_16x16x32_bf16 v[110:113], v[156:159], v[196:199], v[110:113]
	v_mfma_f32_16x16x32_bf16 v[106:109], v[164:167], v[196:199], v[106:109]
	v_mfma_f32_16x16x32_bf16 v[94:97], v[156:159], v[204:207], v[94:97]
	v_mfma_f32_16x16x32_bf16 v[90:93], v[164:167], v[204:207], v[90:93]
	v_mfma_f32_16x16x32_bf16 v[78:81], v[156:159], v[212:215], v[78:81]
	v_mfma_f32_16x16x32_bf16 v[74:77], v[164:167], v[212:215], v[74:77]
	v_mfma_f32_16x16x32_bf16 v[126:129], v[160:163], v[192:195], v[126:129]
	v_mfma_f32_16x16x32_bf16 v[122:125], v[168:171], v[192:195], v[122:125]
	v_mfma_f32_16x16x32_bf16 v[110:113], v[160:163], v[200:203], v[110:113]
	v_mfma_f32_16x16x32_bf16 v[106:109], v[168:171], v[200:203], v[106:109]
	v_mfma_f32_16x16x32_bf16 v[94:97], v[160:163], v[208:211], v[94:97]
	v_mfma_f32_16x16x32_bf16 v[90:93], v[168:171], v[208:211], v[90:93]
	v_mfma_f32_16x16x32_bf16 v[78:81], v[160:163], v[216:219], v[78:81]
	v_mfma_f32_16x16x32_bf16 v[74:77], v[168:171], v[216:219], v[74:77]
	v_mfma_f32_16x16x32_bf16 v[118:121], v[172:175], v[188:191], v[118:121]
	v_mfma_f32_16x16x32_bf16 v[114:117], v[180:183], v[188:191], v[114:117]
	v_mfma_f32_16x16x32_bf16 v[102:105], v[172:175], v[196:199], v[102:105]
	v_mfma_f32_16x16x32_bf16 v[98:101], v[180:183], v[196:199], v[98:101]
	v_mfma_f32_16x16x32_bf16 v[86:89], v[172:175], v[204:207], v[86:89]
	v_mfma_f32_16x16x32_bf16 v[82:85], v[180:183], v[204:207], v[82:85]
	v_mfma_f32_16x16x32_bf16 v[70:73], v[172:175], v[212:215], v[70:73]
	v_mfma_f32_16x16x32_bf16 v[66:69], v[180:183], v[212:215], v[66:69]
	v_mfma_f32_16x16x32_bf16 v[118:121], v[176:179], v[192:195], v[118:121]
	v_mfma_f32_16x16x32_bf16 v[114:117], v[184:187], v[192:195], v[114:117]
	v_mfma_f32_16x16x32_bf16 v[102:105], v[176:179], v[200:203], v[102:105]
	v_mfma_f32_16x16x32_bf16 v[98:101], v[184:187], v[200:203], v[98:101]
	v_mfma_f32_16x16x32_bf16 v[86:89], v[176:179], v[208:211], v[86:89]
	v_mfma_f32_16x16x32_bf16 v[82:85], v[184:187], v[208:211], v[82:85]
	v_mfma_f32_16x16x32_bf16 v[70:73], v[176:179], v[216:219], v[70:73]
	v_mfma_f32_16x16x32_bf16 v[66:69], v[184:187], v[216:219], v[66:69]
	s_barrier
	s_add_i32 s58, s72, s39
	s_mov_b32 m0, s58
	ds_read_b128 v[188:191], v154 offset:16384
	ds_read_b128 v[192:195], v154 offset:17408
	ds_read_b128 v[196:199], v154 offset:18432
	ds_read_b128 v[200:203], v154 offset:19456
	ds_read_b128 v[204:207], v154 offset:20480
	ds_read_b128 v[208:211], v154 offset:21504
	ds_read_b128 v[212:215], v154 offset:22528
	ds_read_b128 v[216:219], v154 offset:23552
	global_load_lds_dwordx4 v132, s[30:31]
	s_add_i32 m0, s58, 0x2000
	s_add_u32 s58, s30, 0x4000
	s_addc_u32 s59, s31, 0
	s_add_i32 s64, s73, s39
	global_load_lds_dwordx4 v136, s[30:31]
	s_mov_b32 m0, s64
	s_nop 0
	global_load_lds_dwordx4 v132, s[58:59]
	s_add_i32 m0, s64, 0x2000
	s_nop 0
	global_load_lds_dwordx4 v136, s[58:59]
	s_mov_b32 m0, s40
	s_nop 0
	global_load_lds_dwordx4 v130, s[34:35]
	s_mov_b32 m0, s41
	s_nop 0
	global_load_lds_dwordx4 v134, s[34:35]
	s_waitcnt vmcnt(8) lgkmcnt(0)
	s_barrier
	v_mfma_f32_16x16x32_bf16 v[62:65], v[156:159], v[188:191], v[62:65]
	v_mfma_f32_16x16x32_bf16 v[58:61], v[164:167], v[188:191], v[58:61]
	v_mfma_f32_16x16x32_bf16 v[46:49], v[156:159], v[196:199], v[46:49]
	v_mfma_f32_16x16x32_bf16 v[42:45], v[164:167], v[196:199], v[42:45]
	v_mfma_f32_16x16x32_bf16 v[30:33], v[156:159], v[204:207], v[30:33]
	v_mfma_f32_16x16x32_bf16 v[26:29], v[164:167], v[204:207], v[26:29]
	v_mfma_f32_16x16x32_bf16 v[14:17], v[156:159], v[212:215], v[14:17]
	v_mfma_f32_16x16x32_bf16 v[10:13], v[164:167], v[212:215], v[10:13]
	v_mfma_f32_16x16x32_bf16 v[62:65], v[160:163], v[192:195], v[62:65]
	v_mfma_f32_16x16x32_bf16 v[58:61], v[168:171], v[192:195], v[58:61]
	v_mfma_f32_16x16x32_bf16 v[46:49], v[160:163], v[200:203], v[46:49]
	v_mfma_f32_16x16x32_bf16 v[42:45], v[168:171], v[200:203], v[42:45]
	v_mfma_f32_16x16x32_bf16 v[30:33], v[160:163], v[208:211], v[30:33]
	v_mfma_f32_16x16x32_bf16 v[26:29], v[168:171], v[208:211], v[26:29]
	v_mfma_f32_16x16x32_bf16 v[14:17], v[160:163], v[216:219], v[14:17]
	v_mfma_f32_16x16x32_bf16 v[10:13], v[168:171], v[216:219], v[10:13]
	v_mfma_f32_16x16x32_bf16 v[54:57], v[172:175], v[188:191], v[54:57]
	v_mfma_f32_16x16x32_bf16 v[50:53], v[180:183], v[188:191], v[50:53]
	v_mfma_f32_16x16x32_bf16 v[38:41], v[172:175], v[196:199], v[38:41]
	v_mfma_f32_16x16x32_bf16 v[34:37], v[180:183], v[196:199], v[34:37]
	v_mfma_f32_16x16x32_bf16 v[22:25], v[172:175], v[204:207], v[22:25]
	v_mfma_f32_16x16x32_bf16 v[18:21], v[180:183], v[204:207], v[18:21]
	v_mfma_f32_16x16x32_bf16 v[6:9], v[172:175], v[212:215], v[6:9]
	v_mfma_f32_16x16x32_bf16 v[2:5], v[180:183], v[212:215], v[2:5]
	v_mfma_f32_16x16x32_bf16 v[54:57], v[176:179], v[192:195], v[54:57]
	v_mfma_f32_16x16x32_bf16 v[50:53], v[184:187], v[192:195], v[50:53]
	v_mfma_f32_16x16x32_bf16 v[38:41], v[176:179], v[200:203], v[38:41]
	v_mfma_f32_16x16x32_bf16 v[34:37], v[184:187], v[200:203], v[34:37]
	v_mfma_f32_16x16x32_bf16 v[22:25], v[176:179], v[208:211], v[22:25]
	v_mfma_f32_16x16x32_bf16 v[18:21], v[184:187], v[208:211], v[18:21]
	v_mfma_f32_16x16x32_bf16 v[6:9], v[176:179], v[216:219], v[6:9]
	v_mfma_f32_16x16x32_bf16 v[2:5], v[184:187], v[216:219], v[2:5]
	s_barrier
; #define PG8_STAGE(bufoff, gbase, voff) do { _Pragma("unroll") for (int _i = 0; _i < 2; ++_i) \
;         __builtin_amdgcn_global_load_lds((const unsigned*)((const char*)(gbase) + (voff)[_i]), (LAS unsigned*)(lds + (bufoff) + ldsw + _i * 8192), 16, 0, 0); } while (0)
; #define PG8_LDA(dst, b, h) do { _Pragma("unroll") for (int m = 0; m < 4; ++m) _Pragma("unroll") for (int k = 0; k < 2; ++k) dst[m][k] = *(const LAS bf16x8*)(lds + PG8_SA(b, h) + aoff + m * 2048 + k * 1024); } while (0)
; #define PG8_LDB(dst, b, h) do { _Pragma("unroll") for (int n = 0; n < 2; ++n) _Pragma("unroll") for (int k = 0; k < 2; ++k) dst[n][k] = *(const LAS bf16x8*)(lds + PG8_SB(b, h) + boff + n * 2048 + k * 1024); } while (0)
; #define PG8_MMA(ai, bj, At, Bt) do { __builtin_amdgcn_s_setprio(1); _Pragma("unroll") for (int m = 0; m < 4; ++m) _Pragma("unroll") for (int n = 0; n < 2; ++n) _Pragma("unroll") for (int k = 0; k < 2; ++k) \
;         acc[ai][bj][m][n] = __builtin_amdgcn_mfma_f32_16x16x32_bf16(Bt[n][k], At[m][k], acc[ai][bj][m][n], 0, 0, 0); __builtin_amdgcn_s_setprio(0); } while (0)
; #define PG8_WAIT_V(n) asm volatile("s_waitcnt vmcnt(" #n ")" ::: "memory")
; #define PG8_WAIT_L(n) asm volatile("s_waitcnt lgkmcnt(" #n ")" ::: "memory")
; #define PG8_BAR __builtin_amdgcn_s_barrier()
; #define PG8_SCHED __builtin_amdgcn_sched_barrier(0)
; template <class Epi, class Sched, bool ABLK = false, bool ALIGN_EPI = true, bool SP2 = true, bool BBLK = true>
; __device__ __forceinline__ void gemm_phase(LAS unsigned char* lds, const Gemm g, const Sched& S, const Epi& E) {
;     ...
;             PG8_WAIT_V(8); PG8_WAIT_L(0); PG8_BAR; PG8_MMA(1, 0, At, B0); PG8_MMA(1, 1, At, B1); PG8_BAR; PG8_SCHED;
;             PG8_LDB(B0, 1, 0); PG8_LDB(B1, 1, 1); PG8_SCHED; PG8_LDA(At, 1, 0); PG8_STAGE(PG8_SA(0, 1), a2 + hstepA, voffA);
;             PG8_WAIT_V(8); PG8_WAIT_L(0); PG8_BAR; PG8_MMA(0, 0, At, B0); PG8_MMA(0, 1, At, B1); PG8_BAR; PG8_SCHED;
;             PG8_LDA(At, 1, 1); PG8_STAGE(PG8_SB(1, 0), b3, voffB); PG8_STAGE(PG8_SB(1, 1), b3 + hstepB, voffB); PG8_STAGE(PG8_SA(1, 0), a3, voffA);
;             PG8_WAIT_V(8); PG8_WAIT_L(0); PG8_BAR; PG8_MMA(1, 0, At, B0); PG8_MMA(1, 1, At, B1); PG8_BAR; PG8_SCHED;
	v_add_u32_e32 v155, s60, v150
	ds_read_b128 v[156:159], v155
	ds_read_b128 v[160:163], v155 offset:1024
	ds_read_b128 v[164:167], v155 offset:2048
	ds_read_b128 v[168:171], v155 offset:3072
	v_add_u32_e32 v155, s61, v150
	ds_read_b128 v[172:175], v155
	ds_read_b128 v[176:179], v155 offset:1024
	ds_read_b128 v[180:183], v155 offset:2048
	ds_read_b128 v[184:187], v155 offset:3072
	s_add_u32 s34, s34, 0x80000
	s_addc_u32 s35, s35, 0
	s_mov_b32 m0, s42
	ds_read_b128 v[188:191], v154 offset:32768
	ds_read_b128 v[192:195], v154 offset:33792
	ds_read_b128 v[196:199], v154 offset:34816
	ds_read_b128 v[200:203], v154 offset:35840
	ds_read_b128 v[204:207], v154 offset:36864
	ds_read_b128 v[208:211], v154 offset:37888
	ds_read_b128 v[212:215], v154 offset:38912
	ds_read_b128 v[216:219], v154 offset:39936
	global_load_lds_dwordx4 v130, s[34:35]
	s_mov_b32 m0, s43
	s_nop 0
	global_load_lds_dwordx4 v134, s[34:35]
	s_waitcnt vmcnt(8) lgkmcnt(0)
	s_barrier
	v_mfma_f32_16x16x32_bf16 v[126:129], v[156:159], v[188:191], v[126:129]
	v_mfma_f32_16x16x32_bf16 v[122:125], v[164:167], v[188:191], v[122:125]
	v_mfma_f32_16x16x32_bf16 v[110:113], v[156:159], v[196:199], v[110:113]
	v_mfma_f32_16x16x32_bf16 v[106:109], v[164:167], v[196:199], v[106:109]
	v_mfma_f32_16x16x32_bf16 v[94:97], v[156:159], v[204:207], v[94:97]
	v_mfma_f32_16x16x32_bf16 v[90:93], v[164:167], v[204:207], v[90:93]
	v_mfma_f32_16x16x32_bf16 v[78:81], v[156:159], v[212:215], v[78:81]
	v_mfma_f32_16x16x32_bf16 v[74:77], v[164:167], v[212:215], v[74:77]
	v_mfma_f32_16x16x32_bf16 v[126:129], v[160:163], v[192:195], v[126:129]
	v_mfma_f32_16x16x32_bf16 v[122:125], v[168:171], v[192:195], v[122:125]
	v_mfma_f32_16x16x32_bf16 v[110:113], v[160:163], v[200:203], v[110:113]
	v_mfma_f32_16x16x32_bf16 v[106:109], v[168:171], v[200:203], v[106:109]
	v_mfma_f32_16x16x32_bf16 v[94:97], v[160:163], v[208:211], v[94:97]
	v_mfma_f32_16x16x32_bf16 v[90:93], v[168:171], v[208:211], v[90:93]
	v_mfma_f32_16x16x32_bf16 v[78:81], v[160:163], v[216:219], v[78:81]
	v_mfma_f32_16x16x32_bf16 v[74:77], v[168:171], v[216:219], v[74:77]
	v_mfma_f32_16x16x32_bf16 v[118:121], v[172:175], v[188:191], v[118:121]
	v_mfma_f32_16x16x32_bf16 v[114:117], v[180:183], v[188:191], v[114:117]
	v_mfma_f32_16x16x32_bf16 v[102:105], v[172:175], v[196:199], v[102:105]
	v_mfma_f32_16x16x32_bf16 v[98:101], v[180:183], v[196:199], v[98:101]
	v_mfma_f32_16x16x32_bf16 v[86:89], v[172:175], v[204:207], v[86:89]
	v_mfma_f32_16x16x32_bf16 v[82:85], v[180:183], v[204:207], v[82:85]
	v_mfma_f32_16x16x32_bf16 v[70:73], v[172:175], v[212:215], v[70:73]
	v_mfma_f32_16x16x32_bf16 v[66:69], v[180:183], v[212:215], v[66:69]
	v_mfma_f32_16x16x32_bf16 v[118:121], v[176:179], v[192:195], v[118:121]
	v_mfma_f32_16x16x32_bf16 v[114:117], v[184:187], v[192:195], v[114:117]
	v_mfma_f32_16x16x32_bf16 v[102:105], v[176:179], v[200:203], v[102:105]
	v_mfma_f32_16x16x32_bf16 v[98:101], v[184:187], v[200:203], v[98:101]
	v_mfma_f32_16x16x32_bf16 v[86:89], v[176:179], v[208:211], v[86:89]
	v_mfma_f32_16x16x32_bf16 v[82:85], v[184:187], v[208:211], v[82:85]
	v_mfma_f32_16x16x32_bf16 v[70:73], v[176:179], v[216:219], v[70:73]
	v_mfma_f32_16x16x32_bf16 v[66:69], v[184:187], v[216:219], v[66:69]
	s_barrier
	s_add_u32 s34, s30, 0x8000
	s_addc_u32 s35, s31, 0
	s_add_i32 s58, s60, s39
	s_mov_b32 m0, s58
	ds_read_b128 v[188:191], v154 offset:49152
	ds_read_b128 v[192:195], v154 offset:50176
	ds_read_b128 v[196:199], v154 offset:51200
	ds_read_b128 v[200:203], v154 offset:52224
	ds_read_b128 v[204:207], v154 offset:53248
	ds_read_b128 v[208:211], v154 offset:54272
	ds_read_b128 v[212:215], v154 offset:55296
	ds_read_b128 v[216:219], v154 offset:56320
	global_load_lds_dwordx4 v132, s[34:35]
	s_add_i32 m0, s58, 0x2000
	s_add_u32 s30, s30, 0xc000
	v_lshl_add_u64 v[220:221], s[34:35], 0, v[136:137]
	s_addc_u32 s31, s31, 0
	s_add_i32 s34, s61, s39
	global_load_lds_dwordx4 v[220:221], off
	s_mov_b32 m0, s34
	s_nop 0
	global_load_lds_dwordx4 v132, s[30:31]
	s_add_i32 m0, s34, 0x2000
	s_nop 0
	global_load_lds_dwordx4 v136, s[30:31]
	s_mov_b32 m0, s44
	s_nop 0
	global_load_lds_dwordx4 v130, s[28:29]
	s_mov_b32 m0, s45
	s_nop 0
	global_load_lds_dwordx4 v134, s[28:29]
	s_waitcnt vmcnt(8) lgkmcnt(0)
	s_barrier
	v_mfma_f32_16x16x32_bf16 v[62:65], v[156:159], v[188:191], v[62:65]
	v_mfma_f32_16x16x32_bf16 v[58:61], v[164:167], v[188:191], v[58:61]
	v_mfma_f32_16x16x32_bf16 v[46:49], v[156:159], v[196:199], v[46:49]
	v_mfma_f32_16x16x32_bf16 v[42:45], v[164:167], v[196:199], v[42:45]
	v_mfma_f32_16x16x32_bf16 v[30:33], v[156:159], v[204:207], v[30:33]
	v_mfma_f32_16x16x32_bf16 v[26:29], v[164:167], v[204:207], v[26:29]
	v_mfma_f32_16x16x32_bf16 v[14:17], v[156:159], v[212:215], v[14:17]
	v_mfma_f32_16x16x32_bf16 v[10:13], v[164:167], v[212:215], v[10:13]
	v_mfma_f32_16x16x32_bf16 v[62:65], v[160:163], v[192:195], v[62:65]
	v_mfma_f32_16x16x32_bf16 v[58:61], v[168:171], v[192:195], v[58:61]
	v_mfma_f32_16x16x32_bf16 v[46:49], v[160:163], v[200:203], v[46:49]
	v_mfma_f32_16x16x32_bf16 v[42:45], v[168:171], v[200:203], v[42:45]
	v_mfma_f32_16x16x32_bf16 v[30:33], v[160:163], v[208:211], v[30:33]
	v_mfma_f32_16x16x32_bf16 v[26:29], v[168:171], v[208:211], v[26:29]
	v_mfma_f32_16x16x32_bf16 v[14:17], v[160:163], v[216:219], v[14:17]
	v_mfma_f32_16x16x32_bf16 v[10:13], v[168:171], v[216:219], v[10:13]
	v_mfma_f32_16x16x32_bf16 v[54:57], v[172:175], v[188:191], v[54:57]
	v_mfma_f32_16x16x32_bf16 v[50:53], v[180:183], v[188:191], v[50:53]
	v_mfma_f32_16x16x32_bf16 v[38:41], v[172:175], v[196:199], v[38:41]
	v_mfma_f32_16x16x32_bf16 v[34:37], v[180:183], v[196:199], v[34:37]
	v_mfma_f32_16x16x32_bf16 v[22:25], v[172:175], v[204:207], v[22:25]
	v_mfma_f32_16x16x32_bf16 v[18:21], v[180:183], v[204:207], v[18:21]
	v_mfma_f32_16x16x32_bf16 v[6:9], v[172:175], v[212:215], v[6:9]
	v_mfma_f32_16x16x32_bf16 v[2:5], v[180:183], v[212:215], v[2:5]
	v_mfma_f32_16x16x32_bf16 v[54:57], v[176:179], v[192:195], v[54:57]
	v_mfma_f32_16x16x32_bf16 v[50:53], v[184:187], v[192:195], v[50:53]
	v_mfma_f32_16x16x32_bf16 v[38:41], v[176:179], v[200:203], v[38:41]
	v_mfma_f32_16x16x32_bf16 v[34:37], v[184:187], v[200:203], v[34:37]
	v_mfma_f32_16x16x32_bf16 v[22:25], v[176:179], v[208:211], v[22:25]
	v_mfma_f32_16x16x32_bf16 v[18:21], v[184:187], v[208:211], v[18:21]
	v_mfma_f32_16x16x32_bf16 v[6:9], v[176:179], v[216:219], v[6:9]
	v_mfma_f32_16x16x32_bf16 v[2:5], v[184:187], v[216:219], v[2:5]
	s_barrier
; __device__ __forceinline__ unsigned pk2(float lo, float hi) { const f32x2 v = {lo, hi}; return __builtin_bit_cast(unsigned, __builtin_convertvector(v, bf16x2_t)); }
; __device__ __forceinline__ void store_pair(unsigned char* own, size_t stride8, int hi_off, u32x4 lo, u32x4 hi, bool upper) {
;     const u32x4 tlo = ror8(lo), thi = ror8(hi);
;     const u32x4 A = upper ? thi : lo, B = upper ? hi : tlo;
;     unsigned char* pa = upper ? own - stride8 + hi_off : own;
;     unsigned char* pb = upper ? own + hi_off : own + stride8;
;     *(u32x4*)pa = A; *(u32x4*)pb = B;
; }
;     __device__ __forceinline__ void operator()(const f32x4 (&acc)[2][2][4][2], const Unit& u, int wr, int wc, int fr, int fq) const {
;         const int row0 = u.pm * 256 + wr * 64 + fr, col0 = u.pn * 256 + wc * 64 + 8 * fq;
;         bf16_t* base = u.part == 0 ? Z + (size_t)row0 * D + col0 : P + ((size_t)(u.part - 1) * MS + (row0 - MP)) * D + col0;
; #pragma unroll
;         for (int ai = 0; ai < 2; ++ai)
; #pragma unroll
;             for (int m = 0; m < 4; ++m) { u32x4 w[2];
; #pragma unroll
;                 for (int bj = 0; bj < 2; ++bj) { const f32x4 v0 = acc[ai][bj][m][0], v1 = acc[ai][bj][m][1]; w[bj].x = pk2(v0[0], v0[1]); w[bj].y = pk2(v0[2], v0[3]); w[bj].z = pk2(v1[0], v1[1]); w[bj].w = pk2(v1[2], v1[3]); }
;                 store_pair((unsigned char*)(base + (size_t)(ai * 128 + m * 16) * D), (size_t)8 * D * 2, 64, w[0], w[1], fr >= 8); }
	s_add_u32 s52, s52, 0x10000
	s_addc_u32 s53, s53, 0
	s_add_u32 s26, s26, 0x100
	s_addc_u32 s27, s27, 0
	s_cmp_ge_u32 s57, s47
	s_cbranch_scc0 .LBB0_1716
	v_lshl_add_u32 v147, s48, 8, v1
	v_add_u32_e32 v148, 0xffffe000, v147
	v_sub_co_u32_e64 v146, vcc, s46, 1
	v_mov_b32_e32 v149, s91
	s_nop 0
	v_cndmask_b32_e32 v148, v148, v147, vcc
	v_ashrrev_i32_e32 v147, 31, v146
	v_lshlrev_b64 v[146:147], 23, v[146:147]
	v_lshl_add_u64 v[146:147], s[12:13], 0, v[146:147]
	v_cndmask_b32_e32 v147, v147, v149, vcc
	v_mov_b32_e32 v149, s90
	v_cndmask_b32_e32 v146, v146, v149, vcc
	v_ashrrev_i32_e32 v149, 31, v148
	v_lshl_or_b32 v156, s78, 8, v151
	v_lshlrev_b64 v[148:149], 12, v[148:149]
	v_lshl_add_u64 v[146:147], v[146:147], 0, v[148:149]
	v_ashrrev_i32_e32 v157, 31, v156
	v_cvt_pk_bf16_f32 v126, v126, v127
	v_cvt_pk_bf16_f32 v127, v128, v129
	v_cvt_pk_bf16_f32 v128, v122, v123
	v_cvt_pk_bf16_f32 v124, v124, v125
	v_cvt_pk_bf16_f32 v118, v118, v119
	v_cvt_pk_bf16_f32 v119, v120, v121
	v_cvt_pk_bf16_f32 v114, v114, v115
	v_cvt_pk_bf16_f32 v115, v116, v117
	v_lshl_add_u64 v[146:147], v[156:157], 1, v[146:147]
	v_mov_b32_dpp v120, v126 row_ror:8 row_mask:0xf bank_mask:0xf bound_ctrl:1
	v_mov_b32_dpp v121, v127 row_ror:8 row_mask:0xf bank_mask:0xf bound_ctrl:1
	v_mov_b32_dpp v116, v128 row_ror:8 row_mask:0xf bank_mask:0xf bound_ctrl:1
	v_mov_b32_dpp v117, v124 row_ror:8 row_mask:0xf bank_mask:0xf bound_ctrl:1
	v_mov_b32_dpp v125, v118 row_ror:8 row_mask:0xf bank_mask:0xf bound_ctrl:1
	v_mov_b32_dpp v129, v119 row_ror:8 row_mask:0xf bank_mask:0xf bound_ctrl:1
	v_mov_b32_dpp v148, v114 row_ror:8 row_mask:0xf bank_mask:0xf bound_ctrl:1
	v_mov_b32_dpp v149, v115 row_ror:8 row_mask:0xf bank_mask:0xf bound_ctrl:1
	v_lshl_add_u64 v[122:123], v[146:147], 0, v[138:139]
	v_cndmask_b32_e64 v117, v117, v115, s[8:9]
	v_cndmask_b32_e64 v116, v116, v114, s[8:9]
	v_cndmask_b32_e64 v115, v121, v119, s[8:9]
	v_cndmask_b32_e64 v114, v120, v118, s[8:9]
	v_cndmask_b32_e64 v121, v124, v149, s[8:9]
	v_cndmask_b32_e64 v120, v128, v148, s[8:9]
	v_cndmask_b32_e64 v119, v127, v129, s[8:9]
	v_cndmask_b32_e64 v118, v126, v125, s[8:9]
	v_cvt_pk_bf16_f32 v110, v110, v111
	v_cvt_pk_bf16_f32 v111, v112, v113
	v_cvt_pk_bf16_f32 v112, v106, v107
	v_cvt_pk_bf16_f32 v113, v108, v109
	v_cvt_pk_bf16_f32 v102, v102, v103
	v_cvt_pk_bf16_f32 v103, v104, v105
	v_cvt_pk_bf16_f32 v98, v98, v99
	v_cvt_pk_bf16_f32 v99, v100, v101
	s_mov_b64 s[4:5], 0x10000
	v_lshl_add_u64 v[124:125], v[146:147], 0, v[140:141]
	s_and_b64 vcc, exec, s[6:7]
	s_cbranch_vccz .LBB0_1719
	s_barrier
.LBB0_1719:
	global_store_dwordx4 v[122:123], v[118:121], off
	global_store_dwordx4 v[124:125], v[114:117], off
	v_lshl_add_u64 v[106:107], v[146:147], 0, s[4:5]
	v_mov_b32_dpp v104, v110 row_ror:8 row_mask:0xf bank_mask:0xf bound_ctrl:1
	v_mov_b32_dpp v105, v111 row_ror:8 row_mask:0xf bank_mask:0xf bound_ctrl:1
	v_mov_b32_dpp v100, v112 row_ror:8 row_mask:0xf bank_mask:0xf bound_ctrl:1
	v_mov_b32_dpp v101, v113 row_ror:8 row_mask:0xf bank_mask:0xf bound_ctrl:1
	v_mov_b32_dpp v114, v102 row_ror:8 row_mask:0xf bank_mask:0xf bound_ctrl:1
	v_mov_b32_dpp v115, v103 row_ror:8 row_mask:0xf bank_mask:0xf bound_ctrl:1
	v_mov_b32_dpp v116, v98 row_ror:8 row_mask:0xf bank_mask:0xf bound_ctrl:1
	v_mov_b32_dpp v117, v99 row_ror:8 row_mask:0xf bank_mask:0xf bound_ctrl:1
	v_lshl_add_u64 v[108:109], v[106:107], 0, v[138:139]
	v_cndmask_b32_e64 v101, v101, v99, s[8:9]
	v_cndmask_b32_e64 v100, v100, v98, s[8:9]
	v_cndmask_b32_e64 v99, v105, v103, s[8:9]
	v_cndmask_b32_e64 v98, v104, v102, s[8:9]
	v_cndmask_b32_e64 v105, v113, v117, s[8:9]
	v_cndmask_b32_e64 v104, v112, v116, s[8:9]
	v_cndmask_b32_e64 v103, v111, v115, s[8:9]
	v_cndmask_b32_e64 v102, v110, v114, s[8:9]
	v_cvt_pk_bf16_f32 v94, v94, v95
	v_cvt_pk_bf16_f32 v95, v96, v97
	v_cvt_pk_bf16_f32 v96, v90, v91
	v_cvt_pk_bf16_f32 v97, v92, v93
	v_cvt_pk_bf16_f32 v86, v86, v87
	v_cvt_pk_bf16_f32 v87, v88, v89
	v_cvt_pk_bf16_f32 v82, v82, v83
	v_cvt_pk_bf16_f32 v83, v84, v85
	s_mov_b64 s[4:5], 0x20000
	v_lshl_add_u64 v[106:107], v[106:107], 0, v[140:141]
	global_store_dwordx4 v[108:109], v[102:105], off
	global_store_dwordx4 v[106:107], v[98:101], off
	v_lshl_add_u64 v[90:91], v[146:147], 0, s[4:5]
	v_mov_b32_dpp v88, v94 row_ror:8 row_mask:0xf bank_mask:0xf bound_ctrl:1
	v_mov_b32_dpp v89, v95 row_ror:8 row_mask:0xf bank_mask:0xf bound_ctrl:1
	v_mov_b32_dpp v84, v96 row_ror:8 row_mask:0xf bank_mask:0xf bound_ctrl:1
	v_mov_b32_dpp v85, v97 row_ror:8 row_mask:0xf bank_mask:0xf bound_ctrl:1
	v_mov_b32_dpp v98, v86 row_ror:8 row_mask:0xf bank_mask:0xf bound_ctrl:1
	v_mov_b32_dpp v99, v87 row_ror:8 row_mask:0xf bank_mask:0xf bound_ctrl:1
	v_mov_b32_dpp v100, v82 row_ror:8 row_mask:0xf bank_mask:0xf bound_ctrl:1
	v_mov_b32_dpp v101, v83 row_ror:8 row_mask:0xf bank_mask:0xf bound_ctrl:1
	v_lshl_add_u64 v[92:93], v[90:91], 0, v[138:139]
	v_cndmask_b32_e64 v85, v85, v83, s[8:9]
	v_cndmask_b32_e64 v84, v84, v82, s[8:9]
	v_cndmask_b32_e64 v83, v89, v87, s[8:9]
	v_cndmask_b32_e64 v82, v88, v86, s[8:9]
	v_cndmask_b32_e64 v89, v97, v101, s[8:9]
	v_cndmask_b32_e64 v88, v96, v100, s[8:9]
	v_cndmask_b32_e64 v87, v95, v99, s[8:9]
	v_cndmask_b32_e64 v86, v94, v98, s[8:9]
	v_cvt_pk_bf16_f32 v78, v78, v79
	v_cvt_pk_bf16_f32 v79, v80, v81
	v_cvt_pk_bf16_f32 v80, v74, v75
	v_cvt_pk_bf16_f32 v81, v76, v77
	v_cvt_pk_bf16_f32 v70, v70, v71
	v_cvt_pk_bf16_f32 v71, v72, v73
	v_cvt_pk_bf16_f32 v66, v66, v67
	v_cvt_pk_bf16_f32 v67, v68, v69
	s_mov_b64 s[4:5], 0x30000
	v_lshl_add_u64 v[90:91], v[90:91], 0, v[140:141]
	global_store_dwordx4 v[92:93], v[86:89], off
	global_store_dwordx4 v[90:91], v[82:85], off
; __device__ __forceinline__ unsigned pk2(float lo, float hi) { const f32x2 v = {lo, hi}; return __builtin_bit_cast(unsigned, __builtin_convertvector(v, bf16x2_t)); }
; #define PG8_BAR __builtin_amdgcn_s_barrier()
; template <class Epi, class Sched, bool ABLK = false, bool ALIGN_EPI = true, bool SP2 = true, bool BBLK = true>
; __device__ __forceinline__ void gemm_phase(LAS unsigned char* lds, const Gemm g, const Sched& S, const Epi& E) {
;     ...
;         if (!has_next) break;
; #pragma unroll
;         for (int a = 0; a < 2; ++a)
; #pragma unroll
;             for (int b = 0; b < 2; ++b)
; #pragma unroll
;                 for (int m = 0; m < 4; ++m)
; #pragma unroll
;                     for (int n = 0; n < 2; ++n) acc[a][b][m][n] = (f32x4){0.f, 0.f, 0.f, 0.f};
;         cur = nxt; uA = nuA; tbA = ntbA; cB = nB; ++ui;
;         if constexpr (ALIGN_EPI) { if (wr == 1) PG8_BAR; }
;     __device__ __forceinline__ void operator()(const f32x4 (&acc)[2][2][4][2], const Unit& u, int wr, int wc, int fr, int fq) const {
;         const int row0 = u.pm * 256 + wr * 64 + fr, col0 = u.pn * 256 + wc * 64 + 8 * fq;
;         bf16_t* base = u.part == 0 ? Z + (size_t)row0 * D + col0 : P + ((size_t)(u.part - 1) * MS + (row0 - MP)) * D + col0;
; #pragma unroll
;         for (int ai = 0; ai < 2; ++ai)
; #pragma unroll
;             for (int m = 0; m < 4; ++m) { u32x4 w[2];
; #pragma unroll
;                 for (int bj = 0; bj < 2; ++bj) { const f32x4 v0 = acc[ai][bj][m][0], v1 = acc[ai][bj][m][1]; w[bj].x = pk2(v0[0], v0[1]); w[bj].y = pk2(v0[2], v0[3]); w[bj].z = pk2(v1[0], v1[1]); w[bj].w = pk2(v1[2], v1[3]); }
;                 store_pair((unsigned char*)(base + (size_t)(ai * 128 + m * 16) * D), (size_t)8 * D * 2, 64, w[0], w[1], fr >= 8); }
	v_lshl_add_u64 v[74:75], v[146:147], 0, s[4:5]
	v_mov_b32_dpp v72, v78 row_ror:8 row_mask:0xf bank_mask:0xf bound_ctrl:1
	v_mov_b32_dpp v73, v79 row_ror:8 row_mask:0xf bank_mask:0xf bound_ctrl:1
	v_mov_b32_dpp v68, v80 row_ror:8 row_mask:0xf bank_mask:0xf bound_ctrl:1
	v_mov_b32_dpp v69, v81 row_ror:8 row_mask:0xf bank_mask:0xf bound_ctrl:1
	v_mov_b32_dpp v82, v70 row_ror:8 row_mask:0xf bank_mask:0xf bound_ctrl:1
	v_mov_b32_dpp v83, v71 row_ror:8 row_mask:0xf bank_mask:0xf bound_ctrl:1
	v_mov_b32_dpp v84, v66 row_ror:8 row_mask:0xf bank_mask:0xf bound_ctrl:1
	v_mov_b32_dpp v85, v67 row_ror:8 row_mask:0xf bank_mask:0xf bound_ctrl:1
	v_lshl_add_u64 v[76:77], v[74:75], 0, v[138:139]
	v_cndmask_b32_e64 v69, v69, v67, s[8:9]
	v_cndmask_b32_e64 v68, v68, v66, s[8:9]
	v_cndmask_b32_e64 v67, v73, v71, s[8:9]
	v_cndmask_b32_e64 v66, v72, v70, s[8:9]
	v_cndmask_b32_e64 v73, v81, v85, s[8:9]
	v_cndmask_b32_e64 v72, v80, v84, s[8:9]
	v_cndmask_b32_e64 v71, v79, v83, s[8:9]
	v_cndmask_b32_e64 v70, v78, v82, s[8:9]
	v_cvt_pk_bf16_f32 v62, v62, v63
	v_cvt_pk_bf16_f32 v63, v64, v65
	v_cvt_pk_bf16_f32 v64, v58, v59
	v_cvt_pk_bf16_f32 v65, v60, v61
	v_cvt_pk_bf16_f32 v54, v54, v55
	v_cvt_pk_bf16_f32 v55, v56, v57
	v_cvt_pk_bf16_f32 v50, v50, v51
	v_cvt_pk_bf16_f32 v51, v52, v53
	s_mov_b64 s[4:5], 0x80000
	v_lshl_add_u64 v[74:75], v[74:75], 0, v[140:141]
	global_store_dwordx4 v[76:77], v[70:73], off
	global_store_dwordx4 v[74:75], v[66:69], off
	v_lshl_add_u64 v[58:59], v[146:147], 0, s[4:5]
	v_mov_b32_dpp v56, v62 row_ror:8 row_mask:0xf bank_mask:0xf bound_ctrl:1
	v_mov_b32_dpp v57, v63 row_ror:8 row_mask:0xf bank_mask:0xf bound_ctrl:1
	v_mov_b32_dpp v52, v64 row_ror:8 row_mask:0xf bank_mask:0xf bound_ctrl:1
	v_mov_b32_dpp v53, v65 row_ror:8 row_mask:0xf bank_mask:0xf bound_ctrl:1
	v_mov_b32_dpp v66, v54 row_ror:8 row_mask:0xf bank_mask:0xf bound_ctrl:1
	v_mov_b32_dpp v67, v55 row_ror:8 row_mask:0xf bank_mask:0xf bound_ctrl:1
	v_mov_b32_dpp v68, v50 row_ror:8 row_mask:0xf bank_mask:0xf bound_ctrl:1
	v_mov_b32_dpp v69, v51 row_ror:8 row_mask:0xf bank_mask:0xf bound_ctrl:1
	v_lshl_add_u64 v[60:61], v[58:59], 0, v[138:139]
	v_cndmask_b32_e64 v53, v53, v51, s[8:9]
	v_cndmask_b32_e64 v52, v52, v50, s[8:9]
	v_cndmask_b32_e64 v51, v57, v55, s[8:9]
	v_cndmask_b32_e64 v50, v56, v54, s[8:9]
	v_cndmask_b32_e64 v57, v65, v69, s[8:9]
	v_cndmask_b32_e64 v56, v64, v68, s[8:9]
	v_cndmask_b32_e64 v55, v63, v67, s[8:9]
	v_cndmask_b32_e64 v54, v62, v66, s[8:9]
	v_cvt_pk_bf16_f32 v46, v46, v47
	v_cvt_pk_bf16_f32 v47, v48, v49
	v_cvt_pk_bf16_f32 v48, v42, v43
	v_cvt_pk_bf16_f32 v49, v44, v45
	v_cvt_pk_bf16_f32 v38, v38, v39
	v_cvt_pk_bf16_f32 v39, v40, v41
	v_cvt_pk_bf16_f32 v34, v34, v35
	v_cvt_pk_bf16_f32 v35, v36, v37
	v_lshl_add_u64 v[58:59], v[58:59], 0, v[140:141]
	global_store_dwordx4 v[60:61], v[54:57], off
	global_store_dwordx4 v[58:59], v[50:53], off
	v_lshl_add_u64 v[42:43], v[146:147], 0, s[14:15]
	v_mov_b32_dpp v40, v46 row_ror:8 row_mask:0xf bank_mask:0xf bound_ctrl:1
	v_mov_b32_dpp v41, v47 row_ror:8 row_mask:0xf bank_mask:0xf bound_ctrl:1
	v_mov_b32_dpp v36, v48 row_ror:8 row_mask:0xf bank_mask:0xf bound_ctrl:1
	v_mov_b32_dpp v37, v49 row_ror:8 row_mask:0xf bank_mask:0xf bound_ctrl:1
	v_mov_b32_dpp v50, v38 row_ror:8 row_mask:0xf bank_mask:0xf bound_ctrl:1
	v_mov_b32_dpp v51, v39 row_ror:8 row_mask:0xf bank_mask:0xf bound_ctrl:1
	v_mov_b32_dpp v52, v34 row_ror:8 row_mask:0xf bank_mask:0xf bound_ctrl:1
	v_mov_b32_dpp v53, v35 row_ror:8 row_mask:0xf bank_mask:0xf bound_ctrl:1
	v_lshl_add_u64 v[44:45], v[42:43], 0, v[138:139]
	v_cndmask_b32_e64 v37, v37, v35, s[8:9]
	v_cndmask_b32_e64 v36, v36, v34, s[8:9]
	v_cndmask_b32_e64 v35, v41, v39, s[8:9]
	v_cndmask_b32_e64 v34, v40, v38, s[8:9]
	v_cndmask_b32_e64 v41, v49, v53, s[8:9]
	v_cndmask_b32_e64 v40, v48, v52, s[8:9]
	v_cndmask_b32_e64 v39, v47, v51, s[8:9]
	v_cndmask_b32_e64 v38, v46, v50, s[8:9]
	v_cvt_pk_bf16_f32 v30, v30, v31
	v_cvt_pk_bf16_f32 v31, v32, v33
	v_cvt_pk_bf16_f32 v32, v26, v27
	v_cvt_pk_bf16_f32 v33, v28, v29
	v_cvt_pk_bf16_f32 v22, v22, v23
	v_cvt_pk_bf16_f32 v23, v24, v25
	v_cvt_pk_bf16_f32 v18, v18, v19
	v_cvt_pk_bf16_f32 v19, v20, v21
	v_lshl_add_u64 v[42:43], v[42:43], 0, v[140:141]
	global_store_dwordx4 v[44:45], v[38:41], off
	global_store_dwordx4 v[42:43], v[34:37], off
	v_lshl_add_u64 v[26:27], v[146:147], 0, s[16:17]
	v_mov_b32_dpp v24, v30 row_ror:8 row_mask:0xf bank_mask:0xf bound_ctrl:1
	v_mov_b32_dpp v25, v31 row_ror:8 row_mask:0xf bank_mask:0xf bound_ctrl:1
	v_mov_b32_dpp v20, v32 row_ror:8 row_mask:0xf bank_mask:0xf bound_ctrl:1
	v_mov_b32_dpp v21, v33 row_ror:8 row_mask:0xf bank_mask:0xf bound_ctrl:1
	v_mov_b32_dpp v34, v22 row_ror:8 row_mask:0xf bank_mask:0xf bound_ctrl:1
	v_mov_b32_dpp v35, v23 row_ror:8 row_mask:0xf bank_mask:0xf bound_ctrl:1
	v_mov_b32_dpp v36, v18 row_ror:8 row_mask:0xf bank_mask:0xf bound_ctrl:1
	v_mov_b32_dpp v37, v19 row_ror:8 row_mask:0xf bank_mask:0xf bound_ctrl:1
	v_lshl_add_u64 v[28:29], v[26:27], 0, v[138:139]
	v_cndmask_b32_e64 v21, v21, v19, s[8:9]
	v_cndmask_b32_e64 v20, v20, v18, s[8:9]
	v_cndmask_b32_e64 v19, v25, v23, s[8:9]
	v_cndmask_b32_e64 v18, v24, v22, s[8:9]
	v_cndmask_b32_e64 v25, v33, v37, s[8:9]
	v_cndmask_b32_e64 v24, v32, v36, s[8:9]
	v_cndmask_b32_e64 v23, v31, v35, s[8:9]
	v_cndmask_b32_e64 v22, v30, v34, s[8:9]
	v_cvt_pk_bf16_f32 v14, v14, v15
	v_cvt_pk_bf16_f32 v15, v16, v17
	v_cvt_pk_bf16_f32 v16, v10, v11
	v_cvt_pk_bf16_f32 v17, v12, v13
	v_cvt_pk_bf16_f32 v6, v6, v7
	v_cvt_pk_bf16_f32 v7, v8, v9
	v_cvt_pk_bf16_f32 v2, v2, v3
	v_cvt_pk_bf16_f32 v3, v4, v5
	v_lshl_add_u64 v[26:27], v[26:27], 0, v[140:141]
	global_store_dwordx4 v[28:29], v[22:25], off
	global_store_dwordx4 v[26:27], v[18:21], off
	v_lshl_add_u64 v[10:11], v[146:147], 0, s[18:19]
	v_mov_b32_dpp v8, v14 row_ror:8 row_mask:0xf bank_mask:0xf bound_ctrl:1
	v_mov_b32_dpp v9, v15 row_ror:8 row_mask:0xf bank_mask:0xf bound_ctrl:1
	v_mov_b32_dpp v4, v16 row_ror:8 row_mask:0xf bank_mask:0xf bound_ctrl:1
	v_mov_b32_dpp v5, v17 row_ror:8 row_mask:0xf bank_mask:0xf bound_ctrl:1
	v_mov_b32_dpp v18, v6 row_ror:8 row_mask:0xf bank_mask:0xf bound_ctrl:1
	v_mov_b32_dpp v19, v7 row_ror:8 row_mask:0xf bank_mask:0xf bound_ctrl:1
	v_mov_b32_dpp v20, v2 row_ror:8 row_mask:0xf bank_mask:0xf bound_ctrl:1
	v_mov_b32_dpp v21, v3 row_ror:8 row_mask:0xf bank_mask:0xf bound_ctrl:1
	v_lshl_add_u64 v[12:13], v[10:11], 0, v[138:139]
	v_cndmask_b32_e64 v5, v5, v3, s[8:9]
	v_cndmask_b32_e64 v4, v4, v2, s[8:9]
	v_cndmask_b32_e64 v3, v9, v7, s[8:9]
	v_cndmask_b32_e64 v2, v8, v6, s[8:9]
	v_cndmask_b32_e64 v9, v17, v21, s[8:9]
	v_cndmask_b32_e64 v8, v16, v20, s[8:9]
	v_cndmask_b32_e64 v7, v15, v19, s[8:9]
	v_cndmask_b32_e64 v6, v14, v18, s[8:9]
	s_and_b64 vcc, exec, s[10:11]
	s_mov_b64 s[10:11], -1
	v_lshl_add_u64 v[10:11], v[10:11], 0, v[140:141]
	global_store_dwordx4 v[12:13], v[6:9], off
	global_store_dwordx4 v[10:11], v[2:5], off
	s_cbranch_vccnz .LBB0_1714
	s_andn2_b64 vcc, exec, s[2:3]
	s_cbranch_vccnz .LBB0_1713
	s_barrier
	s_branch .LBB0_1713

; #define PG8_STAGE(bufoff, gbase, voff) do { _Pragma("unroll") for (int _i = 0; _i < 2; ++_i) \
;         __builtin_amdgcn_global_load_lds((const unsigned*)((const char*)(gbase) + (voff)[_i]), (LAS unsigned*)(lds + (bufoff) + ldsw + _i * 8192), 16, 0, 0); } while (0)
; #define PG8_LDA(dst, b, h) do { _Pragma("unroll") for (int m = 0; m < 4; ++m) _Pragma("unroll") for (int k = 0; k < 2; ++k) dst[m][k] = *(const LAS bf16x8*)(lds + PG8_SA(b, h) + aoff + m * 2048 + k * 1024); } while (0)
; #define PG8_LDB(dst, b, h) do { _Pragma("unroll") for (int n = 0; n < 2; ++n) _Pragma("unroll") for (int k = 0; k < 2; ++k) dst[n][k] = *(const LAS bf16x8*)(lds + PG8_SB(b, h) + boff + n * 2048 + k * 1024); } while (0)
; #define PG8_MMA(ai, bj, At, Bt) do { __builtin_amdgcn_s_setprio(1); _Pragma("unroll") for (int m = 0; m < 4; ++m) _Pragma("unroll") for (int n = 0; n < 2; ++n) _Pragma("unroll") for (int k = 0; k < 2; ++k) \
;         acc[ai][bj][m][n] = __builtin_amdgcn_mfma_f32_16x16x32_bf16(Bt[n][k], At[m][k], acc[ai][bj][m][n], 0, 0, 0); __builtin_amdgcn_s_setprio(0); } while (0)
; #define PG8_WAIT_V(n) asm volatile("s_waitcnt vmcnt(" #n ")" ::: "memory")
; template <class Epi, class Sched, bool ABLK = false, bool ALIGN_EPI = true, bool SP2 = true, bool BBLK = true>
; __device__ __forceinline__ void gemm_phase(LAS unsigned char* lds, const Gemm g, const Sched& S, const Epi& E) {
;     ...
;         for (int t = 0; t < nt; t += 2) {
;             const bool last = (t == nt - 2);
;             const char* a1 = a_tile(uA, tbA + t + 1);
;             const char* a2 = last ? a_tile(nuA, ntbA) : a_tile(uA, tbA + t + 2); const char* b2 = last ? nB : cB + (size_t)(t + 2) * kstepB;
;             const char* a3 = last ? a_tile(nuA, ntbA + 1) : a_tile(uA, tbA + t + 3); const char* b3 = b2 + kstepB;
;             if (last && has_next) S.a_ready(nxt);
;             if constexpr (SP2) {
;             PG8_LDB(B0, 0, 0); PG8_LDB(B1, 0, 1); PG8_SCHED; PG8_LDA(At, 0, 0); PG8_STAGE(PG8_SA(1, 1), a1 + hstepA, voffA);
;             PG8_WAIT_V(8); PG8_WAIT_L(0); PG8_BAR; PG8_MMA(0, 0, At, B0); PG8_MMA(0, 1, At, B1); PG8_BAR; PG8_SCHED;
;             PG8_LDA(At, 0, 1); PG8_STAGE(PG8_SB(0, 0), b2, voffB); PG8_STAGE(PG8_SB(0, 1), b2 + hstepB, voffB); PG8_STAGE(PG8_SA(0, 0), a2, voffA);
;             PG8_WAIT_V(8); PG8_WAIT_L(0); PG8_BAR; PG8_MMA(1, 0, At, B0); PG8_MMA(1, 1, At, B1); PG8_BAR; PG8_SCHED;
.LBB0_1842:
	ds_read_b128 v[172:175], v168
	ds_read_b128 v[176:179], v168 offset:1024
	ds_read_b128 v[180:183], v168 offset:2048
	ds_read_b128 v[184:187], v168 offset:3072
	ds_read_b128 v[188:191], v169
	ds_read_b128 v[192:195], v169 offset:1024
	ds_read_b128 v[196:199], v169 offset:2048
	ds_read_b128 v[200:203], v169 offset:3072
	s_add_u32 s30, s26, s28
	s_addc_u32 s31, s27, s29
	s_add_u32 s36, s30, 0x100
	s_addc_u32 s37, s31, 0
	s_add_u32 s30, s30, 0x180
	s_addc_u32 s31, s31, 0
	s_cmpk_eq_i32 s28, 0xf00
	s_cselect_b32 s31, s51, s31
	s_cselect_b32 s30, s23, s30
	s_cselect_b32 s35, s11, s53
	s_cselect_b32 s34, s15, s52
	s_cselect_b32 s37, s4, s37
	s_cselect_b32 s36, s5, s36
	s_mov_b32 m0, s47
	v_lshl_add_u64 v[236:237], v[164:165], 0, s[28:29]
	ds_read_b128 v[204:207], v170
	ds_read_b128 v[208:211], v170 offset:1024
	ds_read_b128 v[212:215], v170 offset:2048
	ds_read_b128 v[216:219], v170 offset:3072
	ds_read_b128 v[220:223], v170 offset:4096
	ds_read_b128 v[224:227], v170 offset:5120
	ds_read_b128 v[228:231], v170 offset:6144
	ds_read_b128 v[232:235], v170 offset:7168
	global_load_lds_dwordx4 v[236:237], off
	v_lshl_add_u64 v[236:237], v[166:167], 0, s[28:29]
	s_mov_b32 m0, s48
	s_nop 0
	global_load_lds_dwordx4 v[236:237], off
	s_waitcnt vmcnt(8) lgkmcnt(0)
	s_barrier
	v_mfma_f32_16x16x32_bf16 v[126:129], v[172:175], v[204:207], v[126:129]
	v_mfma_f32_16x16x32_bf16 v[122:125], v[180:183], v[204:207], v[122:125]
	v_mfma_f32_16x16x32_bf16 v[110:113], v[172:175], v[212:215], v[110:113]
	v_mfma_f32_16x16x32_bf16 v[106:109], v[180:183], v[212:215], v[106:109]
	v_mfma_f32_16x16x32_bf16 v[94:97], v[172:175], v[220:223], v[94:97]
	v_mfma_f32_16x16x32_bf16 v[90:93], v[180:183], v[220:223], v[90:93]
	v_mfma_f32_16x16x32_bf16 v[78:81], v[172:175], v[228:231], v[78:81]
	v_mfma_f32_16x16x32_bf16 v[74:77], v[180:183], v[228:231], v[74:77]
	v_mfma_f32_16x16x32_bf16 v[126:129], v[176:179], v[208:211], v[126:129]
	v_mfma_f32_16x16x32_bf16 v[122:125], v[184:187], v[208:211], v[122:125]
	v_mfma_f32_16x16x32_bf16 v[110:113], v[176:179], v[216:219], v[110:113]
	v_mfma_f32_16x16x32_bf16 v[106:109], v[184:187], v[216:219], v[106:109]
	v_mfma_f32_16x16x32_bf16 v[94:97], v[176:179], v[224:227], v[94:97]
	v_mfma_f32_16x16x32_bf16 v[90:93], v[184:187], v[224:227], v[90:93]
	v_mfma_f32_16x16x32_bf16 v[78:81], v[176:179], v[232:235], v[78:81]
	v_mfma_f32_16x16x32_bf16 v[74:77], v[184:187], v[232:235], v[74:77]
	v_mfma_f32_16x16x32_bf16 v[118:121], v[188:191], v[204:207], v[118:121]
	v_mfma_f32_16x16x32_bf16 v[114:117], v[196:199], v[204:207], v[114:117]
	v_mfma_f32_16x16x32_bf16 v[102:105], v[188:191], v[212:215], v[102:105]
	v_mfma_f32_16x16x32_bf16 v[98:101], v[196:199], v[212:215], v[98:101]
	v_mfma_f32_16x16x32_bf16 v[86:89], v[188:191], v[220:223], v[86:89]
	v_mfma_f32_16x16x32_bf16 v[82:85], v[196:199], v[220:223], v[82:85]
	v_mfma_f32_16x16x32_bf16 v[70:73], v[188:191], v[228:231], v[70:73]
	v_mfma_f32_16x16x32_bf16 v[66:69], v[196:199], v[228:231], v[66:69]
	v_mfma_f32_16x16x32_bf16 v[118:121], v[192:195], v[208:211], v[118:121]
	v_mfma_f32_16x16x32_bf16 v[114:117], v[200:203], v[208:211], v[114:117]
	v_mfma_f32_16x16x32_bf16 v[102:105], v[192:195], v[216:219], v[102:105]
	v_mfma_f32_16x16x32_bf16 v[98:101], v[200:203], v[216:219], v[98:101]
	v_mfma_f32_16x16x32_bf16 v[86:89], v[192:195], v[224:227], v[86:89]
	v_mfma_f32_16x16x32_bf16 v[82:85], v[200:203], v[224:227], v[82:85]
	v_mfma_f32_16x16x32_bf16 v[70:73], v[192:195], v[232:235], v[70:73]
	v_mfma_f32_16x16x32_bf16 v[66:69], v[200:203], v[232:235], v[66:69]
	s_barrier
	s_mov_b32 m0, s49
	s_add_u32 s56, s34, 0x4000
	ds_read_b128 v[204:207], v170 offset:16384
	ds_read_b128 v[208:211], v170 offset:17408
	ds_read_b128 v[212:215], v170 offset:18432
	ds_read_b128 v[216:219], v170 offset:19456
	ds_read_b128 v[220:223], v170 offset:20480
	ds_read_b128 v[224:227], v170 offset:21504
	ds_read_b128 v[228:231], v170 offset:22528
	ds_read_b128 v[232:235], v170 offset:23552
	global_load_lds_dwordx4 v134, s[34:35]
	s_mov_b32 m0, s50
	s_addc_u32 s57, s35, 0
	s_add_i32 s55, s73, s39
	global_load_lds_dwordx4 v130, s[34:35]
	s_mov_b32 m0, s55
	s_nop 0
	global_load_lds_dwordx4 v134, s[56:57]
	s_add_i32 m0, s55, 0x2000
	s_nop 0
	global_load_lds_dwordx4 v130, s[56:57]
	s_mov_b32 m0, s25
	s_nop 0
	global_load_lds_dwordx4 v136, s[36:37]
	s_mov_b32 m0, s40
	s_nop 0
	global_load_lds_dwordx4 v132, s[36:37]
	s_waitcnt vmcnt(8) lgkmcnt(0)
	s_barrier
	v_mfma_f32_16x16x32_bf16 v[62:65], v[172:175], v[204:207], v[62:65]
	v_mfma_f32_16x16x32_bf16 v[58:61], v[180:183], v[204:207], v[58:61]
	v_mfma_f32_16x16x32_bf16 v[46:49], v[172:175], v[212:215], v[46:49]
	v_mfma_f32_16x16x32_bf16 v[42:45], v[180:183], v[212:215], v[42:45]
	v_mfma_f32_16x16x32_bf16 v[30:33], v[172:175], v[220:223], v[30:33]
	v_mfma_f32_16x16x32_bf16 v[26:29], v[180:183], v[220:223], v[26:29]
	v_mfma_f32_16x16x32_bf16 v[14:17], v[172:175], v[228:231], v[14:17]
	v_mfma_f32_16x16x32_bf16 v[10:13], v[180:183], v[228:231], v[10:13]
	v_mfma_f32_16x16x32_bf16 v[62:65], v[176:179], v[208:211], v[62:65]
	v_mfma_f32_16x16x32_bf16 v[58:61], v[184:187], v[208:211], v[58:61]
	v_mfma_f32_16x16x32_bf16 v[46:49], v[176:179], v[216:219], v[46:49]
	v_mfma_f32_16x16x32_bf16 v[42:45], v[184:187], v[216:219], v[42:45]
	v_mfma_f32_16x16x32_bf16 v[30:33], v[176:179], v[224:227], v[30:33]
	v_mfma_f32_16x16x32_bf16 v[26:29], v[184:187], v[224:227], v[26:29]
	v_mfma_f32_16x16x32_bf16 v[14:17], v[176:179], v[232:235], v[14:17]
	v_mfma_f32_16x16x32_bf16 v[10:13], v[184:187], v[232:235], v[10:13]
	v_mfma_f32_16x16x32_bf16 v[54:57], v[188:191], v[204:207], v[54:57]
	v_mfma_f32_16x16x32_bf16 v[50:53], v[196:199], v[204:207], v[50:53]
	v_mfma_f32_16x16x32_bf16 v[38:41], v[188:191], v[212:215], v[38:41]
	v_mfma_f32_16x16x32_bf16 v[34:37], v[196:199], v[212:215], v[34:37]
	v_mfma_f32_16x16x32_bf16 v[22:25], v[188:191], v[220:223], v[22:25]
	v_mfma_f32_16x16x32_bf16 v[18:21], v[196:199], v[220:223], v[18:21]
	v_mfma_f32_16x16x32_bf16 v[6:9], v[188:191], v[228:231], v[6:9]
	v_mfma_f32_16x16x32_bf16 v[2:5], v[196:199], v[228:231], v[2:5]
	v_mfma_f32_16x16x32_bf16 v[54:57], v[192:195], v[208:211], v[54:57]
	v_mfma_f32_16x16x32_bf16 v[50:53], v[200:203], v[208:211], v[50:53]
	v_mfma_f32_16x16x32_bf16 v[38:41], v[192:195], v[216:219], v[38:41]
	v_mfma_f32_16x16x32_bf16 v[34:37], v[200:203], v[216:219], v[34:37]
	v_mfma_f32_16x16x32_bf16 v[22:25], v[192:195], v[224:227], v[22:25]
	v_mfma_f32_16x16x32_bf16 v[18:21], v[200:203], v[224:227], v[18:21]
	v_mfma_f32_16x16x32_bf16 v[6:9], v[192:195], v[232:235], v[6:9]
	v_mfma_f32_16x16x32_bf16 v[2:5], v[200:203], v[232:235], v[2:5]
	s_barrier
; #define PG8_STAGE(bufoff, gbase, voff) do { _Pragma("unroll") for (int _i = 0; _i < 2; ++_i) \
;         __builtin_amdgcn_global_load_lds((const unsigned*)((const char*)(gbase) + (voff)[_i]), (LAS unsigned*)(lds + (bufoff) + ldsw + _i * 8192), 16, 0, 0); } while (0)
; #define PG8_LDA(dst, b, h) do { _Pragma("unroll") for (int m = 0; m < 4; ++m) _Pragma("unroll") for (int k = 0; k < 2; ++k) dst[m][k] = *(const LAS bf16x8*)(lds + PG8_SA(b, h) + aoff + m * 2048 + k * 1024); } while (0)
; #define PG8_LDB(dst, b, h) do { _Pragma("unroll") for (int n = 0; n < 2; ++n) _Pragma("unroll") for (int k = 0; k < 2; ++k) dst[n][k] = *(const LAS bf16x8*)(lds + PG8_SB(b, h) + boff + n * 2048 + k * 1024); } while (0)
; #define PG8_MMA(ai, bj, At, Bt) do { __builtin_amdgcn_s_setprio(1); _Pragma("unroll") for (int m = 0; m < 4; ++m) _Pragma("unroll") for (int n = 0; n < 2; ++n) _Pragma("unroll") for (int k = 0; k < 2; ++k) \
;         acc[ai][bj][m][n] = __builtin_amdgcn_mfma_f32_16x16x32_bf16(Bt[n][k], At[m][k], acc[ai][bj][m][n], 0, 0, 0); __builtin_amdgcn_s_setprio(0); } while (0)
; #define PG8_WAIT_V(n) asm volatile("s_waitcnt vmcnt(" #n ")" ::: "memory")
; #define PG8_WAIT_L(n) asm volatile("s_waitcnt lgkmcnt(" #n ")" ::: "memory")
; #define PG8_BAR __builtin_amdgcn_s_barrier()
; #define PG8_SCHED __builtin_amdgcn_sched_barrier(0)
; template <class Epi, class Sched, bool ABLK = false, bool ALIGN_EPI = true, bool SP2 = true, bool BBLK = true>
; __device__ __forceinline__ void gemm_phase(LAS unsigned char* lds, const Gemm g, const Sched& S, const Epi& E) {
;     ...
;             PG8_LDB(B0, 1, 0); PG8_LDB(B1, 1, 1); PG8_SCHED; PG8_LDA(At, 1, 0); PG8_STAGE(PG8_SA(0, 1), a2 + hstepA, voffA);
;             PG8_WAIT_V(8); PG8_WAIT_L(0); PG8_BAR; PG8_MMA(0, 0, At, B0); PG8_MMA(0, 1, At, B1); PG8_BAR; PG8_SCHED;
;             PG8_LDA(At, 1, 1); PG8_STAGE(PG8_SB(1, 0), b3, voffB); PG8_STAGE(PG8_SB(1, 1), b3 + hstepB, voffB); PG8_STAGE(PG8_SA(1, 0), a3, voffA);
	v_add_u32_e32 v171, s60, v1
	ds_read_b128 v[172:175], v171
	ds_read_b128 v[176:179], v171 offset:1024
	ds_read_b128 v[180:183], v171 offset:2048
	ds_read_b128 v[184:187], v171 offset:3072
	v_add_u32_e32 v171, s61, v1
	ds_read_b128 v[188:191], v171
	ds_read_b128 v[192:195], v171 offset:1024
	ds_read_b128 v[196:199], v171 offset:2048
	ds_read_b128 v[200:203], v171 offset:3072
	s_add_u32 s36, s36, 0x80000
	s_addc_u32 s37, s37, 0
	s_mov_b32 m0, s41
	ds_read_b128 v[204:207], v170 offset:32768
	ds_read_b128 v[208:211], v170 offset:33792
	ds_read_b128 v[212:215], v170 offset:34816
	ds_read_b128 v[216:219], v170 offset:35840
	ds_read_b128 v[220:223], v170 offset:36864
	ds_read_b128 v[224:227], v170 offset:37888
	ds_read_b128 v[228:231], v170 offset:38912
	ds_read_b128 v[232:235], v170 offset:39936
	global_load_lds_dwordx4 v136, s[36:37]
	s_mov_b32 m0, s42
	s_nop 0
	global_load_lds_dwordx4 v132, s[36:37]
	s_waitcnt vmcnt(8) lgkmcnt(0)
	s_barrier
	v_mfma_f32_16x16x32_bf16 v[126:129], v[172:175], v[204:207], v[126:129]
	v_mfma_f32_16x16x32_bf16 v[122:125], v[180:183], v[204:207], v[122:125]
	v_mfma_f32_16x16x32_bf16 v[110:113], v[172:175], v[212:215], v[110:113]
	v_mfma_f32_16x16x32_bf16 v[106:109], v[180:183], v[212:215], v[106:109]
	v_mfma_f32_16x16x32_bf16 v[94:97], v[172:175], v[220:223], v[94:97]
	v_mfma_f32_16x16x32_bf16 v[90:93], v[180:183], v[220:223], v[90:93]
	v_mfma_f32_16x16x32_bf16 v[78:81], v[172:175], v[228:231], v[78:81]
	v_mfma_f32_16x16x32_bf16 v[74:77], v[180:183], v[228:231], v[74:77]
	v_mfma_f32_16x16x32_bf16 v[126:129], v[176:179], v[208:211], v[126:129]
	v_mfma_f32_16x16x32_bf16 v[122:125], v[184:187], v[208:211], v[122:125]
	v_mfma_f32_16x16x32_bf16 v[110:113], v[176:179], v[216:219], v[110:113]
	v_mfma_f32_16x16x32_bf16 v[106:109], v[184:187], v[216:219], v[106:109]
	v_mfma_f32_16x16x32_bf16 v[94:97], v[176:179], v[224:227], v[94:97]
	v_mfma_f32_16x16x32_bf16 v[90:93], v[184:187], v[224:227], v[90:93]
	v_mfma_f32_16x16x32_bf16 v[78:81], v[176:179], v[232:235], v[78:81]
	v_mfma_f32_16x16x32_bf16 v[74:77], v[184:187], v[232:235], v[74:77]
	v_mfma_f32_16x16x32_bf16 v[118:121], v[188:191], v[204:207], v[118:121]
	v_mfma_f32_16x16x32_bf16 v[114:117], v[196:199], v[204:207], v[114:117]
	v_mfma_f32_16x16x32_bf16 v[102:105], v[188:191], v[212:215], v[102:105]
	v_mfma_f32_16x16x32_bf16 v[98:101], v[196:199], v[212:215], v[98:101]
	v_mfma_f32_16x16x32_bf16 v[86:89], v[188:191], v[220:223], v[86:89]
	v_mfma_f32_16x16x32_bf16 v[82:85], v[196:199], v[220:223], v[82:85]
	v_mfma_f32_16x16x32_bf16 v[70:73], v[188:191], v[228:231], v[70:73]
	v_mfma_f32_16x16x32_bf16 v[66:69], v[196:199], v[228:231], v[66:69]
	v_mfma_f32_16x16x32_bf16 v[118:121], v[192:195], v[208:211], v[118:121]
	v_mfma_f32_16x16x32_bf16 v[114:117], v[200:203], v[208:211], v[114:117]
	v_mfma_f32_16x16x32_bf16 v[102:105], v[192:195], v[216:219], v[102:105]
	v_mfma_f32_16x16x32_bf16 v[98:101], v[200:203], v[216:219], v[98:101]
	v_mfma_f32_16x16x32_bf16 v[86:89], v[192:195], v[224:227], v[86:89]
	v_mfma_f32_16x16x32_bf16 v[82:85], v[200:203], v[224:227], v[82:85]
	v_mfma_f32_16x16x32_bf16 v[70:73], v[192:195], v[232:235], v[70:73]
	v_mfma_f32_16x16x32_bf16 v[66:69], v[200:203], v[232:235], v[66:69]
	s_barrier
	s_add_u32 s36, s34, 0x8000
	s_addc_u32 s37, s35, 0
	s_add_i32 s55, s60, s39
	s_mov_b32 m0, s55
	ds_read_b128 v[204:207], v170 offset:49152
	ds_read_b128 v[208:211], v170 offset:50176
	ds_read_b128 v[212:215], v170 offset:51200
	ds_read_b128 v[216:219], v170 offset:52224
	ds_read_b128 v[220:223], v170 offset:53248
	ds_read_b128 v[224:227], v170 offset:54272
	ds_read_b128 v[228:231], v170 offset:55296
	ds_read_b128 v[232:235], v170 offset:56320
	global_load_lds_dwordx4 v134, s[36:37]
	s_add_i32 m0, s55, 0x2000
	s_add_u32 s34, s34, 0xc000
	v_lshl_add_u64 v[236:237], s[36:37], 0, v[130:131]
	s_addc_u32 s35, s35, 0
	s_add_i32 s36, s61, s39
	global_load_lds_dwordx4 v[236:237], off
	s_mov_b32 m0, s36
	s_nop 0
	global_load_lds_dwordx4 v134, s[34:35]
	s_add_i32 m0, s36, 0x2000
	s_nop 0
	global_load_lds_dwordx4 v130, s[34:35]
	s_mov_b32 m0, s45
	s_nop 0
	global_load_lds_dwordx4 v136, s[30:31]
	s_mov_b32 m0, s46
	s_nop 0
	global_load_lds_dwordx4 v132, s[30:31]
	s_waitcnt vmcnt(8) lgkmcnt(0)
	s_barrier
; __device__ __forceinline__ unsigned pk2(float lo, float hi) { const f32x2 v = {lo, hi}; return __builtin_bit_cast(unsigned, __builtin_convertvector(v, bf16x2_t)); }
; __device__ __forceinline__ void store_pair(unsigned char* own, size_t stride8, int hi_off, u32x4 lo, u32x4 hi, bool upper) {
;     const u32x4 tlo = ror8(lo), thi = ror8(hi);
;     const u32x4 A = upper ? thi : lo, B = upper ? hi : tlo;
;     unsigned char* pa = upper ? own - stride8 + hi_off : own;
;     unsigned char* pb = upper ? own + hi_off : own + stride8;
;     *(u32x4*)pa = A; *(u32x4*)pb = B;
; }
;     __device__ __forceinline__ void operator()(const f32x4 (&acc)[2][2][4][2], const Unit& u, int wr, int wc, int fr, int fq) const {
; #pragma unroll
;         for (int ai = 0; ai < 2; ++ai)
; #pragma unroll
;             for (int m = 0; m < 4; ++m) { unsigned char* rowp = (unsigned char*)(H + ((size_t)(u.pm * (FF / 64) + u.pn * 4 + wc) * 256 + (wr * 64 + fr + ai * 128 + m * 16)) * 64 + 8 * fq); u32x4 w[2];
; #pragma unroll
;                 for (int bj = 0; bj < 2; ++bj) { f32x4 v0 = acc[ai][bj][m][0], v1 = acc[ai][bj][m][1];
; #pragma unroll
;                     for (int j = 0; j < 4; ++j) { const float a = fmaxf(v0[j], 0.f), b = fmaxf(v1[j], 0.f); v0[j] = a * a; v1[j] = b * b; }
;                     w[bj].x = pk2(v0[0], v0[1]); w[bj].y = pk2(v0[2], v0[3]); w[bj].z = pk2(v1[0], v1[1]); w[bj].w = pk2(v1[2], v1[3]); }
;                 store_pair(rowp, (size_t)8 * 64 * 2, 64, w[0], w[1], fr >= 8); }
	v_mfma_f32_16x16x32_bf16 v[62:65], v[172:175], v[204:207], v[62:65]
	v_mfma_f32_16x16x32_bf16 v[58:61], v[180:183], v[204:207], v[58:61]
	v_mfma_f32_16x16x32_bf16 v[46:49], v[172:175], v[212:215], v[46:49]
	v_mfma_f32_16x16x32_bf16 v[42:45], v[180:183], v[212:215], v[42:45]
	v_mfma_f32_16x16x32_bf16 v[30:33], v[172:175], v[220:223], v[30:33]
	v_mfma_f32_16x16x32_bf16 v[26:29], v[180:183], v[220:223], v[26:29]
	v_mfma_f32_16x16x32_bf16 v[14:17], v[172:175], v[228:231], v[14:17]
	v_mfma_f32_16x16x32_bf16 v[10:13], v[180:183], v[228:231], v[10:13]
	v_mfma_f32_16x16x32_bf16 v[62:65], v[176:179], v[208:211], v[62:65]
	v_mfma_f32_16x16x32_bf16 v[58:61], v[184:187], v[208:211], v[58:61]
	v_mfma_f32_16x16x32_bf16 v[46:49], v[176:179], v[216:219], v[46:49]
	v_mfma_f32_16x16x32_bf16 v[42:45], v[184:187], v[216:219], v[42:45]
	v_mfma_f32_16x16x32_bf16 v[30:33], v[176:179], v[224:227], v[30:33]
	v_mfma_f32_16x16x32_bf16 v[26:29], v[184:187], v[224:227], v[26:29]
	v_mfma_f32_16x16x32_bf16 v[14:17], v[176:179], v[232:235], v[14:17]
	v_mfma_f32_16x16x32_bf16 v[10:13], v[184:187], v[232:235], v[10:13]
	v_mfma_f32_16x16x32_bf16 v[54:57], v[188:191], v[204:207], v[54:57]
	v_mfma_f32_16x16x32_bf16 v[50:53], v[196:199], v[204:207], v[50:53]
	v_mfma_f32_16x16x32_bf16 v[38:41], v[188:191], v[212:215], v[38:41]
	v_mfma_f32_16x16x32_bf16 v[34:37], v[196:199], v[212:215], v[34:37]
	v_mfma_f32_16x16x32_bf16 v[22:25], v[188:191], v[220:223], v[22:25]
	v_mfma_f32_16x16x32_bf16 v[18:21], v[196:199], v[220:223], v[18:21]
	v_mfma_f32_16x16x32_bf16 v[6:9], v[188:191], v[228:231], v[6:9]
	v_mfma_f32_16x16x32_bf16 v[2:5], v[196:199], v[228:231], v[2:5]
	v_mfma_f32_16x16x32_bf16 v[54:57], v[192:195], v[208:211], v[54:57]
	v_mfma_f32_16x16x32_bf16 v[50:53], v[200:203], v[208:211], v[50:53]
	v_mfma_f32_16x16x32_bf16 v[38:41], v[192:195], v[216:219], v[38:41]
	v_mfma_f32_16x16x32_bf16 v[34:37], v[200:203], v[216:219], v[34:37]
	v_mfma_f32_16x16x32_bf16 v[22:25], v[192:195], v[224:227], v[22:25]
	v_mfma_f32_16x16x32_bf16 v[18:21], v[200:203], v[224:227], v[18:21]
	v_mfma_f32_16x16x32_bf16 v[6:9], v[192:195], v[232:235], v[6:9]
	v_mfma_f32_16x16x32_bf16 v[2:5], v[200:203], v[232:235], v[2:5]
	s_barrier
	s_add_i32 s54, s54, 2
	s_add_u32 s28, s28, 0x100
	s_addc_u32 s29, s29, 0
	s_add_u32 s52, s52, 0x10000
	s_addc_u32 s53, s53, 0
	s_cmp_gt_u32 s54, 29
	s_cbranch_scc0 .LBB0_1842
	s_lshl_b32 s4, s22, 7
	s_lshl_b32 s5, s24, 2
	s_add_i32 s5, s5, s4
	s_or_b32 s4, s5, s44
	s_ashr_i32 s5, s4, 31
	s_lshl_b64 s[4:5], s[4:5], 15
	s_add_u32 s22, s62, s4
	v_max_f32_e32 v126, 0, v126
	v_max_f32_e32 v122, 0, v122
	v_max_f32_e32 v127, 0, v127
	v_max_f32_e32 v123, 0, v123
	v_max_f32_e32 v128, 0, v128
	v_max_f32_e32 v124, 0, v124
	v_max_f32_e32 v129, 0, v129
	v_max_f32_e32 v125, 0, v125
	v_max_f32_e32 v118, 0, v118
	v_max_f32_e32 v114, 0, v114
	v_max_f32_e32 v119, 0, v119
	v_max_f32_e32 v115, 0, v115
	v_max_f32_e32 v120, 0, v120
	v_max_f32_e32 v116, 0, v116
	v_max_f32_e32 v121, 0, v121
	v_max_f32_e32 v117, 0, v117
	s_addc_u32 s23, s83, s5
	v_pk_mul_f32 v[126:127], v[126:127], v[126:127]
	v_pk_mul_f32 v[122:123], v[122:123], v[122:123]
	v_pk_mul_f32 v[128:129], v[128:129], v[128:129]
	v_pk_mul_f32 v[124:125], v[124:125], v[124:125]
	v_pk_mul_f32 v[118:119], v[118:119], v[118:119]
	v_pk_mul_f32 v[114:115], v[114:115], v[114:115]
	v_pk_mul_f32 v[120:121], v[120:121], v[120:121]
	v_pk_mul_f32 v[116:117], v[116:117], v[116:117]
	v_lshl_add_u64 v[164:165], s[22:23], 0, v[144:145]
	v_cvt_pk_bf16_f32 v126, v126, v127
	v_cvt_pk_bf16_f32 v127, v128, v129
	v_cvt_pk_bf16_f32 v128, v122, v123
	v_cvt_pk_bf16_f32 v129, v124, v125
	v_cvt_pk_bf16_f32 v118, v118, v119
	v_cvt_pk_bf16_f32 v119, v120, v121
	v_cvt_pk_bf16_f32 v114, v114, v115
	v_cvt_pk_bf16_f32 v115, v116, v117
	v_lshl_add_u64 v[122:123], v[164:165], 0, v[138:139]
	v_mov_b32_dpp v120, v126 row_ror:8 row_mask:0xf bank_mask:0xf bound_ctrl:1
	v_mov_b32_dpp v121, v127 row_ror:8 row_mask:0xf bank_mask:0xf bound_ctrl:1
	v_mov_b32_dpp v116, v128 row_ror:8 row_mask:0xf bank_mask:0xf bound_ctrl:1
	v_mov_b32_dpp v117, v129 row_ror:8 row_mask:0xf bank_mask:0xf bound_ctrl:1
	v_mov_b32_dpp v164, v118 row_ror:8 row_mask:0xf bank_mask:0xf bound_ctrl:1
	v_mov_b32_dpp v165, v119 row_ror:8 row_mask:0xf bank_mask:0xf bound_ctrl:1
	v_mov_b32_dpp v166, v114 row_ror:8 row_mask:0xf bank_mask:0xf bound_ctrl:1
	v_mov_b32_dpp v167, v115 row_ror:8 row_mask:0xf bank_mask:0xf bound_ctrl:1
	v_max_f32_e32 v110, 0, v110
	v_max_f32_e32 v106, 0, v106
	v_max_f32_e32 v111, 0, v111
	v_max_f32_e32 v107, 0, v107
	v_max_f32_e32 v112, 0, v112
	v_max_f32_e32 v108, 0, v108
	v_max_f32_e32 v113, 0, v113
	v_max_f32_e32 v109, 0, v109
	v_max_f32_e32 v102, 0, v102
	v_max_f32_e32 v98, 0, v98
	v_max_f32_e32 v103, 0, v103
	v_max_f32_e32 v99, 0, v99
	v_max_f32_e32 v104, 0, v104
	v_max_f32_e32 v100, 0, v100
	v_max_f32_e32 v105, 0, v105
	v_max_f32_e32 v101, 0, v101
	v_lshl_add_u64 v[124:125], v[122:123], 0, v[140:141]
	v_cndmask_b32_e64 v117, v117, v115, s[8:9]
	v_cndmask_b32_e64 v116, v116, v114, s[8:9]
	v_cndmask_b32_e64 v115, v121, v119, s[8:9]
	v_cndmask_b32_e64 v114, v120, v118, s[8:9]
	v_cndmask_b32_e64 v121, v129, v167, s[8:9]
	v_cndmask_b32_e64 v120, v128, v166, s[8:9]
	v_cndmask_b32_e64 v119, v127, v165, s[8:9]
	v_cndmask_b32_e64 v118, v126, v164, s[8:9]
	v_pk_mul_f32 v[110:111], v[110:111], v[110:111]
	v_pk_mul_f32 v[106:107], v[106:107], v[106:107]
	v_pk_mul_f32 v[112:113], v[112:113], v[112:113]
	v_pk_mul_f32 v[108:109], v[108:109], v[108:109]
	v_pk_mul_f32 v[102:103], v[102:103], v[102:103]
	v_pk_mul_f32 v[98:99], v[98:99], v[98:99]
	v_pk_mul_f32 v[104:105], v[104:105], v[104:105]
	v_pk_mul_f32 v[100:101], v[100:101], v[100:101]
	v_lshl_add_u64 v[122:123], v[122:123], 0, v[142:143]
	s_and_b64 vcc, exec, s[6:7]
	s_cbranch_vccz .LBB0_1845
	s_barrier

; #define PG8_STAGE(bufoff, gbase, voff) do { _Pragma("unroll") for (int _i = 0; _i < 2; ++_i) \
;         __builtin_amdgcn_global_load_lds((const unsigned*)((const char*)(gbase) + (voff)[_i]), (LAS unsigned*)(lds + (bufoff) + ldsw + _i * 8192), 16, 0, 0); } while (0)
; #define PG8_LDA(dst, b, h) do { _Pragma("unroll") for (int m = 0; m < 4; ++m) _Pragma("unroll") for (int k = 0; k < 2; ++k) dst[m][k] = *(const LAS bf16x8*)(lds + PG8_SA(b, h) + aoff + m * 2048 + k * 1024); } while (0)
; #define PG8_LDB(dst, b, h) do { _Pragma("unroll") for (int n = 0; n < 2; ++n) _Pragma("unroll") for (int k = 0; k < 2; ++k) dst[n][k] = *(const LAS bf16x8*)(lds + PG8_SB(b, h) + boff + n * 2048 + k * 1024); } while (0)
; #define PG8_MMA(ai, bj, At, Bt) do { __builtin_amdgcn_s_setprio(1); _Pragma("unroll") for (int m = 0; m < 4; ++m) _Pragma("unroll") for (int n = 0; n < 2; ++n) _Pragma("unroll") for (int k = 0; k < 2; ++k) \
;         acc[ai][bj][m][n] = __builtin_amdgcn_mfma_f32_16x16x32_bf16(Bt[n][k], At[m][k], acc[ai][bj][m][n], 0, 0, 0); __builtin_amdgcn_s_setprio(0); } while (0)
; #define PG8_WAIT_V(n) asm volatile("s_waitcnt vmcnt(" #n ")" ::: "memory")
; #define PG8_WAIT_L(n) asm volatile("s_waitcnt lgkmcnt(" #n ")" ::: "memory")
; template <class Epi, class Sched, bool ABLK = false, bool ALIGN_EPI = true, bool SP2 = true, bool BBLK = true>
; __device__ __forceinline__ void gemm_phase(LAS unsigned char* lds, const Gemm g, const Sched& S, const Epi& E) {
;     ...
;         for (int t = 0; t < nt; t += 2) {
;             const bool last = (t == nt - 2);
;             const char* a1 = a_tile(uA, tbA + t + 1);
;             const char* a2 = last ? a_tile(nuA, ntbA) : a_tile(uA, tbA + t + 2); const char* b2 = last ? nB : cB + (size_t)(t + 2) * kstepB;
;             const char* a3 = last ? a_tile(nuA, ntbA + 1) : a_tile(uA, tbA + t + 3); const char* b3 = b2 + kstepB;
;             if (last && has_next) S.a_ready(nxt);
;             if constexpr (SP2) {
;             PG8_LDB(B0, 0, 0); PG8_LDB(B1, 0, 1); PG8_SCHED; PG8_LDA(At, 0, 0); PG8_STAGE(PG8_SA(1, 1), a1 + hstepA, voffA);
;             PG8_WAIT_V(8); PG8_WAIT_L(0); PG8_BAR; PG8_MMA(0, 0, At, B0); PG8_MMA(0, 1, At, B1); PG8_BAR; PG8_SCHED;
;             PG8_LDA(At, 0, 1); PG8_STAGE(PG8_SB(0, 0), b2, voffB); PG8_STAGE(PG8_SB(0, 1), b2 + hstepB, voffB); PG8_STAGE(PG8_SA(0, 0), a2, voffA);
.LBB0_1907:
	ds_read_b128 v[152:155], v148
	ds_read_b128 v[156:159], v148 offset:1024
	ds_read_b128 v[160:163], v148 offset:2048
	ds_read_b128 v[164:167], v148 offset:3072
	ds_read_b128 v[168:171], v149
	ds_read_b128 v[172:175], v149 offset:1024
	ds_read_b128 v[176:179], v149 offset:2048
	ds_read_b128 v[180:183], v149 offset:3072
	s_add_u32 s34, s55, s30
	s_addc_u32 s35, s56, s31
	s_add_u32 s38, s34, 0x10000
	s_addc_u32 s39, s35, 0
	s_add_i32 s58, s58, 2
	s_add_u32 s36, s53, s30
	s_addc_u32 s37, s54, s31
	s_add_u32 s34, s34, 0x18000
	s_addc_u32 s35, s35, 0
	s_cmp_eq_u32 s57, s30
	s_cselect_b32 s35, s52, s35
	s_cselect_b32 s34, s51, s34
	s_cselect_b32 s37, s4, s37
	s_cselect_b32 s36, s5, s36
	s_cselect_b32 s39, s50, s39
	s_cselect_b32 s38, s27, s38
	v_lshl_add_u64 v[216:217], v[142:143], 0, s[30:31]
	s_add_i32 m0, s41, 0xc000
	ds_read_b128 v[184:187], v150
	ds_read_b128 v[188:191], v150 offset:1024
	ds_read_b128 v[192:195], v150 offset:2048
	ds_read_b128 v[196:199], v150 offset:3072
	ds_read_b128 v[200:203], v150 offset:4096
	ds_read_b128 v[204:207], v150 offset:5120
	ds_read_b128 v[208:211], v150 offset:6144
	ds_read_b128 v[212:215], v150 offset:7168
	global_load_lds_dwordx4 v[216:217], off
	v_lshl_add_u64 v[216:217], v[144:145], 0, s[30:31]
	s_add_i32 m0, s41, 0xe000
	s_nop 0
	global_load_lds_dwordx4 v[216:217], off
	s_waitcnt vmcnt(8) lgkmcnt(0)
	s_barrier
	v_mfma_f32_16x16x32_bf16 v[126:129], v[152:155], v[184:187], v[126:129]
	v_mfma_f32_16x16x32_bf16 v[122:125], v[160:163], v[184:187], v[122:125]
	v_mfma_f32_16x16x32_bf16 v[110:113], v[152:155], v[192:195], v[110:113]
	v_mfma_f32_16x16x32_bf16 v[106:109], v[160:163], v[192:195], v[106:109]
	v_mfma_f32_16x16x32_bf16 v[94:97], v[152:155], v[200:203], v[94:97]
	v_mfma_f32_16x16x32_bf16 v[90:93], v[160:163], v[200:203], v[90:93]
	v_mfma_f32_16x16x32_bf16 v[78:81], v[152:155], v[208:211], v[78:81]
	v_mfma_f32_16x16x32_bf16 v[74:77], v[160:163], v[208:211], v[74:77]
	v_mfma_f32_16x16x32_bf16 v[126:129], v[156:159], v[188:191], v[126:129]
	v_mfma_f32_16x16x32_bf16 v[122:125], v[164:167], v[188:191], v[122:125]
	v_mfma_f32_16x16x32_bf16 v[110:113], v[156:159], v[196:199], v[110:113]
	v_mfma_f32_16x16x32_bf16 v[106:109], v[164:167], v[196:199], v[106:109]
	v_mfma_f32_16x16x32_bf16 v[94:97], v[156:159], v[204:207], v[94:97]
	v_mfma_f32_16x16x32_bf16 v[90:93], v[164:167], v[204:207], v[90:93]
	v_mfma_f32_16x16x32_bf16 v[78:81], v[156:159], v[212:215], v[78:81]
	v_mfma_f32_16x16x32_bf16 v[74:77], v[164:167], v[212:215], v[74:77]
	v_mfma_f32_16x16x32_bf16 v[118:121], v[168:171], v[184:187], v[118:121]
	v_mfma_f32_16x16x32_bf16 v[114:117], v[176:179], v[184:187], v[114:117]
	v_mfma_f32_16x16x32_bf16 v[102:105], v[168:171], v[192:195], v[102:105]
	v_mfma_f32_16x16x32_bf16 v[98:101], v[176:179], v[192:195], v[98:101]
	v_mfma_f32_16x16x32_bf16 v[86:89], v[168:171], v[200:203], v[86:89]
	v_mfma_f32_16x16x32_bf16 v[82:85], v[176:179], v[200:203], v[82:85]
	v_mfma_f32_16x16x32_bf16 v[70:73], v[168:171], v[208:211], v[70:73]
	v_mfma_f32_16x16x32_bf16 v[66:69], v[176:179], v[208:211], v[66:69]
	v_mfma_f32_16x16x32_bf16 v[118:121], v[172:175], v[188:191], v[118:121]
	v_mfma_f32_16x16x32_bf16 v[114:117], v[180:183], v[188:191], v[114:117]
	v_mfma_f32_16x16x32_bf16 v[102:105], v[172:175], v[196:199], v[102:105]
	v_mfma_f32_16x16x32_bf16 v[98:101], v[180:183], v[196:199], v[98:101]
	v_mfma_f32_16x16x32_bf16 v[86:89], v[172:175], v[204:207], v[86:89]
	v_mfma_f32_16x16x32_bf16 v[82:85], v[180:183], v[204:207], v[82:85]
	v_mfma_f32_16x16x32_bf16 v[70:73], v[172:175], v[212:215], v[70:73]
	v_mfma_f32_16x16x32_bf16 v[66:69], v[180:183], v[212:215], v[66:69]
	s_barrier
	s_add_i32 s59, s72, s40
	s_mov_b32 m0, s59
	ds_read_b128 v[184:187], v150 offset:16384
	ds_read_b128 v[188:191], v150 offset:17408
	ds_read_b128 v[192:195], v150 offset:18432
	ds_read_b128 v[196:199], v150 offset:19456
	ds_read_b128 v[200:203], v150 offset:20480
	ds_read_b128 v[204:207], v150 offset:21504
	ds_read_b128 v[208:211], v150 offset:22528
	ds_read_b128 v[212:215], v150 offset:23552
	global_load_lds_dwordx4 v130, s[36:37]
	s_add_i32 m0, s59, 0x2000
	s_add_u32 s64, s36, 0x4000
	s_addc_u32 s65, s37, 0
	s_add_i32 s59, s73, s40
	global_load_lds_dwordx4 v132, s[36:37]
	s_mov_b32 m0, s59
	s_nop 0
	global_load_lds_dwordx4 v130, s[64:65]
	s_add_i32 m0, s59, 0x2000
	s_nop 0
	global_load_lds_dwordx4 v132, s[64:65]
	s_mov_b32 m0, s41
	s_nop 0
	global_load_lds_dwordx4 v130, s[38:39]
	s_mov_b32 m0, s42
	s_nop 0
	global_load_lds_dwordx4 v132, s[38:39]
	s_waitcnt vmcnt(8) lgkmcnt(0)
	s_barrier
; #define PG8_STAGE(bufoff, gbase, voff) do { _Pragma("unroll") for (int _i = 0; _i < 2; ++_i) \
;         __builtin_amdgcn_global_load_lds((const unsigned*)((const char*)(gbase) + (voff)[_i]), (LAS unsigned*)(lds + (bufoff) + ldsw + _i * 8192), 16, 0, 0); } while (0)
; #define PG8_LDA(dst, b, h) do { _Pragma("unroll") for (int m = 0; m < 4; ++m) _Pragma("unroll") for (int k = 0; k < 2; ++k) dst[m][k] = *(const LAS bf16x8*)(lds + PG8_SA(b, h) + aoff + m * 2048 + k * 1024); } while (0)
; #define PG8_LDB(dst, b, h) do { _Pragma("unroll") for (int n = 0; n < 2; ++n) _Pragma("unroll") for (int k = 0; k < 2; ++k) dst[n][k] = *(const LAS bf16x8*)(lds + PG8_SB(b, h) + boff + n * 2048 + k * 1024); } while (0)
; #define PG8_MMA(ai, bj, At, Bt) do { __builtin_amdgcn_s_setprio(1); _Pragma("unroll") for (int m = 0; m < 4; ++m) _Pragma("unroll") for (int n = 0; n < 2; ++n) _Pragma("unroll") for (int k = 0; k < 2; ++k) \
;         acc[ai][bj][m][n] = __builtin_amdgcn_mfma_f32_16x16x32_bf16(Bt[n][k], At[m][k], acc[ai][bj][m][n], 0, 0, 0); __builtin_amdgcn_s_setprio(0); } while (0)
; #define PG8_WAIT_V(n) asm volatile("s_waitcnt vmcnt(" #n ")" ::: "memory")
; #define PG8_WAIT_L(n) asm volatile("s_waitcnt lgkmcnt(" #n ")" ::: "memory")
; #define PG8_BAR __builtin_amdgcn_s_barrier()
; #define PG8_SCHED __builtin_amdgcn_sched_barrier(0)
; template <class Epi, class Sched, bool ABLK = false, bool ALIGN_EPI = true, bool SP2 = true, bool BBLK = true>
; __device__ __forceinline__ void gemm_phase(LAS unsigned char* lds, const Gemm g, const Sched& S, const Epi& E) {
;     ...
;             PG8_WAIT_V(8); PG8_WAIT_L(0); PG8_BAR; PG8_MMA(1, 0, At, B0); PG8_MMA(1, 1, At, B1); PG8_BAR; PG8_SCHED;
;             PG8_LDB(B0, 1, 0); PG8_LDB(B1, 1, 1); PG8_SCHED; PG8_LDA(At, 1, 0); PG8_STAGE(PG8_SA(0, 1), a2 + hstepA, voffA);
;             PG8_WAIT_V(8); PG8_WAIT_L(0); PG8_BAR; PG8_MMA(0, 0, At, B0); PG8_MMA(0, 1, At, B1); PG8_BAR; PG8_SCHED;
	v_mfma_f32_16x16x32_bf16 v[62:65], v[152:155], v[184:187], v[62:65]
	v_mfma_f32_16x16x32_bf16 v[58:61], v[160:163], v[184:187], v[58:61]
	v_mfma_f32_16x16x32_bf16 v[46:49], v[152:155], v[192:195], v[46:49]
	v_mfma_f32_16x16x32_bf16 v[42:45], v[160:163], v[192:195], v[42:45]
	v_mfma_f32_16x16x32_bf16 v[30:33], v[152:155], v[200:203], v[30:33]
	v_mfma_f32_16x16x32_bf16 v[26:29], v[160:163], v[200:203], v[26:29]
	v_mfma_f32_16x16x32_bf16 v[14:17], v[152:155], v[208:211], v[14:17]
	v_mfma_f32_16x16x32_bf16 v[10:13], v[160:163], v[208:211], v[10:13]
	v_mfma_f32_16x16x32_bf16 v[62:65], v[156:159], v[188:191], v[62:65]
	v_mfma_f32_16x16x32_bf16 v[58:61], v[164:167], v[188:191], v[58:61]
	v_mfma_f32_16x16x32_bf16 v[46:49], v[156:159], v[196:199], v[46:49]
	v_mfma_f32_16x16x32_bf16 v[42:45], v[164:167], v[196:199], v[42:45]
	v_mfma_f32_16x16x32_bf16 v[30:33], v[156:159], v[204:207], v[30:33]
	v_mfma_f32_16x16x32_bf16 v[26:29], v[164:167], v[204:207], v[26:29]
	v_mfma_f32_16x16x32_bf16 v[14:17], v[156:159], v[212:215], v[14:17]
	v_mfma_f32_16x16x32_bf16 v[10:13], v[164:167], v[212:215], v[10:13]
	v_mfma_f32_16x16x32_bf16 v[54:57], v[168:171], v[184:187], v[54:57]
	v_mfma_f32_16x16x32_bf16 v[50:53], v[176:179], v[184:187], v[50:53]
	v_mfma_f32_16x16x32_bf16 v[38:41], v[168:171], v[192:195], v[38:41]
	v_mfma_f32_16x16x32_bf16 v[34:37], v[176:179], v[192:195], v[34:37]
	v_mfma_f32_16x16x32_bf16 v[22:25], v[168:171], v[200:203], v[22:25]
	v_mfma_f32_16x16x32_bf16 v[18:21], v[176:179], v[200:203], v[18:21]
	v_mfma_f32_16x16x32_bf16 v[6:9], v[168:171], v[208:211], v[6:9]
	v_mfma_f32_16x16x32_bf16 v[2:5], v[176:179], v[208:211], v[2:5]
	v_mfma_f32_16x16x32_bf16 v[54:57], v[172:175], v[188:191], v[54:57]
	v_mfma_f32_16x16x32_bf16 v[50:53], v[180:183], v[188:191], v[50:53]
	v_mfma_f32_16x16x32_bf16 v[38:41], v[172:175], v[196:199], v[38:41]
	v_mfma_f32_16x16x32_bf16 v[34:37], v[180:183], v[196:199], v[34:37]
	v_mfma_f32_16x16x32_bf16 v[22:25], v[172:175], v[204:207], v[22:25]
	v_mfma_f32_16x16x32_bf16 v[18:21], v[180:183], v[204:207], v[18:21]
	v_mfma_f32_16x16x32_bf16 v[6:9], v[172:175], v[212:215], v[6:9]
	v_mfma_f32_16x16x32_bf16 v[2:5], v[180:183], v[212:215], v[2:5]
	s_barrier
	v_add_u32_e32 v151, s60, v146
	ds_read_b128 v[152:155], v151
	ds_read_b128 v[156:159], v151 offset:1024
	ds_read_b128 v[160:163], v151 offset:2048
	ds_read_b128 v[164:167], v151 offset:3072
	v_add_u32_e32 v151, s61, v146
	ds_read_b128 v[168:171], v151
	ds_read_b128 v[172:175], v151 offset:1024
	ds_read_b128 v[176:179], v151 offset:2048
	ds_read_b128 v[180:183], v151 offset:3072
	s_add_u32 s38, s38, 0x4000
	s_addc_u32 s39, s39, 0
	s_mov_b32 m0, s43
	ds_read_b128 v[184:187], v150 offset:32768
	ds_read_b128 v[188:191], v150 offset:33792
	ds_read_b128 v[192:195], v150 offset:34816
	ds_read_b128 v[196:199], v150 offset:35840
	ds_read_b128 v[200:203], v150 offset:36864
	ds_read_b128 v[204:207], v150 offset:37888
	ds_read_b128 v[208:211], v150 offset:38912
	ds_read_b128 v[212:215], v150 offset:39936
	global_load_lds_dwordx4 v130, s[38:39]
	s_mov_b32 m0, s44
	s_nop 0
	global_load_lds_dwordx4 v132, s[38:39]
	s_waitcnt vmcnt(8) lgkmcnt(0)
	s_barrier
	v_mfma_f32_16x16x32_bf16 v[126:129], v[152:155], v[184:187], v[126:129]
	v_mfma_f32_16x16x32_bf16 v[122:125], v[160:163], v[184:187], v[122:125]
	v_mfma_f32_16x16x32_bf16 v[110:113], v[152:155], v[192:195], v[110:113]
	v_mfma_f32_16x16x32_bf16 v[106:109], v[160:163], v[192:195], v[106:109]
	v_mfma_f32_16x16x32_bf16 v[94:97], v[152:155], v[200:203], v[94:97]
	v_mfma_f32_16x16x32_bf16 v[90:93], v[160:163], v[200:203], v[90:93]
	v_mfma_f32_16x16x32_bf16 v[78:81], v[152:155], v[208:211], v[78:81]
	v_mfma_f32_16x16x32_bf16 v[74:77], v[160:163], v[208:211], v[74:77]
	v_mfma_f32_16x16x32_bf16 v[126:129], v[156:159], v[188:191], v[126:129]
	v_mfma_f32_16x16x32_bf16 v[122:125], v[164:167], v[188:191], v[122:125]
	v_mfma_f32_16x16x32_bf16 v[110:113], v[156:159], v[196:199], v[110:113]
	v_mfma_f32_16x16x32_bf16 v[106:109], v[164:167], v[196:199], v[106:109]
	v_mfma_f32_16x16x32_bf16 v[94:97], v[156:159], v[204:207], v[94:97]
	v_mfma_f32_16x16x32_bf16 v[90:93], v[164:167], v[204:207], v[90:93]
	v_mfma_f32_16x16x32_bf16 v[78:81], v[156:159], v[212:215], v[78:81]
	v_mfma_f32_16x16x32_bf16 v[74:77], v[164:167], v[212:215], v[74:77]
	v_mfma_f32_16x16x32_bf16 v[118:121], v[168:171], v[184:187], v[118:121]
	v_mfma_f32_16x16x32_bf16 v[114:117], v[176:179], v[184:187], v[114:117]
	v_mfma_f32_16x16x32_bf16 v[102:105], v[168:171], v[192:195], v[102:105]
	v_mfma_f32_16x16x32_bf16 v[98:101], v[176:179], v[192:195], v[98:101]
	v_mfma_f32_16x16x32_bf16 v[86:89], v[168:171], v[200:203], v[86:89]
	v_mfma_f32_16x16x32_bf16 v[82:85], v[176:179], v[200:203], v[82:85]
	v_mfma_f32_16x16x32_bf16 v[70:73], v[168:171], v[208:211], v[70:73]
	v_mfma_f32_16x16x32_bf16 v[66:69], v[176:179], v[208:211], v[66:69]
	v_mfma_f32_16x16x32_bf16 v[118:121], v[172:175], v[188:191], v[118:121]
	v_mfma_f32_16x16x32_bf16 v[114:117], v[180:183], v[188:191], v[114:117]
	v_mfma_f32_16x16x32_bf16 v[102:105], v[172:175], v[196:199], v[102:105]
	v_mfma_f32_16x16x32_bf16 v[98:101], v[180:183], v[196:199], v[98:101]
	v_mfma_f32_16x16x32_bf16 v[86:89], v[172:175], v[204:207], v[86:89]
	v_mfma_f32_16x16x32_bf16 v[82:85], v[180:183], v[204:207], v[82:85]
	v_mfma_f32_16x16x32_bf16 v[70:73], v[172:175], v[212:215], v[70:73]
	v_mfma_f32_16x16x32_bf16 v[66:69], v[180:183], v[212:215], v[66:69]
	s_barrier
; template <class Epi, class Sched, bool ABLK = false, bool ALIGN_EPI = true, bool SP2 = true, bool BBLK = true>
; __device__ __forceinline__ void gemm_phase(LAS unsigned char* lds, const Gemm g, const Sched& S, const Epi& E) {
;     ...
;             PG8_WAIT_V(8); PG8_WAIT_L(0); PG8_BAR; PG8_MMA(0, 0, At, B0); PG8_MMA(0, 1, At, B1); PG8_BAR; PG8_SCHED;
;             PG8_LDA(At, 1, 1); PG8_STAGE(PG8_SB(1, 0), b3, voffB); PG8_STAGE(PG8_SB(1, 1), b3 + hstepB, voffB); PG8_STAGE(PG8_SA(1, 0), a3, voffA);
;             PG8_WAIT_V(8); PG8_WAIT_L(0); PG8_BAR; PG8_MMA(1, 0, At, B0); PG8_MMA(1, 1, At, B1); PG8_BAR; PG8_SCHED;
;             } else {
;             PG8_LDB(B0, 0, 0); PG8_SCHED; PG8_LDA(At, 0, 0); PG8_STAGE(PG8_SA(1, 1), a1 + hstepA, voffA);
;             PG8_WAIT_L(8); PG8_BAR; PG8_WAIT_L(0); PG8_MMA(0, 0, At, B0); PG8_BAR; PG8_SCHED;
;             PG8_LDB(B1, 0, 1); PG8_STAGE(PG8_SB(0, 0), b2, voffB);
;             PG8_BAR; PG8_WAIT_L(0); PG8_MMA(0, 1, At, B1); PG8_BAR;
;             PG8_LDA(At, 0, 1); PG8_STAGE(PG8_SA(0, 0), a2, voffA);
;             PG8_BAR; PG8_WAIT_L(0); PG8_MMA(1, 0, At, B0); PG8_BAR; PG8_SCHED;
;             PG8_STAGE(PG8_SB(0, 1), b2 + hstepB, voffB);
;             PG8_WAIT_V(6); PG8_BAR; PG8_MMA(1, 1, At, B1); PG8_BAR;
;             PG8_LDB(B0, 1, 0); PG8_SCHED; PG8_LDA(At, 1, 0); PG8_STAGE(PG8_SA(0, 1), a2 + hstepA, voffA);
;             PG8_WAIT_L(8); PG8_BAR; PG8_WAIT_L(0); PG8_MMA(0, 0, At, B0); PG8_BAR; PG8_SCHED;
;             PG8_LDB(B1, 1, 1); PG8_STAGE(PG8_SB(1, 0), b3, voffB);
;             PG8_BAR; PG8_WAIT_L(0); PG8_MMA(0, 1, At, B1); PG8_BAR;
;             PG8_LDA(At, 1, 1); PG8_STAGE(PG8_SA(1, 0), a3, voffA);
;             PG8_BAR; PG8_WAIT_L(0); PG8_MMA(1, 0, At, B0); PG8_BAR; PG8_SCHED;
;             PG8_STAGE(PG8_SB(1, 1), b3 + hstepB, voffB);
;             PG8_WAIT_V(6); PG8_BAR; PG8_MMA(1, 1, At, B1); PG8_BAR;
;             }
;         }
;         if constexpr (ALIGN_EPI) { if (wr == 0) PG8_BAR; }
;     __device__ __forceinline__ void operator()(const f32x4 (&acc)[2][2][4][2], const Unit& u, int wr, int wc, int fr, int fq) const {
;         const int row0 = u.pm * 256 + wr * 64 + fr, col0 = u.pn * 256 + wc * 64 + 8 * fq;
;         bf16_t* base = u.part == 0 ? Z + (size_t)row0 * D + col0 : P + ((size_t)(u.part - 1) * MS + (row0 - MP)) * D + col0;
; #pragma unroll
;         for (int ai = 0; ai < 2; ++ai)
	s_add_u32 s38, s36, 0x8000
	s_addc_u32 s39, s37, 0
	s_add_i32 s59, s60, s40
	s_mov_b32 m0, s59
	ds_read_b128 v[184:187], v150 offset:49152
	ds_read_b128 v[188:191], v150 offset:50176
	ds_read_b128 v[192:195], v150 offset:51200
	ds_read_b128 v[196:199], v150 offset:52224
	ds_read_b128 v[200:203], v150 offset:53248
	ds_read_b128 v[204:207], v150 offset:54272
	ds_read_b128 v[208:211], v150 offset:55296
	ds_read_b128 v[212:215], v150 offset:56320
	global_load_lds_dwordx4 v130, s[38:39]
	s_add_i32 m0, s59, 0x2000
	s_add_u32 s36, s36, 0xc000
	v_lshl_add_u64 v[216:217], s[38:39], 0, v[132:133]
	s_addc_u32 s37, s37, 0
	s_add_i32 s38, s61, s40
	global_load_lds_dwordx4 v[216:217], off
	s_mov_b32 m0, s38
	s_nop 0
	global_load_lds_dwordx4 v130, s[36:37]
	s_add_i32 m0, s38, 0x2000
	s_nop 0
	global_load_lds_dwordx4 v132, s[36:37]
	s_mov_b32 m0, s45
	s_nop 0
	global_load_lds_dwordx4 v130, s[34:35]
	s_mov_b32 m0, s46
	s_nop 0
	global_load_lds_dwordx4 v132, s[34:35]
	s_waitcnt vmcnt(8) lgkmcnt(0)
	s_barrier
	v_mfma_f32_16x16x32_bf16 v[62:65], v[152:155], v[184:187], v[62:65]
	v_mfma_f32_16x16x32_bf16 v[58:61], v[160:163], v[184:187], v[58:61]
	v_mfma_f32_16x16x32_bf16 v[46:49], v[152:155], v[192:195], v[46:49]
	v_mfma_f32_16x16x32_bf16 v[42:45], v[160:163], v[192:195], v[42:45]
	v_mfma_f32_16x16x32_bf16 v[30:33], v[152:155], v[200:203], v[30:33]
	v_mfma_f32_16x16x32_bf16 v[26:29], v[160:163], v[200:203], v[26:29]
	v_mfma_f32_16x16x32_bf16 v[14:17], v[152:155], v[208:211], v[14:17]
	v_mfma_f32_16x16x32_bf16 v[10:13], v[160:163], v[208:211], v[10:13]
	v_mfma_f32_16x16x32_bf16 v[62:65], v[156:159], v[188:191], v[62:65]
	v_mfma_f32_16x16x32_bf16 v[58:61], v[164:167], v[188:191], v[58:61]
	v_mfma_f32_16x16x32_bf16 v[46:49], v[156:159], v[196:199], v[46:49]
	v_mfma_f32_16x16x32_bf16 v[42:45], v[164:167], v[196:199], v[42:45]
	v_mfma_f32_16x16x32_bf16 v[30:33], v[156:159], v[204:207], v[30:33]
	v_mfma_f32_16x16x32_bf16 v[26:29], v[164:167], v[204:207], v[26:29]
	v_mfma_f32_16x16x32_bf16 v[14:17], v[156:159], v[212:215], v[14:17]
	v_mfma_f32_16x16x32_bf16 v[10:13], v[164:167], v[212:215], v[10:13]
	v_mfma_f32_16x16x32_bf16 v[54:57], v[168:171], v[184:187], v[54:57]
	v_mfma_f32_16x16x32_bf16 v[50:53], v[176:179], v[184:187], v[50:53]
	v_mfma_f32_16x16x32_bf16 v[38:41], v[168:171], v[192:195], v[38:41]
	v_mfma_f32_16x16x32_bf16 v[34:37], v[176:179], v[192:195], v[34:37]
	v_mfma_f32_16x16x32_bf16 v[22:25], v[168:171], v[200:203], v[22:25]
	v_mfma_f32_16x16x32_bf16 v[18:21], v[176:179], v[200:203], v[18:21]
	v_mfma_f32_16x16x32_bf16 v[6:9], v[168:171], v[208:211], v[6:9]
	v_mfma_f32_16x16x32_bf16 v[2:5], v[176:179], v[208:211], v[2:5]
	v_mfma_f32_16x16x32_bf16 v[54:57], v[172:175], v[188:191], v[54:57]
	v_mfma_f32_16x16x32_bf16 v[50:53], v[180:183], v[188:191], v[50:53]
	v_mfma_f32_16x16x32_bf16 v[38:41], v[172:175], v[196:199], v[38:41]
	v_mfma_f32_16x16x32_bf16 v[34:37], v[180:183], v[196:199], v[34:37]
	v_mfma_f32_16x16x32_bf16 v[22:25], v[172:175], v[204:207], v[22:25]
	v_mfma_f32_16x16x32_bf16 v[18:21], v[180:183], v[204:207], v[18:21]
	v_mfma_f32_16x16x32_bf16 v[6:9], v[172:175], v[212:215], v[6:9]
	v_mfma_f32_16x16x32_bf16 v[2:5], v[180:183], v[212:215], v[2:5]
	s_barrier
	s_add_u32 s30, s30, 0x10000
	s_addc_u32 s31, s31, 0
	s_cmp_ge_u32 s58, s48
	s_cbranch_scc0 .LBB0_1907
	v_lshl_add_u32 v143, s49, 8, v1
	v_add_u32_e32 v144, 0xffffe000, v143
	v_sub_co_u32_e64 v142, vcc, s47, 1
	v_mov_b32_e32 v145, s91
	s_nop 0
	v_cndmask_b32_e32 v144, v144, v143, vcc
	v_ashrrev_i32_e32 v143, 31, v142
	v_lshlrev_b64 v[142:143], 23, v[142:143]
	v_lshl_add_u64 v[142:143], s[12:13], 0, v[142:143]
	v_cndmask_b32_e32 v143, v143, v145, vcc
	v_mov_b32_e32 v145, s90
	v_cndmask_b32_e32 v142, v142, v145, vcc
	v_ashrrev_i32_e32 v145, 31, v144
	v_lshl_or_b32 v152, s78, 8, v147
	v_lshlrev_b64 v[144:145], 12, v[144:145]
	v_lshl_add_u64 v[142:143], v[142:143], 0, v[144:145]
	v_ashrrev_i32_e32 v153, 31, v152
	v_cvt_pk_bf16_f32 v126, v126, v127
	v_cvt_pk_bf16_f32 v127, v128, v129
	v_cvt_pk_bf16_f32 v128, v122, v123
	v_cvt_pk_bf16_f32 v124, v124, v125
	v_cvt_pk_bf16_f32 v118, v118, v119
	v_cvt_pk_bf16_f32 v119, v120, v121
	v_cvt_pk_bf16_f32 v114, v114, v115
	v_cvt_pk_bf16_f32 v115, v116, v117
	v_lshl_add_u64 v[142:143], v[152:153], 1, v[142:143]
	v_mov_b32_dpp v120, v126 row_ror:8 row_mask:0xf bank_mask:0xf bound_ctrl:1
	v_mov_b32_dpp v121, v127 row_ror:8 row_mask:0xf bank_mask:0xf bound_ctrl:1
	v_mov_b32_dpp v116, v128 row_ror:8 row_mask:0xf bank_mask:0xf bound_ctrl:1
	v_mov_b32_dpp v117, v124 row_ror:8 row_mask:0xf bank_mask:0xf bound_ctrl:1
	v_mov_b32_dpp v125, v118 row_ror:8 row_mask:0xf bank_mask:0xf bound_ctrl:1
	v_mov_b32_dpp v129, v119 row_ror:8 row_mask:0xf bank_mask:0xf bound_ctrl:1
	v_mov_b32_dpp v144, v114 row_ror:8 row_mask:0xf bank_mask:0xf bound_ctrl:1
	v_mov_b32_dpp v145, v115 row_ror:8 row_mask:0xf bank_mask:0xf bound_ctrl:1
	v_lshl_add_u64 v[122:123], v[142:143], 0, v[134:135]
	v_cndmask_b32_e64 v117, v117, v115, s[8:9]
	v_cndmask_b32_e64 v116, v116, v114, s[8:9]
	v_cndmask_b32_e64 v115, v121, v119, s[8:9]
	v_cndmask_b32_e64 v114, v120, v118, s[8:9]
	v_cndmask_b32_e64 v121, v124, v145, s[8:9]
	v_cndmask_b32_e64 v120, v128, v144, s[8:9]
	v_cndmask_b32_e64 v119, v127, v129, s[8:9]
	v_cndmask_b32_e64 v118, v126, v125, s[8:9]
	v_cvt_pk_bf16_f32 v110, v110, v111
	v_cvt_pk_bf16_f32 v111, v112, v113
	v_cvt_pk_bf16_f32 v112, v106, v107
	v_cvt_pk_bf16_f32 v113, v108, v109
	v_cvt_pk_bf16_f32 v102, v102, v103
	v_cvt_pk_bf16_f32 v103, v104, v105
	v_cvt_pk_bf16_f32 v98, v98, v99
	v_cvt_pk_bf16_f32 v99, v100, v101
	s_mov_b64 s[4:5], 0x10000
	v_lshl_add_u64 v[124:125], v[142:143], 0, v[136:137]
	s_and_b64 vcc, exec, s[6:7]
	s_cbranch_vccz .LBB0_1910
	s_barrier
; __device__ __forceinline__ unsigned pk2(float lo, float hi) { const f32x2 v = {lo, hi}; return __builtin_bit_cast(unsigned, __builtin_convertvector(v, bf16x2_t)); }
; __device__ __forceinline__ void store_pair(unsigned char* own, size_t stride8, int hi_off, u32x4 lo, u32x4 hi, bool upper) {
;     const u32x4 tlo = ror8(lo), thi = ror8(hi);
;     const u32x4 A = upper ? thi : lo, B = upper ? hi : tlo;
;     unsigned char* pa = upper ? own - stride8 + hi_off : own;
;     unsigned char* pb = upper ? own + hi_off : own + stride8;
;     *(u32x4*)pa = A; *(u32x4*)pb = B;
; }
;     __device__ __forceinline__ void operator()(const f32x4 (&acc)[2][2][4][2], const Unit& u, int wr, int wc, int fr, int fq) const {
;         const int row0 = u.pm * 256 + wr * 64 + fr, col0 = u.pn * 256 + wc * 64 + 8 * fq;
;         bf16_t* base = u.part == 0 ? Z + (size_t)row0 * D + col0 : P + ((size_t)(u.part - 1) * MS + (row0 - MP)) * D + col0;
; #pragma unroll
;         for (int ai = 0; ai < 2; ++ai)
; #pragma unroll
;             for (int m = 0; m < 4; ++m) { u32x4 w[2];
; #pragma unroll
;                 for (int bj = 0; bj < 2; ++bj) { const f32x4 v0 = acc[ai][bj][m][0], v1 = acc[ai][bj][m][1]; w[bj].x = pk2(v0[0], v0[1]); w[bj].y = pk2(v0[2], v0[3]); w[bj].z = pk2(v1[0], v1[1]); w[bj].w = pk2(v1[2], v1[3]); }
;                 store_pair((unsigned char*)(base + (size_t)(ai * 128 + m * 16) * D), (size_t)8 * D * 2, 64, w[0], w[1], fr >= 8); }
.LBB0_1910:
	global_store_dwordx4 v[122:123], v[118:121], off
	global_store_dwordx4 v[124:125], v[114:117], off
	v_lshl_add_u64 v[106:107], v[142:143], 0, s[4:5]
	v_mov_b32_dpp v104, v110 row_ror:8 row_mask:0xf bank_mask:0xf bound_ctrl:1
	v_mov_b32_dpp v105, v111 row_ror:8 row_mask:0xf bank_mask:0xf bound_ctrl:1
	v_mov_b32_dpp v100, v112 row_ror:8 row_mask:0xf bank_mask:0xf bound_ctrl:1
	v_mov_b32_dpp v101, v113 row_ror:8 row_mask:0xf bank_mask:0xf bound_ctrl:1
	v_mov_b32_dpp v114, v102 row_ror:8 row_mask:0xf bank_mask:0xf bound_ctrl:1
	v_mov_b32_dpp v115, v103 row_ror:8 row_mask:0xf bank_mask:0xf bound_ctrl:1
	v_mov_b32_dpp v116, v98 row_ror:8 row_mask:0xf bank_mask:0xf bound_ctrl:1
	v_mov_b32_dpp v117, v99 row_ror:8 row_mask:0xf bank_mask:0xf bound_ctrl:1
	v_lshl_add_u64 v[108:109], v[106:107], 0, v[134:135]
	v_cndmask_b32_e64 v101, v101, v99, s[8:9]
	v_cndmask_b32_e64 v100, v100, v98, s[8:9]
	v_cndmask_b32_e64 v99, v105, v103, s[8:9]
	v_cndmask_b32_e64 v98, v104, v102, s[8:9]
	v_cndmask_b32_e64 v105, v113, v117, s[8:9]
	v_cndmask_b32_e64 v104, v112, v116, s[8:9]
	v_cndmask_b32_e64 v103, v111, v115, s[8:9]
	v_cndmask_b32_e64 v102, v110, v114, s[8:9]
	v_cvt_pk_bf16_f32 v94, v94, v95
	v_cvt_pk_bf16_f32 v95, v96, v97
	v_cvt_pk_bf16_f32 v96, v90, v91
	v_cvt_pk_bf16_f32 v97, v92, v93
	v_cvt_pk_bf16_f32 v86, v86, v87
	v_cvt_pk_bf16_f32 v87, v88, v89
	v_cvt_pk_bf16_f32 v82, v82, v83
	v_cvt_pk_bf16_f32 v83, v84, v85
	s_mov_b64 s[4:5], 0x20000
	v_lshl_add_u64 v[106:107], v[106:107], 0, v[136:137]
	global_store_dwordx4 v[108:109], v[102:105], off
	global_store_dwordx4 v[106:107], v[98:101], off
	v_lshl_add_u64 v[90:91], v[142:143], 0, s[4:5]
	v_mov_b32_dpp v88, v94 row_ror:8 row_mask:0xf bank_mask:0xf bound_ctrl:1
	v_mov_b32_dpp v89, v95 row_ror:8 row_mask:0xf bank_mask:0xf bound_ctrl:1
	v_mov_b32_dpp v84, v96 row_ror:8 row_mask:0xf bank_mask:0xf bound_ctrl:1
	v_mov_b32_dpp v85, v97 row_ror:8 row_mask:0xf bank_mask:0xf bound_ctrl:1
	v_mov_b32_dpp v98, v86 row_ror:8 row_mask:0xf bank_mask:0xf bound_ctrl:1
	v_mov_b32_dpp v99, v87 row_ror:8 row_mask:0xf bank_mask:0xf bound_ctrl:1
	v_mov_b32_dpp v100, v82 row_ror:8 row_mask:0xf bank_mask:0xf bound_ctrl:1
	v_mov_b32_dpp v101, v83 row_ror:8 row_mask:0xf bank_mask:0xf bound_ctrl:1
	v_lshl_add_u64 v[92:93], v[90:91], 0, v[134:135]
	v_cndmask_b32_e64 v85, v85, v83, s[8:9]
	v_cndmask_b32_e64 v84, v84, v82, s[8:9]
	v_cndmask_b32_e64 v83, v89, v87, s[8:9]
	v_cndmask_b32_e64 v82, v88, v86, s[8:9]
	v_cndmask_b32_e64 v89, v97, v101, s[8:9]
	v_cndmask_b32_e64 v88, v96, v100, s[8:9]
	v_cndmask_b32_e64 v87, v95, v99, s[8:9]
	v_cndmask_b32_e64 v86, v94, v98, s[8:9]
	v_cvt_pk_bf16_f32 v78, v78, v79
	v_cvt_pk_bf16_f32 v79, v80, v81
	v_cvt_pk_bf16_f32 v80, v74, v75
	v_cvt_pk_bf16_f32 v81, v76, v77
	v_cvt_pk_bf16_f32 v70, v70, v71
	v_cvt_pk_bf16_f32 v71, v72, v73
	v_cvt_pk_bf16_f32 v66, v66, v67
	v_cvt_pk_bf16_f32 v67, v68, v69
	v_lshl_add_u64 v[90:91], v[90:91], 0, v[136:137]
	global_store_dwordx4 v[92:93], v[86:89], off
	global_store_dwordx4 v[90:91], v[82:85], off
	v_lshl_add_u64 v[74:75], v[142:143], 0, s[14:15]
	v_mov_b32_dpp v72, v78 row_ror:8 row_mask:0xf bank_mask:0xf bound_ctrl:1
	v_mov_b32_dpp v73, v79 row_ror:8 row_mask:0xf bank_mask:0xf bound_ctrl:1
	v_mov_b32_dpp v68, v80 row_ror:8 row_mask:0xf bank_mask:0xf bound_ctrl:1
	v_mov_b32_dpp v69, v81 row_ror:8 row_mask:0xf bank_mask:0xf bound_ctrl:1
	v_mov_b32_dpp v82, v70 row_ror:8 row_mask:0xf bank_mask:0xf bound_ctrl:1
	v_mov_b32_dpp v83, v71 row_ror:8 row_mask:0xf bank_mask:0xf bound_ctrl:1
	v_mov_b32_dpp v84, v66 row_ror:8 row_mask:0xf bank_mask:0xf bound_ctrl:1
	v_mov_b32_dpp v85, v67 row_ror:8 row_mask:0xf bank_mask:0xf bound_ctrl:1
	v_lshl_add_u64 v[76:77], v[74:75], 0, v[134:135]
	v_cndmask_b32_e64 v69, v69, v67, s[8:9]
	v_cndmask_b32_e64 v68, v68, v66, s[8:9]
	v_cndmask_b32_e64 v67, v73, v71, s[8:9]
	v_cndmask_b32_e64 v66, v72, v70, s[8:9]
	v_cndmask_b32_e64 v73, v81, v85, s[8:9]
	v_cndmask_b32_e64 v72, v80, v84, s[8:9]
	v_cndmask_b32_e64 v71, v79, v83, s[8:9]
	v_cndmask_b32_e64 v70, v78, v82, s[8:9]
	v_cvt_pk_bf16_f32 v62, v62, v63
	v_cvt_pk_bf16_f32 v63, v64, v65
	v_cvt_pk_bf16_f32 v64, v58, v59
	v_cvt_pk_bf16_f32 v65, v60, v61
	v_cvt_pk_bf16_f32 v54, v54, v55
	v_cvt_pk_bf16_f32 v55, v56, v57
	v_cvt_pk_bf16_f32 v50, v50, v51
	v_cvt_pk_bf16_f32 v51, v52, v53
	v_lshl_add_u64 v[74:75], v[74:75], 0, v[136:137]
	global_store_dwordx4 v[76:77], v[70:73], off
	global_store_dwordx4 v[74:75], v[66:69], off
	v_lshl_add_u64 v[58:59], v[142:143], 0, s[16:17]
	v_mov_b32_dpp v56, v62 row_ror:8 row_mask:0xf bank_mask:0xf bound_ctrl:1
	v_mov_b32_dpp v57, v63 row_ror:8 row_mask:0xf bank_mask:0xf bound_ctrl:1
	v_mov_b32_dpp v52, v64 row_ror:8 row_mask:0xf bank_mask:0xf bound_ctrl:1
	v_mov_b32_dpp v53, v65 row_ror:8 row_mask:0xf bank_mask:0xf bound_ctrl:1
	v_mov_b32_dpp v66, v54 row_ror:8 row_mask:0xf bank_mask:0xf bound_ctrl:1
	v_mov_b32_dpp v67, v55 row_ror:8 row_mask:0xf bank_mask:0xf bound_ctrl:1
	v_mov_b32_dpp v68, v50 row_ror:8 row_mask:0xf bank_mask:0xf bound_ctrl:1
; __device__ __forceinline__ unsigned pk2(float lo, float hi) { const f32x2 v = {lo, hi}; return __builtin_bit_cast(unsigned, __builtin_convertvector(v, bf16x2_t)); }
; #define PG8_BAR __builtin_amdgcn_s_barrier()
; template <class Epi, class Sched, bool ABLK = false, bool ALIGN_EPI = true, bool SP2 = true, bool BBLK = true>
; __device__ __forceinline__ void gemm_phase(LAS unsigned char* lds, const Gemm g, const Sched& S, const Epi& E) {
;     ...
;         if (!has_next) break;
; #pragma unroll
;         for (int a = 0; a < 2; ++a)
; #pragma unroll
;             for (int b = 0; b < 2; ++b)
; #pragma unroll
;                 for (int m = 0; m < 4; ++m)
; #pragma unroll
;                     for (int n = 0; n < 2; ++n) acc[a][b][m][n] = (f32x4){0.f, 0.f, 0.f, 0.f};
;         cur = nxt; uA = nuA; tbA = ntbA; cB = nB; ++ui;
;         if constexpr (ALIGN_EPI) { if (wr == 1) PG8_BAR; }
;     __device__ __forceinline__ void operator()(const f32x4 (&acc)[2][2][4][2], const Unit& u, int wr, int wc, int fr, int fq) const {
;         const int row0 = u.pm * 256 + wr * 64 + fr, col0 = u.pn * 256 + wc * 64 + 8 * fq;
;         bf16_t* base = u.part == 0 ? Z + (size_t)row0 * D + col0 : P + ((size_t)(u.part - 1) * MS + (row0 - MP)) * D + col0;
; #pragma unroll
;         for (int ai = 0; ai < 2; ++ai)
; #pragma unroll
;             for (int m = 0; m < 4; ++m) { u32x4 w[2];
; #pragma unroll
;                 for (int bj = 0; bj < 2; ++bj) { const f32x4 v0 = acc[ai][bj][m][0], v1 = acc[ai][bj][m][1]; w[bj].x = pk2(v0[0], v0[1]); w[bj].y = pk2(v0[2], v0[3]); w[bj].z = pk2(v1[0], v1[1]); w[bj].w = pk2(v1[2], v1[3]); }
;                 store_pair((unsigned char*)(base + (size_t)(ai * 128 + m * 16) * D), (size_t)8 * D * 2, 64, w[0], w[1], fr >= 8); }
	v_mov_b32_dpp v69, v51 row_ror:8 row_mask:0xf bank_mask:0xf bound_ctrl:1
	v_lshl_add_u64 v[60:61], v[58:59], 0, v[134:135]
	v_cndmask_b32_e64 v53, v53, v51, s[8:9]
	v_cndmask_b32_e64 v52, v52, v50, s[8:9]
	v_cndmask_b32_e64 v51, v57, v55, s[8:9]
	v_cndmask_b32_e64 v50, v56, v54, s[8:9]
	v_cndmask_b32_e64 v57, v65, v69, s[8:9]
	v_cndmask_b32_e64 v56, v64, v68, s[8:9]
	v_cndmask_b32_e64 v55, v63, v67, s[8:9]
	v_cndmask_b32_e64 v54, v62, v66, s[8:9]
	v_cvt_pk_bf16_f32 v46, v46, v47
	v_cvt_pk_bf16_f32 v47, v48, v49
	v_cvt_pk_bf16_f32 v48, v42, v43
	v_cvt_pk_bf16_f32 v49, v44, v45
	v_cvt_pk_bf16_f32 v38, v38, v39
	v_cvt_pk_bf16_f32 v39, v40, v41
	v_cvt_pk_bf16_f32 v34, v34, v35
	v_cvt_pk_bf16_f32 v35, v36, v37
	v_lshl_add_u64 v[58:59], v[58:59], 0, v[136:137]
	global_store_dwordx4 v[60:61], v[54:57], off
	global_store_dwordx4 v[58:59], v[50:53], off
	v_lshl_add_u64 v[42:43], v[142:143], 0, s[18:19]
	v_mov_b32_dpp v40, v46 row_ror:8 row_mask:0xf bank_mask:0xf bound_ctrl:1
	v_mov_b32_dpp v41, v47 row_ror:8 row_mask:0xf bank_mask:0xf bound_ctrl:1
	v_mov_b32_dpp v36, v48 row_ror:8 row_mask:0xf bank_mask:0xf bound_ctrl:1
	v_mov_b32_dpp v37, v49 row_ror:8 row_mask:0xf bank_mask:0xf bound_ctrl:1
	v_mov_b32_dpp v50, v38 row_ror:8 row_mask:0xf bank_mask:0xf bound_ctrl:1
	v_mov_b32_dpp v51, v39 row_ror:8 row_mask:0xf bank_mask:0xf bound_ctrl:1
	v_mov_b32_dpp v52, v34 row_ror:8 row_mask:0xf bank_mask:0xf bound_ctrl:1
	v_mov_b32_dpp v53, v35 row_ror:8 row_mask:0xf bank_mask:0xf bound_ctrl:1
	v_lshl_add_u64 v[44:45], v[42:43], 0, v[134:135]
	v_cndmask_b32_e64 v37, v37, v35, s[8:9]
	v_cndmask_b32_e64 v36, v36, v34, s[8:9]
	v_cndmask_b32_e64 v35, v41, v39, s[8:9]
	v_cndmask_b32_e64 v34, v40, v38, s[8:9]
	v_cndmask_b32_e64 v41, v49, v53, s[8:9]
	v_cndmask_b32_e64 v40, v48, v52, s[8:9]
	v_cndmask_b32_e64 v39, v47, v51, s[8:9]
	v_cndmask_b32_e64 v38, v46, v50, s[8:9]
	v_cvt_pk_bf16_f32 v30, v30, v31
	v_cvt_pk_bf16_f32 v31, v32, v33
	v_cvt_pk_bf16_f32 v32, v26, v27
	v_cvt_pk_bf16_f32 v33, v28, v29
	v_cvt_pk_bf16_f32 v22, v22, v23
	v_cvt_pk_bf16_f32 v23, v24, v25
	v_cvt_pk_bf16_f32 v18, v18, v19
	v_cvt_pk_bf16_f32 v19, v20, v21
	v_lshl_add_u64 v[42:43], v[42:43], 0, v[136:137]
	global_store_dwordx4 v[44:45], v[38:41], off
	global_store_dwordx4 v[42:43], v[34:37], off
	v_lshl_add_u64 v[26:27], v[142:143], 0, s[20:21]
	v_mov_b32_dpp v24, v30 row_ror:8 row_mask:0xf bank_mask:0xf bound_ctrl:1
	v_mov_b32_dpp v25, v31 row_ror:8 row_mask:0xf bank_mask:0xf bound_ctrl:1
	v_mov_b32_dpp v20, v32 row_ror:8 row_mask:0xf bank_mask:0xf bound_ctrl:1
	v_mov_b32_dpp v21, v33 row_ror:8 row_mask:0xf bank_mask:0xf bound_ctrl:1
	v_mov_b32_dpp v34, v22 row_ror:8 row_mask:0xf bank_mask:0xf bound_ctrl:1
	v_mov_b32_dpp v35, v23 row_ror:8 row_mask:0xf bank_mask:0xf bound_ctrl:1
	v_mov_b32_dpp v36, v18 row_ror:8 row_mask:0xf bank_mask:0xf bound_ctrl:1
	v_mov_b32_dpp v37, v19 row_ror:8 row_mask:0xf bank_mask:0xf bound_ctrl:1
	v_lshl_add_u64 v[28:29], v[26:27], 0, v[134:135]
	v_cndmask_b32_e64 v21, v21, v19, s[8:9]
	v_cndmask_b32_e64 v20, v20, v18, s[8:9]
	v_cndmask_b32_e64 v19, v25, v23, s[8:9]
	v_cndmask_b32_e64 v18, v24, v22, s[8:9]
	v_cndmask_b32_e64 v25, v33, v37, s[8:9]
	v_cndmask_b32_e64 v24, v32, v36, s[8:9]
	v_cndmask_b32_e64 v23, v31, v35, s[8:9]
	v_cndmask_b32_e64 v22, v30, v34, s[8:9]
	v_cvt_pk_bf16_f32 v14, v14, v15
	v_cvt_pk_bf16_f32 v15, v16, v17
	v_cvt_pk_bf16_f32 v16, v10, v11
	v_cvt_pk_bf16_f32 v17, v12, v13
	v_cvt_pk_bf16_f32 v6, v6, v7
	v_cvt_pk_bf16_f32 v7, v8, v9
	v_cvt_pk_bf16_f32 v2, v2, v3
	v_cvt_pk_bf16_f32 v3, v4, v5
	v_lshl_add_u64 v[26:27], v[26:27], 0, v[136:137]
	global_store_dwordx4 v[28:29], v[22:25], off
	global_store_dwordx4 v[26:27], v[18:21], off
	v_lshl_add_u64 v[10:11], v[142:143], 0, s[22:23]
	v_mov_b32_dpp v8, v14 row_ror:8 row_mask:0xf bank_mask:0xf bound_ctrl:1
	v_mov_b32_dpp v9, v15 row_ror:8 row_mask:0xf bank_mask:0xf bound_ctrl:1
	v_mov_b32_dpp v4, v16 row_ror:8 row_mask:0xf bank_mask:0xf bound_ctrl:1
	v_mov_b32_dpp v5, v17 row_ror:8 row_mask:0xf bank_mask:0xf bound_ctrl:1
	v_mov_b32_dpp v18, v6 row_ror:8 row_mask:0xf bank_mask:0xf bound_ctrl:1
	v_mov_b32_dpp v19, v7 row_ror:8 row_mask:0xf bank_mask:0xf bound_ctrl:1
	v_mov_b32_dpp v20, v2 row_ror:8 row_mask:0xf bank_mask:0xf bound_ctrl:1
	v_mov_b32_dpp v21, v3 row_ror:8 row_mask:0xf bank_mask:0xf bound_ctrl:1
	v_lshl_add_u64 v[12:13], v[10:11], 0, v[134:135]
	v_cndmask_b32_e64 v5, v5, v3, s[8:9]
	v_cndmask_b32_e64 v4, v4, v2, s[8:9]
	v_cndmask_b32_e64 v3, v9, v7, s[8:9]
	v_cndmask_b32_e64 v2, v8, v6, s[8:9]
	v_cndmask_b32_e64 v9, v17, v21, s[8:9]
	v_cndmask_b32_e64 v8, v16, v20, s[8:9]
	v_cndmask_b32_e64 v7, v15, v19, s[8:9]
	v_cndmask_b32_e64 v6, v14, v18, s[8:9]
	s_and_b64 vcc, exec, s[10:11]
	s_mov_b64 s[10:11], -1
	v_lshl_add_u64 v[10:11], v[10:11], 0, v[136:137]
	global_store_dwordx4 v[12:13], v[6:9], off
	global_store_dwordx4 v[10:11], v[2:5], off
	s_cbranch_vccnz .LBB0_1905
	s_andn2_b64 vcc, exec, s[2:3]
	s_cbranch_vccnz .LBB0_1904
	s_barrier
	s_branch .LBB0_1904

; #define PG8_STAGE(bufoff, gbase, voff) do { _Pragma("unroll") for (int _i = 0; _i < 2; ++_i) \
;         __builtin_amdgcn_global_load_lds((const unsigned*)((const char*)(gbase) + (voff)[_i]), (LAS unsigned*)(lds + (bufoff) + ldsw + _i * 8192), 16, 0, 0); } while (0)
; #define PG8_LDA(dst, b, h) do { _Pragma("unroll") for (int m = 0; m < 4; ++m) _Pragma("unroll") for (int k = 0; k < 2; ++k) dst[m][k] = *(const LAS bf16x8*)(lds + PG8_SA(b, h) + aoff + m * 2048 + k * 1024); } while (0)
; #define PG8_LDB(dst, b, h) do { _Pragma("unroll") for (int n = 0; n < 2; ++n) _Pragma("unroll") for (int k = 0; k < 2; ++k) dst[n][k] = *(const LAS bf16x8*)(lds + PG8_SB(b, h) + boff + n * 2048 + k * 1024); } while (0)
; #define PG8_MMA(ai, bj, At, Bt) do { __builtin_amdgcn_s_setprio(1); _Pragma("unroll") for (int m = 0; m < 4; ++m) _Pragma("unroll") for (int n = 0; n < 2; ++n) _Pragma("unroll") for (int k = 0; k < 2; ++k) \
;         acc[ai][bj][m][n] = __builtin_amdgcn_mfma_f32_16x16x32_bf16(Bt[n][k], At[m][k], acc[ai][bj][m][n], 0, 0, 0); __builtin_amdgcn_s_setprio(0); } while (0)
; #define PG8_WAIT_V(n) asm volatile("s_waitcnt vmcnt(" #n ")" ::: "memory")
; template <class Epi, class Sched, bool ABLK = false, bool ALIGN_EPI = true, bool SP2 = true, bool BBLK = true>
; __device__ __forceinline__ void gemm_phase(LAS unsigned char* lds, const Gemm g, const Sched& S, const Epi& E) {
;     ...
;         for (int t = 0; t < nt; t += 2) {
;             const bool last = (t == nt - 2);
;             const char* a1 = a_tile(uA, tbA + t + 1);
;             const char* a2 = last ? a_tile(nuA, ntbA) : a_tile(uA, tbA + t + 2); const char* b2 = last ? nB : cB + (size_t)(t + 2) * kstepB;
;             const char* a3 = last ? a_tile(nuA, ntbA + 1) : a_tile(uA, tbA + t + 3); const char* b3 = b2 + kstepB;
;             if (last && has_next) S.a_ready(nxt);
;             if constexpr (SP2) {
;             PG8_LDB(B0, 0, 0); PG8_LDB(B1, 0, 1); PG8_SCHED; PG8_LDA(At, 0, 0); PG8_STAGE(PG8_SA(1, 1), a1 + hstepA, voffA);
;             PG8_WAIT_V(8); PG8_WAIT_L(0); PG8_BAR; PG8_MMA(0, 0, At, B0); PG8_MMA(0, 1, At, B1); PG8_BAR; PG8_SCHED;
;             PG8_LDA(At, 0, 1); PG8_STAGE(PG8_SB(0, 0), b2, voffB); PG8_STAGE(PG8_SB(0, 1), b2 + hstepB, voffB); PG8_STAGE(PG8_SA(0, 0), a2, voffA);
;             PG8_WAIT_V(8); PG8_WAIT_L(0); PG8_BAR; PG8_MMA(1, 0, At, B0); PG8_MMA(1, 1, At, B1); PG8_BAR; PG8_SCHED;
.LBB0_2263:
	ds_read_b128 v[172:175], v168
	ds_read_b128 v[176:179], v168 offset:1024
	ds_read_b128 v[180:183], v168 offset:2048
	ds_read_b128 v[184:187], v168 offset:3072
	ds_read_b128 v[188:191], v169
	ds_read_b128 v[192:195], v169 offset:1024
	ds_read_b128 v[196:199], v169 offset:2048
	ds_read_b128 v[200:203], v169 offset:3072
	s_add_u32 s30, s26, s28
	s_addc_u32 s31, s27, s29
	s_add_u32 s36, s30, 0x100
	s_addc_u32 s37, s31, 0
	s_add_u32 s30, s30, 0x180
	s_addc_u32 s31, s31, 0
	s_cmpk_eq_i32 s28, 0xf00
	s_cselect_b32 s31, s54, s31
	s_cselect_b32 s30, s23, s30
	s_cselect_b32 s35, s13, s56
	s_cselect_b32 s34, s15, s55
	s_cselect_b32 s37, s4, s37
	s_cselect_b32 s36, s5, s36
	s_mov_b32 m0, s50
	v_lshl_add_u64 v[236:237], v[164:165], 0, s[28:29]
	ds_read_b128 v[204:207], v170
	ds_read_b128 v[208:211], v170 offset:1024
	ds_read_b128 v[212:215], v170 offset:2048
	ds_read_b128 v[216:219], v170 offset:3072
	ds_read_b128 v[220:223], v170 offset:4096
	ds_read_b128 v[224:227], v170 offset:5120
	ds_read_b128 v[228:231], v170 offset:6144
	ds_read_b128 v[232:235], v170 offset:7168
	global_load_lds_dwordx4 v[236:237], off
	v_lshl_add_u64 v[236:237], v[166:167], 0, s[28:29]
	s_mov_b32 m0, s51
	s_nop 0
	global_load_lds_dwordx4 v[236:237], off
	s_waitcnt vmcnt(8) lgkmcnt(0)
	s_barrier
	v_mfma_f32_16x16x32_bf16 v[126:129], v[172:175], v[204:207], v[126:129]
	v_mfma_f32_16x16x32_bf16 v[122:125], v[180:183], v[204:207], v[122:125]
	v_mfma_f32_16x16x32_bf16 v[110:113], v[172:175], v[212:215], v[110:113]
	v_mfma_f32_16x16x32_bf16 v[106:109], v[180:183], v[212:215], v[106:109]
	v_mfma_f32_16x16x32_bf16 v[94:97], v[172:175], v[220:223], v[94:97]
	v_mfma_f32_16x16x32_bf16 v[90:93], v[180:183], v[220:223], v[90:93]
	v_mfma_f32_16x16x32_bf16 v[78:81], v[172:175], v[228:231], v[78:81]
	v_mfma_f32_16x16x32_bf16 v[74:77], v[180:183], v[228:231], v[74:77]
	v_mfma_f32_16x16x32_bf16 v[126:129], v[176:179], v[208:211], v[126:129]
	v_mfma_f32_16x16x32_bf16 v[122:125], v[184:187], v[208:211], v[122:125]
	v_mfma_f32_16x16x32_bf16 v[110:113], v[176:179], v[216:219], v[110:113]
	v_mfma_f32_16x16x32_bf16 v[106:109], v[184:187], v[216:219], v[106:109]
	v_mfma_f32_16x16x32_bf16 v[94:97], v[176:179], v[224:227], v[94:97]
	v_mfma_f32_16x16x32_bf16 v[90:93], v[184:187], v[224:227], v[90:93]
	v_mfma_f32_16x16x32_bf16 v[78:81], v[176:179], v[232:235], v[78:81]
	v_mfma_f32_16x16x32_bf16 v[74:77], v[184:187], v[232:235], v[74:77]
	v_mfma_f32_16x16x32_bf16 v[118:121], v[188:191], v[204:207], v[118:121]
	v_mfma_f32_16x16x32_bf16 v[114:117], v[196:199], v[204:207], v[114:117]
	v_mfma_f32_16x16x32_bf16 v[102:105], v[188:191], v[212:215], v[102:105]
	v_mfma_f32_16x16x32_bf16 v[98:101], v[196:199], v[212:215], v[98:101]
	v_mfma_f32_16x16x32_bf16 v[86:89], v[188:191], v[220:223], v[86:89]
	v_mfma_f32_16x16x32_bf16 v[82:85], v[196:199], v[220:223], v[82:85]
	v_mfma_f32_16x16x32_bf16 v[70:73], v[188:191], v[228:231], v[70:73]
	v_mfma_f32_16x16x32_bf16 v[66:69], v[196:199], v[228:231], v[66:69]
	v_mfma_f32_16x16x32_bf16 v[118:121], v[192:195], v[208:211], v[118:121]
	v_mfma_f32_16x16x32_bf16 v[114:117], v[200:203], v[208:211], v[114:117]
	v_mfma_f32_16x16x32_bf16 v[102:105], v[192:195], v[216:219], v[102:105]
	v_mfma_f32_16x16x32_bf16 v[98:101], v[200:203], v[216:219], v[98:101]
	v_mfma_f32_16x16x32_bf16 v[86:89], v[192:195], v[224:227], v[86:89]
	v_mfma_f32_16x16x32_bf16 v[82:85], v[200:203], v[224:227], v[82:85]
	v_mfma_f32_16x16x32_bf16 v[70:73], v[192:195], v[232:235], v[70:73]
	v_mfma_f32_16x16x32_bf16 v[66:69], v[200:203], v[232:235], v[66:69]
	s_barrier
	s_mov_b32 m0, s52
	s_add_u32 s58, s34, 0x4000
	ds_read_b128 v[204:207], v170 offset:16384
	ds_read_b128 v[208:211], v170 offset:17408
	ds_read_b128 v[212:215], v170 offset:18432
	ds_read_b128 v[216:219], v170 offset:19456
	ds_read_b128 v[220:223], v170 offset:20480
	ds_read_b128 v[224:227], v170 offset:21504
	ds_read_b128 v[228:231], v170 offset:22528
	ds_read_b128 v[232:235], v170 offset:23552
	global_load_lds_dwordx4 v134, s[34:35]
	s_mov_b32 m0, s53
	s_addc_u32 s59, s35, 0
	s_add_i32 s62, s73, s40
	global_load_lds_dwordx4 v130, s[34:35]
	s_mov_b32 m0, s62
	s_nop 0
	global_load_lds_dwordx4 v134, s[58:59]
	s_add_i32 m0, s62, 0x2000
	s_nop 0
	global_load_lds_dwordx4 v130, s[58:59]
	s_mov_b32 m0, s25
	s_nop 0
	global_load_lds_dwordx4 v136, s[36:37]
	s_mov_b32 m0, s43
	s_nop 0
	global_load_lds_dwordx4 v132, s[36:37]
	s_waitcnt vmcnt(8) lgkmcnt(0)
	s_barrier
	v_mfma_f32_16x16x32_bf16 v[62:65], v[172:175], v[204:207], v[62:65]
	v_mfma_f32_16x16x32_bf16 v[58:61], v[180:183], v[204:207], v[58:61]
	v_mfma_f32_16x16x32_bf16 v[46:49], v[172:175], v[212:215], v[46:49]
	v_mfma_f32_16x16x32_bf16 v[42:45], v[180:183], v[212:215], v[42:45]
	v_mfma_f32_16x16x32_bf16 v[30:33], v[172:175], v[220:223], v[30:33]
	v_mfma_f32_16x16x32_bf16 v[26:29], v[180:183], v[220:223], v[26:29]
	v_mfma_f32_16x16x32_bf16 v[14:17], v[172:175], v[228:231], v[14:17]
	v_mfma_f32_16x16x32_bf16 v[10:13], v[180:183], v[228:231], v[10:13]
	v_mfma_f32_16x16x32_bf16 v[62:65], v[176:179], v[208:211], v[62:65]
	v_mfma_f32_16x16x32_bf16 v[58:61], v[184:187], v[208:211], v[58:61]
	v_mfma_f32_16x16x32_bf16 v[46:49], v[176:179], v[216:219], v[46:49]
	v_mfma_f32_16x16x32_bf16 v[42:45], v[184:187], v[216:219], v[42:45]
	v_mfma_f32_16x16x32_bf16 v[30:33], v[176:179], v[224:227], v[30:33]
	v_mfma_f32_16x16x32_bf16 v[26:29], v[184:187], v[224:227], v[26:29]
	v_mfma_f32_16x16x32_bf16 v[14:17], v[176:179], v[232:235], v[14:17]
	v_mfma_f32_16x16x32_bf16 v[10:13], v[184:187], v[232:235], v[10:13]
	v_mfma_f32_16x16x32_bf16 v[54:57], v[188:191], v[204:207], v[54:57]
	v_mfma_f32_16x16x32_bf16 v[50:53], v[196:199], v[204:207], v[50:53]
	v_mfma_f32_16x16x32_bf16 v[38:41], v[188:191], v[212:215], v[38:41]
	v_mfma_f32_16x16x32_bf16 v[34:37], v[196:199], v[212:215], v[34:37]
	v_mfma_f32_16x16x32_bf16 v[22:25], v[188:191], v[220:223], v[22:25]
	v_mfma_f32_16x16x32_bf16 v[18:21], v[196:199], v[220:223], v[18:21]
	v_mfma_f32_16x16x32_bf16 v[6:9], v[188:191], v[228:231], v[6:9]
	v_mfma_f32_16x16x32_bf16 v[2:5], v[196:199], v[228:231], v[2:5]
	v_mfma_f32_16x16x32_bf16 v[54:57], v[192:195], v[208:211], v[54:57]
	v_mfma_f32_16x16x32_bf16 v[50:53], v[200:203], v[208:211], v[50:53]
	v_mfma_f32_16x16x32_bf16 v[38:41], v[192:195], v[216:219], v[38:41]
	v_mfma_f32_16x16x32_bf16 v[34:37], v[200:203], v[216:219], v[34:37]
	v_mfma_f32_16x16x32_bf16 v[22:25], v[192:195], v[224:227], v[22:25]
	v_mfma_f32_16x16x32_bf16 v[18:21], v[200:203], v[224:227], v[18:21]
	v_mfma_f32_16x16x32_bf16 v[6:9], v[192:195], v[232:235], v[6:9]
	v_mfma_f32_16x16x32_bf16 v[2:5], v[200:203], v[232:235], v[2:5]
	s_barrier
; #define PG8_STAGE(bufoff, gbase, voff) do { _Pragma("unroll") for (int _i = 0; _i < 2; ++_i) \
;         __builtin_amdgcn_global_load_lds((const unsigned*)((const char*)(gbase) + (voff)[_i]), (LAS unsigned*)(lds + (bufoff) + ldsw + _i * 8192), 16, 0, 0); } while (0)
; #define PG8_LDA(dst, b, h) do { _Pragma("unroll") for (int m = 0; m < 4; ++m) _Pragma("unroll") for (int k = 0; k < 2; ++k) dst[m][k] = *(const LAS bf16x8*)(lds + PG8_SA(b, h) + aoff + m * 2048 + k * 1024); } while (0)
; #define PG8_LDB(dst, b, h) do { _Pragma("unroll") for (int n = 0; n < 2; ++n) _Pragma("unroll") for (int k = 0; k < 2; ++k) dst[n][k] = *(const LAS bf16x8*)(lds + PG8_SB(b, h) + boff + n * 2048 + k * 1024); } while (0)
; #define PG8_MMA(ai, bj, At, Bt) do { __builtin_amdgcn_s_setprio(1); _Pragma("unroll") for (int m = 0; m < 4; ++m) _Pragma("unroll") for (int n = 0; n < 2; ++n) _Pragma("unroll") for (int k = 0; k < 2; ++k) \
;         acc[ai][bj][m][n] = __builtin_amdgcn_mfma_f32_16x16x32_bf16(Bt[n][k], At[m][k], acc[ai][bj][m][n], 0, 0, 0); __builtin_amdgcn_s_setprio(0); } while (0)
; #define PG8_WAIT_V(n) asm volatile("s_waitcnt vmcnt(" #n ")" ::: "memory")
; #define PG8_WAIT_L(n) asm volatile("s_waitcnt lgkmcnt(" #n ")" ::: "memory")
; #define PG8_BAR __builtin_amdgcn_s_barrier()
; #define PG8_SCHED __builtin_amdgcn_sched_barrier(0)
; template <class Epi, class Sched, bool ABLK = false, bool ALIGN_EPI = true, bool SP2 = true, bool BBLK = true>
; __device__ __forceinline__ void gemm_phase(LAS unsigned char* lds, const Gemm g, const Sched& S, const Epi& E) {
;     ...
;             PG8_WAIT_V(8); PG8_WAIT_L(0); PG8_BAR; PG8_MMA(1, 0, At, B0); PG8_MMA(1, 1, At, B1); PG8_BAR; PG8_SCHED;
;             PG8_LDB(B0, 1, 0); PG8_LDB(B1, 1, 1); PG8_SCHED; PG8_LDA(At, 1, 0); PG8_STAGE(PG8_SA(0, 1), a2 + hstepA, voffA);
;             PG8_WAIT_V(8); PG8_WAIT_L(0); PG8_BAR; PG8_MMA(0, 0, At, B0); PG8_MMA(0, 1, At, B1); PG8_BAR; PG8_SCHED;
;             PG8_LDA(At, 1, 1); PG8_STAGE(PG8_SB(1, 0), b3, voffB); PG8_STAGE(PG8_SB(1, 1), b3 + hstepB, voffB); PG8_STAGE(PG8_SA(1, 0), a3, voffA);
;             PG8_WAIT_V(8); PG8_WAIT_L(0); PG8_BAR; PG8_MMA(1, 0, At, B0); PG8_MMA(1, 1, At, B1); PG8_BAR; PG8_SCHED;
	v_add_u32_e32 v171, s60, v1
	ds_read_b128 v[172:175], v171
	ds_read_b128 v[176:179], v171 offset:1024
	ds_read_b128 v[180:183], v171 offset:2048
	ds_read_b128 v[184:187], v171 offset:3072
	v_add_u32_e32 v171, s61, v1
	ds_read_b128 v[188:191], v171
	ds_read_b128 v[192:195], v171 offset:1024
	ds_read_b128 v[196:199], v171 offset:2048
	ds_read_b128 v[200:203], v171 offset:3072
	s_add_u32 s36, s36, 0x80000
	s_addc_u32 s37, s37, 0
	s_mov_b32 m0, s44
	ds_read_b128 v[204:207], v170 offset:32768
	ds_read_b128 v[208:211], v170 offset:33792
	ds_read_b128 v[212:215], v170 offset:34816
	ds_read_b128 v[216:219], v170 offset:35840
	ds_read_b128 v[220:223], v170 offset:36864
	ds_read_b128 v[224:227], v170 offset:37888
	ds_read_b128 v[228:231], v170 offset:38912
	ds_read_b128 v[232:235], v170 offset:39936
	global_load_lds_dwordx4 v136, s[36:37]
	s_mov_b32 m0, s45
	s_nop 0
	global_load_lds_dwordx4 v132, s[36:37]
	s_waitcnt vmcnt(8) lgkmcnt(0)
	s_barrier
	v_mfma_f32_16x16x32_bf16 v[126:129], v[172:175], v[204:207], v[126:129]
	v_mfma_f32_16x16x32_bf16 v[122:125], v[180:183], v[204:207], v[122:125]
	v_mfma_f32_16x16x32_bf16 v[110:113], v[172:175], v[212:215], v[110:113]
	v_mfma_f32_16x16x32_bf16 v[106:109], v[180:183], v[212:215], v[106:109]
	v_mfma_f32_16x16x32_bf16 v[94:97], v[172:175], v[220:223], v[94:97]
	v_mfma_f32_16x16x32_bf16 v[90:93], v[180:183], v[220:223], v[90:93]
	v_mfma_f32_16x16x32_bf16 v[78:81], v[172:175], v[228:231], v[78:81]
	v_mfma_f32_16x16x32_bf16 v[74:77], v[180:183], v[228:231], v[74:77]
	v_mfma_f32_16x16x32_bf16 v[126:129], v[176:179], v[208:211], v[126:129]
	v_mfma_f32_16x16x32_bf16 v[122:125], v[184:187], v[208:211], v[122:125]
	v_mfma_f32_16x16x32_bf16 v[110:113], v[176:179], v[216:219], v[110:113]
	v_mfma_f32_16x16x32_bf16 v[106:109], v[184:187], v[216:219], v[106:109]
	v_mfma_f32_16x16x32_bf16 v[94:97], v[176:179], v[224:227], v[94:97]
	v_mfma_f32_16x16x32_bf16 v[90:93], v[184:187], v[224:227], v[90:93]
	v_mfma_f32_16x16x32_bf16 v[78:81], v[176:179], v[232:235], v[78:81]
	v_mfma_f32_16x16x32_bf16 v[74:77], v[184:187], v[232:235], v[74:77]
	v_mfma_f32_16x16x32_bf16 v[118:121], v[188:191], v[204:207], v[118:121]
	v_mfma_f32_16x16x32_bf16 v[114:117], v[196:199], v[204:207], v[114:117]
	v_mfma_f32_16x16x32_bf16 v[102:105], v[188:191], v[212:215], v[102:105]
	v_mfma_f32_16x16x32_bf16 v[98:101], v[196:199], v[212:215], v[98:101]
	v_mfma_f32_16x16x32_bf16 v[86:89], v[188:191], v[220:223], v[86:89]
	v_mfma_f32_16x16x32_bf16 v[82:85], v[196:199], v[220:223], v[82:85]
	v_mfma_f32_16x16x32_bf16 v[70:73], v[188:191], v[228:231], v[70:73]
	v_mfma_f32_16x16x32_bf16 v[66:69], v[196:199], v[228:231], v[66:69]
	v_mfma_f32_16x16x32_bf16 v[118:121], v[192:195], v[208:211], v[118:121]
	v_mfma_f32_16x16x32_bf16 v[114:117], v[200:203], v[208:211], v[114:117]
	v_mfma_f32_16x16x32_bf16 v[102:105], v[192:195], v[216:219], v[102:105]
	v_mfma_f32_16x16x32_bf16 v[98:101], v[200:203], v[216:219], v[98:101]
	v_mfma_f32_16x16x32_bf16 v[86:89], v[192:195], v[224:227], v[86:89]
	v_mfma_f32_16x16x32_bf16 v[82:85], v[200:203], v[224:227], v[82:85]
	v_mfma_f32_16x16x32_bf16 v[70:73], v[192:195], v[232:235], v[70:73]
	v_mfma_f32_16x16x32_bf16 v[66:69], v[200:203], v[232:235], v[66:69]
	s_barrier
	s_add_u32 s36, s34, 0x8000
	s_addc_u32 s37, s35, 0
	s_add_i32 s58, s60, s40
	s_mov_b32 m0, s58
	ds_read_b128 v[204:207], v170 offset:49152
	ds_read_b128 v[208:211], v170 offset:50176
	ds_read_b128 v[212:215], v170 offset:51200
	ds_read_b128 v[216:219], v170 offset:52224
	ds_read_b128 v[220:223], v170 offset:53248
	ds_read_b128 v[224:227], v170 offset:54272
	ds_read_b128 v[228:231], v170 offset:55296
	ds_read_b128 v[232:235], v170 offset:56320
	global_load_lds_dwordx4 v134, s[36:37]
	s_add_i32 m0, s58, 0x2000
	s_add_u32 s34, s34, 0xc000
	v_lshl_add_u64 v[236:237], s[36:37], 0, v[130:131]
	s_addc_u32 s35, s35, 0
	s_add_i32 s36, s61, s40
	global_load_lds_dwordx4 v[236:237], off
	s_mov_b32 m0, s36
	s_nop 0
	global_load_lds_dwordx4 v134, s[34:35]
	s_add_i32 m0, s36, 0x2000
	s_nop 0
	global_load_lds_dwordx4 v130, s[34:35]
	s_mov_b32 m0, s48
	s_nop 0
	global_load_lds_dwordx4 v136, s[30:31]
	s_mov_b32 m0, s49
	s_nop 0
	global_load_lds_dwordx4 v132, s[30:31]
	s_waitcnt vmcnt(8) lgkmcnt(0)
	s_barrier
	v_mfma_f32_16x16x32_bf16 v[62:65], v[172:175], v[204:207], v[62:65]
	v_mfma_f32_16x16x32_bf16 v[58:61], v[180:183], v[204:207], v[58:61]
	v_mfma_f32_16x16x32_bf16 v[46:49], v[172:175], v[212:215], v[46:49]
	v_mfma_f32_16x16x32_bf16 v[42:45], v[180:183], v[212:215], v[42:45]
	v_mfma_f32_16x16x32_bf16 v[30:33], v[172:175], v[220:223], v[30:33]
	v_mfma_f32_16x16x32_bf16 v[26:29], v[180:183], v[220:223], v[26:29]
	v_mfma_f32_16x16x32_bf16 v[14:17], v[172:175], v[228:231], v[14:17]
	v_mfma_f32_16x16x32_bf16 v[10:13], v[180:183], v[228:231], v[10:13]
	v_mfma_f32_16x16x32_bf16 v[62:65], v[176:179], v[208:211], v[62:65]
	v_mfma_f32_16x16x32_bf16 v[58:61], v[184:187], v[208:211], v[58:61]
	v_mfma_f32_16x16x32_bf16 v[46:49], v[176:179], v[216:219], v[46:49]
	v_mfma_f32_16x16x32_bf16 v[42:45], v[184:187], v[216:219], v[42:45]
	v_mfma_f32_16x16x32_bf16 v[30:33], v[176:179], v[224:227], v[30:33]
	v_mfma_f32_16x16x32_bf16 v[26:29], v[184:187], v[224:227], v[26:29]
	v_mfma_f32_16x16x32_bf16 v[14:17], v[176:179], v[232:235], v[14:17]
	v_mfma_f32_16x16x32_bf16 v[10:13], v[184:187], v[232:235], v[10:13]
	v_mfma_f32_16x16x32_bf16 v[54:57], v[188:191], v[204:207], v[54:57]
	v_mfma_f32_16x16x32_bf16 v[50:53], v[196:199], v[204:207], v[50:53]
	v_mfma_f32_16x16x32_bf16 v[38:41], v[188:191], v[212:215], v[38:41]
	v_mfma_f32_16x16x32_bf16 v[34:37], v[196:199], v[212:215], v[34:37]
	v_mfma_f32_16x16x32_bf16 v[22:25], v[188:191], v[220:223], v[22:25]
	v_mfma_f32_16x16x32_bf16 v[18:21], v[196:199], v[220:223], v[18:21]
	v_mfma_f32_16x16x32_bf16 v[6:9], v[188:191], v[228:231], v[6:9]
	v_mfma_f32_16x16x32_bf16 v[2:5], v[196:199], v[228:231], v[2:5]
	v_mfma_f32_16x16x32_bf16 v[54:57], v[192:195], v[208:211], v[54:57]
	v_mfma_f32_16x16x32_bf16 v[50:53], v[200:203], v[208:211], v[50:53]
	v_mfma_f32_16x16x32_bf16 v[38:41], v[192:195], v[216:219], v[38:41]
	v_mfma_f32_16x16x32_bf16 v[34:37], v[200:203], v[216:219], v[34:37]
	v_mfma_f32_16x16x32_bf16 v[22:25], v[192:195], v[224:227], v[22:25]
	v_mfma_f32_16x16x32_bf16 v[18:21], v[200:203], v[224:227], v[18:21]
	v_mfma_f32_16x16x32_bf16 v[6:9], v[192:195], v[232:235], v[6:9]
	v_mfma_f32_16x16x32_bf16 v[2:5], v[200:203], v[232:235], v[2:5]
	s_barrier
; __device__ __forceinline__ unsigned pk2(float lo, float hi) { const f32x2 v = {lo, hi}; return __builtin_bit_cast(unsigned, __builtin_convertvector(v, bf16x2_t)); }
; __device__ __forceinline__ void store_pair(unsigned char* own, size_t stride8, int hi_off, u32x4 lo, u32x4 hi, bool upper) {
;     const u32x4 tlo = ror8(lo), thi = ror8(hi);
;     const u32x4 A = upper ? thi : lo, B = upper ? hi : tlo;
;     unsigned char* pa = upper ? own - stride8 + hi_off : own;
;     unsigned char* pb = upper ? own + hi_off : own + stride8;
;     *(u32x4*)pa = A; *(u32x4*)pb = B;
; }
;     __device__ __forceinline__ void operator()(const f32x4 (&acc)[2][2][4][2], const Unit& u, int wr, int wc, int fr, int fq) const {
; #pragma unroll
;         for (int ai = 0; ai < 2; ++ai)
; #pragma unroll
;             for (int m = 0; m < 4; ++m) { unsigned char* rowp = (unsigned char*)(H + ((size_t)(u.pm * (FF / 64) + u.pn * 4 + wc) * 256 + (wr * 64 + fr + ai * 128 + m * 16)) * 64 + 8 * fq); u32x4 w[2];
; #pragma unroll
;                 for (int bj = 0; bj < 2; ++bj) { f32x4 v0 = acc[ai][bj][m][0], v1 = acc[ai][bj][m][1];
; #pragma unroll
;                     for (int j = 0; j < 4; ++j) { const float a = fmaxf(v0[j], 0.f), b = fmaxf(v1[j], 0.f); v0[j] = a * a; v1[j] = b * b; }
;                     w[bj].x = pk2(v0[0], v0[1]); w[bj].y = pk2(v0[2], v0[3]); w[bj].z = pk2(v1[0], v1[1]); w[bj].w = pk2(v1[2], v1[3]); }
;                 store_pair(rowp, (size_t)8 * 64 * 2, 64, w[0], w[1], fr >= 8); }
	s_add_i32 s57, s57, 2
	s_add_u32 s28, s28, 0x100
	s_addc_u32 s29, s29, 0
	s_add_u32 s55, s55, 0x10000
	s_addc_u32 s56, s56, 0
	s_cmp_gt_u32 s57, 29
	s_cbranch_scc0 .LBB0_2263
	s_lshl_b32 s4, s22, 7
	s_lshl_b32 s5, s24, 2
	s_add_i32 s5, s5, s4
	s_or_b32 s4, s5, s47
	s_ashr_i32 s5, s4, 31
	s_lshl_b64 s[4:5], s[4:5], 15
	s_add_u32 s22, s1, s4
	v_max_f32_e32 v126, 0, v126
	v_max_f32_e32 v122, 0, v122
	v_max_f32_e32 v127, 0, v127
	v_max_f32_e32 v123, 0, v123
	v_max_f32_e32 v128, 0, v128
	v_max_f32_e32 v124, 0, v124
	v_max_f32_e32 v129, 0, v129
	v_max_f32_e32 v125, 0, v125
	v_max_f32_e32 v118, 0, v118
	v_max_f32_e32 v114, 0, v114
	v_max_f32_e32 v119, 0, v119
	v_max_f32_e32 v115, 0, v115
	v_max_f32_e32 v120, 0, v120
	v_max_f32_e32 v116, 0, v116
	v_max_f32_e32 v121, 0, v121
	v_max_f32_e32 v117, 0, v117
	s_addc_u32 s23, s33, s5
	v_pk_mul_f32 v[126:127], v[126:127], v[126:127]
	v_pk_mul_f32 v[122:123], v[122:123], v[122:123]
	v_pk_mul_f32 v[128:129], v[128:129], v[128:129]
	v_pk_mul_f32 v[124:125], v[124:125], v[124:125]
	v_pk_mul_f32 v[118:119], v[118:119], v[118:119]
	v_pk_mul_f32 v[114:115], v[114:115], v[114:115]
	v_pk_mul_f32 v[120:121], v[120:121], v[120:121]
	v_pk_mul_f32 v[116:117], v[116:117], v[116:117]
	v_lshl_add_u64 v[164:165], s[22:23], 0, v[144:145]
	v_cvt_pk_bf16_f32 v126, v126, v127
	v_cvt_pk_bf16_f32 v127, v128, v129
	v_cvt_pk_bf16_f32 v128, v122, v123
	v_cvt_pk_bf16_f32 v129, v124, v125
	v_cvt_pk_bf16_f32 v118, v118, v119
	v_cvt_pk_bf16_f32 v119, v120, v121
	v_cvt_pk_bf16_f32 v114, v114, v115
	v_cvt_pk_bf16_f32 v115, v116, v117
	v_lshl_add_u64 v[122:123], v[164:165], 0, v[138:139]
	v_mov_b32_dpp v120, v126 row_ror:8 row_mask:0xf bank_mask:0xf bound_ctrl:1
	v_mov_b32_dpp v121, v127 row_ror:8 row_mask:0xf bank_mask:0xf bound_ctrl:1
	v_mov_b32_dpp v116, v128 row_ror:8 row_mask:0xf bank_mask:0xf bound_ctrl:1
	v_mov_b32_dpp v117, v129 row_ror:8 row_mask:0xf bank_mask:0xf bound_ctrl:1
	v_mov_b32_dpp v164, v118 row_ror:8 row_mask:0xf bank_mask:0xf bound_ctrl:1
	v_mov_b32_dpp v165, v119 row_ror:8 row_mask:0xf bank_mask:0xf bound_ctrl:1
	v_mov_b32_dpp v166, v114 row_ror:8 row_mask:0xf bank_mask:0xf bound_ctrl:1
	v_mov_b32_dpp v167, v115 row_ror:8 row_mask:0xf bank_mask:0xf bound_ctrl:1
	v_max_f32_e32 v110, 0, v110
	v_max_f32_e32 v106, 0, v106
	v_max_f32_e32 v111, 0, v111
	v_max_f32_e32 v107, 0, v107
	v_max_f32_e32 v112, 0, v112
	v_max_f32_e32 v108, 0, v108
	v_max_f32_e32 v113, 0, v113
	v_max_f32_e32 v109, 0, v109
	v_max_f32_e32 v102, 0, v102
	v_max_f32_e32 v98, 0, v98
	v_max_f32_e32 v103, 0, v103
	v_max_f32_e32 v99, 0, v99
	v_max_f32_e32 v104, 0, v104
	v_max_f32_e32 v100, 0, v100
	v_max_f32_e32 v105, 0, v105
	v_max_f32_e32 v101, 0, v101
	v_lshl_add_u64 v[124:125], v[122:123], 0, v[140:141]
	v_cndmask_b32_e64 v117, v117, v115, s[2:3]
	v_cndmask_b32_e64 v116, v116, v114, s[2:3]
	v_cndmask_b32_e64 v115, v121, v119, s[2:3]
	v_cndmask_b32_e64 v114, v120, v118, s[2:3]
	v_cndmask_b32_e64 v121, v129, v167, s[2:3]
	v_cndmask_b32_e64 v120, v128, v166, s[2:3]
	v_cndmask_b32_e64 v119, v127, v165, s[2:3]
	v_cndmask_b32_e64 v118, v126, v164, s[2:3]
	v_pk_mul_f32 v[110:111], v[110:111], v[110:111]
	v_pk_mul_f32 v[106:107], v[106:107], v[106:107]
	v_pk_mul_f32 v[112:113], v[112:113], v[112:113]
	v_pk_mul_f32 v[108:109], v[108:109], v[108:109]
	v_pk_mul_f32 v[102:103], v[102:103], v[102:103]
	v_pk_mul_f32 v[98:99], v[98:99], v[98:99]
	v_pk_mul_f32 v[104:105], v[104:105], v[104:105]
	v_pk_mul_f32 v[100:101], v[100:101], v[100:101]
	v_lshl_add_u64 v[122:123], v[122:123], 0, v[142:143]
	s_and_b64 vcc, exec, s[10:11]
	s_cbranch_vccz .LBB0_2266
	s_barrier
.LBB0_2266:
	global_store_dwordx4 v[124:125], v[118:121], off
	global_store_dwordx4 v[122:123], v[114:117], off
	v_cvt_pk_bf16_f32 v110, v110, v111
	v_cvt_pk_bf16_f32 v111, v112, v113
	v_lshl_add_u64 v[114:115], s[22:23], 0, v[146:147]
	v_cvt_pk_bf16_f32 v112, v106, v107
	v_cvt_pk_bf16_f32 v113, v108, v109
	v_cvt_pk_bf16_f32 v102, v102, v103
	v_cvt_pk_bf16_f32 v103, v104, v105
	v_cvt_pk_bf16_f32 v98, v98, v99
	v_cvt_pk_bf16_f32 v99, v100, v101
	v_lshl_add_u64 v[106:107], v[114:115], 0, v[138:139]
	v_mov_b32_dpp v104, v110 row_ror:8 row_mask:0xf bank_mask:0xf bound_ctrl:1
	v_mov_b32_dpp v105, v111 row_ror:8 row_mask:0xf bank_mask:0xf bound_ctrl:1
	v_mov_b32_dpp v100, v112 row_ror:8 row_mask:0xf bank_mask:0xf bound_ctrl:1
	v_mov_b32_dpp v101, v113 row_ror:8 row_mask:0xf bank_mask:0xf bound_ctrl:1
	v_mov_b32_dpp v114, v102 row_ror:8 row_mask:0xf bank_mask:0xf bound_ctrl:1
	v_mov_b32_dpp v115, v103 row_ror:8 row_mask:0xf bank_mask:0xf bound_ctrl:1
	v_mov_b32_dpp v116, v98 row_ror:8 row_mask:0xf bank_mask:0xf bound_ctrl:1
	v_mov_b32_dpp v117, v99 row_ror:8 row_mask:0xf bank_mask:0xf bound_ctrl:1
	v_max_f32_e32 v94, 0, v94
	v_max_f32_e32 v90, 0, v90
	v_max_f32_e32 v95, 0, v95
	v_max_f32_e32 v91, 0, v91
	v_max_f32_e32 v96, 0, v96
	v_max_f32_e32 v92, 0, v92
	v_max_f32_e32 v97, 0, v97
	v_max_f32_e32 v93, 0, v93
	v_max_f32_e32 v86, 0, v86
	v_max_f32_e32 v82, 0, v82
	v_max_f32_e32 v87, 0, v87
	v_max_f32_e32 v83, 0, v83
	v_max_f32_e32 v88, 0, v88
	v_max_f32_e32 v84, 0, v84
	v_max_f32_e32 v89, 0, v89
	v_max_f32_e32 v85, 0, v85
	v_lshl_add_u64 v[108:109], v[106:107], 0, v[140:141]
	v_cndmask_b32_e64 v101, v101, v99, s[2:3]
	v_cndmask_b32_e64 v100, v100, v98, s[2:3]
	v_cndmask_b32_e64 v99, v105, v103, s[2:3]
	v_cndmask_b32_e64 v98, v104, v102, s[2:3]
	v_cndmask_b32_e64 v105, v113, v117, s[2:3]
	v_cndmask_b32_e64 v104, v112, v116, s[2:3]
	v_cndmask_b32_e64 v103, v111, v115, s[2:3]
	v_cndmask_b32_e64 v102, v110, v114, s[2:3]
	v_pk_mul_f32 v[94:95], v[94:95], v[94:95]
	v_pk_mul_f32 v[90:91], v[90:91], v[90:91]
; __device__ __forceinline__ unsigned pk2(float lo, float hi) { const f32x2 v = {lo, hi}; return __builtin_bit_cast(unsigned, __builtin_convertvector(v, bf16x2_t)); }
; __device__ __forceinline__ u32x4 ror8(u32x4 v) { u32x4 r;
; #pragma unroll
;     for (int i = 0; i < 4; ++i) r[i] = (unsigned)__builtin_amdgcn_mov_dpp((int)v[i], 0x128, 0xf, 0xf, true);
;     return r; }
; __device__ __forceinline__ void store_pair(unsigned char* own, size_t stride8, int hi_off, u32x4 lo, u32x4 hi, bool upper) {
;     const u32x4 tlo = ror8(lo), thi = ror8(hi);
;     const u32x4 A = upper ? thi : lo, B = upper ? hi : tlo;
;     unsigned char* pa = upper ? own - stride8 + hi_off : own;
;     unsigned char* pb = upper ? own + hi_off : own + stride8;
;     *(u32x4*)pa = A; *(u32x4*)pb = B;
;     __device__ __forceinline__ void operator()(const f32x4 (&acc)[2][2][4][2], const Unit& u, int wr, int wc, int fr, int fq) const {
;     ...
;             for (int m = 0; m < 4; ++m) { unsigned char* rowp = (unsigned char*)(H + ((size_t)(u.pm * (FF / 64) + u.pn * 4 + wc) * 256 + (wr * 64 + fr + ai * 128 + m * 16)) * 64 + 8 * fq); u32x4 w[2];
; #pragma unroll
;                 for (int bj = 0; bj < 2; ++bj) { f32x4 v0 = acc[ai][bj][m][0], v1 = acc[ai][bj][m][1];
; #pragma unroll
;                     for (int j = 0; j < 4; ++j) { const float a = fmaxf(v0[j], 0.f), b = fmaxf(v1[j], 0.f); v0[j] = a * a; v1[j] = b * b; }
;                     w[bj].x = pk2(v0[0], v0[1]); w[bj].y = pk2(v0[2], v0[3]); w[bj].z = pk2(v1[0], v1[1]); w[bj].w = pk2(v1[2], v1[3]); }
;                 store_pair(rowp, (size_t)8 * 64 * 2, 64, w[0], w[1], fr >= 8); }
	v_pk_mul_f32 v[96:97], v[96:97], v[96:97]
	v_pk_mul_f32 v[92:93], v[92:93], v[92:93]
	v_pk_mul_f32 v[86:87], v[86:87], v[86:87]
	v_pk_mul_f32 v[82:83], v[82:83], v[82:83]
	v_pk_mul_f32 v[88:89], v[88:89], v[88:89]
	v_pk_mul_f32 v[84:85], v[84:85], v[84:85]
	v_lshl_add_u64 v[106:107], v[106:107], 0, v[142:143]
	global_store_dwordx4 v[108:109], v[102:105], off
	global_store_dwordx4 v[106:107], v[98:101], off
	v_cvt_pk_bf16_f32 v94, v94, v95
	v_cvt_pk_bf16_f32 v95, v96, v97
	v_lshl_add_u64 v[98:99], s[22:23], 0, v[148:149]
	v_cvt_pk_bf16_f32 v96, v90, v91
	v_cvt_pk_bf16_f32 v97, v92, v93
	v_cvt_pk_bf16_f32 v86, v86, v87
	v_cvt_pk_bf16_f32 v87, v88, v89
	v_cvt_pk_bf16_f32 v82, v82, v83
	v_cvt_pk_bf16_f32 v83, v84, v85
	v_lshl_add_u64 v[90:91], v[98:99], 0, v[138:139]
	v_mov_b32_dpp v88, v94 row_ror:8 row_mask:0xf bank_mask:0xf bound_ctrl:1
	v_mov_b32_dpp v89, v95 row_ror:8 row_mask:0xf bank_mask:0xf bound_ctrl:1
	v_mov_b32_dpp v84, v96 row_ror:8 row_mask:0xf bank_mask:0xf bound_ctrl:1
	v_mov_b32_dpp v85, v97 row_ror:8 row_mask:0xf bank_mask:0xf bound_ctrl:1
	v_mov_b32_dpp v98, v86 row_ror:8 row_mask:0xf bank_mask:0xf bound_ctrl:1
	v_mov_b32_dpp v99, v87 row_ror:8 row_mask:0xf bank_mask:0xf bound_ctrl:1
	v_mov_b32_dpp v100, v82 row_ror:8 row_mask:0xf bank_mask:0xf bound_ctrl:1
	v_mov_b32_dpp v101, v83 row_ror:8 row_mask:0xf bank_mask:0xf bound_ctrl:1
	v_max_f32_e32 v78, 0, v78
	v_max_f32_e32 v74, 0, v74
	v_max_f32_e32 v79, 0, v79
	v_max_f32_e32 v75, 0, v75
	v_max_f32_e32 v80, 0, v80
	v_max_f32_e32 v76, 0, v76
	v_max_f32_e32 v81, 0, v81
	v_max_f32_e32 v77, 0, v77
	v_max_f32_e32 v70, 0, v70
	v_max_f32_e32 v66, 0, v66
	v_max_f32_e32 v71, 0, v71
	v_max_f32_e32 v67, 0, v67
	v_max_f32_e32 v72, 0, v72
	v_max_f32_e32 v68, 0, v68
	v_max_f32_e32 v73, 0, v73
	v_max_f32_e32 v69, 0, v69
	v_lshl_add_u64 v[92:93], v[90:91], 0, v[140:141]
	v_cndmask_b32_e64 v85, v85, v83, s[2:3]
	v_cndmask_b32_e64 v84, v84, v82, s[2:3]
	v_cndmask_b32_e64 v83, v89, v87, s[2:3]
	v_cndmask_b32_e64 v82, v88, v86, s[2:3]
	v_cndmask_b32_e64 v89, v97, v101, s[2:3]
	v_cndmask_b32_e64 v88, v96, v100, s[2:3]
	v_cndmask_b32_e64 v87, v95, v99, s[2:3]
	v_cndmask_b32_e64 v86, v94, v98, s[2:3]
	v_pk_mul_f32 v[78:79], v[78:79], v[78:79]
	v_pk_mul_f32 v[74:75], v[74:75], v[74:75]
	v_pk_mul_f32 v[80:81], v[80:81], v[80:81]
	v_pk_mul_f32 v[76:77], v[76:77], v[76:77]
	v_pk_mul_f32 v[70:71], v[70:71], v[70:71]
	v_pk_mul_f32 v[66:67], v[66:67], v[66:67]
	v_pk_mul_f32 v[72:73], v[72:73], v[72:73]
	v_pk_mul_f32 v[68:69], v[68:69], v[68:69]
	v_lshl_add_u64 v[90:91], v[90:91], 0, v[142:143]
	global_store_dwordx4 v[92:93], v[86:89], off
	global_store_dwordx4 v[90:91], v[82:85], off
	v_cvt_pk_bf16_f32 v78, v78, v79
	v_cvt_pk_bf16_f32 v79, v80, v81
	v_lshl_add_u64 v[82:83], s[22:23], 0, v[150:151]
	v_cvt_pk_bf16_f32 v80, v74, v75
	v_cvt_pk_bf16_f32 v81, v76, v77
	v_cvt_pk_bf16_f32 v70, v70, v71
	v_cvt_pk_bf16_f32 v71, v72, v73
	v_cvt_pk_bf16_f32 v66, v66, v67
	v_cvt_pk_bf16_f32 v67, v68, v69
	v_lshl_add_u64 v[74:75], v[82:83], 0, v[138:139]
	v_mov_b32_dpp v72, v78 row_ror:8 row_mask:0xf bank_mask:0xf bound_ctrl:1
	v_mov_b32_dpp v73, v79 row_ror:8 row_mask:0xf bank_mask:0xf bound_ctrl:1
	v_mov_b32_dpp v68, v80 row_ror:8 row_mask:0xf bank_mask:0xf bound_ctrl:1
	v_mov_b32_dpp v69, v81 row_ror:8 row_mask:0xf bank_mask:0xf bound_ctrl:1
	v_mov_b32_dpp v82, v70 row_ror:8 row_mask:0xf bank_mask:0xf bound_ctrl:1
	v_mov_b32_dpp v83, v71 row_ror:8 row_mask:0xf bank_mask:0xf bound_ctrl:1
	v_mov_b32_dpp v84, v66 row_ror:8 row_mask:0xf bank_mask:0xf bound_ctrl:1
	v_mov_b32_dpp v85, v67 row_ror:8 row_mask:0xf bank_mask:0xf bound_ctrl:1
	v_max_f32_e32 v62, 0, v62
	v_max_f32_e32 v58, 0, v58
	v_max_f32_e32 v63, 0, v63
	v_max_f32_e32 v59, 0, v59
	v_max_f32_e32 v64, 0, v64
	v_max_f32_e32 v60, 0, v60
	v_max_f32_e32 v65, 0, v65
	v_max_f32_e32 v61, 0, v61
	v_max_f32_e32 v54, 0, v54
	v_max_f32_e32 v50, 0, v50
	v_max_f32_e32 v55, 0, v55
	v_max_f32_e32 v51, 0, v51
	v_max_f32_e32 v56, 0, v56
	v_max_f32_e32 v52, 0, v52
	v_max_f32_e32 v57, 0, v57
	v_max_f32_e32 v53, 0, v53
	v_lshl_add_u64 v[76:77], v[74:75], 0, v[140:141]
	v_cndmask_b32_e64 v69, v69, v67, s[2:3]
	v_cndmask_b32_e64 v68, v68, v66, s[2:3]
	v_cndmask_b32_e64 v67, v73, v71, s[2:3]
	v_cndmask_b32_e64 v66, v72, v70, s[2:3]
	v_cndmask_b32_e64 v73, v81, v85, s[2:3]
	v_cndmask_b32_e64 v72, v80, v84, s[2:3]
	v_cndmask_b32_e64 v71, v79, v83, s[2:3]
	v_cndmask_b32_e64 v70, v78, v82, s[2:3]
	v_pk_mul_f32 v[62:63], v[62:63], v[62:63]
	v_pk_mul_f32 v[58:59], v[58:59], v[58:59]
	v_pk_mul_f32 v[64:65], v[64:65], v[64:65]
	v_pk_mul_f32 v[60:61], v[60:61], v[60:61]
	v_pk_mul_f32 v[54:55], v[54:55], v[54:55]
	v_pk_mul_f32 v[50:51], v[50:51], v[50:51]
	v_pk_mul_f32 v[56:57], v[56:57], v[56:57]
	v_pk_mul_f32 v[52:53], v[52:53], v[52:53]
	v_lshl_add_u64 v[74:75], v[74:75], 0, v[142:143]
	global_store_dwordx4 v[76:77], v[70:73], off
	global_store_dwordx4 v[74:75], v[66:69], off
	v_cvt_pk_bf16_f32 v62, v62, v63
	v_cvt_pk_bf16_f32 v63, v64, v65
	v_lshl_add_u64 v[66:67], s[22:23], 0, v[152:153]
	v_cvt_pk_bf16_f32 v64, v58, v59
	v_cvt_pk_bf16_f32 v65, v60, v61
	v_cvt_pk_bf16_f32 v54, v54, v55
	v_cvt_pk_bf16_f32 v55, v56, v57
	v_cvt_pk_bf16_f32 v50, v50, v51
	v_cvt_pk_bf16_f32 v51, v52, v53
	v_lshl_add_u64 v[58:59], v[66:67], 0, v[138:139]
	v_mov_b32_dpp v56, v62 row_ror:8 row_mask:0xf bank_mask:0xf bound_ctrl:1
	v_mov_b32_dpp v57, v63 row_ror:8 row_mask:0xf bank_mask:0xf bound_ctrl:1
	v_mov_b32_dpp v52, v64 row_ror:8 row_mask:0xf bank_mask:0xf bound_ctrl:1
	v_mov_b32_dpp v53, v65 row_ror:8 row_mask:0xf bank_mask:0xf bound_ctrl:1
	v_mov_b32_dpp v66, v54 row_ror:8 row_mask:0xf bank_mask:0xf bound_ctrl:1
; __device__ __forceinline__ unsigned pk2(float lo, float hi) { const f32x2 v = {lo, hi}; return __builtin_bit_cast(unsigned, __builtin_convertvector(v, bf16x2_t)); }
; __device__ __forceinline__ u32x4 ror8(u32x4 v) { u32x4 r;
; #pragma unroll
;     for (int i = 0; i < 4; ++i) r[i] = (unsigned)__builtin_amdgcn_mov_dpp((int)v[i], 0x128, 0xf, 0xf, true);
;     return r; }
; __device__ __forceinline__ void store_pair(unsigned char* own, size_t stride8, int hi_off, u32x4 lo, u32x4 hi, bool upper) {
;     const u32x4 tlo = ror8(lo), thi = ror8(hi);
;     const u32x4 A = upper ? thi : lo, B = upper ? hi : tlo;
;     unsigned char* pa = upper ? own - stride8 + hi_off : own;
;     unsigned char* pb = upper ? own + hi_off : own + stride8;
;     *(u32x4*)pa = A; *(u32x4*)pb = B;
;     __device__ __forceinline__ void operator()(const f32x4 (&acc)[2][2][4][2], const Unit& u, int wr, int wc, int fr, int fq) const {
;     ...
;             for (int m = 0; m < 4; ++m) { unsigned char* rowp = (unsigned char*)(H + ((size_t)(u.pm * (FF / 64) + u.pn * 4 + wc) * 256 + (wr * 64 + fr + ai * 128 + m * 16)) * 64 + 8 * fq); u32x4 w[2];
; #pragma unroll
;                 for (int bj = 0; bj < 2; ++bj) { f32x4 v0 = acc[ai][bj][m][0], v1 = acc[ai][bj][m][1];
; #pragma unroll
;                     for (int j = 0; j < 4; ++j) { const float a = fmaxf(v0[j], 0.f), b = fmaxf(v1[j], 0.f); v0[j] = a * a; v1[j] = b * b; }
;                     w[bj].x = pk2(v0[0], v0[1]); w[bj].y = pk2(v0[2], v0[3]); w[bj].z = pk2(v1[0], v1[1]); w[bj].w = pk2(v1[2], v1[3]); }
;                 store_pair(rowp, (size_t)8 * 64 * 2, 64, w[0], w[1], fr >= 8); }
	v_mov_b32_dpp v67, v55 row_ror:8 row_mask:0xf bank_mask:0xf bound_ctrl:1
	v_mov_b32_dpp v68, v50 row_ror:8 row_mask:0xf bank_mask:0xf bound_ctrl:1
	v_mov_b32_dpp v69, v51 row_ror:8 row_mask:0xf bank_mask:0xf bound_ctrl:1
	v_max_f32_e32 v46, 0, v46
	v_max_f32_e32 v42, 0, v42
	v_max_f32_e32 v47, 0, v47
	v_max_f32_e32 v43, 0, v43
	v_max_f32_e32 v48, 0, v48
	v_max_f32_e32 v44, 0, v44
	v_max_f32_e32 v49, 0, v49
	v_max_f32_e32 v45, 0, v45
	v_max_f32_e32 v38, 0, v38
	v_max_f32_e32 v34, 0, v34
	v_max_f32_e32 v39, 0, v39
	v_max_f32_e32 v35, 0, v35
	v_max_f32_e32 v40, 0, v40
	v_max_f32_e32 v36, 0, v36
	v_max_f32_e32 v41, 0, v41
	v_max_f32_e32 v37, 0, v37
	v_lshl_add_u64 v[60:61], v[58:59], 0, v[140:141]
	v_cndmask_b32_e64 v53, v53, v51, s[2:3]
	v_cndmask_b32_e64 v52, v52, v50, s[2:3]
	v_cndmask_b32_e64 v51, v57, v55, s[2:3]
	v_cndmask_b32_e64 v50, v56, v54, s[2:3]
	v_cndmask_b32_e64 v57, v65, v69, s[2:3]
	v_cndmask_b32_e64 v56, v64, v68, s[2:3]
	v_cndmask_b32_e64 v55, v63, v67, s[2:3]
	v_cndmask_b32_e64 v54, v62, v66, s[2:3]
	v_pk_mul_f32 v[46:47], v[46:47], v[46:47]
	v_pk_mul_f32 v[42:43], v[42:43], v[42:43]
	v_pk_mul_f32 v[48:49], v[48:49], v[48:49]
	v_pk_mul_f32 v[44:45], v[44:45], v[44:45]
	v_pk_mul_f32 v[38:39], v[38:39], v[38:39]
	v_pk_mul_f32 v[34:35], v[34:35], v[34:35]
	v_pk_mul_f32 v[40:41], v[40:41], v[40:41]
	v_pk_mul_f32 v[36:37], v[36:37], v[36:37]
	v_lshl_add_u64 v[58:59], v[58:59], 0, v[142:143]
	global_store_dwordx4 v[60:61], v[54:57], off
	global_store_dwordx4 v[58:59], v[50:53], off
	v_cvt_pk_bf16_f32 v46, v46, v47
	v_cvt_pk_bf16_f32 v47, v48, v49
	v_lshl_add_u64 v[50:51], s[22:23], 0, v[154:155]
	v_cvt_pk_bf16_f32 v48, v42, v43
	v_cvt_pk_bf16_f32 v49, v44, v45
	v_cvt_pk_bf16_f32 v38, v38, v39
	v_cvt_pk_bf16_f32 v39, v40, v41
	v_cvt_pk_bf16_f32 v34, v34, v35
	v_cvt_pk_bf16_f32 v35, v36, v37
	v_lshl_add_u64 v[42:43], v[50:51], 0, v[138:139]
	v_mov_b32_dpp v40, v46 row_ror:8 row_mask:0xf bank_mask:0xf bound_ctrl:1
	v_mov_b32_dpp v41, v47 row_ror:8 row_mask:0xf bank_mask:0xf bound_ctrl:1
	v_mov_b32_dpp v36, v48 row_ror:8 row_mask:0xf bank_mask:0xf bound_ctrl:1
	v_mov_b32_dpp v37, v49 row_ror:8 row_mask:0xf bank_mask:0xf bound_ctrl:1
	v_mov_b32_dpp v50, v38 row_ror:8 row_mask:0xf bank_mask:0xf bound_ctrl:1
	v_mov_b32_dpp v51, v39 row_ror:8 row_mask:0xf bank_mask:0xf bound_ctrl:1
	v_mov_b32_dpp v52, v34 row_ror:8 row_mask:0xf bank_mask:0xf bound_ctrl:1
	v_mov_b32_dpp v53, v35 row_ror:8 row_mask:0xf bank_mask:0xf bound_ctrl:1
	v_max_f32_e32 v30, 0, v30
	v_max_f32_e32 v26, 0, v26
	v_max_f32_e32 v31, 0, v31
	v_max_f32_e32 v27, 0, v27
	v_max_f32_e32 v32, 0, v32
	v_max_f32_e32 v28, 0, v28
	v_max_f32_e32 v33, 0, v33
	v_max_f32_e32 v29, 0, v29
	v_max_f32_e32 v22, 0, v22
	v_max_f32_e32 v18, 0, v18
	v_max_f32_e32 v23, 0, v23
	v_max_f32_e32 v19, 0, v19
	v_max_f32_e32 v24, 0, v24
	v_max_f32_e32 v20, 0, v20
	v_max_f32_e32 v25, 0, v25
	v_max_f32_e32 v21, 0, v21
	v_lshl_add_u64 v[44:45], v[42:43], 0, v[140:141]
	v_cndmask_b32_e64 v37, v37, v35, s[2:3]
	v_cndmask_b32_e64 v36, v36, v34, s[2:3]
	v_cndmask_b32_e64 v35, v41, v39, s[2:3]
	v_cndmask_b32_e64 v34, v40, v38, s[2:3]
	v_cndmask_b32_e64 v41, v49, v53, s[2:3]
	v_cndmask_b32_e64 v40, v48, v52, s[2:3]
	v_cndmask_b32_e64 v39, v47, v51, s[2:3]
	v_cndmask_b32_e64 v38, v46, v50, s[2:3]
	v_pk_mul_f32 v[30:31], v[30:31], v[30:31]
	v_pk_mul_f32 v[26:27], v[26:27], v[26:27]
	v_pk_mul_f32 v[32:33], v[32:33], v[32:33]
	v_pk_mul_f32 v[28:29], v[28:29], v[28:29]
	v_pk_mul_f32 v[22:23], v[22:23], v[22:23]
	v_pk_mul_f32 v[18:19], v[18:19], v[18:19]
	v_pk_mul_f32 v[24:25], v[24:25], v[24:25]
	v_pk_mul_f32 v[20:21], v[20:21], v[20:21]
	v_lshl_add_u64 v[42:43], v[42:43], 0, v[142:143]
	global_store_dwordx4 v[44:45], v[38:41], off
	global_store_dwordx4 v[42:43], v[34:37], off
	v_cvt_pk_bf16_f32 v30, v30, v31
; __device__ __forceinline__ unsigned pk2(float lo, float hi) { const f32x2 v = {lo, hi}; return __builtin_bit_cast(unsigned, __builtin_convertvector(v, bf16x2_t)); }
; __device__ __forceinline__ u32x4 ror8(u32x4 v) { u32x4 r;
; #pragma unroll
;     for (int i = 0; i < 4; ++i) r[i] = (unsigned)__builtin_amdgcn_mov_dpp((int)v[i], 0x128, 0xf, 0xf, true);
;     return r; }
; __device__ __forceinline__ void store_pair(unsigned char* own, size_t stride8, int hi_off, u32x4 lo, u32x4 hi, bool upper) {
;     const u32x4 tlo = ror8(lo), thi = ror8(hi);
;     const u32x4 A = upper ? thi : lo, B = upper ? hi : tlo;
;     unsigned char* pa = upper ? own - stride8 + hi_off : own;
;     unsigned char* pb = upper ? own + hi_off : own + stride8;
;     *(u32x4*)pa = A; *(u32x4*)pb = B;
;     __device__ __forceinline__ void operator()(const f32x4 (&acc)[2][2][4][2], const Unit& u, int wr, int wc, int fr, int fq) const {
;     ...
;             for (int m = 0; m < 4; ++m) { unsigned char* rowp = (unsigned char*)(H + ((size_t)(u.pm * (FF / 64) + u.pn * 4 + wc) * 256 + (wr * 64 + fr + ai * 128 + m * 16)) * 64 + 8 * fq); u32x4 w[2];
; #pragma unroll
;                 for (int bj = 0; bj < 2; ++bj) { f32x4 v0 = acc[ai][bj][m][0], v1 = acc[ai][bj][m][1];
; #pragma unroll
;                     for (int j = 0; j < 4; ++j) { const float a = fmaxf(v0[j], 0.f), b = fmaxf(v1[j], 0.f); v0[j] = a * a; v1[j] = b * b; }
;                     w[bj].x = pk2(v0[0], v0[1]); w[bj].y = pk2(v0[2], v0[3]); w[bj].z = pk2(v1[0], v1[1]); w[bj].w = pk2(v1[2], v1[3]); }
;                 store_pair(rowp, (size_t)8 * 64 * 2, 64, w[0], w[1], fr >= 8); }
	v_cvt_pk_bf16_f32 v31, v32, v33
	v_lshl_add_u64 v[34:35], s[22:23], 0, v[156:157]
	v_cvt_pk_bf16_f32 v32, v26, v27
	v_cvt_pk_bf16_f32 v33, v28, v29
	v_cvt_pk_bf16_f32 v22, v22, v23
	v_cvt_pk_bf16_f32 v23, v24, v25
	v_cvt_pk_bf16_f32 v18, v18, v19
	v_cvt_pk_bf16_f32 v19, v20, v21
	v_lshl_add_u64 v[26:27], v[34:35], 0, v[138:139]
	v_mov_b32_dpp v24, v30 row_ror:8 row_mask:0xf bank_mask:0xf bound_ctrl:1
	v_mov_b32_dpp v25, v31 row_ror:8 row_mask:0xf bank_mask:0xf bound_ctrl:1
	v_mov_b32_dpp v20, v32 row_ror:8 row_mask:0xf bank_mask:0xf bound_ctrl:1
	v_mov_b32_dpp v21, v33 row_ror:8 row_mask:0xf bank_mask:0xf bound_ctrl:1
	v_mov_b32_dpp v34, v22 row_ror:8 row_mask:0xf bank_mask:0xf bound_ctrl:1
	v_mov_b32_dpp v35, v23 row_ror:8 row_mask:0xf bank_mask:0xf bound_ctrl:1
	v_mov_b32_dpp v36, v18 row_ror:8 row_mask:0xf bank_mask:0xf bound_ctrl:1
	v_mov_b32_dpp v37, v19 row_ror:8 row_mask:0xf bank_mask:0xf bound_ctrl:1
	v_max_f32_e32 v14, 0, v14
	v_max_f32_e32 v10, 0, v10
	v_max_f32_e32 v15, 0, v15
	v_max_f32_e32 v11, 0, v11
	v_max_f32_e32 v16, 0, v16
	v_max_f32_e32 v12, 0, v12
	v_max_f32_e32 v17, 0, v17
	v_max_f32_e32 v13, 0, v13
	v_max_f32_e32 v6, 0, v6
	v_max_f32_e32 v2, 0, v2
	v_max_f32_e32 v7, 0, v7
	v_max_f32_e32 v3, 0, v3
	v_max_f32_e32 v8, 0, v8
	v_max_f32_e32 v4, 0, v4
	v_max_f32_e32 v9, 0, v9
	v_max_f32_e32 v5, 0, v5
	v_lshl_add_u64 v[28:29], v[26:27], 0, v[140:141]
	v_cndmask_b32_e64 v21, v21, v19, s[2:3]
	v_cndmask_b32_e64 v20, v20, v18, s[2:3]
	v_cndmask_b32_e64 v19, v25, v23, s[2:3]
	v_cndmask_b32_e64 v18, v24, v22, s[2:3]
	v_cndmask_b32_e64 v25, v33, v37, s[2:3]
	v_cndmask_b32_e64 v24, v32, v36, s[2:3]
	v_cndmask_b32_e64 v23, v31, v35, s[2:3]
	v_cndmask_b32_e64 v22, v30, v34, s[2:3]
	v_pk_mul_f32 v[14:15], v[14:15], v[14:15]
	v_pk_mul_f32 v[10:11], v[10:11], v[10:11]
	v_pk_mul_f32 v[16:17], v[16:17], v[16:17]
	v_pk_mul_f32 v[12:13], v[12:13], v[12:13]
	v_pk_mul_f32 v[6:7], v[6:7], v[6:7]
	v_pk_mul_f32 v[2:3], v[2:3], v[2:3]
	v_pk_mul_f32 v[8:9], v[8:9], v[8:9]
	v_pk_mul_f32 v[4:5], v[4:5], v[4:5]
	v_lshl_add_u64 v[26:27], v[26:27], 0, v[142:143]
	global_store_dwordx4 v[28:29], v[22:25], off
	global_store_dwordx4 v[26:27], v[18:21], off
	v_cvt_pk_bf16_f32 v14, v14, v15
	v_cvt_pk_bf16_f32 v15, v16, v17
	v_lshl_add_u64 v[18:19], s[22:23], 0, v[158:159]
	v_cvt_pk_bf16_f32 v16, v10, v11
	v_cvt_pk_bf16_f32 v17, v12, v13
	v_cvt_pk_bf16_f32 v6, v6, v7
	v_cvt_pk_bf16_f32 v7, v8, v9
	v_cvt_pk_bf16_f32 v2, v2, v3
	v_cvt_pk_bf16_f32 v3, v4, v5
	v_lshl_add_u64 v[10:11], v[18:19], 0, v[138:139]
	v_mov_b32_dpp v8, v14 row_ror:8 row_mask:0xf bank_mask:0xf bound_ctrl:1
	v_mov_b32_dpp v9, v15 row_ror:8 row_mask:0xf bank_mask:0xf bound_ctrl:1
	v_mov_b32_dpp v4, v16 row_ror:8 row_mask:0xf bank_mask:0xf bound_ctrl:1
	v_mov_b32_dpp v5, v17 row_ror:8 row_mask:0xf bank_mask:0xf bound_ctrl:1
	v_mov_b32_dpp v18, v6 row_ror:8 row_mask:0xf bank_mask:0xf bound_ctrl:1
	v_mov_b32_dpp v19, v7 row_ror:8 row_mask:0xf bank_mask:0xf bound_ctrl:1
	v_mov_b32_dpp v20, v2 row_ror:8 row_mask:0xf bank_mask:0xf bound_ctrl:1
	v_mov_b32_dpp v21, v3 row_ror:8 row_mask:0xf bank_mask:0xf bound_ctrl:1
	v_lshl_add_u64 v[12:13], v[10:11], 0, v[140:141]
	v_cndmask_b32_e64 v5, v5, v3, s[2:3]
	v_cndmask_b32_e64 v4, v4, v2, s[2:3]
	v_cndmask_b32_e64 v3, v9, v7, s[2:3]
	v_cndmask_b32_e64 v2, v8, v6, s[2:3]
	v_cndmask_b32_e64 v9, v17, v21, s[2:3]
	v_cndmask_b32_e64 v8, v16, v20, s[2:3]
	v_cndmask_b32_e64 v7, v15, v19, s[2:3]
	v_cndmask_b32_e64 v6, v14, v18, s[2:3]
	s_andn2_b64 vcc, exec, s[18:19]
	s_mov_b64 s[4:5], -1
	v_lshl_add_u64 v[10:11], v[10:11], 0, v[142:143]
	global_store_dwordx4 v[12:13], v[6:9], off
	global_store_dwordx4 v[10:11], v[2:5], off
	s_cbranch_vccnz .LBB0_2259
	s_andn2_b64 vcc, exec, s[6:7]
	s_cbranch_vccnz .LBB0_2258
	s_barrier
	s_branch .LBB0_2258

; #define PG8_STAGE(bufoff, gbase, voff) do { _Pragma("unroll") for (int _i = 0; _i < 2; ++_i) \
;         __builtin_amdgcn_global_load_lds((const unsigned*)((const char*)(gbase) + (voff)[_i]), (LAS unsigned*)(lds + (bufoff) + ldsw + _i * 8192), 16, 0, 0); } while (0)
; #define PG8_LDA(dst, b, h) do { _Pragma("unroll") for (int m = 0; m < 4; ++m) _Pragma("unroll") for (int k = 0; k < 2; ++k) dst[m][k] = *(const LAS bf16x8*)(lds + PG8_SA(b, h) + aoff + m * 2048 + k * 1024); } while (0)
; #define PG8_LDB(dst, b, h) do { _Pragma("unroll") for (int n = 0; n < 2; ++n) _Pragma("unroll") for (int k = 0; k < 2; ++k) dst[n][k] = *(const LAS bf16x8*)(lds + PG8_SB(b, h) + boff + n * 2048 + k * 1024); } while (0)
; #define PG8_MMA(ai, bj, At, Bt) do { __builtin_amdgcn_s_setprio(1); _Pragma("unroll") for (int m = 0; m < 4; ++m) _Pragma("unroll") for (int n = 0; n < 2; ++n) _Pragma("unroll") for (int k = 0; k < 2; ++k) \
;         acc[ai][bj][m][n] = __builtin_amdgcn_mfma_f32_16x16x32_bf16(Bt[n][k], At[m][k], acc[ai][bj][m][n], 0, 0, 0); __builtin_amdgcn_s_setprio(0); } while (0)
; #define PG8_WAIT_V(n) asm volatile("s_waitcnt vmcnt(" #n ")" ::: "memory")
; template <class Epi, class Sched, bool ABLK = false, bool ALIGN_EPI = true, bool SP2 = true, bool BBLK = true>
; __device__ __forceinline__ void gemm_phase(LAS unsigned char* lds, const Gemm g, const Sched& S, const Epi& E) {
;     ...
;         for (int t = 0; t < nt; t += 2) {
;             const bool last = (t == nt - 2);
;             const char* a1 = a_tile(uA, tbA + t + 1);
;             const char* a2 = last ? a_tile(nuA, ntbA) : a_tile(uA, tbA + t + 2); const char* b2 = last ? nB : cB + (size_t)(t + 2) * kstepB;
;             const char* a3 = last ? a_tile(nuA, ntbA + 1) : a_tile(uA, tbA + t + 3); const char* b3 = b2 + kstepB;
;             if (last && has_next) S.a_ready(nxt);
;             if constexpr (SP2) {
;             PG8_LDB(B0, 0, 0); PG8_LDB(B1, 0, 1); PG8_SCHED; PG8_LDA(At, 0, 0); PG8_STAGE(PG8_SA(1, 1), a1 + hstepA, voffA);
;             PG8_WAIT_V(8); PG8_WAIT_L(0); PG8_BAR; PG8_MMA(0, 0, At, B0); PG8_MMA(0, 1, At, B1); PG8_BAR; PG8_SCHED;
;             PG8_LDA(At, 0, 1); PG8_STAGE(PG8_SB(0, 0), b2, voffB); PG8_STAGE(PG8_SB(0, 1), b2 + hstepB, voffB); PG8_STAGE(PG8_SA(0, 0), a2, voffA);
;             PG8_WAIT_V(8); PG8_WAIT_L(0); PG8_BAR; PG8_MMA(1, 0, At, B0); PG8_MMA(1, 1, At, B1); PG8_BAR; PG8_SCHED;
.LBB0_2328:
	ds_read_b128 v[152:155], v148
	ds_read_b128 v[156:159], v148 offset:1024
	ds_read_b128 v[160:163], v148 offset:2048
	ds_read_b128 v[164:167], v148 offset:3072
	ds_read_b128 v[168:171], v149
	ds_read_b128 v[172:175], v149 offset:1024
	ds_read_b128 v[176:179], v149 offset:2048
	ds_read_b128 v[180:183], v149 offset:3072
	s_add_u32 s40, s64, s38
	s_addc_u32 s41, s65, s39
	s_add_u32 s44, s40, 0x10000
	s_addc_u32 s45, s41, 0
	s_add_i32 s67, s67, 2
	s_add_u32 s42, s62, s38
	s_addc_u32 s43, s63, s39
	s_add_u32 s40, s40, 0x18000
	s_addc_u32 s41, s41, 0
	s_cmp_eq_u32 s66, s38
	s_cselect_b32 s41, s59, s41
	s_cselect_b32 s40, s58, s40
	s_cselect_b32 s43, s4, s43
	s_cselect_b32 s42, s5, s42
	s_cselect_b32 s45, s57, s45
	s_cselect_b32 s44, s35, s44
	v_lshl_add_u64 v[216:217], v[142:143], 0, s[38:39]
	s_add_i32 m0, s49, 0xc000
	ds_read_b128 v[184:187], v150
	ds_read_b128 v[188:191], v150 offset:1024
	ds_read_b128 v[192:195], v150 offset:2048
	ds_read_b128 v[196:199], v150 offset:3072
	ds_read_b128 v[200:203], v150 offset:4096
	ds_read_b128 v[204:207], v150 offset:5120
	ds_read_b128 v[208:211], v150 offset:6144
	ds_read_b128 v[212:215], v150 offset:7168
	global_load_lds_dwordx4 v[216:217], off
	v_lshl_add_u64 v[216:217], v[144:145], 0, s[38:39]
	s_add_i32 m0, s49, 0xe000
	s_nop 0
	global_load_lds_dwordx4 v[216:217], off
	s_waitcnt vmcnt(8) lgkmcnt(0)
	s_barrier
	v_mfma_f32_16x16x32_bf16 v[126:129], v[152:155], v[184:187], v[126:129]
	v_mfma_f32_16x16x32_bf16 v[122:125], v[160:163], v[184:187], v[122:125]
	v_mfma_f32_16x16x32_bf16 v[110:113], v[152:155], v[192:195], v[110:113]
	v_mfma_f32_16x16x32_bf16 v[106:109], v[160:163], v[192:195], v[106:109]
	v_mfma_f32_16x16x32_bf16 v[94:97], v[152:155], v[200:203], v[94:97]
	v_mfma_f32_16x16x32_bf16 v[90:93], v[160:163], v[200:203], v[90:93]
	v_mfma_f32_16x16x32_bf16 v[78:81], v[152:155], v[208:211], v[78:81]
	v_mfma_f32_16x16x32_bf16 v[74:77], v[160:163], v[208:211], v[74:77]
	v_mfma_f32_16x16x32_bf16 v[126:129], v[156:159], v[188:191], v[126:129]
	v_mfma_f32_16x16x32_bf16 v[122:125], v[164:167], v[188:191], v[122:125]
	v_mfma_f32_16x16x32_bf16 v[110:113], v[156:159], v[196:199], v[110:113]
	v_mfma_f32_16x16x32_bf16 v[106:109], v[164:167], v[196:199], v[106:109]
	v_mfma_f32_16x16x32_bf16 v[94:97], v[156:159], v[204:207], v[94:97]
	v_mfma_f32_16x16x32_bf16 v[90:93], v[164:167], v[204:207], v[90:93]
	v_mfma_f32_16x16x32_bf16 v[78:81], v[156:159], v[212:215], v[78:81]
	v_mfma_f32_16x16x32_bf16 v[74:77], v[164:167], v[212:215], v[74:77]
	v_mfma_f32_16x16x32_bf16 v[118:121], v[168:171], v[184:187], v[118:121]
	v_mfma_f32_16x16x32_bf16 v[114:117], v[176:179], v[184:187], v[114:117]
	v_mfma_f32_16x16x32_bf16 v[102:105], v[168:171], v[192:195], v[102:105]
	v_mfma_f32_16x16x32_bf16 v[98:101], v[176:179], v[192:195], v[98:101]
	v_mfma_f32_16x16x32_bf16 v[86:89], v[168:171], v[200:203], v[86:89]
	v_mfma_f32_16x16x32_bf16 v[82:85], v[176:179], v[200:203], v[82:85]
	v_mfma_f32_16x16x32_bf16 v[70:73], v[168:171], v[208:211], v[70:73]
	v_mfma_f32_16x16x32_bf16 v[66:69], v[176:179], v[208:211], v[66:69]
	v_mfma_f32_16x16x32_bf16 v[118:121], v[172:175], v[188:191], v[118:121]
	v_mfma_f32_16x16x32_bf16 v[114:117], v[180:183], v[188:191], v[114:117]
	v_mfma_f32_16x16x32_bf16 v[102:105], v[172:175], v[196:199], v[102:105]
	v_mfma_f32_16x16x32_bf16 v[98:101], v[180:183], v[196:199], v[98:101]
	v_mfma_f32_16x16x32_bf16 v[86:89], v[172:175], v[204:207], v[86:89]
	v_mfma_f32_16x16x32_bf16 v[82:85], v[180:183], v[204:207], v[82:85]
	v_mfma_f32_16x16x32_bf16 v[70:73], v[172:175], v[212:215], v[70:73]
	v_mfma_f32_16x16x32_bf16 v[66:69], v[180:183], v[212:215], v[66:69]
	s_barrier
	s_add_i32 s70, s72, s48
	s_mov_b32 m0, s70
	ds_read_b128 v[184:187], v150 offset:16384
	ds_read_b128 v[188:191], v150 offset:17408
	ds_read_b128 v[192:195], v150 offset:18432
	ds_read_b128 v[196:199], v150 offset:19456
	ds_read_b128 v[200:203], v150 offset:20480
	ds_read_b128 v[204:207], v150 offset:21504
	ds_read_b128 v[208:211], v150 offset:22528
	ds_read_b128 v[212:215], v150 offset:23552
	global_load_lds_dwordx4 v130, s[42:43]
	s_add_i32 m0, s70, 0x2000
	s_add_u32 s76, s42, 0x4000
	s_addc_u32 s77, s43, 0
	s_add_i32 s70, s73, s48
	global_load_lds_dwordx4 v132, s[42:43]
	s_mov_b32 m0, s70
	s_nop 0
	global_load_lds_dwordx4 v130, s[76:77]
	s_add_i32 m0, s70, 0x2000
	s_nop 0
	global_load_lds_dwordx4 v132, s[76:77]
	s_mov_b32 m0, s49
	s_nop 0
	global_load_lds_dwordx4 v130, s[44:45]
	s_mov_b32 m0, s50
	s_nop 0
	global_load_lds_dwordx4 v132, s[44:45]
	s_waitcnt vmcnt(8) lgkmcnt(0)
	s_barrier
; #define PG8_STAGE(bufoff, gbase, voff) do { _Pragma("unroll") for (int _i = 0; _i < 2; ++_i) \
;         __builtin_amdgcn_global_load_lds((const unsigned*)((const char*)(gbase) + (voff)[_i]), (LAS unsigned*)(lds + (bufoff) + ldsw + _i * 8192), 16, 0, 0); } while (0)
; #define PG8_LDA(dst, b, h) do { _Pragma("unroll") for (int m = 0; m < 4; ++m) _Pragma("unroll") for (int k = 0; k < 2; ++k) dst[m][k] = *(const LAS bf16x8*)(lds + PG8_SA(b, h) + aoff + m * 2048 + k * 1024); } while (0)
; #define PG8_LDB(dst, b, h) do { _Pragma("unroll") for (int n = 0; n < 2; ++n) _Pragma("unroll") for (int k = 0; k < 2; ++k) dst[n][k] = *(const LAS bf16x8*)(lds + PG8_SB(b, h) + boff + n * 2048 + k * 1024); } while (0)
; #define PG8_MMA(ai, bj, At, Bt) do { __builtin_amdgcn_s_setprio(1); _Pragma("unroll") for (int m = 0; m < 4; ++m) _Pragma("unroll") for (int n = 0; n < 2; ++n) _Pragma("unroll") for (int k = 0; k < 2; ++k) \
;         acc[ai][bj][m][n] = __builtin_amdgcn_mfma_f32_16x16x32_bf16(Bt[n][k], At[m][k], acc[ai][bj][m][n], 0, 0, 0); __builtin_amdgcn_s_setprio(0); } while (0)
; #define PG8_WAIT_V(n) asm volatile("s_waitcnt vmcnt(" #n ")" ::: "memory")
; #define PG8_WAIT_L(n) asm volatile("s_waitcnt lgkmcnt(" #n ")" ::: "memory")
; #define PG8_BAR __builtin_amdgcn_s_barrier()
; #define PG8_SCHED __builtin_amdgcn_sched_barrier(0)
; template <class Epi, class Sched, bool ABLK = false, bool ALIGN_EPI = true, bool SP2 = true, bool BBLK = true>
; __device__ __forceinline__ void gemm_phase(LAS unsigned char* lds, const Gemm g, const Sched& S, const Epi& E) {
;     ...
;             PG8_LDA(At, 0, 1); PG8_STAGE(PG8_SB(0, 0), b2, voffB); PG8_STAGE(PG8_SB(0, 1), b2 + hstepB, voffB); PG8_STAGE(PG8_SA(0, 0), a2, voffA);
;             PG8_WAIT_V(8); PG8_WAIT_L(0); PG8_BAR; PG8_MMA(1, 0, At, B0); PG8_MMA(1, 1, At, B1); PG8_BAR; PG8_SCHED;
;             PG8_LDB(B0, 1, 0); PG8_LDB(B1, 1, 1); PG8_SCHED; PG8_LDA(At, 1, 0); PG8_STAGE(PG8_SA(0, 1), a2 + hstepA, voffA);
;             PG8_WAIT_V(8); PG8_WAIT_L(0); PG8_BAR; PG8_MMA(0, 0, At, B0); PG8_MMA(0, 1, At, B1); PG8_BAR; PG8_SCHED;
;             PG8_LDA(At, 1, 1); PG8_STAGE(PG8_SB(1, 0), b3, voffB); PG8_STAGE(PG8_SB(1, 1), b3 + hstepB, voffB); PG8_STAGE(PG8_SA(1, 0), a3, voffA);
	v_mfma_f32_16x16x32_bf16 v[62:65], v[152:155], v[184:187], v[62:65]
	v_mfma_f32_16x16x32_bf16 v[58:61], v[160:163], v[184:187], v[58:61]
	v_mfma_f32_16x16x32_bf16 v[46:49], v[152:155], v[192:195], v[46:49]
	v_mfma_f32_16x16x32_bf16 v[42:45], v[160:163], v[192:195], v[42:45]
	v_mfma_f32_16x16x32_bf16 v[30:33], v[152:155], v[200:203], v[30:33]
	v_mfma_f32_16x16x32_bf16 v[26:29], v[160:163], v[200:203], v[26:29]
	v_mfma_f32_16x16x32_bf16 v[14:17], v[152:155], v[208:211], v[14:17]
	v_mfma_f32_16x16x32_bf16 v[10:13], v[160:163], v[208:211], v[10:13]
	v_mfma_f32_16x16x32_bf16 v[62:65], v[156:159], v[188:191], v[62:65]
	v_mfma_f32_16x16x32_bf16 v[58:61], v[164:167], v[188:191], v[58:61]
	v_mfma_f32_16x16x32_bf16 v[46:49], v[156:159], v[196:199], v[46:49]
	v_mfma_f32_16x16x32_bf16 v[42:45], v[164:167], v[196:199], v[42:45]
	v_mfma_f32_16x16x32_bf16 v[30:33], v[156:159], v[204:207], v[30:33]
	v_mfma_f32_16x16x32_bf16 v[26:29], v[164:167], v[204:207], v[26:29]
	v_mfma_f32_16x16x32_bf16 v[14:17], v[156:159], v[212:215], v[14:17]
	v_mfma_f32_16x16x32_bf16 v[10:13], v[164:167], v[212:215], v[10:13]
	v_mfma_f32_16x16x32_bf16 v[54:57], v[168:171], v[184:187], v[54:57]
	v_mfma_f32_16x16x32_bf16 v[50:53], v[176:179], v[184:187], v[50:53]
	v_mfma_f32_16x16x32_bf16 v[38:41], v[168:171], v[192:195], v[38:41]
	v_mfma_f32_16x16x32_bf16 v[34:37], v[176:179], v[192:195], v[34:37]
	v_mfma_f32_16x16x32_bf16 v[22:25], v[168:171], v[200:203], v[22:25]
	v_mfma_f32_16x16x32_bf16 v[18:21], v[176:179], v[200:203], v[18:21]
	v_mfma_f32_16x16x32_bf16 v[6:9], v[168:171], v[208:211], v[6:9]
	v_mfma_f32_16x16x32_bf16 v[2:5], v[176:179], v[208:211], v[2:5]
	v_mfma_f32_16x16x32_bf16 v[54:57], v[172:175], v[188:191], v[54:57]
	v_mfma_f32_16x16x32_bf16 v[50:53], v[180:183], v[188:191], v[50:53]
	v_mfma_f32_16x16x32_bf16 v[38:41], v[172:175], v[196:199], v[38:41]
	v_mfma_f32_16x16x32_bf16 v[34:37], v[180:183], v[196:199], v[34:37]
	v_mfma_f32_16x16x32_bf16 v[22:25], v[172:175], v[204:207], v[22:25]
	v_mfma_f32_16x16x32_bf16 v[18:21], v[180:183], v[204:207], v[18:21]
	v_mfma_f32_16x16x32_bf16 v[6:9], v[172:175], v[212:215], v[6:9]
	v_mfma_f32_16x16x32_bf16 v[2:5], v[180:183], v[212:215], v[2:5]
	s_barrier
	v_add_u32_e32 v151, s60, v146
	ds_read_b128 v[152:155], v151
	ds_read_b128 v[156:159], v151 offset:1024
	ds_read_b128 v[160:163], v151 offset:2048
	ds_read_b128 v[164:167], v151 offset:3072
	v_add_u32_e32 v151, s61, v146
	ds_read_b128 v[168:171], v151
	ds_read_b128 v[172:175], v151 offset:1024
	ds_read_b128 v[176:179], v151 offset:2048
	ds_read_b128 v[180:183], v151 offset:3072
	s_add_u32 s44, s44, 0x4000
	s_addc_u32 s45, s45, 0
	s_mov_b32 m0, s51
	ds_read_b128 v[184:187], v150 offset:32768
	ds_read_b128 v[188:191], v150 offset:33792
	ds_read_b128 v[192:195], v150 offset:34816
	ds_read_b128 v[196:199], v150 offset:35840
	ds_read_b128 v[200:203], v150 offset:36864
	ds_read_b128 v[204:207], v150 offset:37888
	ds_read_b128 v[208:211], v150 offset:38912
	ds_read_b128 v[212:215], v150 offset:39936
	global_load_lds_dwordx4 v130, s[44:45]
	s_mov_b32 m0, s52
	s_nop 0
	global_load_lds_dwordx4 v132, s[44:45]
	s_waitcnt vmcnt(8) lgkmcnt(0)
	s_barrier
	v_mfma_f32_16x16x32_bf16 v[126:129], v[152:155], v[184:187], v[126:129]
	v_mfma_f32_16x16x32_bf16 v[122:125], v[160:163], v[184:187], v[122:125]
	v_mfma_f32_16x16x32_bf16 v[110:113], v[152:155], v[192:195], v[110:113]
	v_mfma_f32_16x16x32_bf16 v[106:109], v[160:163], v[192:195], v[106:109]
	v_mfma_f32_16x16x32_bf16 v[94:97], v[152:155], v[200:203], v[94:97]
	v_mfma_f32_16x16x32_bf16 v[90:93], v[160:163], v[200:203], v[90:93]
	v_mfma_f32_16x16x32_bf16 v[78:81], v[152:155], v[208:211], v[78:81]
	v_mfma_f32_16x16x32_bf16 v[74:77], v[160:163], v[208:211], v[74:77]
	v_mfma_f32_16x16x32_bf16 v[126:129], v[156:159], v[188:191], v[126:129]
	v_mfma_f32_16x16x32_bf16 v[122:125], v[164:167], v[188:191], v[122:125]
	v_mfma_f32_16x16x32_bf16 v[110:113], v[156:159], v[196:199], v[110:113]
	v_mfma_f32_16x16x32_bf16 v[106:109], v[164:167], v[196:199], v[106:109]
	v_mfma_f32_16x16x32_bf16 v[94:97], v[156:159], v[204:207], v[94:97]
	v_mfma_f32_16x16x32_bf16 v[90:93], v[164:167], v[204:207], v[90:93]
	v_mfma_f32_16x16x32_bf16 v[78:81], v[156:159], v[212:215], v[78:81]
	v_mfma_f32_16x16x32_bf16 v[74:77], v[164:167], v[212:215], v[74:77]
	v_mfma_f32_16x16x32_bf16 v[118:121], v[168:171], v[184:187], v[118:121]
	v_mfma_f32_16x16x32_bf16 v[114:117], v[176:179], v[184:187], v[114:117]
	v_mfma_f32_16x16x32_bf16 v[102:105], v[168:171], v[192:195], v[102:105]
	v_mfma_f32_16x16x32_bf16 v[98:101], v[176:179], v[192:195], v[98:101]
	v_mfma_f32_16x16x32_bf16 v[86:89], v[168:171], v[200:203], v[86:89]
	v_mfma_f32_16x16x32_bf16 v[82:85], v[176:179], v[200:203], v[82:85]
	v_mfma_f32_16x16x32_bf16 v[70:73], v[168:171], v[208:211], v[70:73]
	v_mfma_f32_16x16x32_bf16 v[66:69], v[176:179], v[208:211], v[66:69]
	v_mfma_f32_16x16x32_bf16 v[118:121], v[172:175], v[188:191], v[118:121]
	v_mfma_f32_16x16x32_bf16 v[114:117], v[180:183], v[188:191], v[114:117]
	v_mfma_f32_16x16x32_bf16 v[102:105], v[172:175], v[196:199], v[102:105]
	v_mfma_f32_16x16x32_bf16 v[98:101], v[180:183], v[196:199], v[98:101]
	v_mfma_f32_16x16x32_bf16 v[86:89], v[172:175], v[204:207], v[86:89]
	v_mfma_f32_16x16x32_bf16 v[82:85], v[180:183], v[204:207], v[82:85]
	v_mfma_f32_16x16x32_bf16 v[70:73], v[172:175], v[212:215], v[70:73]
	v_mfma_f32_16x16x32_bf16 v[66:69], v[180:183], v[212:215], v[66:69]
	s_barrier
; __device__ __forceinline__ unsigned pk2(float lo, float hi) { const f32x2 v = {lo, hi}; return __builtin_bit_cast(unsigned, __builtin_convertvector(v, bf16x2_t)); }
; #define PG8_STAGE(bufoff, gbase, voff) do { _Pragma("unroll") for (int _i = 0; _i < 2; ++_i) \
;         __builtin_amdgcn_global_load_lds((const unsigned*)((const char*)(gbase) + (voff)[_i]), (LAS unsigned*)(lds + (bufoff) + ldsw + _i * 8192), 16, 0, 0); } while (0)
; #define PG8_LDA(dst, b, h) do { _Pragma("unroll") for (int m = 0; m < 4; ++m) _Pragma("unroll") for (int k = 0; k < 2; ++k) dst[m][k] = *(const LAS bf16x8*)(lds + PG8_SA(b, h) + aoff + m * 2048 + k * 1024); } while (0)
; #define PG8_MMA(ai, bj, At, Bt) do { __builtin_amdgcn_s_setprio(1); _Pragma("unroll") for (int m = 0; m < 4; ++m) _Pragma("unroll") for (int n = 0; n < 2; ++n) _Pragma("unroll") for (int k = 0; k < 2; ++k) \
;         acc[ai][bj][m][n] = __builtin_amdgcn_mfma_f32_16x16x32_bf16(Bt[n][k], At[m][k], acc[ai][bj][m][n], 0, 0, 0); __builtin_amdgcn_s_setprio(0); } while (0)
; template <class Epi, class Sched, bool ABLK = false, bool ALIGN_EPI = true, bool SP2 = true, bool BBLK = true>
; __device__ __forceinline__ void gemm_phase(LAS unsigned char* lds, const Gemm g, const Sched& S, const Epi& E) {
;     ...
;             PG8_LDA(At, 1, 1); PG8_STAGE(PG8_SB(1, 0), b3, voffB); PG8_STAGE(PG8_SB(1, 1), b3 + hstepB, voffB); PG8_STAGE(PG8_SA(1, 0), a3, voffA);
;             PG8_WAIT_V(8); PG8_WAIT_L(0); PG8_BAR; PG8_MMA(1, 0, At, B0); PG8_MMA(1, 1, At, B1); PG8_BAR; PG8_SCHED;
;     __device__ __forceinline__ void operator()(const f32x4 (&acc)[2][2][4][2], const Unit& u, int wr, int wc, int fr, int fq) const {
;         const int row0 = u.pm * 256 + wr * 64 + fr, col0 = u.pn * 256 + wc * 64 + 8 * fq;
;         bf16_t* base = u.part == 0 ? Z + (size_t)row0 * D + col0 : P + ((size_t)(u.part - 1) * MS + (row0 - MP)) * D + col0;
; #pragma unroll
;         for (int ai = 0; ai < 2; ++ai)
; #pragma unroll
;             for (int m = 0; m < 4; ++m) { u32x4 w[2];
; #pragma unroll
;                 for (int bj = 0; bj < 2; ++bj) { const f32x4 v0 = acc[ai][bj][m][0], v1 = acc[ai][bj][m][1]; w[bj].x = pk2(v0[0], v0[1]); w[bj].y = pk2(v0[2], v0[3]); w[bj].z = pk2(v1[0], v1[1]); w[bj].w = pk2(v1[2], v1[3]); }
;                 store_pair((unsigned char*)(base + (size_t)(ai * 128 + m * 16) * D), (size_t)8 * D * 2, 64, w[0], w[1], fr >= 8); }
	s_add_u32 s44, s42, 0x8000
	s_addc_u32 s45, s43, 0
	s_add_i32 s70, s60, s48
	s_mov_b32 m0, s70
	ds_read_b128 v[184:187], v150 offset:49152
	ds_read_b128 v[188:191], v150 offset:50176
	ds_read_b128 v[192:195], v150 offset:51200
	ds_read_b128 v[196:199], v150 offset:52224
	ds_read_b128 v[200:203], v150 offset:53248
	ds_read_b128 v[204:207], v150 offset:54272
	ds_read_b128 v[208:211], v150 offset:55296
	ds_read_b128 v[212:215], v150 offset:56320
	global_load_lds_dwordx4 v130, s[44:45]
	s_add_i32 m0, s70, 0x2000
	s_add_u32 s42, s42, 0xc000
	v_lshl_add_u64 v[216:217], s[44:45], 0, v[132:133]
	s_addc_u32 s43, s43, 0
	s_add_i32 s44, s61, s48
	global_load_lds_dwordx4 v[216:217], off
	s_mov_b32 m0, s44
	s_nop 0
	global_load_lds_dwordx4 v130, s[42:43]
	s_add_i32 m0, s44, 0x2000
	s_nop 0
	global_load_lds_dwordx4 v132, s[42:43]
	s_mov_b32 m0, s53
	s_nop 0
	global_load_lds_dwordx4 v130, s[40:41]
	s_mov_b32 m0, s54
	s_nop 0
	global_load_lds_dwordx4 v132, s[40:41]
	s_waitcnt vmcnt(8) lgkmcnt(0)
	s_barrier
	v_mfma_f32_16x16x32_bf16 v[62:65], v[152:155], v[184:187], v[62:65]
	v_mfma_f32_16x16x32_bf16 v[58:61], v[160:163], v[184:187], v[58:61]
	v_mfma_f32_16x16x32_bf16 v[46:49], v[152:155], v[192:195], v[46:49]
	v_mfma_f32_16x16x32_bf16 v[42:45], v[160:163], v[192:195], v[42:45]
	v_mfma_f32_16x16x32_bf16 v[30:33], v[152:155], v[200:203], v[30:33]
	v_mfma_f32_16x16x32_bf16 v[26:29], v[160:163], v[200:203], v[26:29]
	v_mfma_f32_16x16x32_bf16 v[14:17], v[152:155], v[208:211], v[14:17]
	v_mfma_f32_16x16x32_bf16 v[10:13], v[160:163], v[208:211], v[10:13]
	v_mfma_f32_16x16x32_bf16 v[62:65], v[156:159], v[188:191], v[62:65]
	v_mfma_f32_16x16x32_bf16 v[58:61], v[164:167], v[188:191], v[58:61]
	v_mfma_f32_16x16x32_bf16 v[46:49], v[156:159], v[196:199], v[46:49]
	v_mfma_f32_16x16x32_bf16 v[42:45], v[164:167], v[196:199], v[42:45]
	v_mfma_f32_16x16x32_bf16 v[30:33], v[156:159], v[204:207], v[30:33]
	v_mfma_f32_16x16x32_bf16 v[26:29], v[164:167], v[204:207], v[26:29]
	v_mfma_f32_16x16x32_bf16 v[14:17], v[156:159], v[212:215], v[14:17]
	v_mfma_f32_16x16x32_bf16 v[10:13], v[164:167], v[212:215], v[10:13]
	v_mfma_f32_16x16x32_bf16 v[54:57], v[168:171], v[184:187], v[54:57]
	v_mfma_f32_16x16x32_bf16 v[50:53], v[176:179], v[184:187], v[50:53]
	v_mfma_f32_16x16x32_bf16 v[38:41], v[168:171], v[192:195], v[38:41]
	v_mfma_f32_16x16x32_bf16 v[34:37], v[176:179], v[192:195], v[34:37]
	v_mfma_f32_16x16x32_bf16 v[22:25], v[168:171], v[200:203], v[22:25]
	v_mfma_f32_16x16x32_bf16 v[18:21], v[176:179], v[200:203], v[18:21]
	v_mfma_f32_16x16x32_bf16 v[6:9], v[168:171], v[208:211], v[6:9]
	v_mfma_f32_16x16x32_bf16 v[2:5], v[176:179], v[208:211], v[2:5]
	v_mfma_f32_16x16x32_bf16 v[54:57], v[172:175], v[188:191], v[54:57]
	v_mfma_f32_16x16x32_bf16 v[50:53], v[180:183], v[188:191], v[50:53]
	v_mfma_f32_16x16x32_bf16 v[38:41], v[172:175], v[196:199], v[38:41]
	v_mfma_f32_16x16x32_bf16 v[34:37], v[180:183], v[196:199], v[34:37]
	v_mfma_f32_16x16x32_bf16 v[22:25], v[172:175], v[204:207], v[22:25]
	v_mfma_f32_16x16x32_bf16 v[18:21], v[180:183], v[204:207], v[18:21]
	v_mfma_f32_16x16x32_bf16 v[6:9], v[172:175], v[212:215], v[6:9]
	v_mfma_f32_16x16x32_bf16 v[2:5], v[180:183], v[212:215], v[2:5]
	s_barrier
	s_add_u32 s38, s38, 0x10000
	s_addc_u32 s39, s39, 0
	s_cmp_ge_u32 s67, s56
	s_cbranch_scc0 .LBB0_2328
	v_lshl_add_u32 v143, s82, 8, v1
	v_add_u32_e32 v144, 0xffffe000, v143
	v_sub_co_u32_e64 v142, vcc, s55, 1
	v_mov_b32_e32 v145, s9
	s_nop 0
	v_cndmask_b32_e32 v144, v144, v143, vcc
	v_ashrrev_i32_e32 v143, 31, v142
	v_lshlrev_b64 v[142:143], 23, v[142:143]
	v_lshl_add_u64 v[142:143], s[12:13], 0, v[142:143]
	v_cndmask_b32_e32 v143, v143, v145, vcc
	v_mov_b32_e32 v145, s8
	v_cndmask_b32_e32 v142, v142, v145, vcc
	v_ashrrev_i32_e32 v145, 31, v144
	v_lshl_or_b32 v152, s78, 8, v147
	v_lshlrev_b64 v[144:145], 12, v[144:145]
	v_lshl_add_u64 v[142:143], v[142:143], 0, v[144:145]
	v_ashrrev_i32_e32 v153, 31, v152
	v_cvt_pk_bf16_f32 v126, v126, v127
	v_cvt_pk_bf16_f32 v127, v128, v129
	v_cvt_pk_bf16_f32 v128, v122, v123
	v_cvt_pk_bf16_f32 v124, v124, v125
	v_cvt_pk_bf16_f32 v118, v118, v119
	v_cvt_pk_bf16_f32 v119, v120, v121
	v_cvt_pk_bf16_f32 v114, v114, v115
	v_cvt_pk_bf16_f32 v115, v116, v117
	v_lshl_add_u64 v[142:143], v[152:153], 1, v[142:143]
	v_mov_b32_dpp v120, v126 row_ror:8 row_mask:0xf bank_mask:0xf bound_ctrl:1
	v_mov_b32_dpp v121, v127 row_ror:8 row_mask:0xf bank_mask:0xf bound_ctrl:1
	v_mov_b32_dpp v116, v128 row_ror:8 row_mask:0xf bank_mask:0xf bound_ctrl:1
	v_mov_b32_dpp v117, v124 row_ror:8 row_mask:0xf bank_mask:0xf bound_ctrl:1
	v_mov_b32_dpp v125, v118 row_ror:8 row_mask:0xf bank_mask:0xf bound_ctrl:1
	v_mov_b32_dpp v129, v119 row_ror:8 row_mask:0xf bank_mask:0xf bound_ctrl:1
	v_mov_b32_dpp v144, v114 row_ror:8 row_mask:0xf bank_mask:0xf bound_ctrl:1
	v_mov_b32_dpp v145, v115 row_ror:8 row_mask:0xf bank_mask:0xf bound_ctrl:1
	v_lshl_add_u64 v[122:123], v[142:143], 0, v[134:135]
	v_cndmask_b32_e64 v117, v117, v115, s[2:3]
	v_cndmask_b32_e64 v116, v116, v114, s[2:3]
	v_cndmask_b32_e64 v115, v121, v119, s[2:3]
	v_cndmask_b32_e64 v114, v120, v118, s[2:3]
	v_cndmask_b32_e64 v121, v124, v145, s[2:3]
	v_cndmask_b32_e64 v120, v128, v144, s[2:3]
	v_cndmask_b32_e64 v119, v127, v129, s[2:3]
	v_cndmask_b32_e64 v118, v126, v125, s[2:3]
	v_cvt_pk_bf16_f32 v110, v110, v111
	v_cvt_pk_bf16_f32 v111, v112, v113
	v_cvt_pk_bf16_f32 v112, v106, v107
	v_cvt_pk_bf16_f32 v113, v108, v109
	v_cvt_pk_bf16_f32 v102, v102, v103
	v_cvt_pk_bf16_f32 v103, v104, v105
	v_cvt_pk_bf16_f32 v98, v98, v99
	v_cvt_pk_bf16_f32 v99, v100, v101
	v_lshl_add_u64 v[124:125], v[142:143], 0, v[136:137]
	s_and_b64 vcc, exec, s[14:15]
	s_cbranch_vccz .LBB0_2331
	s_barrier
; __device__ __forceinline__ unsigned pk2(float lo, float hi) { const f32x2 v = {lo, hi}; return __builtin_bit_cast(unsigned, __builtin_convertvector(v, bf16x2_t)); }
; __device__ __forceinline__ u32x4 ror8(u32x4 v) { u32x4 r;
; #pragma unroll
;     for (int i = 0; i < 4; ++i) r[i] = (unsigned)__builtin_amdgcn_mov_dpp((int)v[i], 0x128, 0xf, 0xf, true);
;     return r; }
; __device__ __forceinline__ void store_pair(unsigned char* own, size_t stride8, int hi_off, u32x4 lo, u32x4 hi, bool upper) {
;     const u32x4 tlo = ror8(lo), thi = ror8(hi);
;     const u32x4 A = upper ? thi : lo, B = upper ? hi : tlo;
;     unsigned char* pa = upper ? own - stride8 + hi_off : own;
;     unsigned char* pb = upper ? own + hi_off : own + stride8;
;     *(u32x4*)pa = A; *(u32x4*)pb = B;
;     __device__ __forceinline__ void operator()(const f32x4 (&acc)[2][2][4][2], const Unit& u, int wr, int wc, int fr, int fq) const {
;     ...
;         bf16_t* base = u.part == 0 ? Z + (size_t)row0 * D + col0 : P + ((size_t)(u.part - 1) * MS + (row0 - MP)) * D + col0;
; #pragma unroll
;         for (int ai = 0; ai < 2; ++ai)
; #pragma unroll
;             for (int m = 0; m < 4; ++m) { u32x4 w[2];
; #pragma unroll
;                 for (int bj = 0; bj < 2; ++bj) { const f32x4 v0 = acc[ai][bj][m][0], v1 = acc[ai][bj][m][1]; w[bj].x = pk2(v0[0], v0[1]); w[bj].y = pk2(v0[2], v0[3]); w[bj].z = pk2(v1[0], v1[1]); w[bj].w = pk2(v1[2], v1[3]); }
;                 store_pair((unsigned char*)(base + (size_t)(ai * 128 + m * 16) * D), (size_t)8 * D * 2, 64, w[0], w[1], fr >= 8); }
.LBB0_2331:
	global_store_dwordx4 v[122:123], v[118:121], off
	global_store_dwordx4 v[124:125], v[114:117], off
	v_lshl_add_u64 v[106:107], v[142:143], 0, s[16:17]
	v_mov_b32_dpp v104, v110 row_ror:8 row_mask:0xf bank_mask:0xf bound_ctrl:1
	v_mov_b32_dpp v105, v111 row_ror:8 row_mask:0xf bank_mask:0xf bound_ctrl:1
	v_mov_b32_dpp v100, v112 row_ror:8 row_mask:0xf bank_mask:0xf bound_ctrl:1
	v_mov_b32_dpp v101, v113 row_ror:8 row_mask:0xf bank_mask:0xf bound_ctrl:1
	v_mov_b32_dpp v114, v102 row_ror:8 row_mask:0xf bank_mask:0xf bound_ctrl:1
	v_mov_b32_dpp v115, v103 row_ror:8 row_mask:0xf bank_mask:0xf bound_ctrl:1
	v_mov_b32_dpp v116, v98 row_ror:8 row_mask:0xf bank_mask:0xf bound_ctrl:1
	v_mov_b32_dpp v117, v99 row_ror:8 row_mask:0xf bank_mask:0xf bound_ctrl:1
	v_lshl_add_u64 v[108:109], v[106:107], 0, v[134:135]
	v_cndmask_b32_e64 v101, v101, v99, s[2:3]
	v_cndmask_b32_e64 v100, v100, v98, s[2:3]
	v_cndmask_b32_e64 v99, v105, v103, s[2:3]
	v_cndmask_b32_e64 v98, v104, v102, s[2:3]
	v_cndmask_b32_e64 v105, v113, v117, s[2:3]
	v_cndmask_b32_e64 v104, v112, v116, s[2:3]
	v_cndmask_b32_e64 v103, v111, v115, s[2:3]
	v_cndmask_b32_e64 v102, v110, v114, s[2:3]
	v_cvt_pk_bf16_f32 v94, v94, v95
	v_cvt_pk_bf16_f32 v95, v96, v97
	v_cvt_pk_bf16_f32 v96, v90, v91
	v_cvt_pk_bf16_f32 v97, v92, v93
	v_cvt_pk_bf16_f32 v86, v86, v87
	v_cvt_pk_bf16_f32 v87, v88, v89
	v_cvt_pk_bf16_f32 v82, v82, v83
	v_cvt_pk_bf16_f32 v83, v84, v85
	v_lshl_add_u64 v[106:107], v[106:107], 0, v[136:137]
	global_store_dwordx4 v[108:109], v[102:105], off
	global_store_dwordx4 v[106:107], v[98:101], off
	v_lshl_add_u64 v[90:91], v[142:143], 0, s[18:19]
	v_mov_b32_dpp v88, v94 row_ror:8 row_mask:0xf bank_mask:0xf bound_ctrl:1
	v_mov_b32_dpp v89, v95 row_ror:8 row_mask:0xf bank_mask:0xf bound_ctrl:1
	v_mov_b32_dpp v84, v96 row_ror:8 row_mask:0xf bank_mask:0xf bound_ctrl:1
	v_mov_b32_dpp v85, v97 row_ror:8 row_mask:0xf bank_mask:0xf bound_ctrl:1
	v_mov_b32_dpp v98, v86 row_ror:8 row_mask:0xf bank_mask:0xf bound_ctrl:1
	v_mov_b32_dpp v99, v87 row_ror:8 row_mask:0xf bank_mask:0xf bound_ctrl:1
	v_mov_b32_dpp v100, v82 row_ror:8 row_mask:0xf bank_mask:0xf bound_ctrl:1
	v_mov_b32_dpp v101, v83 row_ror:8 row_mask:0xf bank_mask:0xf bound_ctrl:1
	v_lshl_add_u64 v[92:93], v[90:91], 0, v[134:135]
	v_cndmask_b32_e64 v85, v85, v83, s[2:3]
	v_cndmask_b32_e64 v84, v84, v82, s[2:3]
	v_cndmask_b32_e64 v83, v89, v87, s[2:3]
	v_cndmask_b32_e64 v82, v88, v86, s[2:3]
	v_cndmask_b32_e64 v89, v97, v101, s[2:3]
	v_cndmask_b32_e64 v88, v96, v100, s[2:3]
	v_cndmask_b32_e64 v87, v95, v99, s[2:3]
	v_cndmask_b32_e64 v86, v94, v98, s[2:3]
	v_cvt_pk_bf16_f32 v78, v78, v79
	v_cvt_pk_bf16_f32 v79, v80, v81
	v_cvt_pk_bf16_f32 v80, v74, v75
	v_cvt_pk_bf16_f32 v81, v76, v77
	v_cvt_pk_bf16_f32 v70, v70, v71
	v_cvt_pk_bf16_f32 v71, v72, v73
	v_cvt_pk_bf16_f32 v66, v66, v67
	v_cvt_pk_bf16_f32 v67, v68, v69
	v_lshl_add_u64 v[90:91], v[90:91], 0, v[136:137]
	global_store_dwordx4 v[92:93], v[86:89], off
	global_store_dwordx4 v[90:91], v[82:85], off
	v_lshl_add_u64 v[74:75], v[142:143], 0, s[20:21]
	v_mov_b32_dpp v72, v78 row_ror:8 row_mask:0xf bank_mask:0xf bound_ctrl:1
	v_mov_b32_dpp v73, v79 row_ror:8 row_mask:0xf bank_mask:0xf bound_ctrl:1
	v_mov_b32_dpp v68, v80 row_ror:8 row_mask:0xf bank_mask:0xf bound_ctrl:1
	v_mov_b32_dpp v69, v81 row_ror:8 row_mask:0xf bank_mask:0xf bound_ctrl:1
	v_mov_b32_dpp v82, v70 row_ror:8 row_mask:0xf bank_mask:0xf bound_ctrl:1
	v_mov_b32_dpp v83, v71 row_ror:8 row_mask:0xf bank_mask:0xf bound_ctrl:1
	v_mov_b32_dpp v84, v66 row_ror:8 row_mask:0xf bank_mask:0xf bound_ctrl:1
	v_mov_b32_dpp v85, v67 row_ror:8 row_mask:0xf bank_mask:0xf bound_ctrl:1
	v_lshl_add_u64 v[76:77], v[74:75], 0, v[134:135]
	v_cndmask_b32_e64 v69, v69, v67, s[2:3]
	v_cndmask_b32_e64 v68, v68, v66, s[2:3]
	v_cndmask_b32_e64 v67, v73, v71, s[2:3]
	v_cndmask_b32_e64 v66, v72, v70, s[2:3]
	v_cndmask_b32_e64 v73, v81, v85, s[2:3]
	v_cndmask_b32_e64 v72, v80, v84, s[2:3]
	v_cndmask_b32_e64 v71, v79, v83, s[2:3]
	v_cndmask_b32_e64 v70, v78, v82, s[2:3]
	v_cvt_pk_bf16_f32 v62, v62, v63
	v_cvt_pk_bf16_f32 v63, v64, v65
	v_cvt_pk_bf16_f32 v64, v58, v59
	v_cvt_pk_bf16_f32 v65, v60, v61
	v_cvt_pk_bf16_f32 v54, v54, v55
	v_cvt_pk_bf16_f32 v55, v56, v57
	v_cvt_pk_bf16_f32 v50, v50, v51
	v_cvt_pk_bf16_f32 v51, v52, v53
	v_lshl_add_u64 v[74:75], v[74:75], 0, v[136:137]
	global_store_dwordx4 v[76:77], v[70:73], off
	global_store_dwordx4 v[74:75], v[66:69], off
	v_lshl_add_u64 v[58:59], v[142:143], 0, s[22:23]
	v_mov_b32_dpp v56, v62 row_ror:8 row_mask:0xf bank_mask:0xf bound_ctrl:1
	v_mov_b32_dpp v57, v63 row_ror:8 row_mask:0xf bank_mask:0xf bound_ctrl:1
	v_mov_b32_dpp v52, v64 row_ror:8 row_mask:0xf bank_mask:0xf bound_ctrl:1
	v_mov_b32_dpp v53, v65 row_ror:8 row_mask:0xf bank_mask:0xf bound_ctrl:1
	v_mov_b32_dpp v66, v54 row_ror:8 row_mask:0xf bank_mask:0xf bound_ctrl:1
	v_mov_b32_dpp v67, v55 row_ror:8 row_mask:0xf bank_mask:0xf bound_ctrl:1
	v_mov_b32_dpp v68, v50 row_ror:8 row_mask:0xf bank_mask:0xf bound_ctrl:1
; __device__ __forceinline__ unsigned pk2(float lo, float hi) { const f32x2 v = {lo, hi}; return __builtin_bit_cast(unsigned, __builtin_convertvector(v, bf16x2_t)); }
; __device__ __forceinline__ u32x4 ror8(u32x4 v) { u32x4 r;
; #pragma unroll
;     for (int i = 0; i < 4; ++i) r[i] = (unsigned)__builtin_amdgcn_mov_dpp((int)v[i], 0x128, 0xf, 0xf, true);
;     return r; }
; __device__ __forceinline__ void store_pair(unsigned char* own, size_t stride8, int hi_off, u32x4 lo, u32x4 hi, bool upper) {
;     const u32x4 tlo = ror8(lo), thi = ror8(hi);
;     const u32x4 A = upper ? thi : lo, B = upper ? hi : tlo;
;     unsigned char* pa = upper ? own - stride8 + hi_off : own;
;     unsigned char* pb = upper ? own + hi_off : own + stride8;
;     *(u32x4*)pa = A; *(u32x4*)pb = B;
;     __device__ __forceinline__ void operator()(const f32x4 (&acc)[2][2][4][2], const Unit& u, int wr, int wc, int fr, int fq) const {
;     ...
;         for (int ai = 0; ai < 2; ++ai)
; #pragma unroll
;             for (int m = 0; m < 4; ++m) { u32x4 w[2];
; #pragma unroll
;                 for (int bj = 0; bj < 2; ++bj) { const f32x4 v0 = acc[ai][bj][m][0], v1 = acc[ai][bj][m][1]; w[bj].x = pk2(v0[0], v0[1]); w[bj].y = pk2(v0[2], v0[3]); w[bj].z = pk2(v1[0], v1[1]); w[bj].w = pk2(v1[2], v1[3]); }
;                 store_pair((unsigned char*)(base + (size_t)(ai * 128 + m * 16) * D), (size_t)8 * D * 2, 64, w[0], w[1], fr >= 8); }
	v_mov_b32_dpp v69, v51 row_ror:8 row_mask:0xf bank_mask:0xf bound_ctrl:1
	v_lshl_add_u64 v[60:61], v[58:59], 0, v[134:135]
	v_cndmask_b32_e64 v53, v53, v51, s[2:3]
	v_cndmask_b32_e64 v52, v52, v50, s[2:3]
	v_cndmask_b32_e64 v51, v57, v55, s[2:3]
	v_cndmask_b32_e64 v50, v56, v54, s[2:3]
	v_cndmask_b32_e64 v57, v65, v69, s[2:3]
	v_cndmask_b32_e64 v56, v64, v68, s[2:3]
	v_cndmask_b32_e64 v55, v63, v67, s[2:3]
	v_cndmask_b32_e64 v54, v62, v66, s[2:3]
	v_cvt_pk_bf16_f32 v46, v46, v47
	v_cvt_pk_bf16_f32 v47, v48, v49
	v_cvt_pk_bf16_f32 v48, v42, v43
	v_cvt_pk_bf16_f32 v49, v44, v45
	v_cvt_pk_bf16_f32 v38, v38, v39
	v_cvt_pk_bf16_f32 v39, v40, v41
	v_cvt_pk_bf16_f32 v34, v34, v35
	v_cvt_pk_bf16_f32 v35, v36, v37
	v_lshl_add_u64 v[58:59], v[58:59], 0, v[136:137]
	global_store_dwordx4 v[60:61], v[54:57], off
	global_store_dwordx4 v[58:59], v[50:53], off
	v_lshl_add_u64 v[42:43], v[142:143], 0, s[24:25]
	v_mov_b32_dpp v40, v46 row_ror:8 row_mask:0xf bank_mask:0xf bound_ctrl:1
	v_mov_b32_dpp v41, v47 row_ror:8 row_mask:0xf bank_mask:0xf bound_ctrl:1
	v_mov_b32_dpp v36, v48 row_ror:8 row_mask:0xf bank_mask:0xf bound_ctrl:1
	v_mov_b32_dpp v37, v49 row_ror:8 row_mask:0xf bank_mask:0xf bound_ctrl:1
	v_mov_b32_dpp v50, v38 row_ror:8 row_mask:0xf bank_mask:0xf bound_ctrl:1
	v_mov_b32_dpp v51, v39 row_ror:8 row_mask:0xf bank_mask:0xf bound_ctrl:1
	v_mov_b32_dpp v52, v34 row_ror:8 row_mask:0xf bank_mask:0xf bound_ctrl:1
	v_mov_b32_dpp v53, v35 row_ror:8 row_mask:0xf bank_mask:0xf bound_ctrl:1
	v_lshl_add_u64 v[44:45], v[42:43], 0, v[134:135]
	v_cndmask_b32_e64 v37, v37, v35, s[2:3]
	v_cndmask_b32_e64 v36, v36, v34, s[2:3]
	v_cndmask_b32_e64 v35, v41, v39, s[2:3]
	v_cndmask_b32_e64 v34, v40, v38, s[2:3]
	v_cndmask_b32_e64 v41, v49, v53, s[2:3]
	v_cndmask_b32_e64 v40, v48, v52, s[2:3]
	v_cndmask_b32_e64 v39, v47, v51, s[2:3]
	v_cndmask_b32_e64 v38, v46, v50, s[2:3]
	v_cvt_pk_bf16_f32 v30, v30, v31
	v_cvt_pk_bf16_f32 v31, v32, v33
	v_cvt_pk_bf16_f32 v32, v26, v27
	v_cvt_pk_bf16_f32 v33, v28, v29
	v_cvt_pk_bf16_f32 v22, v22, v23
	v_cvt_pk_bf16_f32 v23, v24, v25
	v_cvt_pk_bf16_f32 v18, v18, v19
	v_cvt_pk_bf16_f32 v19, v20, v21
	v_lshl_add_u64 v[42:43], v[42:43], 0, v[136:137]
	global_store_dwordx4 v[44:45], v[38:41], off
	global_store_dwordx4 v[42:43], v[34:37], off
	v_lshl_add_u64 v[26:27], v[142:143], 0, s[26:27]
	v_mov_b32_dpp v24, v30 row_ror:8 row_mask:0xf bank_mask:0xf bound_ctrl:1
	v_mov_b32_dpp v25, v31 row_ror:8 row_mask:0xf bank_mask:0xf bound_ctrl:1
	v_mov_b32_dpp v20, v32 row_ror:8 row_mask:0xf bank_mask:0xf bound_ctrl:1
	v_mov_b32_dpp v21, v33 row_ror:8 row_mask:0xf bank_mask:0xf bound_ctrl:1
	v_mov_b32_dpp v34, v22 row_ror:8 row_mask:0xf bank_mask:0xf bound_ctrl:1
	v_mov_b32_dpp v35, v23 row_ror:8 row_mask:0xf bank_mask:0xf bound_ctrl:1
	v_mov_b32_dpp v36, v18 row_ror:8 row_mask:0xf bank_mask:0xf bound_ctrl:1
	v_mov_b32_dpp v37, v19 row_ror:8 row_mask:0xf bank_mask:0xf bound_ctrl:1
	v_lshl_add_u64 v[28:29], v[26:27], 0, v[134:135]
	v_cndmask_b32_e64 v21, v21, v19, s[2:3]
	v_cndmask_b32_e64 v20, v20, v18, s[2:3]
	v_cndmask_b32_e64 v19, v25, v23, s[2:3]
	v_cndmask_b32_e64 v18, v24, v22, s[2:3]
	v_cndmask_b32_e64 v25, v33, v37, s[2:3]
	v_cndmask_b32_e64 v24, v32, v36, s[2:3]
	v_cndmask_b32_e64 v23, v31, v35, s[2:3]
	v_cndmask_b32_e64 v22, v30, v34, s[2:3]
	v_cvt_pk_bf16_f32 v14, v14, v15
	v_cvt_pk_bf16_f32 v15, v16, v17
	v_cvt_pk_bf16_f32 v16, v10, v11
	v_cvt_pk_bf16_f32 v17, v12, v13
	v_cvt_pk_bf16_f32 v6, v6, v7
	v_cvt_pk_bf16_f32 v7, v8, v9
	v_cvt_pk_bf16_f32 v2, v2, v3
	v_cvt_pk_bf16_f32 v3, v4, v5
	v_lshl_add_u64 v[26:27], v[26:27], 0, v[136:137]
	global_store_dwordx4 v[28:29], v[22:25], off
	global_store_dwordx4 v[26:27], v[18:21], off
	v_lshl_add_u64 v[10:11], v[142:143], 0, s[28:29]
	v_mov_b32_dpp v8, v14 row_ror:8 row_mask:0xf bank_mask:0xf bound_ctrl:1
	v_mov_b32_dpp v9, v15 row_ror:8 row_mask:0xf bank_mask:0xf bound_ctrl:1
	v_mov_b32_dpp v4, v16 row_ror:8 row_mask:0xf bank_mask:0xf bound_ctrl:1
	v_mov_b32_dpp v5, v17 row_ror:8 row_mask:0xf bank_mask:0xf bound_ctrl:1
	v_mov_b32_dpp v18, v6 row_ror:8 row_mask:0xf bank_mask:0xf bound_ctrl:1
	v_mov_b32_dpp v19, v7 row_ror:8 row_mask:0xf bank_mask:0xf bound_ctrl:1
	v_mov_b32_dpp v20, v2 row_ror:8 row_mask:0xf bank_mask:0xf bound_ctrl:1
	v_mov_b32_dpp v21, v3 row_ror:8 row_mask:0xf bank_mask:0xf bound_ctrl:1
	v_lshl_add_u64 v[12:13], v[10:11], 0, v[134:135]
	v_cndmask_b32_e64 v5, v5, v3, s[2:3]
	v_cndmask_b32_e64 v4, v4, v2, s[2:3]
	v_cndmask_b32_e64 v3, v9, v7, s[2:3]
	v_cndmask_b32_e64 v2, v8, v6, s[2:3]
	v_cndmask_b32_e64 v9, v17, v21, s[2:3]
	v_cndmask_b32_e64 v8, v16, v20, s[2:3]
	v_cndmask_b32_e64 v7, v15, v19, s[2:3]
	v_cndmask_b32_e64 v6, v14, v18, s[2:3]
	s_and_b64 vcc, exec, s[6:7]
	s_mov_b64 s[6:7], -1
	v_lshl_add_u64 v[10:11], v[10:11], 0, v[136:137]
	global_store_dwordx4 v[12:13], v[6:9], off
	global_store_dwordx4 v[10:11], v[2:5], off
	s_cbranch_vccnz .LBB0_2326
	s_andn2_b64 vcc, exec, s[10:11]
	s_cbranch_vccnz .LBB0_2325
	s_barrier
	s_branch .LBB0_2325
